# speedup vs baseline: 1.0005x; 1.0005x over previous
;     DI size_t aoff(const Unit& u, size_t tstep) const { return (size_t)u.pm * tstep; }
;     DI size_t boff(const Unit& u, size_t tstep) const { return (size_t)u.pn * tstep; }
;     DI bool next(int i, Unit& u) const { const long L = (long)i * G + c; if (L >= np) return false; u.pm = pmv; u.pn = (int)(L % nN); u.ks = (int)(L / nN); return true; }
;     DI size_t aoff(const Unit& u, size_t) const { return (size_t)u.ks * kbytes; }
;     DI size_t boff(const Unit& u, size_t tstep) const { return (size_t)u.pn * tstep + (size_t)u.ks * kbytes; }
;     DI bool next(int i, Unit& u) const { Unit t; if (!S.next(i / 3, t)) return false; u.pm = t.pm; u.pn = t.pn; u.ks = i % 3; return true; }
;     DI size_t aoff(const Unit& u, size_t tstep) const { return (u.ks < 2 ? offU : offOA) + (size_t)u.pm * tstep; }
; #define PG8_LDA(dst, b, h) do { _Pragma("unroll") for (int m = 0; m < 4; ++m) _Pragma("unroll") for (int k = 0; k < 2; ++k) dst[m][k] = *(const LAS bf16x8*)(lds + PG8_SA(b, h) + aoff + m * 2048 + k * 1024); } while (0)
; template <class Epi, class Sched>
; DI void gemm_phase(LAS unsigned char* lds, const Gemm g, const Sched& S, const Epi& E) {
;     ...
;         const bool has_next = S.next(ui + 1, nxt);
;         const char* nA = has_next ? (const char*)g.A + S.aoff(nxt, tstep) : cA; const char* nB = has_next ? (const char*)g.Bt + S.boff(nxt, tstep) : cB;
;         for (int t = 0; t < nt; t += 2) {
;             if constexpr (Epi::HAS_MID) { if (t == E.mid_t(nt)) { int fr3 = fr, fq3 = fq; asm volatile("" : "+v"(fr3), "+v"(fq3)); E.mid(acc, cur, wr, wc, fr3, fq3); } }
;             const bool last = (t == nt - 2);
;             const char* a1 = cA + (size_t)(t + 1) * kstep;
;             const char* a2 = last ? nA : cA + (size_t)(t + 2) * kstep; const char* b2 = last ? nB : cB + (size_t)(t + 2) * kstep;
;             const char* a3 = a2 + kstep; const char* b3 = b2 + kstep;
;             PG8_LDB(B0, 0, 0); PG8_SCHED; PG8_LDA(At, 0, 0); PG8_STAGE(PG8_SA(1, 1), a1 + hstep, voffA);
;             PG8_WAIT_L(8); PG8_BAR; PG8_WAIT_L(0); PG8_MMA(0, 0, At, B0); PG8_BAR; PG8_SCHED;
;             PG8_LDB(B1, 0, 1); PG8_STAGE(PG8_SB(0, 0), b2, voffB);
;             PG8_BAR; PG8_WAIT_L(0); PG8_MMA(0, 1, At, B1); PG8_BAR;
;             PG8_LDA(At, 0, 1); PG8_STAGE(PG8_SA(0, 0), a2, voffA);
;             PG8_BAR; PG8_WAIT_L(0); PG8_MMA(1, 0, At, B0); PG8_BAR; PG8_SCHED;
.LBB0_218:
	s_ashr_i32 s17, s16, 31
	s_lshl_b64 s[0:1], s[16:17], 20
	v_cmp_lt_i64_e32 vcc, s[18:19], v[140:141]
	s_add_u32 s18, s47, s0
	s_addc_u32 s19, s48, s1
	s_and_b64 s[0:1], vcc, exec
	s_cselect_b32 s17, s19, s41
	s_cselect_b32 s65, s18, s40
	s_ashr_i32 s15, s14, 31
	s_lshl_b64 s[0:1], s[14:15], 20
	s_add_u32 s36, s49, s0
	s_addc_u32 s37, s50, s1
	s_and_b64 s[0:1], vcc, exec
	s_cselect_b32 s15, s37, s43
	s_cselect_b32 s66, s36, s42
	s_add_u32 s40, s40, 0x80080
	s_addc_u32 s41, s41, 0
	s_add_u32 s67, s42, 0x100
	v_mov_b32_e32 v0, 0
	s_addc_u32 s68, s43, 0
	s_mov_b32 s69, -2
	ds_read_b128 v[150:153], v147
	ds_read_b128 v[154:157], v147 offset:1024
	ds_read_b128 v[162:165], v147 offset:2048
	ds_read_b128 v[166:169], v147 offset:3072
	s_add_i32 m0, s39, 0xc000
	ds_read_b128 v[170:173], v148
	ds_read_b128 v[174:177], v148 offset:1024
	ds_read_b128 v[178:181], v148 offset:2048
	ds_read_b128 v[188:191], v148 offset:3072
	ds_read_b128 v[194:197], v148 offset:4096
	ds_read_b128 v[198:201], v148 offset:5120
	ds_read_b128 v[202:205], v148 offset:6144
	global_load_lds_dwordx4 v136, s[40:41]
	s_add_i32 m0, s39, 0xe000
	ds_read_b128 v[206:209], v148 offset:7168
	global_load_lds_dwordx4 v138, s[40:41]
	s_add_u32 s0, s40, 0xfff80080
	s_addc_u32 s1, s41, -1
	s_cmp_eq_u32 s69, 28
	s_cselect_b32 s45, s17, s1
	s_cselect_b32 s44, s65, s0
	s_cselect_b32 s43, s15, s68
	s_cselect_b32 s42, s66, s67
	s_waitcnt lgkmcnt(8)
	s_barrier
	s_waitcnt lgkmcnt(0)
	s_setprio 1
	v_mfma_f32_16x16x32_bf16 v[124:127], v[150:153], v[170:173], 0
	v_mfma_f32_16x16x32_bf16 v[120:123], v[162:165], v[170:173], 0
	v_mfma_f32_16x16x32_bf16 v[108:111], v[150:153], v[178:181], 0
	v_mfma_f32_16x16x32_bf16 v[104:107], v[162:165], v[178:181], 0
	v_mfma_f32_16x16x32_bf16 v[92:95], v[150:153], v[194:197], 0
	v_mfma_f32_16x16x32_bf16 v[88:91], v[162:165], v[194:197], 0
	v_mfma_f32_16x16x32_bf16 v[76:79], v[150:153], v[202:205], 0
	v_mfma_f32_16x16x32_bf16 v[72:75], v[162:165], v[202:205], 0
	v_mfma_f32_16x16x32_bf16 v[124:127], v[154:157], v[174:177], v[124:127]
	v_mfma_f32_16x16x32_bf16 v[120:123], v[166:169], v[174:177], v[120:123]
	v_mfma_f32_16x16x32_bf16 v[108:111], v[154:157], v[188:191], v[108:111]
	v_mfma_f32_16x16x32_bf16 v[104:107], v[166:169], v[188:191], v[104:107]
	v_mfma_f32_16x16x32_bf16 v[92:95], v[154:157], v[198:201], v[92:95]
	v_mfma_f32_16x16x32_bf16 v[88:91], v[166:169], v[198:201], v[88:91]
	v_mfma_f32_16x16x32_bf16 v[76:79], v[154:157], v[206:209], v[76:79]
	v_mfma_f32_16x16x32_bf16 v[72:75], v[166:169], v[206:209], v[72:75]
	s_setprio 0
	s_barrier
	s_add_i32 s0, s34, s52
	s_mov_b32 m0, s0
	ds_read_b128 v[210:213], v149
	ds_read_b128 v[214:217], v149 offset:1024
	ds_read_b128 v[218:221], v149 offset:2048
	global_load_lds_dwordx4 v130, s[42:43]
	s_add_i32 m0, s0, 0x2000
	ds_read_b128 v[222:225], v149 offset:3072
	global_load_lds_dwordx4 v134, s[42:43]
	s_barrier
	s_waitcnt lgkmcnt(0)
	s_setprio 1
	v_mfma_f32_16x16x32_bf16 v[116:119], v[210:213], v[170:173], 0
	v_mfma_f32_16x16x32_bf16 v[112:115], v[218:221], v[170:173], 0
	v_mfma_f32_16x16x32_bf16 v[100:103], v[210:213], v[178:181], 0
	v_mfma_f32_16x16x32_bf16 v[96:99], v[218:221], v[178:181], 0
	v_mfma_f32_16x16x32_bf16 v[84:87], v[210:213], v[194:197], 0
	v_mfma_f32_16x16x32_bf16 v[80:83], v[218:221], v[194:197], 0
	v_mfma_f32_16x16x32_bf16 v[68:71], v[210:213], v[202:205], 0
	v_mfma_f32_16x16x32_bf16 v[64:67], v[218:221], v[202:205], 0
	v_mfma_f32_16x16x32_bf16 v[116:119], v[214:217], v[174:177], v[116:119]
	v_mfma_f32_16x16x32_bf16 v[112:115], v[222:225], v[174:177], v[112:115]
	v_mfma_f32_16x16x32_bf16 v[100:103], v[214:217], v[188:191], v[100:103]
	v_mfma_f32_16x16x32_bf16 v[96:99], v[222:225], v[188:191], v[96:99]
	v_mfma_f32_16x16x32_bf16 v[84:87], v[214:217], v[198:201], v[84:87]
	v_mfma_f32_16x16x32_bf16 v[80:83], v[222:225], v[198:201], v[80:83]
	v_mfma_f32_16x16x32_bf16 v[68:71], v[214:217], v[206:209], v[68:71]
	v_mfma_f32_16x16x32_bf16 v[64:67], v[222:225], v[206:209], v[64:67]
	s_setprio 0
	s_mov_b32 m0, s39
	s_barrier
	ds_read_b128 v[170:173], v148 offset:16384
	ds_read_b128 v[174:177], v148 offset:17408
	ds_read_b128 v[178:181], v148 offset:18432
	ds_read_b128 v[188:191], v148 offset:19456
	ds_read_b128 v[194:197], v148 offset:20480
	ds_read_b128 v[198:201], v148 offset:21504
	ds_read_b128 v[202:205], v148 offset:22528
	global_load_lds_dwordx4 v128, s[44:45]
	s_mov_b32 m0, s53
	ds_read_b128 v[206:209], v148 offset:23552
	global_load_lds_dwordx4 v132, s[44:45]
	s_barrier
	s_waitcnt lgkmcnt(0)
	s_setprio 1
	v_mfma_f32_16x16x32_bf16 v[60:63], v[150:153], v[170:173], 0
	v_mfma_f32_16x16x32_bf16 v[56:59], v[162:165], v[170:173], 0
	v_mfma_f32_16x16x32_bf16 v[44:47], v[150:153], v[178:181], 0
	v_mfma_f32_16x16x32_bf16 v[40:43], v[162:165], v[178:181], 0
	v_mfma_f32_16x16x32_bf16 v[28:31], v[150:153], v[194:197], 0
	v_mfma_f32_16x16x32_bf16 v[24:27], v[162:165], v[194:197], 0
	v_mfma_f32_16x16x32_bf16 v[12:15], v[150:153], v[202:205], 0
	v_mfma_f32_16x16x32_bf16 v[8:11], v[162:165], v[202:205], 0
	v_mfma_f32_16x16x32_bf16 v[60:63], v[154:157], v[174:177], v[60:63]
	v_mfma_f32_16x16x32_bf16 v[56:59], v[166:169], v[174:177], v[56:59]
	v_mfma_f32_16x16x32_bf16 v[44:47], v[154:157], v[188:191], v[44:47]
	v_mfma_f32_16x16x32_bf16 v[40:43], v[166:169], v[188:191], v[40:43]
	v_mfma_f32_16x16x32_bf16 v[28:31], v[154:157], v[198:201], v[28:31]
	v_mfma_f32_16x16x32_bf16 v[24:27], v[166:169], v[198:201], v[24:27]
	v_mfma_f32_16x16x32_bf16 v[12:15], v[154:157], v[206:209], v[12:15]
	v_mfma_f32_16x16x32_bf16 v[8:11], v[166:169], v[206:209], v[8:11]
	s_setprio 0
	s_barrier
; #define PG8_STAGE(bufoff, gbase, voff) do { _Pragma("unroll") for (int _i = 0; _i < 2; ++_i) \
;         __builtin_amdgcn_global_load_lds((const unsigned*)((const char*)(gbase) + (voff)[_i]), (LAS unsigned*)(lds + (bufoff) + ldsw + _i * 8192), 16, 0, 0); } while (0)
; #define PG8_LDA(dst, b, h) do { _Pragma("unroll") for (int m = 0; m < 4; ++m) _Pragma("unroll") for (int k = 0; k < 2; ++k) dst[m][k] = *(const LAS bf16x8*)(lds + PG8_SA(b, h) + aoff + m * 2048 + k * 1024); } while (0)
; #define PG8_LDB(dst, b, h) do { _Pragma("unroll") for (int n = 0; n < 2; ++n) _Pragma("unroll") for (int k = 0; k < 2; ++k) dst[n][k] = *(const LAS bf16x8*)(lds + PG8_SB(b, h) + boff + n * 2048 + k * 1024); } while (0)
; #define PG8_MMA(ai, bj, At, Bt) do { __builtin_amdgcn_s_setprio(1); _Pragma("unroll") for (int m = 0; m < 4; ++m) _Pragma("unroll") for (int n = 0; n < 2; ++n) _Pragma("unroll") for (int k = 0; k < 2; ++k) \
;         acc[ai][bj][m][n] = __builtin_amdgcn_mfma_f32_16x16x32_bf16(Bt[n][k], At[m][k], acc[ai][bj][m][n], 0, 0, 0); __builtin_amdgcn_s_setprio(0); } while (0)
; #define PG8_WAIT_V(n) asm volatile("s_waitcnt vmcnt(" #n ")" ::: "memory")
; #define PG8_WAIT_L(n) asm volatile("s_waitcnt lgkmcnt(" #n ")" ::: "memory")
; #define PG8_BAR __builtin_amdgcn_s_barrier()
; #define PG8_SCHED __builtin_amdgcn_sched_barrier(0)
; template <class Epi, class Sched>
; DI void gemm_phase(LAS unsigned char* lds, const Gemm g, const Sched& S, const Epi& E) {
;     ...
;             PG8_STAGE(PG8_SB(0, 1), b2 + hstep, voffB);
;             PG8_WAIT_V(6); PG8_BAR; PG8_MMA(1, 1, At, B1); PG8_BAR;
;             PG8_LDB(B0, 1, 0); PG8_SCHED; PG8_LDA(At, 1, 0); PG8_STAGE(PG8_SA(0, 1), a2 + hstep, voffA);
;             PG8_WAIT_L(8); PG8_BAR; PG8_WAIT_L(0); PG8_MMA(0, 0, At, B0); PG8_BAR; PG8_SCHED;
;             PG8_LDB(B1, 1, 1); PG8_STAGE(PG8_SB(1, 0), b3, voffB);
	s_add_i32 s4, s35, s52
	s_mov_b32 m0, s4
	s_add_u32 s0, s42, 0x80000
	s_addc_u32 s1, s43, 0
	global_load_lds_dwordx4 v130, s[0:1]
	s_add_i32 m0, s4, 0x2000
	s_add_i32 s4, 0, 0x18000
	global_load_lds_dwordx4 v134, s[0:1]
	s_waitcnt vmcnt(6)
	s_barrier
	s_setprio 1
	v_mfma_f32_16x16x32_bf16 v[52:55], v[210:213], v[170:173], 0
	v_mfma_f32_16x16x32_bf16 v[48:51], v[218:221], v[170:173], 0
	v_mfma_f32_16x16x32_bf16 v[36:39], v[210:213], v[178:181], 0
	v_mfma_f32_16x16x32_bf16 v[32:35], v[218:221], v[178:181], 0
	v_mfma_f32_16x16x32_bf16 v[20:23], v[210:213], v[194:197], 0
	v_mfma_f32_16x16x32_bf16 v[16:19], v[218:221], v[194:197], 0
	v_mfma_f32_16x16x32_bf16 v[4:7], v[210:213], v[202:205], 0
	v_mfma_f32_16x16x32_bf16 v[0:3], v[218:221], v[202:205], 0
	v_mfma_f32_16x16x32_bf16 v[52:55], v[214:217], v[174:177], v[52:55]
	v_mfma_f32_16x16x32_bf16 v[48:51], v[222:225], v[174:177], v[48:51]
	v_mfma_f32_16x16x32_bf16 v[36:39], v[214:217], v[188:191], v[36:39]
	v_mfma_f32_16x16x32_bf16 v[32:35], v[222:225], v[188:191], v[32:35]
	v_mfma_f32_16x16x32_bf16 v[20:23], v[214:217], v[198:201], v[20:23]
	v_mfma_f32_16x16x32_bf16 v[16:19], v[222:225], v[198:201], v[16:19]
	v_mfma_f32_16x16x32_bf16 v[4:7], v[214:217], v[206:209], v[4:7]
	v_mfma_f32_16x16x32_bf16 v[0:3], v[222:225], v[206:209], v[0:3]
	s_setprio 0
	v_add_u32_e32 v158, s4, v146
	s_barrier
	ds_read_b128 v[150:153], v158
	ds_read_b128 v[154:157], v158 offset:1024
	ds_read_b128 v[162:165], v158 offset:2048
	ds_read_b128 v[166:169], v158 offset:3072
	s_add_u32 s0, s44, 0x80000
	s_addc_u32 s1, s45, 0
	s_mov_b32 m0, s54
	ds_read_b128 v[170:173], v148 offset:32768
	ds_read_b128 v[174:177], v148 offset:33792
	ds_read_b128 v[178:181], v148 offset:34816
	ds_read_b128 v[188:191], v148 offset:35840
	ds_read_b128 v[194:197], v148 offset:36864
	ds_read_b128 v[198:201], v148 offset:37888
	ds_read_b128 v[202:205], v148 offset:38912
	global_load_lds_dwordx4 v128, s[0:1]
	s_mov_b32 m0, s55
	ds_read_b128 v[206:209], v148 offset:39936
	global_load_lds_dwordx4 v132, s[0:1]
	s_waitcnt lgkmcnt(8)
	s_barrier
	s_waitcnt lgkmcnt(0)
	s_setprio 1
	v_mfma_f32_16x16x32_bf16 v[124:127], v[150:153], v[170:173], v[124:127]
	v_mfma_f32_16x16x32_bf16 v[120:123], v[162:165], v[170:173], v[120:123]
	v_mfma_f32_16x16x32_bf16 v[108:111], v[150:153], v[178:181], v[108:111]
	v_mfma_f32_16x16x32_bf16 v[104:107], v[162:165], v[178:181], v[104:107]
	v_mfma_f32_16x16x32_bf16 v[92:95], v[150:153], v[194:197], v[92:95]
	v_mfma_f32_16x16x32_bf16 v[88:91], v[162:165], v[194:197], v[88:91]
	v_mfma_f32_16x16x32_bf16 v[76:79], v[150:153], v[202:205], v[76:79]
	v_mfma_f32_16x16x32_bf16 v[72:75], v[162:165], v[202:205], v[72:75]
	v_mfma_f32_16x16x32_bf16 v[124:127], v[154:157], v[174:177], v[124:127]
	v_mfma_f32_16x16x32_bf16 v[120:123], v[166:169], v[174:177], v[120:123]
	v_mfma_f32_16x16x32_bf16 v[108:111], v[154:157], v[188:191], v[108:111]
	v_mfma_f32_16x16x32_bf16 v[104:107], v[166:169], v[188:191], v[104:107]
	v_mfma_f32_16x16x32_bf16 v[92:95], v[154:157], v[198:201], v[92:95]
	v_mfma_f32_16x16x32_bf16 v[88:91], v[166:169], v[198:201], v[88:91]
	v_mfma_f32_16x16x32_bf16 v[76:79], v[154:157], v[206:209], v[76:79]
	v_mfma_f32_16x16x32_bf16 v[72:75], v[166:169], v[206:209], v[72:75]
	s_setprio 0
	s_barrier
	s_add_i32 s5, 0, 0x1c000
	s_add_i32 s0, s4, s52
	v_add_u32_e32 v159, s5, v146
	s_add_i32 m0, s0, 0xffffff80
	ds_read_b128 v[210:213], v159
	ds_read_b128 v[214:217], v159 offset:1024
	ds_read_b128 v[218:221], v159 offset:2048
	global_load_lds_dwordx4 v130, s[42:43] offset:128
	s_add_i32 m0, s0, 0x1f80
	ds_read_b128 v[222:225], v159 offset:3072
	global_load_lds_dwordx4 v134, s[42:43] offset:128
	s_barrier
; #define PG8_STAGE(bufoff, gbase, voff) do { _Pragma("unroll") for (int _i = 0; _i < 2; ++_i) \
;         __builtin_amdgcn_global_load_lds((const unsigned*)((const char*)(gbase) + (voff)[_i]), (LAS unsigned*)(lds + (bufoff) + ldsw + _i * 8192), 16, 0, 0); } while (0)
; #define PG8_LDA(dst, b, h) do { _Pragma("unroll") for (int m = 0; m < 4; ++m) _Pragma("unroll") for (int k = 0; k < 2; ++k) dst[m][k] = *(const LAS bf16x8*)(lds + PG8_SA(b, h) + aoff + m * 2048 + k * 1024); } while (0)
; #define PG8_MMA(ai, bj, At, Bt) do { __builtin_amdgcn_s_setprio(1); _Pragma("unroll") for (int m = 0; m < 4; ++m) _Pragma("unroll") for (int n = 0; n < 2; ++n) _Pragma("unroll") for (int k = 0; k < 2; ++k) \
;         acc[ai][bj][m][n] = __builtin_amdgcn_mfma_f32_16x16x32_bf16(Bt[n][k], At[m][k], acc[ai][bj][m][n], 0, 0, 0); __builtin_amdgcn_s_setprio(0); } while (0)
; #define PG8_WAIT_V(n) asm volatile("s_waitcnt vmcnt(" #n ")" ::: "memory")
; #define PG8_WAIT_L(n) asm volatile("s_waitcnt lgkmcnt(" #n ")" ::: "memory")
; #define PG8_BAR __builtin_amdgcn_s_barrier()
; #define PG8_SCHED __builtin_amdgcn_sched_barrier(0)
; template <class Epi, class Sched>
; DI void gemm_phase(LAS unsigned char* lds, const Gemm g, const Sched& S, const Epi& E) {
;     ...
;             PG8_BAR; PG8_WAIT_L(0); PG8_MMA(0, 1, At, B1); PG8_BAR;
;             PG8_LDA(At, 1, 1); PG8_STAGE(PG8_SA(1, 0), a3, voffA);
;             PG8_BAR; PG8_WAIT_L(0); PG8_MMA(1, 0, At, B0); PG8_BAR; PG8_SCHED;
;             PG8_STAGE(PG8_SB(1, 1), b3 + hstep, voffB);
;             PG8_WAIT_V(6); PG8_BAR; PG8_MMA(1, 1, At, B1); PG8_BAR;
;         }
	s_waitcnt lgkmcnt(0)
	s_setprio 1
	v_mfma_f32_16x16x32_bf16 v[116:119], v[210:213], v[170:173], v[116:119]
	v_mfma_f32_16x16x32_bf16 v[112:115], v[218:221], v[170:173], v[112:115]
	v_mfma_f32_16x16x32_bf16 v[100:103], v[210:213], v[178:181], v[100:103]
	v_mfma_f32_16x16x32_bf16 v[96:99], v[218:221], v[178:181], v[96:99]
	v_mfma_f32_16x16x32_bf16 v[84:87], v[210:213], v[194:197], v[84:87]
	v_mfma_f32_16x16x32_bf16 v[80:83], v[218:221], v[194:197], v[80:83]
	v_mfma_f32_16x16x32_bf16 v[68:71], v[210:213], v[202:205], v[68:71]
	v_mfma_f32_16x16x32_bf16 v[64:67], v[218:221], v[202:205], v[64:67]
	v_mfma_f32_16x16x32_bf16 v[116:119], v[214:217], v[174:177], v[116:119]
	v_mfma_f32_16x16x32_bf16 v[112:115], v[222:225], v[174:177], v[112:115]
	v_mfma_f32_16x16x32_bf16 v[100:103], v[214:217], v[188:191], v[100:103]
	v_mfma_f32_16x16x32_bf16 v[96:99], v[222:225], v[188:191], v[96:99]
	v_mfma_f32_16x16x32_bf16 v[84:87], v[214:217], v[198:201], v[84:87]
	v_mfma_f32_16x16x32_bf16 v[80:83], v[222:225], v[198:201], v[80:83]
	v_mfma_f32_16x16x32_bf16 v[68:71], v[214:217], v[206:209], v[68:71]
	v_mfma_f32_16x16x32_bf16 v[64:67], v[222:225], v[206:209], v[64:67]
	s_setprio 0
	s_add_i32 m0, s59, 0xffffff80
	s_barrier
	ds_read_b128 v[170:173], v148 offset:49152
	ds_read_b128 v[174:177], v148 offset:50176
	ds_read_b128 v[178:181], v148 offset:51200
	ds_read_b128 v[188:191], v148 offset:52224
	ds_read_b128 v[194:197], v148 offset:53248
	ds_read_b128 v[198:201], v148 offset:54272
	ds_read_b128 v[202:205], v148 offset:55296
	global_load_lds_dwordx4 v128, s[44:45] offset:128
	s_add_i32 m0, s60, 0xffffff80
	ds_read_b128 v[206:209], v148 offset:56320
	global_load_lds_dwordx4 v132, s[44:45] offset:128
	s_barrier
	s_waitcnt lgkmcnt(0)
	s_setprio 1
	v_mfma_f32_16x16x32_bf16 v[60:63], v[150:153], v[170:173], v[60:63]
	v_mfma_f32_16x16x32_bf16 v[56:59], v[162:165], v[170:173], v[56:59]
	v_mfma_f32_16x16x32_bf16 v[44:47], v[150:153], v[178:181], v[44:47]
	v_mfma_f32_16x16x32_bf16 v[40:43], v[162:165], v[178:181], v[40:43]
	v_mfma_f32_16x16x32_bf16 v[28:31], v[150:153], v[194:197], v[28:31]
	v_mfma_f32_16x16x32_bf16 v[24:27], v[162:165], v[194:197], v[24:27]
	v_mfma_f32_16x16x32_bf16 v[12:15], v[150:153], v[202:205], v[12:15]
	v_mfma_f32_16x16x32_bf16 v[8:11], v[162:165], v[202:205], v[8:11]
	v_mfma_f32_16x16x32_bf16 v[60:63], v[154:157], v[174:177], v[60:63]
	v_mfma_f32_16x16x32_bf16 v[56:59], v[166:169], v[174:177], v[56:59]
	v_mfma_f32_16x16x32_bf16 v[44:47], v[154:157], v[188:191], v[44:47]
	v_mfma_f32_16x16x32_bf16 v[40:43], v[166:169], v[188:191], v[40:43]
	v_mfma_f32_16x16x32_bf16 v[28:31], v[154:157], v[198:201], v[28:31]
	v_mfma_f32_16x16x32_bf16 v[24:27], v[166:169], v[198:201], v[24:27]
	v_mfma_f32_16x16x32_bf16 v[12:15], v[154:157], v[206:209], v[12:15]
	v_mfma_f32_16x16x32_bf16 v[8:11], v[166:169], v[206:209], v[8:11]
	s_setprio 0
	s_barrier
	s_add_i32 s4, s5, s52
	s_mov_b32 m0, s4
	s_add_u32 s0, s42, 0x80080
	s_addc_u32 s1, s43, 0
	global_load_lds_dwordx4 v130, s[0:1]
	s_add_i32 m0, s4, 0x2000
	s_add_i32 s69, s69, 2
	global_load_lds_dwordx4 v134, s[0:1]
	s_add_u32 s40, s40, 0x100
	s_addc_u32 s41, s41, 0
	s_add_u32 s67, s67, 0x100
	s_addc_u32 s68, s68, 0
	s_cmp_gt_u32 s69, 29
	s_waitcnt vmcnt(6)
	s_barrier
	s_setprio 1
	v_mfma_f32_16x16x32_bf16 v[52:55], v[210:213], v[170:173], v[52:55]
	v_mfma_f32_16x16x32_bf16 v[48:51], v[218:221], v[170:173], v[48:51]
	v_mfma_f32_16x16x32_bf16 v[36:39], v[210:213], v[178:181], v[36:39]
	v_mfma_f32_16x16x32_bf16 v[32:35], v[218:221], v[178:181], v[32:35]
	v_mfma_f32_16x16x32_bf16 v[20:23], v[210:213], v[194:197], v[20:23]
	v_mfma_f32_16x16x32_bf16 v[16:19], v[218:221], v[194:197], v[16:19]
	v_mfma_f32_16x16x32_bf16 v[4:7], v[210:213], v[202:205], v[4:7]
	v_mfma_f32_16x16x32_bf16 v[0:3], v[218:221], v[202:205], v[0:3]
	v_mfma_f32_16x16x32_bf16 v[52:55], v[214:217], v[174:177], v[52:55]
	v_mfma_f32_16x16x32_bf16 v[48:51], v[222:225], v[174:177], v[48:51]
	v_mfma_f32_16x16x32_bf16 v[36:39], v[214:217], v[188:191], v[36:39]
	v_mfma_f32_16x16x32_bf16 v[32:35], v[222:225], v[188:191], v[32:35]
	v_mfma_f32_16x16x32_bf16 v[20:23], v[214:217], v[198:201], v[20:23]
	v_mfma_f32_16x16x32_bf16 v[16:19], v[222:225], v[198:201], v[16:19]
	v_mfma_f32_16x16x32_bf16 v[4:7], v[214:217], v[206:209], v[4:7]
	v_mfma_f32_16x16x32_bf16 v[0:3], v[222:225], v[206:209], v[0:3]
	s_setprio 0
	s_cbranch_scc0 .Lrot_219
	s_barrier
	s_branch .Lpeel_done_219

; #define PG8_STAGE(bufoff, gbase, voff) do { _Pragma("unroll") for (int _i = 0; _i < 2; ++_i) \
;         __builtin_amdgcn_global_load_lds((const unsigned*)((const char*)(gbase) + (voff)[_i]), (LAS unsigned*)(lds + (bufoff) + ldsw + _i * 8192), 16, 0, 0); } while (0)
; #define PG8_LDA(dst, b, h) do { _Pragma("unroll") for (int m = 0; m < 4; ++m) _Pragma("unroll") for (int k = 0; k < 2; ++k) dst[m][k] = *(const LAS bf16x8*)(lds + PG8_SA(b, h) + aoff + m * 2048 + k * 1024); } while (0)
; #define PG8_LDB(dst, b, h) do { _Pragma("unroll") for (int n = 0; n < 2; ++n) _Pragma("unroll") for (int k = 0; k < 2; ++k) dst[n][k] = *(const LAS bf16x8*)(lds + PG8_SB(b, h) + boff + n * 2048 + k * 1024); } while (0)
; #define PG8_MMA(ai, bj, At, Bt) do { __builtin_amdgcn_s_setprio(1); _Pragma("unroll") for (int m = 0; m < 4; ++m) _Pragma("unroll") for (int n = 0; n < 2; ++n) _Pragma("unroll") for (int k = 0; k < 2; ++k) \
;         acc[ai][bj][m][n] = __builtin_amdgcn_mfma_f32_16x16x32_bf16(Bt[n][k], At[m][k], acc[ai][bj][m][n], 0, 0, 0); __builtin_amdgcn_s_setprio(0); } while (0)
; #define PG8_WAIT_V(n) asm volatile("s_waitcnt vmcnt(" #n ")" ::: "memory")
; #define PG8_WAIT_L(n) asm volatile("s_waitcnt lgkmcnt(" #n ")" ::: "memory")
; #define PG8_BAR __builtin_amdgcn_s_barrier()
; #define PG8_SCHED __builtin_amdgcn_sched_barrier(0)
; template <class Epi, class Sched>
; DI void gemm_phase(LAS unsigned char* lds, const Gemm g, const Sched& S, const Epi& E) {
;     ...
;             PG8_LDB(B0, 0, 0); PG8_SCHED; PG8_LDA(At, 0, 0); PG8_STAGE(PG8_SA(1, 1), a1 + hstep, voffA);
;             PG8_WAIT_L(8); PG8_BAR; PG8_WAIT_L(0); PG8_MMA(0, 0, At, B0); PG8_BAR; PG8_SCHED;
;             PG8_LDB(B1, 0, 1); PG8_STAGE(PG8_SB(0, 0), b2, voffB);
;             PG8_BAR; PG8_WAIT_L(0); PG8_MMA(0, 1, At, B1); PG8_BAR;
;             PG8_LDA(At, 0, 1); PG8_STAGE(PG8_SA(0, 0), a2, voffA);
;             PG8_BAR; PG8_WAIT_L(0); PG8_MMA(1, 0, At, B0); PG8_BAR; PG8_SCHED;
;             PG8_STAGE(PG8_SB(0, 1), b2 + hstep, voffB);
;             PG8_WAIT_V(6); PG8_BAR; PG8_MMA(1, 1, At, B1); PG8_BAR;
.LBB0_219:
	ds_read_b128 v[150:153], v147
	ds_read_b128 v[154:157], v147 offset:1024
	ds_read_b128 v[162:165], v147 offset:2048
	ds_read_b128 v[166:169], v147 offset:3072
	s_add_i32 m0, s39, 0xc000
	ds_read_b128 v[170:173], v148
	ds_read_b128 v[174:177], v148 offset:1024
	ds_read_b128 v[178:181], v148 offset:2048
	ds_read_b128 v[188:191], v148 offset:3072
	ds_read_b128 v[194:197], v148 offset:4096
	ds_read_b128 v[198:201], v148 offset:5120
	ds_read_b128 v[202:205], v148 offset:6144
	global_load_lds_dwordx4 v136, s[40:41]
	s_add_i32 m0, s39, 0xe000
	ds_read_b128 v[206:209], v148 offset:7168
	global_load_lds_dwordx4 v138, s[40:41]
	s_add_u32 s0, s40, 0xfff80080
	s_addc_u32 s1, s41, -1
	s_cmp_eq_u32 s69, 28
	s_cselect_b32 s45, s17, s1
	s_cselect_b32 s44, s65, s0
	s_cselect_b32 s43, s15, s68
	s_cselect_b32 s42, s66, s67
	s_waitcnt lgkmcnt(8)
	s_barrier
	s_waitcnt lgkmcnt(0)
	s_setprio 1
	v_mfma_f32_16x16x32_bf16 v[124:127], v[150:153], v[170:173], v[124:127]
	v_mfma_f32_16x16x32_bf16 v[120:123], v[162:165], v[170:173], v[120:123]
	v_mfma_f32_16x16x32_bf16 v[108:111], v[150:153], v[178:181], v[108:111]
	v_mfma_f32_16x16x32_bf16 v[104:107], v[162:165], v[178:181], v[104:107]
	v_mfma_f32_16x16x32_bf16 v[92:95], v[150:153], v[194:197], v[92:95]
	v_mfma_f32_16x16x32_bf16 v[88:91], v[162:165], v[194:197], v[88:91]
	v_mfma_f32_16x16x32_bf16 v[76:79], v[150:153], v[202:205], v[76:79]
	v_mfma_f32_16x16x32_bf16 v[72:75], v[162:165], v[202:205], v[72:75]
	v_mfma_f32_16x16x32_bf16 v[124:127], v[154:157], v[174:177], v[124:127]
	v_mfma_f32_16x16x32_bf16 v[120:123], v[166:169], v[174:177], v[120:123]
	v_mfma_f32_16x16x32_bf16 v[108:111], v[154:157], v[188:191], v[108:111]
	v_mfma_f32_16x16x32_bf16 v[104:107], v[166:169], v[188:191], v[104:107]
	v_mfma_f32_16x16x32_bf16 v[92:95], v[154:157], v[198:201], v[92:95]
	v_mfma_f32_16x16x32_bf16 v[88:91], v[166:169], v[198:201], v[88:91]
	v_mfma_f32_16x16x32_bf16 v[76:79], v[154:157], v[206:209], v[76:79]
	v_mfma_f32_16x16x32_bf16 v[72:75], v[166:169], v[206:209], v[72:75]
	s_setprio 0
	s_barrier
	s_add_i32 s0, s34, s52
	s_mov_b32 m0, s0
	ds_read_b128 v[210:213], v149
	ds_read_b128 v[214:217], v149 offset:1024
	ds_read_b128 v[218:221], v149 offset:2048
	global_load_lds_dwordx4 v130, s[42:43]
	s_add_i32 m0, s0, 0x2000
	ds_read_b128 v[222:225], v149 offset:3072
	global_load_lds_dwordx4 v134, s[42:43]
	s_barrier
	s_waitcnt lgkmcnt(0)
	s_setprio 1
	v_mfma_f32_16x16x32_bf16 v[116:119], v[210:213], v[170:173], v[116:119]
	v_mfma_f32_16x16x32_bf16 v[112:115], v[218:221], v[170:173], v[112:115]
	v_mfma_f32_16x16x32_bf16 v[100:103], v[210:213], v[178:181], v[100:103]
	v_mfma_f32_16x16x32_bf16 v[96:99], v[218:221], v[178:181], v[96:99]
	v_mfma_f32_16x16x32_bf16 v[84:87], v[210:213], v[194:197], v[84:87]
	v_mfma_f32_16x16x32_bf16 v[80:83], v[218:221], v[194:197], v[80:83]
	v_mfma_f32_16x16x32_bf16 v[68:71], v[210:213], v[202:205], v[68:71]
	v_mfma_f32_16x16x32_bf16 v[64:67], v[218:221], v[202:205], v[64:67]
	v_mfma_f32_16x16x32_bf16 v[116:119], v[214:217], v[174:177], v[116:119]
	v_mfma_f32_16x16x32_bf16 v[112:115], v[222:225], v[174:177], v[112:115]
	v_mfma_f32_16x16x32_bf16 v[100:103], v[214:217], v[188:191], v[100:103]
	v_mfma_f32_16x16x32_bf16 v[96:99], v[222:225], v[188:191], v[96:99]
	v_mfma_f32_16x16x32_bf16 v[84:87], v[214:217], v[198:201], v[84:87]
	v_mfma_f32_16x16x32_bf16 v[80:83], v[222:225], v[198:201], v[80:83]
	v_mfma_f32_16x16x32_bf16 v[68:71], v[214:217], v[206:209], v[68:71]
	v_mfma_f32_16x16x32_bf16 v[64:67], v[222:225], v[206:209], v[64:67]
	s_setprio 0
	s_mov_b32 m0, s39
	s_barrier
	ds_read_b128 v[170:173], v148 offset:16384
	ds_read_b128 v[174:177], v148 offset:17408
	ds_read_b128 v[178:181], v148 offset:18432
	ds_read_b128 v[188:191], v148 offset:19456
	ds_read_b128 v[194:197], v148 offset:20480
	ds_read_b128 v[198:201], v148 offset:21504
	ds_read_b128 v[202:205], v148 offset:22528
	global_load_lds_dwordx4 v128, s[44:45]
	s_mov_b32 m0, s53
	ds_read_b128 v[206:209], v148 offset:23552
	global_load_lds_dwordx4 v132, s[44:45]
	s_barrier
	s_waitcnt lgkmcnt(0)
	s_setprio 1
	v_mfma_f32_16x16x32_bf16 v[60:63], v[150:153], v[170:173], v[60:63]
	v_mfma_f32_16x16x32_bf16 v[56:59], v[162:165], v[170:173], v[56:59]
	v_mfma_f32_16x16x32_bf16 v[44:47], v[150:153], v[178:181], v[44:47]
	v_mfma_f32_16x16x32_bf16 v[40:43], v[162:165], v[178:181], v[40:43]
	v_mfma_f32_16x16x32_bf16 v[28:31], v[150:153], v[194:197], v[28:31]
	v_mfma_f32_16x16x32_bf16 v[24:27], v[162:165], v[194:197], v[24:27]
	v_mfma_f32_16x16x32_bf16 v[12:15], v[150:153], v[202:205], v[12:15]
	v_mfma_f32_16x16x32_bf16 v[8:11], v[162:165], v[202:205], v[8:11]
	v_mfma_f32_16x16x32_bf16 v[60:63], v[154:157], v[174:177], v[60:63]
	v_mfma_f32_16x16x32_bf16 v[56:59], v[166:169], v[174:177], v[56:59]
	v_mfma_f32_16x16x32_bf16 v[44:47], v[154:157], v[188:191], v[44:47]
	v_mfma_f32_16x16x32_bf16 v[40:43], v[166:169], v[188:191], v[40:43]
	v_mfma_f32_16x16x32_bf16 v[28:31], v[154:157], v[198:201], v[28:31]
	v_mfma_f32_16x16x32_bf16 v[24:27], v[166:169], v[198:201], v[24:27]
	v_mfma_f32_16x16x32_bf16 v[12:15], v[154:157], v[206:209], v[12:15]
	v_mfma_f32_16x16x32_bf16 v[8:11], v[166:169], v[206:209], v[8:11]
	s_setprio 0
	s_barrier
	s_add_i32 s4, s35, s52
	s_mov_b32 m0, s4
	s_add_u32 s0, s42, 0x80000
	s_addc_u32 s1, s43, 0
	global_load_lds_dwordx4 v130, s[0:1]
	s_add_i32 m0, s4, 0x2000
	s_add_i32 s4, 0, 0x18000
	global_load_lds_dwordx4 v134, s[0:1]
	s_waitcnt vmcnt(6)
	s_barrier
; #define PG8_STAGE(bufoff, gbase, voff) do { _Pragma("unroll") for (int _i = 0; _i < 2; ++_i) \
;         __builtin_amdgcn_global_load_lds((const unsigned*)((const char*)(gbase) + (voff)[_i]), (LAS unsigned*)(lds + (bufoff) + ldsw + _i * 8192), 16, 0, 0); } while (0)
; #define PG8_LDA(dst, b, h) do { _Pragma("unroll") for (int m = 0; m < 4; ++m) _Pragma("unroll") for (int k = 0; k < 2; ++k) dst[m][k] = *(const LAS bf16x8*)(lds + PG8_SA(b, h) + aoff + m * 2048 + k * 1024); } while (0)
; #define PG8_LDB(dst, b, h) do { _Pragma("unroll") for (int n = 0; n < 2; ++n) _Pragma("unroll") for (int k = 0; k < 2; ++k) dst[n][k] = *(const LAS bf16x8*)(lds + PG8_SB(b, h) + boff + n * 2048 + k * 1024); } while (0)
; #define PG8_MMA(ai, bj, At, Bt) do { __builtin_amdgcn_s_setprio(1); _Pragma("unroll") for (int m = 0; m < 4; ++m) _Pragma("unroll") for (int n = 0; n < 2; ++n) _Pragma("unroll") for (int k = 0; k < 2; ++k) \
;         acc[ai][bj][m][n] = __builtin_amdgcn_mfma_f32_16x16x32_bf16(Bt[n][k], At[m][k], acc[ai][bj][m][n], 0, 0, 0); __builtin_amdgcn_s_setprio(0); } while (0)
; #define PG8_WAIT_V(n) asm volatile("s_waitcnt vmcnt(" #n ")" ::: "memory")
; #define PG8_WAIT_L(n) asm volatile("s_waitcnt lgkmcnt(" #n ")" ::: "memory")
; #define PG8_BAR __builtin_amdgcn_s_barrier()
; #define PG8_SCHED __builtin_amdgcn_sched_barrier(0)
; template <class Epi, class Sched>
; DI void gemm_phase(LAS unsigned char* lds, const Gemm g, const Sched& S, const Epi& E) {
;     ...
;             PG8_WAIT_V(6); PG8_BAR; PG8_MMA(1, 1, At, B1); PG8_BAR;
;             PG8_LDB(B0, 1, 0); PG8_SCHED; PG8_LDA(At, 1, 0); PG8_STAGE(PG8_SA(0, 1), a2 + hstep, voffA);
;             PG8_WAIT_L(8); PG8_BAR; PG8_WAIT_L(0); PG8_MMA(0, 0, At, B0); PG8_BAR; PG8_SCHED;
;             PG8_LDB(B1, 1, 1); PG8_STAGE(PG8_SB(1, 0), b3, voffB);
	s_setprio 1
	v_mfma_f32_16x16x32_bf16 v[52:55], v[210:213], v[170:173], v[52:55]
	v_mfma_f32_16x16x32_bf16 v[48:51], v[218:221], v[170:173], v[48:51]
	v_mfma_f32_16x16x32_bf16 v[36:39], v[210:213], v[178:181], v[36:39]
	v_mfma_f32_16x16x32_bf16 v[32:35], v[218:221], v[178:181], v[32:35]
	v_mfma_f32_16x16x32_bf16 v[20:23], v[210:213], v[194:197], v[20:23]
	v_mfma_f32_16x16x32_bf16 v[16:19], v[218:221], v[194:197], v[16:19]
	v_mfma_f32_16x16x32_bf16 v[4:7], v[210:213], v[202:205], v[4:7]
	v_mfma_f32_16x16x32_bf16 v[0:3], v[218:221], v[202:205], v[0:3]
	v_mfma_f32_16x16x32_bf16 v[52:55], v[214:217], v[174:177], v[52:55]
	v_mfma_f32_16x16x32_bf16 v[48:51], v[222:225], v[174:177], v[48:51]
	v_mfma_f32_16x16x32_bf16 v[36:39], v[214:217], v[188:191], v[36:39]
	v_mfma_f32_16x16x32_bf16 v[32:35], v[222:225], v[188:191], v[32:35]
	v_mfma_f32_16x16x32_bf16 v[20:23], v[214:217], v[198:201], v[20:23]
	v_mfma_f32_16x16x32_bf16 v[16:19], v[222:225], v[198:201], v[16:19]
	v_mfma_f32_16x16x32_bf16 v[4:7], v[214:217], v[206:209], v[4:7]
	v_mfma_f32_16x16x32_bf16 v[0:3], v[222:225], v[206:209], v[0:3]
	s_setprio 0
	s_barrier
	ds_read_b128 v[150:153], v158
	ds_read_b128 v[154:157], v158 offset:1024
	ds_read_b128 v[162:165], v158 offset:2048
	ds_read_b128 v[166:169], v158 offset:3072
	s_add_u32 s0, s44, 0x80000
	s_addc_u32 s1, s45, 0
	s_mov_b32 m0, s54
	ds_read_b128 v[170:173], v148 offset:32768
	ds_read_b128 v[174:177], v148 offset:33792
	ds_read_b128 v[178:181], v148 offset:34816
	ds_read_b128 v[188:191], v148 offset:35840
	ds_read_b128 v[194:197], v148 offset:36864
	ds_read_b128 v[198:201], v148 offset:37888
	ds_read_b128 v[202:205], v148 offset:38912
	global_load_lds_dwordx4 v128, s[0:1]
	s_mov_b32 m0, s55
	ds_read_b128 v[206:209], v148 offset:39936
	global_load_lds_dwordx4 v132, s[0:1]
	s_waitcnt lgkmcnt(8)
	s_barrier
	s_waitcnt lgkmcnt(0)
	s_setprio 1
	v_mfma_f32_16x16x32_bf16 v[124:127], v[150:153], v[170:173], v[124:127]
	v_mfma_f32_16x16x32_bf16 v[120:123], v[162:165], v[170:173], v[120:123]
	v_mfma_f32_16x16x32_bf16 v[108:111], v[150:153], v[178:181], v[108:111]
	v_mfma_f32_16x16x32_bf16 v[104:107], v[162:165], v[178:181], v[104:107]
	v_mfma_f32_16x16x32_bf16 v[92:95], v[150:153], v[194:197], v[92:95]
	v_mfma_f32_16x16x32_bf16 v[88:91], v[162:165], v[194:197], v[88:91]
	v_mfma_f32_16x16x32_bf16 v[76:79], v[150:153], v[202:205], v[76:79]
	v_mfma_f32_16x16x32_bf16 v[72:75], v[162:165], v[202:205], v[72:75]
	v_mfma_f32_16x16x32_bf16 v[124:127], v[154:157], v[174:177], v[124:127]
	v_mfma_f32_16x16x32_bf16 v[120:123], v[166:169], v[174:177], v[120:123]
	v_mfma_f32_16x16x32_bf16 v[108:111], v[154:157], v[188:191], v[108:111]
	v_mfma_f32_16x16x32_bf16 v[104:107], v[166:169], v[188:191], v[104:107]
	v_mfma_f32_16x16x32_bf16 v[92:95], v[154:157], v[198:201], v[92:95]
	v_mfma_f32_16x16x32_bf16 v[88:91], v[166:169], v[198:201], v[88:91]
	v_mfma_f32_16x16x32_bf16 v[76:79], v[154:157], v[206:209], v[76:79]
	v_mfma_f32_16x16x32_bf16 v[72:75], v[166:169], v[206:209], v[72:75]
	s_setprio 0
	s_barrier
	s_add_i32 s5, 0, 0x1c000
	s_add_i32 s0, s4, s52
	s_add_i32 m0, s0, 0xffffff80
	ds_read_b128 v[210:213], v159
	ds_read_b128 v[214:217], v159 offset:1024
	ds_read_b128 v[218:221], v159 offset:2048
	global_load_lds_dwordx4 v130, s[42:43] offset:128
	s_add_i32 m0, s0, 0x1f80
	ds_read_b128 v[222:225], v159 offset:3072
	global_load_lds_dwordx4 v134, s[42:43] offset:128
	s_barrier
; #define PG8_STAGE(bufoff, gbase, voff) do { _Pragma("unroll") for (int _i = 0; _i < 2; ++_i) \
;         __builtin_amdgcn_global_load_lds((const unsigned*)((const char*)(gbase) + (voff)[_i]), (LAS unsigned*)(lds + (bufoff) + ldsw + _i * 8192), 16, 0, 0); } while (0)
; #define PG8_LDA(dst, b, h) do { _Pragma("unroll") for (int m = 0; m < 4; ++m) _Pragma("unroll") for (int k = 0; k < 2; ++k) dst[m][k] = *(const LAS bf16x8*)(lds + PG8_SA(b, h) + aoff + m * 2048 + k * 1024); } while (0)
; #define PG8_MMA(ai, bj, At, Bt) do { __builtin_amdgcn_s_setprio(1); _Pragma("unroll") for (int m = 0; m < 4; ++m) _Pragma("unroll") for (int n = 0; n < 2; ++n) _Pragma("unroll") for (int k = 0; k < 2; ++k) \
;         acc[ai][bj][m][n] = __builtin_amdgcn_mfma_f32_16x16x32_bf16(Bt[n][k], At[m][k], acc[ai][bj][m][n], 0, 0, 0); __builtin_amdgcn_s_setprio(0); } while (0)
; #define PG8_WAIT_V(n) asm volatile("s_waitcnt vmcnt(" #n ")" ::: "memory")
; #define PG8_WAIT_L(n) asm volatile("s_waitcnt lgkmcnt(" #n ")" ::: "memory")
; #define PG8_BAR __builtin_amdgcn_s_barrier()
; #define PG8_SCHED __builtin_amdgcn_sched_barrier(0)
; template <class Epi, class Sched>
; DI void gemm_phase(LAS unsigned char* lds, const Gemm g, const Sched& S, const Epi& E) {
;     ...
;             PG8_BAR; PG8_WAIT_L(0); PG8_MMA(0, 1, At, B1); PG8_BAR;
;             PG8_LDA(At, 1, 1); PG8_STAGE(PG8_SA(1, 0), a3, voffA);
;             PG8_BAR; PG8_WAIT_L(0); PG8_MMA(1, 0, At, B0); PG8_BAR; PG8_SCHED;
;             PG8_STAGE(PG8_SB(1, 1), b3 + hstep, voffB);
;             PG8_WAIT_V(6); PG8_BAR; PG8_MMA(1, 1, At, B1); PG8_BAR;
;         }
	s_waitcnt lgkmcnt(0)
	s_setprio 1
	v_mfma_f32_16x16x32_bf16 v[116:119], v[210:213], v[170:173], v[116:119]
	v_mfma_f32_16x16x32_bf16 v[112:115], v[218:221], v[170:173], v[112:115]
	v_mfma_f32_16x16x32_bf16 v[100:103], v[210:213], v[178:181], v[100:103]
	v_mfma_f32_16x16x32_bf16 v[96:99], v[218:221], v[178:181], v[96:99]
	v_mfma_f32_16x16x32_bf16 v[84:87], v[210:213], v[194:197], v[84:87]
	v_mfma_f32_16x16x32_bf16 v[80:83], v[218:221], v[194:197], v[80:83]
	v_mfma_f32_16x16x32_bf16 v[68:71], v[210:213], v[202:205], v[68:71]
	v_mfma_f32_16x16x32_bf16 v[64:67], v[218:221], v[202:205], v[64:67]
	v_mfma_f32_16x16x32_bf16 v[116:119], v[214:217], v[174:177], v[116:119]
	v_mfma_f32_16x16x32_bf16 v[112:115], v[222:225], v[174:177], v[112:115]
	v_mfma_f32_16x16x32_bf16 v[100:103], v[214:217], v[188:191], v[100:103]
	v_mfma_f32_16x16x32_bf16 v[96:99], v[222:225], v[188:191], v[96:99]
	v_mfma_f32_16x16x32_bf16 v[84:87], v[214:217], v[198:201], v[84:87]
	v_mfma_f32_16x16x32_bf16 v[80:83], v[222:225], v[198:201], v[80:83]
	v_mfma_f32_16x16x32_bf16 v[68:71], v[214:217], v[206:209], v[68:71]
	v_mfma_f32_16x16x32_bf16 v[64:67], v[222:225], v[206:209], v[64:67]
	s_setprio 0
	s_add_i32 m0, s59, 0xffffff80
	s_barrier
	ds_read_b128 v[170:173], v148 offset:49152
	ds_read_b128 v[174:177], v148 offset:50176
	ds_read_b128 v[178:181], v148 offset:51200
	ds_read_b128 v[188:191], v148 offset:52224
	ds_read_b128 v[194:197], v148 offset:53248
	ds_read_b128 v[198:201], v148 offset:54272
	ds_read_b128 v[202:205], v148 offset:55296
	global_load_lds_dwordx4 v128, s[44:45] offset:128
	s_add_i32 m0, s60, 0xffffff80
	ds_read_b128 v[206:209], v148 offset:56320
	global_load_lds_dwordx4 v132, s[44:45] offset:128
	s_barrier
	s_waitcnt lgkmcnt(0)
	s_setprio 1
	v_mfma_f32_16x16x32_bf16 v[60:63], v[150:153], v[170:173], v[60:63]
	v_mfma_f32_16x16x32_bf16 v[56:59], v[162:165], v[170:173], v[56:59]
	v_mfma_f32_16x16x32_bf16 v[44:47], v[150:153], v[178:181], v[44:47]
	v_mfma_f32_16x16x32_bf16 v[40:43], v[162:165], v[178:181], v[40:43]
	v_mfma_f32_16x16x32_bf16 v[28:31], v[150:153], v[194:197], v[28:31]
	v_mfma_f32_16x16x32_bf16 v[24:27], v[162:165], v[194:197], v[24:27]
	v_mfma_f32_16x16x32_bf16 v[12:15], v[150:153], v[202:205], v[12:15]
	v_mfma_f32_16x16x32_bf16 v[8:11], v[162:165], v[202:205], v[8:11]
	v_mfma_f32_16x16x32_bf16 v[60:63], v[154:157], v[174:177], v[60:63]
	v_mfma_f32_16x16x32_bf16 v[56:59], v[166:169], v[174:177], v[56:59]
	v_mfma_f32_16x16x32_bf16 v[44:47], v[154:157], v[188:191], v[44:47]
	v_mfma_f32_16x16x32_bf16 v[40:43], v[166:169], v[188:191], v[40:43]
	v_mfma_f32_16x16x32_bf16 v[28:31], v[154:157], v[198:201], v[28:31]
	v_mfma_f32_16x16x32_bf16 v[24:27], v[166:169], v[198:201], v[24:27]
	v_mfma_f32_16x16x32_bf16 v[12:15], v[154:157], v[206:209], v[12:15]
	v_mfma_f32_16x16x32_bf16 v[8:11], v[166:169], v[206:209], v[8:11]
	s_setprio 0
	s_barrier
	s_add_i32 s4, s5, s52
	s_mov_b32 m0, s4
	s_add_u32 s0, s42, 0x80080
	s_addc_u32 s1, s43, 0
	global_load_lds_dwordx4 v130, s[0:1]
	s_add_i32 m0, s4, 0x2000
	s_add_i32 s69, s69, 2
	global_load_lds_dwordx4 v134, s[0:1]
	s_add_u32 s40, s40, 0x100
	s_addc_u32 s41, s41, 0
	s_add_u32 s67, s67, 0x100
	s_addc_u32 s68, s68, 0
	s_cmp_gt_u32 s69, 29
	s_waitcnt vmcnt(6)
	s_barrier
	s_setprio 1
	v_mfma_f32_16x16x32_bf16 v[52:55], v[210:213], v[170:173], v[52:55]
	v_mfma_f32_16x16x32_bf16 v[48:51], v[218:221], v[170:173], v[48:51]
	v_mfma_f32_16x16x32_bf16 v[36:39], v[210:213], v[178:181], v[36:39]
	v_mfma_f32_16x16x32_bf16 v[32:35], v[218:221], v[178:181], v[32:35]
	v_mfma_f32_16x16x32_bf16 v[20:23], v[210:213], v[194:197], v[20:23]
	v_mfma_f32_16x16x32_bf16 v[16:19], v[218:221], v[194:197], v[16:19]
	v_mfma_f32_16x16x32_bf16 v[4:7], v[210:213], v[202:205], v[4:7]
	v_mfma_f32_16x16x32_bf16 v[0:3], v[218:221], v[202:205], v[0:3]
	v_mfma_f32_16x16x32_bf16 v[52:55], v[214:217], v[174:177], v[52:55]
	v_mfma_f32_16x16x32_bf16 v[48:51], v[222:225], v[174:177], v[48:51]
	v_mfma_f32_16x16x32_bf16 v[36:39], v[214:217], v[188:191], v[36:39]
	v_mfma_f32_16x16x32_bf16 v[32:35], v[222:225], v[188:191], v[32:35]
	v_mfma_f32_16x16x32_bf16 v[20:23], v[214:217], v[198:201], v[20:23]
	v_mfma_f32_16x16x32_bf16 v[16:19], v[222:225], v[198:201], v[16:19]
	v_mfma_f32_16x16x32_bf16 v[4:7], v[214:217], v[206:209], v[4:7]
	v_mfma_f32_16x16x32_bf16 v[0:3], v[222:225], v[206:209], v[0:3]
	s_setprio 0
	s_cbranch_scc0 .Lrot_219
	s_barrier

;     DI size_t aoff(const Unit& u, size_t tstep) const { return (size_t)u.pm * tstep; }
;     DI size_t boff(const Unit& u, size_t tstep) const { return (size_t)u.pn * tstep; }
;     DI bool next(int i, Unit& u) const { const long L = (long)i * G + c; if (L >= np) return false; u.pm = pmv; u.pn = (int)(L % nN); u.ks = (int)(L / nN); return true; }
;     DI size_t aoff(const Unit& u, size_t) const { return (size_t)u.ks * kbytes; }
;     DI size_t boff(const Unit& u, size_t tstep) const { return (size_t)u.pn * tstep + (size_t)u.ks * kbytes; }
;     DI bool next(int i, Unit& u) const { Unit t; if (!S.next(i / 3, t)) return false; u.pm = t.pm; u.pn = t.pn; u.ks = i % 3; return true; }
;     DI size_t aoff(const Unit& u, size_t tstep) const { return (u.ks < 2 ? offU : offOA) + (size_t)u.pm * tstep; }
; #define PG8_WAIT_V(n) asm volatile("s_waitcnt vmcnt(" #n ")" ::: "memory")
; template <class Epi, class Sched>
; DI void gemm_phase(LAS unsigned char* lds, const Gemm g, const Sched& S, const Epi& E) {
;     ...
;         const bool has_next = S.next(ui + 1, nxt);
;         const char* nA = has_next ? (const char*)g.A + S.aoff(nxt, tstep) : cA; const char* nB = has_next ? (const char*)g.Bt + S.boff(nxt, tstep) : cB;
;         for (int t = 0; t < nt; t += 2) {
;             if constexpr (Epi::HAS_MID) { if (t == E.mid_t(nt)) { int fr3 = fr, fq3 = fq; asm volatile("" : "+v"(fr3), "+v"(fq3)); E.mid(acc, cur, wr, wc, fr3, fq3); } }
;             const bool last = (t == nt - 2);
;             const char* a1 = cA + (size_t)(t + 1) * kstep;
;             const char* a2 = last ? nA : cA + (size_t)(t + 2) * kstep; const char* b2 = last ? nB : cB + (size_t)(t + 2) * kstep;
;             const char* a3 = a2 + kstep; const char* b3 = b2 + kstep;
;             PG8_LDB(B0, 0, 0); PG8_SCHED; PG8_LDA(At, 0, 0); PG8_STAGE(PG8_SA(1, 1), a1 + hstep, voffA);
;             PG8_WAIT_L(8); PG8_BAR; PG8_WAIT_L(0); PG8_MMA(0, 0, At, B0); PG8_BAR; PG8_SCHED;
;             PG8_LDB(B1, 0, 1); PG8_STAGE(PG8_SB(0, 0), b2, voffB);
;             PG8_BAR; PG8_WAIT_L(0); PG8_MMA(0, 1, At, B1); PG8_BAR;
;             PG8_LDA(At, 0, 1); PG8_STAGE(PG8_SA(0, 0), a2, voffA);
;             PG8_BAR; PG8_WAIT_L(0); PG8_MMA(1, 0, At, B0); PG8_BAR; PG8_SCHED;
;             PG8_STAGE(PG8_SB(0, 1), b2 + hstep, voffB);
;             PG8_WAIT_V(6); PG8_BAR; PG8_MMA(1, 1, At, B1); PG8_BAR;
.LBB0_296:
	s_add_u32 s40, s40, 0x160080
	s_addc_u32 s41, s41, 0
	s_add_u32 s35, s42, 0x100
	v_mov_b32_e32 v0, 0
	s_addc_u32 s68, s43, 0
	s_mov_b32 s69, -2
	s_waitcnt lgkmcnt(0)
	ds_read_b128 v[144:147], v158
	ds_read_b128 v[164:167], v158 offset:1024
	ds_read_b128 v[168:171], v158 offset:2048
	ds_read_b128 v[172:175], v158 offset:3072
	s_add_u32 s0, s40, 0xffea0080
	s_addc_u32 s1, s41, -1
	s_cmpk_eq_i32 s69, 0x54
	s_cselect_b32 s45, s9, s1
	s_cselect_b32 s44, s8, s0
	s_cselect_b32 s43, s11, s68
	s_cselect_b32 s42, s10, s35
	s_add_i32 m0, s54, 0xc000
	ds_read_b128 v[176:179], v159
	ds_read_b128 v[180:183], v159 offset:1024
	ds_read_b128 v[188:191], v159 offset:2048
	ds_read_b128 v[194:197], v159 offset:3072
	ds_read_b128 v[198:201], v159 offset:4096
	ds_read_b128 v[202:205], v159 offset:5120
	ds_read_b128 v[206:209], v159 offset:6144
	global_load_lds_dwordx4 v136, s[40:41]
	s_add_i32 m0, s54, 0xe000
	ds_read_b128 v[210:213], v159 offset:7168
	global_load_lds_dwordx4 v138, s[40:41]
	s_waitcnt lgkmcnt(8)
	s_barrier
	s_waitcnt lgkmcnt(0)
	s_setprio 1
	v_mfma_f32_16x16x32_bf16 v[124:127], v[144:147], v[176:179], 0
	v_mfma_f32_16x16x32_bf16 v[120:123], v[168:171], v[176:179], 0
	v_mfma_f32_16x16x32_bf16 v[108:111], v[144:147], v[188:191], 0
	v_mfma_f32_16x16x32_bf16 v[104:107], v[168:171], v[188:191], 0
	v_mfma_f32_16x16x32_bf16 v[92:95], v[144:147], v[198:201], 0
	v_mfma_f32_16x16x32_bf16 v[88:91], v[168:171], v[198:201], 0
	v_mfma_f32_16x16x32_bf16 v[76:79], v[144:147], v[206:209], 0
	v_mfma_f32_16x16x32_bf16 v[72:75], v[168:171], v[206:209], 0
	v_mfma_f32_16x16x32_bf16 v[124:127], v[164:167], v[180:183], v[124:127]
	v_mfma_f32_16x16x32_bf16 v[120:123], v[172:175], v[180:183], v[120:123]
	v_mfma_f32_16x16x32_bf16 v[108:111], v[164:167], v[194:197], v[108:111]
	v_mfma_f32_16x16x32_bf16 v[104:107], v[172:175], v[194:197], v[104:107]
	v_mfma_f32_16x16x32_bf16 v[92:95], v[164:167], v[202:205], v[92:95]
	v_mfma_f32_16x16x32_bf16 v[88:91], v[172:175], v[202:205], v[88:91]
	v_mfma_f32_16x16x32_bf16 v[76:79], v[164:167], v[210:213], v[76:79]
	v_mfma_f32_16x16x32_bf16 v[72:75], v[172:175], v[210:213], v[72:75]
	s_setprio 0
	s_barrier
	s_add_i32 s0, s63, s53
	s_mov_b32 m0, s0
	ds_read_b128 v[214:217], v161
	ds_read_b128 v[218:221], v161 offset:1024
	ds_read_b128 v[222:225], v161 offset:2048
	global_load_lds_dwordx4 v130, s[42:43]
	s_add_i32 m0, s0, 0x2000
	ds_read_b128 v[226:229], v161 offset:3072
	global_load_lds_dwordx4 v134, s[42:43]
	s_barrier
	s_waitcnt lgkmcnt(0)
	s_setprio 1
	v_mfma_f32_16x16x32_bf16 v[116:119], v[214:217], v[176:179], 0
	v_mfma_f32_16x16x32_bf16 v[112:115], v[222:225], v[176:179], 0
	v_mfma_f32_16x16x32_bf16 v[100:103], v[214:217], v[188:191], 0
	v_mfma_f32_16x16x32_bf16 v[96:99], v[222:225], v[188:191], 0
	v_mfma_f32_16x16x32_bf16 v[84:87], v[214:217], v[198:201], 0
	v_mfma_f32_16x16x32_bf16 v[80:83], v[222:225], v[198:201], 0
	v_mfma_f32_16x16x32_bf16 v[68:71], v[214:217], v[206:209], 0
	v_mfma_f32_16x16x32_bf16 v[64:67], v[222:225], v[206:209], 0
	v_mfma_f32_16x16x32_bf16 v[116:119], v[218:221], v[180:183], v[116:119]
	v_mfma_f32_16x16x32_bf16 v[112:115], v[226:229], v[180:183], v[112:115]
	v_mfma_f32_16x16x32_bf16 v[100:103], v[218:221], v[194:197], v[100:103]
	v_mfma_f32_16x16x32_bf16 v[96:99], v[226:229], v[194:197], v[96:99]
	v_mfma_f32_16x16x32_bf16 v[84:87], v[218:221], v[202:205], v[84:87]
	v_mfma_f32_16x16x32_bf16 v[80:83], v[226:229], v[202:205], v[80:83]
	v_mfma_f32_16x16x32_bf16 v[68:71], v[218:221], v[210:213], v[68:71]
	v_mfma_f32_16x16x32_bf16 v[64:67], v[226:229], v[210:213], v[64:67]
	s_setprio 0
	s_mov_b32 m0, s54
	s_barrier
	ds_read_b128 v[176:179], v159 offset:16384
	ds_read_b128 v[180:183], v159 offset:17408
	ds_read_b128 v[188:191], v159 offset:18432
	ds_read_b128 v[194:197], v159 offset:19456
	ds_read_b128 v[198:201], v159 offset:20480
	ds_read_b128 v[202:205], v159 offset:21504
	ds_read_b128 v[206:209], v159 offset:22528
	global_load_lds_dwordx4 v128, s[44:45]
	s_mov_b32 m0, s55
	ds_read_b128 v[210:213], v159 offset:23552
	global_load_lds_dwordx4 v132, s[44:45]
	s_barrier
	s_waitcnt lgkmcnt(0)
	s_setprio 1
	v_mfma_f32_16x16x32_bf16 v[60:63], v[144:147], v[176:179], 0
	v_mfma_f32_16x16x32_bf16 v[56:59], v[168:171], v[176:179], 0
	v_mfma_f32_16x16x32_bf16 v[44:47], v[144:147], v[188:191], 0
	v_mfma_f32_16x16x32_bf16 v[40:43], v[168:171], v[188:191], 0
	v_mfma_f32_16x16x32_bf16 v[28:31], v[144:147], v[198:201], 0
	v_mfma_f32_16x16x32_bf16 v[24:27], v[168:171], v[198:201], 0
	v_mfma_f32_16x16x32_bf16 v[12:15], v[144:147], v[206:209], 0
	v_mfma_f32_16x16x32_bf16 v[8:11], v[168:171], v[206:209], 0
	v_mfma_f32_16x16x32_bf16 v[60:63], v[164:167], v[180:183], v[60:63]
	v_mfma_f32_16x16x32_bf16 v[56:59], v[172:175], v[180:183], v[56:59]
	v_mfma_f32_16x16x32_bf16 v[44:47], v[164:167], v[194:197], v[44:47]
	v_mfma_f32_16x16x32_bf16 v[40:43], v[172:175], v[194:197], v[40:43]
	v_mfma_f32_16x16x32_bf16 v[28:31], v[164:167], v[202:205], v[28:31]
	v_mfma_f32_16x16x32_bf16 v[24:27], v[172:175], v[202:205], v[24:27]
	v_mfma_f32_16x16x32_bf16 v[12:15], v[164:167], v[210:213], v[12:15]
	v_mfma_f32_16x16x32_bf16 v[8:11], v[172:175], v[210:213], v[8:11]
	s_setprio 0
	s_barrier
	s_add_i32 s4, s64, s53
	s_mov_b32 m0, s4
	s_add_u32 s0, s42, 0x160000
	s_addc_u32 s1, s43, 0
	global_load_lds_dwordx4 v130, s[0:1]
	s_add_i32 m0, s4, 0x2000
	s_add_i32 s4, 0, 0x18000
	global_load_lds_dwordx4 v134, s[0:1]
	s_waitcnt vmcnt(6)
	s_barrier
; #define PG8_STAGE(bufoff, gbase, voff) do { _Pragma("unroll") for (int _i = 0; _i < 2; ++_i) \
;         __builtin_amdgcn_global_load_lds((const unsigned*)((const char*)(gbase) + (voff)[_i]), (LAS unsigned*)(lds + (bufoff) + ldsw + _i * 8192), 16, 0, 0); } while (0)
; #define PG8_LDA(dst, b, h) do { _Pragma("unroll") for (int m = 0; m < 4; ++m) _Pragma("unroll") for (int k = 0; k < 2; ++k) dst[m][k] = *(const LAS bf16x8*)(lds + PG8_SA(b, h) + aoff + m * 2048 + k * 1024); } while (0)
; #define PG8_LDB(dst, b, h) do { _Pragma("unroll") for (int n = 0; n < 2; ++n) _Pragma("unroll") for (int k = 0; k < 2; ++k) dst[n][k] = *(const LAS bf16x8*)(lds + PG8_SB(b, h) + boff + n * 2048 + k * 1024); } while (0)
; #define PG8_MMA(ai, bj, At, Bt) do { __builtin_amdgcn_s_setprio(1); _Pragma("unroll") for (int m = 0; m < 4; ++m) _Pragma("unroll") for (int n = 0; n < 2; ++n) _Pragma("unroll") for (int k = 0; k < 2; ++k) \
;         acc[ai][bj][m][n] = __builtin_amdgcn_mfma_f32_16x16x32_bf16(Bt[n][k], At[m][k], acc[ai][bj][m][n], 0, 0, 0); __builtin_amdgcn_s_setprio(0); } while (0)
; #define PG8_WAIT_V(n) asm volatile("s_waitcnt vmcnt(" #n ")" ::: "memory")
; #define PG8_WAIT_L(n) asm volatile("s_waitcnt lgkmcnt(" #n ")" ::: "memory")
; #define PG8_BAR __builtin_amdgcn_s_barrier()
; #define PG8_SCHED __builtin_amdgcn_sched_barrier(0)
; template <class Epi, class Sched>
; DI void gemm_phase(LAS unsigned char* lds, const Gemm g, const Sched& S, const Epi& E) {
;     ...
;             PG8_WAIT_V(6); PG8_BAR; PG8_MMA(1, 1, At, B1); PG8_BAR;
;             PG8_LDB(B0, 1, 0); PG8_SCHED; PG8_LDA(At, 1, 0); PG8_STAGE(PG8_SA(0, 1), a2 + hstep, voffA);
;             PG8_WAIT_L(8); PG8_BAR; PG8_WAIT_L(0); PG8_MMA(0, 0, At, B0); PG8_BAR; PG8_SCHED;
;             PG8_LDB(B1, 1, 1); PG8_STAGE(PG8_SB(1, 0), b3, voffB);
	s_setprio 1
	v_mfma_f32_16x16x32_bf16 v[52:55], v[214:217], v[176:179], 0
	v_mfma_f32_16x16x32_bf16 v[48:51], v[222:225], v[176:179], 0
	v_mfma_f32_16x16x32_bf16 v[36:39], v[214:217], v[188:191], 0
	v_mfma_f32_16x16x32_bf16 v[32:35], v[222:225], v[188:191], 0
	v_mfma_f32_16x16x32_bf16 v[20:23], v[214:217], v[198:201], 0
	v_mfma_f32_16x16x32_bf16 v[16:19], v[222:225], v[198:201], 0
	v_mfma_f32_16x16x32_bf16 v[4:7], v[214:217], v[206:209], 0
	v_mfma_f32_16x16x32_bf16 v[0:3], v[222:225], v[206:209], 0
	v_mfma_f32_16x16x32_bf16 v[52:55], v[218:221], v[180:183], v[52:55]
	v_mfma_f32_16x16x32_bf16 v[48:51], v[226:229], v[180:183], v[48:51]
	v_mfma_f32_16x16x32_bf16 v[36:39], v[218:221], v[194:197], v[36:39]
	v_mfma_f32_16x16x32_bf16 v[32:35], v[226:229], v[194:197], v[32:35]
	v_mfma_f32_16x16x32_bf16 v[20:23], v[218:221], v[202:205], v[20:23]
	v_mfma_f32_16x16x32_bf16 v[16:19], v[226:229], v[202:205], v[16:19]
	v_mfma_f32_16x16x32_bf16 v[4:7], v[218:221], v[210:213], v[4:7]
	v_mfma_f32_16x16x32_bf16 v[0:3], v[226:229], v[210:213], v[0:3]
	s_setprio 0
	v_add_u32_e32 v230, s4, v157
	s_barrier
	ds_read_b128 v[144:147], v230
	ds_read_b128 v[164:167], v230 offset:1024
	ds_read_b128 v[168:171], v230 offset:2048
	ds_read_b128 v[172:175], v230 offset:3072
	s_add_u32 s0, s44, 0x160000
	s_addc_u32 s1, s45, 0
	s_mov_b32 m0, s56
	ds_read_b128 v[176:179], v159 offset:32768
	ds_read_b128 v[180:183], v159 offset:33792
	ds_read_b128 v[188:191], v159 offset:34816
	ds_read_b128 v[194:197], v159 offset:35840
	ds_read_b128 v[198:201], v159 offset:36864
	ds_read_b128 v[202:205], v159 offset:37888
	ds_read_b128 v[206:209], v159 offset:38912
	global_load_lds_dwordx4 v128, s[0:1]
	s_mov_b32 m0, s57
	ds_read_b128 v[210:213], v159 offset:39936
	global_load_lds_dwordx4 v132, s[0:1]
	s_waitcnt lgkmcnt(8)
	s_barrier
	s_waitcnt lgkmcnt(0)
	s_setprio 1
	v_mfma_f32_16x16x32_bf16 v[124:127], v[144:147], v[176:179], v[124:127]
	v_mfma_f32_16x16x32_bf16 v[120:123], v[168:171], v[176:179], v[120:123]
	v_mfma_f32_16x16x32_bf16 v[108:111], v[144:147], v[188:191], v[108:111]
	v_mfma_f32_16x16x32_bf16 v[104:107], v[168:171], v[188:191], v[104:107]
	v_mfma_f32_16x16x32_bf16 v[92:95], v[144:147], v[198:201], v[92:95]
	v_mfma_f32_16x16x32_bf16 v[88:91], v[168:171], v[198:201], v[88:91]
	v_mfma_f32_16x16x32_bf16 v[76:79], v[144:147], v[206:209], v[76:79]
	v_mfma_f32_16x16x32_bf16 v[72:75], v[168:171], v[206:209], v[72:75]
	v_mfma_f32_16x16x32_bf16 v[124:127], v[164:167], v[180:183], v[124:127]
	v_mfma_f32_16x16x32_bf16 v[120:123], v[172:175], v[180:183], v[120:123]
	v_mfma_f32_16x16x32_bf16 v[108:111], v[164:167], v[194:197], v[108:111]
	v_mfma_f32_16x16x32_bf16 v[104:107], v[172:175], v[194:197], v[104:107]
	v_mfma_f32_16x16x32_bf16 v[92:95], v[164:167], v[202:205], v[92:95]
	v_mfma_f32_16x16x32_bf16 v[88:91], v[172:175], v[202:205], v[88:91]
	v_mfma_f32_16x16x32_bf16 v[76:79], v[164:167], v[210:213], v[76:79]
	v_mfma_f32_16x16x32_bf16 v[72:75], v[172:175], v[210:213], v[72:75]
	s_setprio 0
	s_barrier
	s_add_i32 s5, 0, 0x1c000
	s_add_i32 s0, s4, s53
	v_add_u32_e32 v231, s5, v157
	s_add_i32 m0, s0, 0xffffff80
	ds_read_b128 v[214:217], v231
	ds_read_b128 v[218:221], v231 offset:1024
	ds_read_b128 v[222:225], v231 offset:2048
	global_load_lds_dwordx4 v130, s[42:43] offset:128
	s_add_i32 m0, s0, 0x1f80
	ds_read_b128 v[226:229], v231 offset:3072
	global_load_lds_dwordx4 v134, s[42:43] offset:128
	s_barrier
; #define PG8_STAGE(bufoff, gbase, voff) do { _Pragma("unroll") for (int _i = 0; _i < 2; ++_i) \
;         __builtin_amdgcn_global_load_lds((const unsigned*)((const char*)(gbase) + (voff)[_i]), (LAS unsigned*)(lds + (bufoff) + ldsw + _i * 8192), 16, 0, 0); } while (0)
; #define PG8_LDA(dst, b, h) do { _Pragma("unroll") for (int m = 0; m < 4; ++m) _Pragma("unroll") for (int k = 0; k < 2; ++k) dst[m][k] = *(const LAS bf16x8*)(lds + PG8_SA(b, h) + aoff + m * 2048 + k * 1024); } while (0)
; #define PG8_MMA(ai, bj, At, Bt) do { __builtin_amdgcn_s_setprio(1); _Pragma("unroll") for (int m = 0; m < 4; ++m) _Pragma("unroll") for (int n = 0; n < 2; ++n) _Pragma("unroll") for (int k = 0; k < 2; ++k) \
;         acc[ai][bj][m][n] = __builtin_amdgcn_mfma_f32_16x16x32_bf16(Bt[n][k], At[m][k], acc[ai][bj][m][n], 0, 0, 0); __builtin_amdgcn_s_setprio(0); } while (0)
; #define PG8_WAIT_V(n) asm volatile("s_waitcnt vmcnt(" #n ")" ::: "memory")
; #define PG8_WAIT_L(n) asm volatile("s_waitcnt lgkmcnt(" #n ")" ::: "memory")
; #define PG8_BAR __builtin_amdgcn_s_barrier()
; #define PG8_SCHED __builtin_amdgcn_sched_barrier(0)
; template <class Epi, class Sched>
; DI void gemm_phase(LAS unsigned char* lds, const Gemm g, const Sched& S, const Epi& E) {
;     ...
;             PG8_BAR; PG8_WAIT_L(0); PG8_MMA(0, 1, At, B1); PG8_BAR;
;             PG8_LDA(At, 1, 1); PG8_STAGE(PG8_SA(1, 0), a3, voffA);
;             PG8_BAR; PG8_WAIT_L(0); PG8_MMA(1, 0, At, B0); PG8_BAR; PG8_SCHED;
;             PG8_STAGE(PG8_SB(1, 1), b3 + hstep, voffB);
;             PG8_WAIT_V(6); PG8_BAR; PG8_MMA(1, 1, At, B1); PG8_BAR;
	s_waitcnt lgkmcnt(0)
	s_setprio 1
	v_mfma_f32_16x16x32_bf16 v[116:119], v[214:217], v[176:179], v[116:119]
	v_mfma_f32_16x16x32_bf16 v[112:115], v[222:225], v[176:179], v[112:115]
	v_mfma_f32_16x16x32_bf16 v[100:103], v[214:217], v[188:191], v[100:103]
	v_mfma_f32_16x16x32_bf16 v[96:99], v[222:225], v[188:191], v[96:99]
	v_mfma_f32_16x16x32_bf16 v[84:87], v[214:217], v[198:201], v[84:87]
	v_mfma_f32_16x16x32_bf16 v[80:83], v[222:225], v[198:201], v[80:83]
	v_mfma_f32_16x16x32_bf16 v[68:71], v[214:217], v[206:209], v[68:71]
	v_mfma_f32_16x16x32_bf16 v[64:67], v[222:225], v[206:209], v[64:67]
	v_mfma_f32_16x16x32_bf16 v[116:119], v[218:221], v[180:183], v[116:119]
	v_mfma_f32_16x16x32_bf16 v[112:115], v[226:229], v[180:183], v[112:115]
	v_mfma_f32_16x16x32_bf16 v[100:103], v[218:221], v[194:197], v[100:103]
	v_mfma_f32_16x16x32_bf16 v[96:99], v[226:229], v[194:197], v[96:99]
	v_mfma_f32_16x16x32_bf16 v[84:87], v[218:221], v[202:205], v[84:87]
	v_mfma_f32_16x16x32_bf16 v[80:83], v[226:229], v[202:205], v[80:83]
	v_mfma_f32_16x16x32_bf16 v[68:71], v[218:221], v[210:213], v[68:71]
	v_mfma_f32_16x16x32_bf16 v[64:67], v[226:229], v[210:213], v[64:67]
	s_setprio 0
	s_add_i32 m0, s61, 0xffffff80
	s_barrier
	ds_read_b128 v[176:179], v159 offset:49152
	ds_read_b128 v[180:183], v159 offset:50176
	ds_read_b128 v[188:191], v159 offset:51200
	ds_read_b128 v[194:197], v159 offset:52224
	ds_read_b128 v[198:201], v159 offset:53248
	ds_read_b128 v[202:205], v159 offset:54272
	ds_read_b128 v[206:209], v159 offset:55296
	global_load_lds_dwordx4 v128, s[44:45] offset:128
	s_add_i32 m0, s62, 0xffffff80
	ds_read_b128 v[210:213], v159 offset:56320
	global_load_lds_dwordx4 v132, s[44:45] offset:128
	s_barrier
	s_waitcnt lgkmcnt(0)
	s_setprio 1
	v_mfma_f32_16x16x32_bf16 v[60:63], v[144:147], v[176:179], v[60:63]
	v_mfma_f32_16x16x32_bf16 v[56:59], v[168:171], v[176:179], v[56:59]
	v_mfma_f32_16x16x32_bf16 v[44:47], v[144:147], v[188:191], v[44:47]
	v_mfma_f32_16x16x32_bf16 v[40:43], v[168:171], v[188:191], v[40:43]
	v_mfma_f32_16x16x32_bf16 v[28:31], v[144:147], v[198:201], v[28:31]
	v_mfma_f32_16x16x32_bf16 v[24:27], v[168:171], v[198:201], v[24:27]
	v_mfma_f32_16x16x32_bf16 v[12:15], v[144:147], v[206:209], v[12:15]
	v_mfma_f32_16x16x32_bf16 v[8:11], v[168:171], v[206:209], v[8:11]
	v_mfma_f32_16x16x32_bf16 v[60:63], v[164:167], v[180:183], v[60:63]
	v_mfma_f32_16x16x32_bf16 v[56:59], v[172:175], v[180:183], v[56:59]
	v_mfma_f32_16x16x32_bf16 v[44:47], v[164:167], v[194:197], v[44:47]
	v_mfma_f32_16x16x32_bf16 v[40:43], v[172:175], v[194:197], v[40:43]
	v_mfma_f32_16x16x32_bf16 v[28:31], v[164:167], v[202:205], v[28:31]
	v_mfma_f32_16x16x32_bf16 v[24:27], v[172:175], v[202:205], v[24:27]
	v_mfma_f32_16x16x32_bf16 v[12:15], v[164:167], v[210:213], v[12:15]
	v_mfma_f32_16x16x32_bf16 v[8:11], v[172:175], v[210:213], v[8:11]
	s_setprio 0
	s_barrier
	s_add_i32 s4, s5, s53
	s_mov_b32 m0, s4
	s_add_u32 s0, s42, 0x160080
	s_addc_u32 s1, s43, 0
	global_load_lds_dwordx4 v130, s[0:1]
	s_add_i32 m0, s4, 0x2000
	s_nop 0
	global_load_lds_dwordx4 v134, s[0:1]
	s_waitcnt vmcnt(6)
	s_barrier
	s_setprio 1
	v_mfma_f32_16x16x32_bf16 v[52:55], v[214:217], v[176:179], v[52:55]
	v_mfma_f32_16x16x32_bf16 v[48:51], v[222:225], v[176:179], v[48:51]
	v_mfma_f32_16x16x32_bf16 v[36:39], v[214:217], v[188:191], v[36:39]
	v_mfma_f32_16x16x32_bf16 v[32:35], v[222:225], v[188:191], v[32:35]
	v_mfma_f32_16x16x32_bf16 v[20:23], v[214:217], v[198:201], v[20:23]
	v_mfma_f32_16x16x32_bf16 v[16:19], v[222:225], v[198:201], v[16:19]
	v_mfma_f32_16x16x32_bf16 v[4:7], v[214:217], v[206:209], v[4:7]
	v_mfma_f32_16x16x32_bf16 v[0:3], v[222:225], v[206:209], v[0:3]
	v_mfma_f32_16x16x32_bf16 v[52:55], v[218:221], v[180:183], v[52:55]
	v_mfma_f32_16x16x32_bf16 v[48:51], v[226:229], v[180:183], v[48:51]
	v_mfma_f32_16x16x32_bf16 v[36:39], v[218:221], v[194:197], v[36:39]
	v_mfma_f32_16x16x32_bf16 v[32:35], v[226:229], v[194:197], v[32:35]
	v_mfma_f32_16x16x32_bf16 v[20:23], v[218:221], v[202:205], v[20:23]
	v_mfma_f32_16x16x32_bf16 v[16:19], v[226:229], v[202:205], v[16:19]
	v_mfma_f32_16x16x32_bf16 v[4:7], v[218:221], v[210:213], v[4:7]
	v_mfma_f32_16x16x32_bf16 v[0:3], v[226:229], v[210:213], v[0:3]
	s_setprio 0
	s_add_i32 s69, s69, 2
	s_add_u32 s40, s40, 0x100
	s_addc_u32 s41, s41, 0
	s_add_u32 s35, s35, 0x100
	s_addc_u32 s68, s68, 0
	s_cmpk_gt_u32 s69, 0x55
	s_cbranch_scc0 .Lrot_297
	s_barrier
	s_branch .Lpeel_done_297

; #define PG8_STAGE(bufoff, gbase, voff) do { _Pragma("unroll") for (int _i = 0; _i < 2; ++_i) \
;         __builtin_amdgcn_global_load_lds((const unsigned*)((const char*)(gbase) + (voff)[_i]), (LAS unsigned*)(lds + (bufoff) + ldsw + _i * 8192), 16, 0, 0); } while (0)
; #define PG8_LDA(dst, b, h) do { _Pragma("unroll") for (int m = 0; m < 4; ++m) _Pragma("unroll") for (int k = 0; k < 2; ++k) dst[m][k] = *(const LAS bf16x8*)(lds + PG8_SA(b, h) + aoff + m * 2048 + k * 1024); } while (0)
; #define PG8_LDB(dst, b, h) do { _Pragma("unroll") for (int n = 0; n < 2; ++n) _Pragma("unroll") for (int k = 0; k < 2; ++k) dst[n][k] = *(const LAS bf16x8*)(lds + PG8_SB(b, h) + boff + n * 2048 + k * 1024); } while (0)
; #define PG8_MMA(ai, bj, At, Bt) do { __builtin_amdgcn_s_setprio(1); _Pragma("unroll") for (int m = 0; m < 4; ++m) _Pragma("unroll") for (int n = 0; n < 2; ++n) _Pragma("unroll") for (int k = 0; k < 2; ++k) \
;         acc[ai][bj][m][n] = __builtin_amdgcn_mfma_f32_16x16x32_bf16(Bt[n][k], At[m][k], acc[ai][bj][m][n], 0, 0, 0); __builtin_amdgcn_s_setprio(0); } while (0)
; #define PG8_WAIT_V(n) asm volatile("s_waitcnt vmcnt(" #n ")" ::: "memory")
; #define PG8_WAIT_L(n) asm volatile("s_waitcnt lgkmcnt(" #n ")" ::: "memory")
; #define PG8_BAR __builtin_amdgcn_s_barrier()
; #define PG8_SCHED __builtin_amdgcn_sched_barrier(0)
; template <class Epi, class Sched>
; DI void gemm_phase(LAS unsigned char* lds, const Gemm g, const Sched& S, const Epi& E) {
;     ...
;             PG8_LDB(B0, 0, 0); PG8_SCHED; PG8_LDA(At, 0, 0); PG8_STAGE(PG8_SA(1, 1), a1 + hstep, voffA);
;             PG8_WAIT_L(8); PG8_BAR; PG8_WAIT_L(0); PG8_MMA(0, 0, At, B0); PG8_BAR; PG8_SCHED;
;             PG8_LDB(B1, 0, 1); PG8_STAGE(PG8_SB(0, 0), b2, voffB);
;             PG8_BAR; PG8_WAIT_L(0); PG8_MMA(0, 1, At, B1); PG8_BAR;
;             PG8_LDA(At, 0, 1); PG8_STAGE(PG8_SA(0, 0), a2, voffA);
;             PG8_BAR; PG8_WAIT_L(0); PG8_MMA(1, 0, At, B0); PG8_BAR; PG8_SCHED;
;             PG8_STAGE(PG8_SB(0, 1), b2 + hstep, voffB);
;             PG8_WAIT_V(6); PG8_BAR; PG8_MMA(1, 1, At, B1); PG8_BAR;
.LBB0_297:
	ds_read_b128 v[144:147], v158
	ds_read_b128 v[164:167], v158 offset:1024
	ds_read_b128 v[168:171], v158 offset:2048
	ds_read_b128 v[172:175], v158 offset:3072
	s_add_u32 s0, s40, 0xffea0080
	s_addc_u32 s1, s41, -1
	s_cmpk_eq_i32 s69, 0x54
	s_cselect_b32 s45, s9, s1
	s_cselect_b32 s44, s8, s0
	s_cselect_b32 s43, s11, s68
	s_cselect_b32 s42, s10, s35
	s_add_i32 m0, s54, 0xc000
	ds_read_b128 v[176:179], v159
	ds_read_b128 v[180:183], v159 offset:1024
	ds_read_b128 v[188:191], v159 offset:2048
	ds_read_b128 v[194:197], v159 offset:3072
	ds_read_b128 v[198:201], v159 offset:4096
	ds_read_b128 v[202:205], v159 offset:5120
	ds_read_b128 v[206:209], v159 offset:6144
	global_load_lds_dwordx4 v136, s[40:41]
	s_add_i32 m0, s54, 0xe000
	ds_read_b128 v[210:213], v159 offset:7168
	global_load_lds_dwordx4 v138, s[40:41]
	s_waitcnt lgkmcnt(8)
	s_barrier
	s_waitcnt lgkmcnt(0)
	s_setprio 1
	v_mfma_f32_16x16x32_bf16 v[124:127], v[144:147], v[176:179], v[124:127]
	v_mfma_f32_16x16x32_bf16 v[120:123], v[168:171], v[176:179], v[120:123]
	v_mfma_f32_16x16x32_bf16 v[108:111], v[144:147], v[188:191], v[108:111]
	v_mfma_f32_16x16x32_bf16 v[104:107], v[168:171], v[188:191], v[104:107]
	v_mfma_f32_16x16x32_bf16 v[92:95], v[144:147], v[198:201], v[92:95]
	v_mfma_f32_16x16x32_bf16 v[88:91], v[168:171], v[198:201], v[88:91]
	v_mfma_f32_16x16x32_bf16 v[76:79], v[144:147], v[206:209], v[76:79]
	v_mfma_f32_16x16x32_bf16 v[72:75], v[168:171], v[206:209], v[72:75]
	v_mfma_f32_16x16x32_bf16 v[124:127], v[164:167], v[180:183], v[124:127]
	v_mfma_f32_16x16x32_bf16 v[120:123], v[172:175], v[180:183], v[120:123]
	v_mfma_f32_16x16x32_bf16 v[108:111], v[164:167], v[194:197], v[108:111]
	v_mfma_f32_16x16x32_bf16 v[104:107], v[172:175], v[194:197], v[104:107]
	v_mfma_f32_16x16x32_bf16 v[92:95], v[164:167], v[202:205], v[92:95]
	v_mfma_f32_16x16x32_bf16 v[88:91], v[172:175], v[202:205], v[88:91]
	v_mfma_f32_16x16x32_bf16 v[76:79], v[164:167], v[210:213], v[76:79]
	v_mfma_f32_16x16x32_bf16 v[72:75], v[172:175], v[210:213], v[72:75]
	s_setprio 0
	s_barrier
	s_add_i32 s0, s63, s53
	s_mov_b32 m0, s0
	ds_read_b128 v[214:217], v161
	ds_read_b128 v[218:221], v161 offset:1024
	ds_read_b128 v[222:225], v161 offset:2048
	global_load_lds_dwordx4 v130, s[42:43]
	s_add_i32 m0, s0, 0x2000
	ds_read_b128 v[226:229], v161 offset:3072
	global_load_lds_dwordx4 v134, s[42:43]
	s_barrier
	s_waitcnt lgkmcnt(0)
	s_setprio 1
	v_mfma_f32_16x16x32_bf16 v[116:119], v[214:217], v[176:179], v[116:119]
	v_mfma_f32_16x16x32_bf16 v[112:115], v[222:225], v[176:179], v[112:115]
	v_mfma_f32_16x16x32_bf16 v[100:103], v[214:217], v[188:191], v[100:103]
	v_mfma_f32_16x16x32_bf16 v[96:99], v[222:225], v[188:191], v[96:99]
	v_mfma_f32_16x16x32_bf16 v[84:87], v[214:217], v[198:201], v[84:87]
	v_mfma_f32_16x16x32_bf16 v[80:83], v[222:225], v[198:201], v[80:83]
	v_mfma_f32_16x16x32_bf16 v[68:71], v[214:217], v[206:209], v[68:71]
	v_mfma_f32_16x16x32_bf16 v[64:67], v[222:225], v[206:209], v[64:67]
	v_mfma_f32_16x16x32_bf16 v[116:119], v[218:221], v[180:183], v[116:119]
	v_mfma_f32_16x16x32_bf16 v[112:115], v[226:229], v[180:183], v[112:115]
	v_mfma_f32_16x16x32_bf16 v[100:103], v[218:221], v[194:197], v[100:103]
	v_mfma_f32_16x16x32_bf16 v[96:99], v[226:229], v[194:197], v[96:99]
	v_mfma_f32_16x16x32_bf16 v[84:87], v[218:221], v[202:205], v[84:87]
	v_mfma_f32_16x16x32_bf16 v[80:83], v[226:229], v[202:205], v[80:83]
	v_mfma_f32_16x16x32_bf16 v[68:71], v[218:221], v[210:213], v[68:71]
	v_mfma_f32_16x16x32_bf16 v[64:67], v[226:229], v[210:213], v[64:67]
	s_setprio 0
	s_mov_b32 m0, s54
	s_barrier
	ds_read_b128 v[176:179], v159 offset:16384
	ds_read_b128 v[180:183], v159 offset:17408
	ds_read_b128 v[188:191], v159 offset:18432
	ds_read_b128 v[194:197], v159 offset:19456
	ds_read_b128 v[198:201], v159 offset:20480
	ds_read_b128 v[202:205], v159 offset:21504
	ds_read_b128 v[206:209], v159 offset:22528
	global_load_lds_dwordx4 v128, s[44:45]
	s_mov_b32 m0, s55
	ds_read_b128 v[210:213], v159 offset:23552
	global_load_lds_dwordx4 v132, s[44:45]
	s_barrier
	s_waitcnt lgkmcnt(0)
	s_setprio 1
	v_mfma_f32_16x16x32_bf16 v[60:63], v[144:147], v[176:179], v[60:63]
	v_mfma_f32_16x16x32_bf16 v[56:59], v[168:171], v[176:179], v[56:59]
	v_mfma_f32_16x16x32_bf16 v[44:47], v[144:147], v[188:191], v[44:47]
	v_mfma_f32_16x16x32_bf16 v[40:43], v[168:171], v[188:191], v[40:43]
	v_mfma_f32_16x16x32_bf16 v[28:31], v[144:147], v[198:201], v[28:31]
	v_mfma_f32_16x16x32_bf16 v[24:27], v[168:171], v[198:201], v[24:27]
	v_mfma_f32_16x16x32_bf16 v[12:15], v[144:147], v[206:209], v[12:15]
	v_mfma_f32_16x16x32_bf16 v[8:11], v[168:171], v[206:209], v[8:11]
	v_mfma_f32_16x16x32_bf16 v[60:63], v[164:167], v[180:183], v[60:63]
	v_mfma_f32_16x16x32_bf16 v[56:59], v[172:175], v[180:183], v[56:59]
	v_mfma_f32_16x16x32_bf16 v[44:47], v[164:167], v[194:197], v[44:47]
	v_mfma_f32_16x16x32_bf16 v[40:43], v[172:175], v[194:197], v[40:43]
	v_mfma_f32_16x16x32_bf16 v[28:31], v[164:167], v[202:205], v[28:31]
	v_mfma_f32_16x16x32_bf16 v[24:27], v[172:175], v[202:205], v[24:27]
	v_mfma_f32_16x16x32_bf16 v[12:15], v[164:167], v[210:213], v[12:15]
	v_mfma_f32_16x16x32_bf16 v[8:11], v[172:175], v[210:213], v[8:11]
	s_setprio 0
	s_barrier
	s_add_i32 s4, s64, s53
	s_mov_b32 m0, s4
	s_add_u32 s0, s42, 0x160000
	s_addc_u32 s1, s43, 0
	global_load_lds_dwordx4 v130, s[0:1]
	s_add_i32 m0, s4, 0x2000
	s_add_i32 s4, 0, 0x18000
	global_load_lds_dwordx4 v134, s[0:1]
	s_waitcnt vmcnt(6)
	s_barrier
; #define PG8_STAGE(bufoff, gbase, voff) do { _Pragma("unroll") for (int _i = 0; _i < 2; ++_i) \
;         __builtin_amdgcn_global_load_lds((const unsigned*)((const char*)(gbase) + (voff)[_i]), (LAS unsigned*)(lds + (bufoff) + ldsw + _i * 8192), 16, 0, 0); } while (0)
; #define PG8_LDA(dst, b, h) do { _Pragma("unroll") for (int m = 0; m < 4; ++m) _Pragma("unroll") for (int k = 0; k < 2; ++k) dst[m][k] = *(const LAS bf16x8*)(lds + PG8_SA(b, h) + aoff + m * 2048 + k * 1024); } while (0)
; #define PG8_LDB(dst, b, h) do { _Pragma("unroll") for (int n = 0; n < 2; ++n) _Pragma("unroll") for (int k = 0; k < 2; ++k) dst[n][k] = *(const LAS bf16x8*)(lds + PG8_SB(b, h) + boff + n * 2048 + k * 1024); } while (0)
; #define PG8_MMA(ai, bj, At, Bt) do { __builtin_amdgcn_s_setprio(1); _Pragma("unroll") for (int m = 0; m < 4; ++m) _Pragma("unroll") for (int n = 0; n < 2; ++n) _Pragma("unroll") for (int k = 0; k < 2; ++k) \
;         acc[ai][bj][m][n] = __builtin_amdgcn_mfma_f32_16x16x32_bf16(Bt[n][k], At[m][k], acc[ai][bj][m][n], 0, 0, 0); __builtin_amdgcn_s_setprio(0); } while (0)
; #define PG8_WAIT_V(n) asm volatile("s_waitcnt vmcnt(" #n ")" ::: "memory")
; #define PG8_WAIT_L(n) asm volatile("s_waitcnt lgkmcnt(" #n ")" ::: "memory")
; #define PG8_BAR __builtin_amdgcn_s_barrier()
; #define PG8_SCHED __builtin_amdgcn_sched_barrier(0)
; template <class Epi, class Sched>
; DI void gemm_phase(LAS unsigned char* lds, const Gemm g, const Sched& S, const Epi& E) {
;     ...
;             PG8_WAIT_V(6); PG8_BAR; PG8_MMA(1, 1, At, B1); PG8_BAR;
;             PG8_LDB(B0, 1, 0); PG8_SCHED; PG8_LDA(At, 1, 0); PG8_STAGE(PG8_SA(0, 1), a2 + hstep, voffA);
;             PG8_WAIT_L(8); PG8_BAR; PG8_WAIT_L(0); PG8_MMA(0, 0, At, B0); PG8_BAR; PG8_SCHED;
;             PG8_LDB(B1, 1, 1); PG8_STAGE(PG8_SB(1, 0), b3, voffB);
	s_setprio 1
	v_mfma_f32_16x16x32_bf16 v[52:55], v[214:217], v[176:179], v[52:55]
	v_mfma_f32_16x16x32_bf16 v[48:51], v[222:225], v[176:179], v[48:51]
	v_mfma_f32_16x16x32_bf16 v[36:39], v[214:217], v[188:191], v[36:39]
	v_mfma_f32_16x16x32_bf16 v[32:35], v[222:225], v[188:191], v[32:35]
	v_mfma_f32_16x16x32_bf16 v[20:23], v[214:217], v[198:201], v[20:23]
	v_mfma_f32_16x16x32_bf16 v[16:19], v[222:225], v[198:201], v[16:19]
	v_mfma_f32_16x16x32_bf16 v[4:7], v[214:217], v[206:209], v[4:7]
	v_mfma_f32_16x16x32_bf16 v[0:3], v[222:225], v[206:209], v[0:3]
	v_mfma_f32_16x16x32_bf16 v[52:55], v[218:221], v[180:183], v[52:55]
	v_mfma_f32_16x16x32_bf16 v[48:51], v[226:229], v[180:183], v[48:51]
	v_mfma_f32_16x16x32_bf16 v[36:39], v[218:221], v[194:197], v[36:39]
	v_mfma_f32_16x16x32_bf16 v[32:35], v[226:229], v[194:197], v[32:35]
	v_mfma_f32_16x16x32_bf16 v[20:23], v[218:221], v[202:205], v[20:23]
	v_mfma_f32_16x16x32_bf16 v[16:19], v[226:229], v[202:205], v[16:19]
	v_mfma_f32_16x16x32_bf16 v[4:7], v[218:221], v[210:213], v[4:7]
	v_mfma_f32_16x16x32_bf16 v[0:3], v[226:229], v[210:213], v[0:3]
	s_setprio 0
	s_barrier
	ds_read_b128 v[144:147], v230
	ds_read_b128 v[164:167], v230 offset:1024
	ds_read_b128 v[168:171], v230 offset:2048
	ds_read_b128 v[172:175], v230 offset:3072
	s_add_u32 s0, s44, 0x160000
	s_addc_u32 s1, s45, 0
	s_mov_b32 m0, s56
	ds_read_b128 v[176:179], v159 offset:32768
	ds_read_b128 v[180:183], v159 offset:33792
	ds_read_b128 v[188:191], v159 offset:34816
	ds_read_b128 v[194:197], v159 offset:35840
	ds_read_b128 v[198:201], v159 offset:36864
	ds_read_b128 v[202:205], v159 offset:37888
	ds_read_b128 v[206:209], v159 offset:38912
	global_load_lds_dwordx4 v128, s[0:1]
	s_mov_b32 m0, s57
	ds_read_b128 v[210:213], v159 offset:39936
	global_load_lds_dwordx4 v132, s[0:1]
	s_waitcnt lgkmcnt(8)
	s_barrier
	s_waitcnt lgkmcnt(0)
	s_setprio 1
	v_mfma_f32_16x16x32_bf16 v[124:127], v[144:147], v[176:179], v[124:127]
	v_mfma_f32_16x16x32_bf16 v[120:123], v[168:171], v[176:179], v[120:123]
	v_mfma_f32_16x16x32_bf16 v[108:111], v[144:147], v[188:191], v[108:111]
	v_mfma_f32_16x16x32_bf16 v[104:107], v[168:171], v[188:191], v[104:107]
	v_mfma_f32_16x16x32_bf16 v[92:95], v[144:147], v[198:201], v[92:95]
	v_mfma_f32_16x16x32_bf16 v[88:91], v[168:171], v[198:201], v[88:91]
	v_mfma_f32_16x16x32_bf16 v[76:79], v[144:147], v[206:209], v[76:79]
	v_mfma_f32_16x16x32_bf16 v[72:75], v[168:171], v[206:209], v[72:75]
	v_mfma_f32_16x16x32_bf16 v[124:127], v[164:167], v[180:183], v[124:127]
	v_mfma_f32_16x16x32_bf16 v[120:123], v[172:175], v[180:183], v[120:123]
	v_mfma_f32_16x16x32_bf16 v[108:111], v[164:167], v[194:197], v[108:111]
	v_mfma_f32_16x16x32_bf16 v[104:107], v[172:175], v[194:197], v[104:107]
	v_mfma_f32_16x16x32_bf16 v[92:95], v[164:167], v[202:205], v[92:95]
	v_mfma_f32_16x16x32_bf16 v[88:91], v[172:175], v[202:205], v[88:91]
	v_mfma_f32_16x16x32_bf16 v[76:79], v[164:167], v[210:213], v[76:79]
	v_mfma_f32_16x16x32_bf16 v[72:75], v[172:175], v[210:213], v[72:75]
	s_setprio 0
	s_barrier
	s_add_i32 s5, 0, 0x1c000
	s_add_i32 s0, s4, s53
	s_add_i32 m0, s0, 0xffffff80
	ds_read_b128 v[214:217], v231
	ds_read_b128 v[218:221], v231 offset:1024
	ds_read_b128 v[222:225], v231 offset:2048
	global_load_lds_dwordx4 v130, s[42:43] offset:128
	s_add_i32 m0, s0, 0x1f80
	ds_read_b128 v[226:229], v231 offset:3072
	global_load_lds_dwordx4 v134, s[42:43] offset:128
	s_barrier
; #define PG8_STAGE(bufoff, gbase, voff) do { _Pragma("unroll") for (int _i = 0; _i < 2; ++_i) \
;         __builtin_amdgcn_global_load_lds((const unsigned*)((const char*)(gbase) + (voff)[_i]), (LAS unsigned*)(lds + (bufoff) + ldsw + _i * 8192), 16, 0, 0); } while (0)
; #define PG8_LDA(dst, b, h) do { _Pragma("unroll") for (int m = 0; m < 4; ++m) _Pragma("unroll") for (int k = 0; k < 2; ++k) dst[m][k] = *(const LAS bf16x8*)(lds + PG8_SA(b, h) + aoff + m * 2048 + k * 1024); } while (0)
; #define PG8_MMA(ai, bj, At, Bt) do { __builtin_amdgcn_s_setprio(1); _Pragma("unroll") for (int m = 0; m < 4; ++m) _Pragma("unroll") for (int n = 0; n < 2; ++n) _Pragma("unroll") for (int k = 0; k < 2; ++k) \
;         acc[ai][bj][m][n] = __builtin_amdgcn_mfma_f32_16x16x32_bf16(Bt[n][k], At[m][k], acc[ai][bj][m][n], 0, 0, 0); __builtin_amdgcn_s_setprio(0); } while (0)
; #define PG8_WAIT_V(n) asm volatile("s_waitcnt vmcnt(" #n ")" ::: "memory")
; #define PG8_WAIT_L(n) asm volatile("s_waitcnt lgkmcnt(" #n ")" ::: "memory")
; #define PG8_BAR __builtin_amdgcn_s_barrier()
; #define PG8_SCHED __builtin_amdgcn_sched_barrier(0)
; template <class Epi, class Sched>
; DI void gemm_phase(LAS unsigned char* lds, const Gemm g, const Sched& S, const Epi& E) {
;     ...
;             PG8_BAR; PG8_WAIT_L(0); PG8_MMA(0, 1, At, B1); PG8_BAR;
;             PG8_LDA(At, 1, 1); PG8_STAGE(PG8_SA(1, 0), a3, voffA);
;             PG8_BAR; PG8_WAIT_L(0); PG8_MMA(1, 0, At, B0); PG8_BAR; PG8_SCHED;
;             PG8_STAGE(PG8_SB(1, 1), b3 + hstep, voffB);
;             PG8_WAIT_V(6); PG8_BAR; PG8_MMA(1, 1, At, B1); PG8_BAR;
	s_waitcnt lgkmcnt(0)
	s_setprio 1
	v_mfma_f32_16x16x32_bf16 v[116:119], v[214:217], v[176:179], v[116:119]
	v_mfma_f32_16x16x32_bf16 v[112:115], v[222:225], v[176:179], v[112:115]
	v_mfma_f32_16x16x32_bf16 v[100:103], v[214:217], v[188:191], v[100:103]
	v_mfma_f32_16x16x32_bf16 v[96:99], v[222:225], v[188:191], v[96:99]
	v_mfma_f32_16x16x32_bf16 v[84:87], v[214:217], v[198:201], v[84:87]
	v_mfma_f32_16x16x32_bf16 v[80:83], v[222:225], v[198:201], v[80:83]
	v_mfma_f32_16x16x32_bf16 v[68:71], v[214:217], v[206:209], v[68:71]
	v_mfma_f32_16x16x32_bf16 v[64:67], v[222:225], v[206:209], v[64:67]
	v_mfma_f32_16x16x32_bf16 v[116:119], v[218:221], v[180:183], v[116:119]
	v_mfma_f32_16x16x32_bf16 v[112:115], v[226:229], v[180:183], v[112:115]
	v_mfma_f32_16x16x32_bf16 v[100:103], v[218:221], v[194:197], v[100:103]
	v_mfma_f32_16x16x32_bf16 v[96:99], v[226:229], v[194:197], v[96:99]
	v_mfma_f32_16x16x32_bf16 v[84:87], v[218:221], v[202:205], v[84:87]
	v_mfma_f32_16x16x32_bf16 v[80:83], v[226:229], v[202:205], v[80:83]
	v_mfma_f32_16x16x32_bf16 v[68:71], v[218:221], v[210:213], v[68:71]
	v_mfma_f32_16x16x32_bf16 v[64:67], v[226:229], v[210:213], v[64:67]
	s_setprio 0
	s_add_i32 m0, s61, 0xffffff80
	s_barrier
	ds_read_b128 v[176:179], v159 offset:49152
	ds_read_b128 v[180:183], v159 offset:50176
	ds_read_b128 v[188:191], v159 offset:51200
	ds_read_b128 v[194:197], v159 offset:52224
	ds_read_b128 v[198:201], v159 offset:53248
	ds_read_b128 v[202:205], v159 offset:54272
	ds_read_b128 v[206:209], v159 offset:55296
	global_load_lds_dwordx4 v128, s[44:45] offset:128
	s_add_i32 m0, s62, 0xffffff80
	ds_read_b128 v[210:213], v159 offset:56320
	global_load_lds_dwordx4 v132, s[44:45] offset:128
	s_barrier
	s_waitcnt lgkmcnt(0)
	s_setprio 1
	v_mfma_f32_16x16x32_bf16 v[60:63], v[144:147], v[176:179], v[60:63]
	v_mfma_f32_16x16x32_bf16 v[56:59], v[168:171], v[176:179], v[56:59]
	v_mfma_f32_16x16x32_bf16 v[44:47], v[144:147], v[188:191], v[44:47]
	v_mfma_f32_16x16x32_bf16 v[40:43], v[168:171], v[188:191], v[40:43]
	v_mfma_f32_16x16x32_bf16 v[28:31], v[144:147], v[198:201], v[28:31]
	v_mfma_f32_16x16x32_bf16 v[24:27], v[168:171], v[198:201], v[24:27]
	v_mfma_f32_16x16x32_bf16 v[12:15], v[144:147], v[206:209], v[12:15]
	v_mfma_f32_16x16x32_bf16 v[8:11], v[168:171], v[206:209], v[8:11]
	v_mfma_f32_16x16x32_bf16 v[60:63], v[164:167], v[180:183], v[60:63]
	v_mfma_f32_16x16x32_bf16 v[56:59], v[172:175], v[180:183], v[56:59]
	v_mfma_f32_16x16x32_bf16 v[44:47], v[164:167], v[194:197], v[44:47]
	v_mfma_f32_16x16x32_bf16 v[40:43], v[172:175], v[194:197], v[40:43]
	v_mfma_f32_16x16x32_bf16 v[28:31], v[164:167], v[202:205], v[28:31]
	v_mfma_f32_16x16x32_bf16 v[24:27], v[172:175], v[202:205], v[24:27]
	v_mfma_f32_16x16x32_bf16 v[12:15], v[164:167], v[210:213], v[12:15]
	v_mfma_f32_16x16x32_bf16 v[8:11], v[172:175], v[210:213], v[8:11]
	s_setprio 0
	s_barrier
	s_add_i32 s4, s5, s53
	s_mov_b32 m0, s4
	s_add_u32 s0, s42, 0x160080
	s_addc_u32 s1, s43, 0
	global_load_lds_dwordx4 v130, s[0:1]
	s_add_i32 m0, s4, 0x2000
	s_nop 0
	global_load_lds_dwordx4 v134, s[0:1]
	s_waitcnt vmcnt(6)
	s_barrier
	s_setprio 1
	v_mfma_f32_16x16x32_bf16 v[52:55], v[214:217], v[176:179], v[52:55]
	v_mfma_f32_16x16x32_bf16 v[48:51], v[222:225], v[176:179], v[48:51]
	v_mfma_f32_16x16x32_bf16 v[36:39], v[214:217], v[188:191], v[36:39]
	v_mfma_f32_16x16x32_bf16 v[32:35], v[222:225], v[188:191], v[32:35]
	v_mfma_f32_16x16x32_bf16 v[20:23], v[214:217], v[198:201], v[20:23]
	v_mfma_f32_16x16x32_bf16 v[16:19], v[222:225], v[198:201], v[16:19]
	v_mfma_f32_16x16x32_bf16 v[4:7], v[214:217], v[206:209], v[4:7]
	v_mfma_f32_16x16x32_bf16 v[0:3], v[222:225], v[206:209], v[0:3]
	v_mfma_f32_16x16x32_bf16 v[52:55], v[218:221], v[180:183], v[52:55]
	v_mfma_f32_16x16x32_bf16 v[48:51], v[226:229], v[180:183], v[48:51]
	v_mfma_f32_16x16x32_bf16 v[36:39], v[218:221], v[194:197], v[36:39]
	v_mfma_f32_16x16x32_bf16 v[32:35], v[226:229], v[194:197], v[32:35]
	v_mfma_f32_16x16x32_bf16 v[20:23], v[218:221], v[202:205], v[20:23]
	v_mfma_f32_16x16x32_bf16 v[16:19], v[226:229], v[202:205], v[16:19]
	v_mfma_f32_16x16x32_bf16 v[4:7], v[218:221], v[210:213], v[4:7]
	v_mfma_f32_16x16x32_bf16 v[0:3], v[226:229], v[210:213], v[0:3]
	s_setprio 0
	s_add_i32 s69, s69, 2
	s_add_u32 s40, s40, 0x100
	s_addc_u32 s41, s41, 0
	s_add_u32 s35, s35, 0x100
	s_addc_u32 s68, s68, 0
	s_cmpk_gt_u32 s69, 0x55
	s_cbranch_scc0 .Lrot_297
	s_barrier

;     DI size_t aoff(const Unit& u, size_t tstep) const { return (size_t)u.pm * tstep; }
;     DI size_t boff(const Unit& u, size_t tstep) const { return (size_t)u.pn * tstep; }
;     DI bool next(int i, Unit& u) const { const long L = (long)i * G + c; if (L >= np) return false; u.pm = pmv; u.pn = (int)(L % nN); u.ks = (int)(L / nN); return true; }
;     DI size_t aoff(const Unit& u, size_t) const { return (size_t)u.ks * kbytes; }
;     DI size_t boff(const Unit& u, size_t tstep) const { return (size_t)u.pn * tstep + (size_t)u.ks * kbytes; }
;     DI bool next(int i, Unit& u) const { Unit t; if (!S.next(i / 3, t)) return false; u.pm = t.pm; u.pn = t.pn; u.ks = i % 3; return true; }
;     DI size_t aoff(const Unit& u, size_t tstep) const { return (u.ks < 2 ? offU : offOA) + (size_t)u.pm * tstep; }
; #define PG8_WAIT_V(n) asm volatile("s_waitcnt vmcnt(" #n ")" ::: "memory")
; template <class Epi, class Sched>
; DI void gemm_phase(LAS unsigned char* lds, const Gemm g, const Sched& S, const Epi& E) {
;     ...
;         const bool has_next = S.next(ui + 1, nxt);
;         const char* nA = has_next ? (const char*)g.A + S.aoff(nxt, tstep) : cA; const char* nB = has_next ? (const char*)g.Bt + S.boff(nxt, tstep) : cB;
;         for (int t = 0; t < nt; t += 2) {
;             if constexpr (Epi::HAS_MID) { if (t == E.mid_t(nt)) { int fr3 = fr, fq3 = fq; asm volatile("" : "+v"(fr3), "+v"(fq3)); E.mid(acc, cur, wr, wc, fr3, fq3); } }
;             const bool last = (t == nt - 2);
;             const char* a1 = cA + (size_t)(t + 1) * kstep;
;             const char* a2 = last ? nA : cA + (size_t)(t + 2) * kstep; const char* b2 = last ? nB : cB + (size_t)(t + 2) * kstep;
;             const char* a3 = a2 + kstep; const char* b3 = b2 + kstep;
;             PG8_LDB(B0, 0, 0); PG8_SCHED; PG8_LDA(At, 0, 0); PG8_STAGE(PG8_SA(1, 1), a1 + hstep, voffA);
;             PG8_WAIT_L(8); PG8_BAR; PG8_WAIT_L(0); PG8_MMA(0, 0, At, B0); PG8_BAR; PG8_SCHED;
;             PG8_LDB(B1, 0, 1); PG8_STAGE(PG8_SB(0, 0), b2, voffB);
;             PG8_BAR; PG8_WAIT_L(0); PG8_MMA(0, 1, At, B1); PG8_BAR;
;             PG8_LDA(At, 0, 1); PG8_STAGE(PG8_SA(0, 0), a2, voffA);
;             PG8_BAR; PG8_WAIT_L(0); PG8_MMA(1, 0, At, B0); PG8_BAR; PG8_SCHED;
;             PG8_STAGE(PG8_SB(0, 1), b2 + hstep, voffB);
;             PG8_WAIT_V(6); PG8_BAR; PG8_MMA(1, 1, At, B1); PG8_BAR;
.LBB0_325:
	s_add_u32 s28, s40, s28
	s_addc_u32 s29, s41, s29
	s_and_b64 s[0:1], s[8:9], exec
	s_cselect_b32 s15, s29, s39
	s_cselect_b32 s17, s28, s38
	s_add_u32 s8, s38, 0x160080
	s_addc_u32 s9, s39, 0
	s_add_u32 s66, s36, 0x100
	v_mov_b32_e32 v0, 0
	s_addc_u32 s67, s37, 0
	s_mov_b32 s68, -2
	ds_read_b128 v[150:153], v141
	ds_read_b128 v[154:157], v141 offset:1024
	ds_read_b128 v[162:165], v141 offset:2048
	ds_read_b128 v[166:169], v141 offset:3072
	s_mov_b32 m0, s58
	ds_read_b128 v[170:173], v142
	ds_read_b128 v[174:177], v142 offset:1024
	ds_read_b128 v[178:181], v142 offset:2048
	ds_read_b128 v[188:191], v142 offset:3072
	ds_read_b128 v[194:197], v142 offset:4096
	ds_read_b128 v[198:201], v142 offset:5120
	ds_read_b128 v[202:205], v142 offset:6144
	global_load_lds_dwordx4 v132, s[8:9]
	s_mov_b32 m0, s59
	ds_read_b128 v[206:209], v142 offset:7168
	global_load_lds_dwordx4 v134, s[8:9]
	s_add_u32 s0, s8, 0xffea0080
	s_addc_u32 s1, s9, -1
	s_cmp_eq_u32 s68, 4
	s_cselect_b32 s39, s15, s1
	s_cselect_b32 s38, s17, s0
	s_cselect_b32 s37, s19, s67
	s_cselect_b32 s36, s18, s66
	s_waitcnt lgkmcnt(8)
	s_barrier
	s_waitcnt lgkmcnt(0)
	s_setprio 1
	v_mfma_f32_16x16x32_bf16 v[124:127], v[150:153], v[170:173], 0
	v_mfma_f32_16x16x32_bf16 v[120:123], v[162:165], v[170:173], 0
	v_mfma_f32_16x16x32_bf16 v[116:119], v[150:153], v[178:181], 0
	v_mfma_f32_16x16x32_bf16 v[112:115], v[162:165], v[178:181], 0
	v_mfma_f32_16x16x32_bf16 v[104:107], v[150:153], v[194:197], 0
	v_mfma_f32_16x16x32_bf16 v[96:99], v[162:165], v[194:197], 0
	v_mfma_f32_16x16x32_bf16 v[88:91], v[150:153], v[202:205], 0
	v_mfma_f32_16x16x32_bf16 v[80:83], v[162:165], v[202:205], 0
	v_mfma_f32_16x16x32_bf16 v[124:127], v[154:157], v[174:177], v[124:127]
	v_mfma_f32_16x16x32_bf16 v[120:123], v[166:169], v[174:177], v[120:123]
	v_mfma_f32_16x16x32_bf16 v[116:119], v[154:157], v[188:191], v[116:119]
	v_mfma_f32_16x16x32_bf16 v[112:115], v[166:169], v[188:191], v[112:115]
	v_mfma_f32_16x16x32_bf16 v[104:107], v[154:157], v[198:201], v[104:107]
	v_mfma_f32_16x16x32_bf16 v[96:99], v[166:169], v[198:201], v[96:99]
	v_mfma_f32_16x16x32_bf16 v[88:91], v[154:157], v[206:209], v[88:91]
	v_mfma_f32_16x16x32_bf16 v[80:83], v[166:169], v[206:209], v[80:83]
	s_setprio 0
	s_barrier
	s_mov_b32 m0, s60
	ds_read_b128 v[210:213], v143
	ds_read_b128 v[214:217], v143 offset:1024
	ds_read_b128 v[218:221], v143 offset:2048
	global_load_lds_dwordx4 v130, s[36:37]
	s_mov_b32 m0, s61
	ds_read_b128 v[222:225], v143 offset:3072
	global_load_lds_dwordx4 v128, s[36:37]
	s_barrier
	s_waitcnt lgkmcnt(0)
	s_setprio 1
	v_mfma_f32_16x16x32_bf16 v[108:111], v[210:213], v[170:173], 0
	v_mfma_f32_16x16x32_bf16 v[100:103], v[218:221], v[170:173], 0
	v_mfma_f32_16x16x32_bf16 v[92:95], v[210:213], v[178:181], 0
	v_mfma_f32_16x16x32_bf16 v[84:87], v[218:221], v[178:181], 0
	v_mfma_f32_16x16x32_bf16 v[76:79], v[210:213], v[194:197], 0
	v_mfma_f32_16x16x32_bf16 v[72:75], v[218:221], v[194:197], 0
	v_mfma_f32_16x16x32_bf16 v[68:71], v[210:213], v[202:205], 0
	v_mfma_f32_16x16x32_bf16 v[64:67], v[218:221], v[202:205], 0
	v_mfma_f32_16x16x32_bf16 v[108:111], v[214:217], v[174:177], v[108:111]
	v_mfma_f32_16x16x32_bf16 v[100:103], v[222:225], v[174:177], v[100:103]
	v_mfma_f32_16x16x32_bf16 v[92:95], v[214:217], v[188:191], v[92:95]
	v_mfma_f32_16x16x32_bf16 v[84:87], v[222:225], v[188:191], v[84:87]
	v_mfma_f32_16x16x32_bf16 v[76:79], v[214:217], v[198:201], v[76:79]
	v_mfma_f32_16x16x32_bf16 v[72:75], v[222:225], v[198:201], v[72:75]
	v_mfma_f32_16x16x32_bf16 v[68:71], v[214:217], v[206:209], v[68:71]
	v_mfma_f32_16x16x32_bf16 v[64:67], v[222:225], v[206:209], v[64:67]
	s_setprio 0
	s_mov_b32 m0, s42
	s_barrier
	ds_read_b128 v[170:173], v142 offset:16384
	ds_read_b128 v[174:177], v142 offset:17408
	ds_read_b128 v[178:181], v142 offset:18432
	ds_read_b128 v[188:191], v142 offset:19456
	ds_read_b128 v[194:197], v142 offset:20480
	ds_read_b128 v[198:201], v142 offset:21504
	ds_read_b128 v[202:205], v142 offset:22528
	global_load_lds_dwordx4 v130, s[38:39]
	s_mov_b32 m0, s43
	ds_read_b128 v[206:209], v142 offset:23552
	global_load_lds_dwordx4 v128, s[38:39]
	s_barrier
	s_waitcnt lgkmcnt(0)
	s_setprio 1
	v_mfma_f32_16x16x32_bf16 v[60:63], v[150:153], v[170:173], 0
	v_mfma_f32_16x16x32_bf16 v[56:59], v[162:165], v[170:173], 0
	v_mfma_f32_16x16x32_bf16 v[52:55], v[150:153], v[178:181], 0
	v_mfma_f32_16x16x32_bf16 v[48:51], v[162:165], v[178:181], 0
	v_mfma_f32_16x16x32_bf16 v[40:43], v[150:153], v[194:197], 0
	v_mfma_f32_16x16x32_bf16 v[32:35], v[162:165], v[194:197], 0
	v_mfma_f32_16x16x32_bf16 v[24:27], v[150:153], v[202:205], 0
	v_mfma_f32_16x16x32_bf16 v[16:19], v[162:165], v[202:205], 0
	v_mfma_f32_16x16x32_bf16 v[60:63], v[154:157], v[174:177], v[60:63]
	v_mfma_f32_16x16x32_bf16 v[56:59], v[166:169], v[174:177], v[56:59]
	v_mfma_f32_16x16x32_bf16 v[52:55], v[154:157], v[188:191], v[52:55]
	v_mfma_f32_16x16x32_bf16 v[48:51], v[166:169], v[188:191], v[48:51]
	v_mfma_f32_16x16x32_bf16 v[40:43], v[154:157], v[198:201], v[40:43]
	v_mfma_f32_16x16x32_bf16 v[32:35], v[166:169], v[198:201], v[32:35]
	v_mfma_f32_16x16x32_bf16 v[24:27], v[154:157], v[206:209], v[24:27]
	v_mfma_f32_16x16x32_bf16 v[16:19], v[166:169], v[206:209], v[16:19]
	s_setprio 0
	s_barrier
	s_add_u32 s0, s36, 0x160000
	s_addc_u32 s1, s37, 0
	s_mov_b32 m0, s62
	s_nop 0
	global_load_lds_dwordx4 v130, s[0:1]
	s_mov_b32 m0, s63
	s_nop 0
	global_load_lds_dwordx4 v128, s[0:1]
	s_waitcnt vmcnt(6)
	s_barrier
; #define PG8_STAGE(bufoff, gbase, voff) do { _Pragma("unroll") for (int _i = 0; _i < 2; ++_i) \
;         __builtin_amdgcn_global_load_lds((const unsigned*)((const char*)(gbase) + (voff)[_i]), (LAS unsigned*)(lds + (bufoff) + ldsw + _i * 8192), 16, 0, 0); } while (0)
; #define PG8_LDA(dst, b, h) do { _Pragma("unroll") for (int m = 0; m < 4; ++m) _Pragma("unroll") for (int k = 0; k < 2; ++k) dst[m][k] = *(const LAS bf16x8*)(lds + PG8_SA(b, h) + aoff + m * 2048 + k * 1024); } while (0)
; #define PG8_LDB(dst, b, h) do { _Pragma("unroll") for (int n = 0; n < 2; ++n) _Pragma("unroll") for (int k = 0; k < 2; ++k) dst[n][k] = *(const LAS bf16x8*)(lds + PG8_SB(b, h) + boff + n * 2048 + k * 1024); } while (0)
; #define PG8_MMA(ai, bj, At, Bt) do { __builtin_amdgcn_s_setprio(1); _Pragma("unroll") for (int m = 0; m < 4; ++m) _Pragma("unroll") for (int n = 0; n < 2; ++n) _Pragma("unroll") for (int k = 0; k < 2; ++k) \
;         acc[ai][bj][m][n] = __builtin_amdgcn_mfma_f32_16x16x32_bf16(Bt[n][k], At[m][k], acc[ai][bj][m][n], 0, 0, 0); __builtin_amdgcn_s_setprio(0); } while (0)
; #define PG8_WAIT_V(n) asm volatile("s_waitcnt vmcnt(" #n ")" ::: "memory")
; #define PG8_WAIT_L(n) asm volatile("s_waitcnt lgkmcnt(" #n ")" ::: "memory")
; #define PG8_BAR __builtin_amdgcn_s_barrier()
; #define PG8_SCHED __builtin_amdgcn_sched_barrier(0)
; template <class Epi, class Sched>
; DI void gemm_phase(LAS unsigned char* lds, const Gemm g, const Sched& S, const Epi& E) {
;     ...
;             PG8_WAIT_V(6); PG8_BAR; PG8_MMA(1, 1, At, B1); PG8_BAR;
;             PG8_LDB(B0, 1, 0); PG8_SCHED; PG8_LDA(At, 1, 0); PG8_STAGE(PG8_SA(0, 1), a2 + hstep, voffA);
;             PG8_WAIT_L(8); PG8_BAR; PG8_WAIT_L(0); PG8_MMA(0, 0, At, B0); PG8_BAR; PG8_SCHED;
;             PG8_LDB(B1, 1, 1); PG8_STAGE(PG8_SB(1, 0), b3, voffB);
	s_setprio 1
	v_mfma_f32_16x16x32_bf16 v[44:47], v[210:213], v[170:173], 0
	v_mfma_f32_16x16x32_bf16 v[36:39], v[218:221], v[170:173], 0
	v_mfma_f32_16x16x32_bf16 v[28:31], v[210:213], v[178:181], 0
	v_mfma_f32_16x16x32_bf16 v[20:23], v[218:221], v[178:181], 0
	v_mfma_f32_16x16x32_bf16 v[12:15], v[210:213], v[194:197], 0
	v_mfma_f32_16x16x32_bf16 v[8:11], v[218:221], v[194:197], 0
	v_mfma_f32_16x16x32_bf16 v[4:7], v[210:213], v[202:205], 0
	v_mfma_f32_16x16x32_bf16 v[0:3], v[218:221], v[202:205], 0
	v_mfma_f32_16x16x32_bf16 v[44:47], v[214:217], v[174:177], v[44:47]
	v_mfma_f32_16x16x32_bf16 v[36:39], v[222:225], v[174:177], v[36:39]
	v_mfma_f32_16x16x32_bf16 v[28:31], v[214:217], v[188:191], v[28:31]
	v_mfma_f32_16x16x32_bf16 v[20:23], v[222:225], v[188:191], v[20:23]
	v_mfma_f32_16x16x32_bf16 v[12:15], v[214:217], v[198:201], v[12:15]
	v_mfma_f32_16x16x32_bf16 v[8:11], v[222:225], v[198:201], v[8:11]
	v_mfma_f32_16x16x32_bf16 v[4:7], v[214:217], v[206:209], v[4:7]
	v_mfma_f32_16x16x32_bf16 v[0:3], v[222:225], v[206:209], v[0:3]
	s_setprio 0
	s_barrier
	ds_read_b128 v[150:153], v144
	ds_read_b128 v[154:157], v144 offset:1024
	ds_read_b128 v[162:165], v144 offset:2048
	ds_read_b128 v[166:169], v144 offset:3072
	s_add_u32 s0, s38, 0x160000
	s_addc_u32 s1, s39, 0
	s_mov_b32 m0, s44
	ds_read_b128 v[170:173], v142 offset:32768
	ds_read_b128 v[174:177], v142 offset:33792
	ds_read_b128 v[178:181], v142 offset:34816
	ds_read_b128 v[188:191], v142 offset:35840
	ds_read_b128 v[194:197], v142 offset:36864
	ds_read_b128 v[198:201], v142 offset:37888
	ds_read_b128 v[202:205], v142 offset:38912
	global_load_lds_dwordx4 v130, s[0:1]
	s_mov_b32 m0, s45
	ds_read_b128 v[206:209], v142 offset:39936
	global_load_lds_dwordx4 v128, s[0:1]
	s_waitcnt lgkmcnt(8)
	s_barrier
	s_waitcnt lgkmcnt(0)
	s_setprio 1
	v_mfma_f32_16x16x32_bf16 v[124:127], v[150:153], v[170:173], v[124:127]
	v_mfma_f32_16x16x32_bf16 v[120:123], v[162:165], v[170:173], v[120:123]
	v_mfma_f32_16x16x32_bf16 v[116:119], v[150:153], v[178:181], v[116:119]
	v_mfma_f32_16x16x32_bf16 v[112:115], v[162:165], v[178:181], v[112:115]
	v_mfma_f32_16x16x32_bf16 v[104:107], v[150:153], v[194:197], v[104:107]
	v_mfma_f32_16x16x32_bf16 v[96:99], v[162:165], v[194:197], v[96:99]
	v_mfma_f32_16x16x32_bf16 v[88:91], v[150:153], v[202:205], v[88:91]
	v_mfma_f32_16x16x32_bf16 v[80:83], v[162:165], v[202:205], v[80:83]
	v_mfma_f32_16x16x32_bf16 v[124:127], v[154:157], v[174:177], v[124:127]
	v_mfma_f32_16x16x32_bf16 v[120:123], v[166:169], v[174:177], v[120:123]
	v_mfma_f32_16x16x32_bf16 v[116:119], v[154:157], v[188:191], v[116:119]
	v_mfma_f32_16x16x32_bf16 v[112:115], v[166:169], v[188:191], v[112:115]
	v_mfma_f32_16x16x32_bf16 v[104:107], v[154:157], v[198:201], v[104:107]
	v_mfma_f32_16x16x32_bf16 v[96:99], v[166:169], v[198:201], v[96:99]
	v_mfma_f32_16x16x32_bf16 v[88:91], v[154:157], v[206:209], v[88:91]
	v_mfma_f32_16x16x32_bf16 v[80:83], v[166:169], v[206:209], v[80:83]
	s_setprio 0
	s_barrier
	s_add_i32 s4, 0, 0x1c000
	s_add_i32 s0, s64, s35
	v_add_u32_e32 v145, s4, v140
	s_add_i32 m0, s0, 0xffffff80
	ds_read_b128 v[210:213], v145
	ds_read_b128 v[214:217], v145 offset:1024
	ds_read_b128 v[218:221], v145 offset:2048
	global_load_lds_dwordx4 v130, s[36:37] offset:128
	s_add_i32 m0, s0, 0x1f80
	ds_read_b128 v[222:225], v145 offset:3072
	global_load_lds_dwordx4 v128, s[36:37] offset:128
	s_barrier
; #define PG8_STAGE(bufoff, gbase, voff) do { _Pragma("unroll") for (int _i = 0; _i < 2; ++_i) \
;         __builtin_amdgcn_global_load_lds((const unsigned*)((const char*)(gbase) + (voff)[_i]), (LAS unsigned*)(lds + (bufoff) + ldsw + _i * 8192), 16, 0, 0); } while (0)
; #define PG8_LDA(dst, b, h) do { _Pragma("unroll") for (int m = 0; m < 4; ++m) _Pragma("unroll") for (int k = 0; k < 2; ++k) dst[m][k] = *(const LAS bf16x8*)(lds + PG8_SA(b, h) + aoff + m * 2048 + k * 1024); } while (0)
; #define PG8_MMA(ai, bj, At, Bt) do { __builtin_amdgcn_s_setprio(1); _Pragma("unroll") for (int m = 0; m < 4; ++m) _Pragma("unroll") for (int n = 0; n < 2; ++n) _Pragma("unroll") for (int k = 0; k < 2; ++k) \
;         acc[ai][bj][m][n] = __builtin_amdgcn_mfma_f32_16x16x32_bf16(Bt[n][k], At[m][k], acc[ai][bj][m][n], 0, 0, 0); __builtin_amdgcn_s_setprio(0); } while (0)
; #define PG8_WAIT_V(n) asm volatile("s_waitcnt vmcnt(" #n ")" ::: "memory")
; #define PG8_WAIT_L(n) asm volatile("s_waitcnt lgkmcnt(" #n ")" ::: "memory")
; #define PG8_BAR __builtin_amdgcn_s_barrier()
; #define PG8_SCHED __builtin_amdgcn_sched_barrier(0)
; template <class Epi, class Sched>
; DI void gemm_phase(LAS unsigned char* lds, const Gemm g, const Sched& S, const Epi& E) {
;     ...
;             PG8_BAR; PG8_WAIT_L(0); PG8_MMA(0, 1, At, B1); PG8_BAR;
;             PG8_LDA(At, 1, 1); PG8_STAGE(PG8_SA(1, 0), a3, voffA);
;             PG8_BAR; PG8_WAIT_L(0); PG8_MMA(1, 0, At, B0); PG8_BAR; PG8_SCHED;
;             PG8_STAGE(PG8_SB(1, 1), b3 + hstep, voffB);
;             PG8_WAIT_V(6); PG8_BAR; PG8_MMA(1, 1, At, B1); PG8_BAR;
	s_waitcnt lgkmcnt(0)
	s_setprio 1
	v_mfma_f32_16x16x32_bf16 v[108:111], v[210:213], v[170:173], v[108:111]
	v_mfma_f32_16x16x32_bf16 v[100:103], v[218:221], v[170:173], v[100:103]
	v_mfma_f32_16x16x32_bf16 v[92:95], v[210:213], v[178:181], v[92:95]
	v_mfma_f32_16x16x32_bf16 v[84:87], v[218:221], v[178:181], v[84:87]
	v_mfma_f32_16x16x32_bf16 v[76:79], v[210:213], v[194:197], v[76:79]
	v_mfma_f32_16x16x32_bf16 v[72:75], v[218:221], v[194:197], v[72:75]
	v_mfma_f32_16x16x32_bf16 v[68:71], v[210:213], v[202:205], v[68:71]
	v_mfma_f32_16x16x32_bf16 v[64:67], v[218:221], v[202:205], v[64:67]
	v_mfma_f32_16x16x32_bf16 v[108:111], v[214:217], v[174:177], v[108:111]
	v_mfma_f32_16x16x32_bf16 v[100:103], v[222:225], v[174:177], v[100:103]
	v_mfma_f32_16x16x32_bf16 v[92:95], v[214:217], v[188:191], v[92:95]
	v_mfma_f32_16x16x32_bf16 v[84:87], v[222:225], v[188:191], v[84:87]
	v_mfma_f32_16x16x32_bf16 v[76:79], v[214:217], v[198:201], v[76:79]
	v_mfma_f32_16x16x32_bf16 v[72:75], v[222:225], v[198:201], v[72:75]
	v_mfma_f32_16x16x32_bf16 v[68:71], v[214:217], v[206:209], v[68:71]
	v_mfma_f32_16x16x32_bf16 v[64:67], v[222:225], v[206:209], v[64:67]
	s_setprio 0
	s_add_i32 m0, s56, 0xffffff80
	s_barrier
	ds_read_b128 v[170:173], v142 offset:49152
	ds_read_b128 v[174:177], v142 offset:50176
	ds_read_b128 v[178:181], v142 offset:51200
	ds_read_b128 v[188:191], v142 offset:52224
	ds_read_b128 v[194:197], v142 offset:53248
	ds_read_b128 v[198:201], v142 offset:54272
	ds_read_b128 v[202:205], v142 offset:55296
	global_load_lds_dwordx4 v130, s[38:39] offset:128
	s_add_i32 m0, s57, 0xffffff80
	ds_read_b128 v[206:209], v142 offset:56320
	global_load_lds_dwordx4 v128, s[38:39] offset:128
	s_barrier
	s_waitcnt lgkmcnt(0)
	s_setprio 1
	v_mfma_f32_16x16x32_bf16 v[60:63], v[150:153], v[170:173], v[60:63]
	v_mfma_f32_16x16x32_bf16 v[56:59], v[162:165], v[170:173], v[56:59]
	v_mfma_f32_16x16x32_bf16 v[52:55], v[150:153], v[178:181], v[52:55]
	v_mfma_f32_16x16x32_bf16 v[48:51], v[162:165], v[178:181], v[48:51]
	v_mfma_f32_16x16x32_bf16 v[40:43], v[150:153], v[194:197], v[40:43]
	v_mfma_f32_16x16x32_bf16 v[32:35], v[162:165], v[194:197], v[32:35]
	v_mfma_f32_16x16x32_bf16 v[24:27], v[150:153], v[202:205], v[24:27]
	v_mfma_f32_16x16x32_bf16 v[16:19], v[162:165], v[202:205], v[16:19]
	v_mfma_f32_16x16x32_bf16 v[60:63], v[154:157], v[174:177], v[60:63]
	v_mfma_f32_16x16x32_bf16 v[56:59], v[166:169], v[174:177], v[56:59]
	v_mfma_f32_16x16x32_bf16 v[52:55], v[154:157], v[188:191], v[52:55]
	v_mfma_f32_16x16x32_bf16 v[48:51], v[166:169], v[188:191], v[48:51]
	v_mfma_f32_16x16x32_bf16 v[40:43], v[154:157], v[198:201], v[40:43]
	v_mfma_f32_16x16x32_bf16 v[32:35], v[166:169], v[198:201], v[32:35]
	v_mfma_f32_16x16x32_bf16 v[24:27], v[154:157], v[206:209], v[24:27]
	v_mfma_f32_16x16x32_bf16 v[16:19], v[166:169], v[206:209], v[16:19]
	s_setprio 0
	s_barrier
	s_add_i32 s4, s4, s35
	s_mov_b32 m0, s4
	s_add_u32 s0, s36, 0x160080
	s_addc_u32 s1, s37, 0
	global_load_lds_dwordx4 v130, s[0:1]
	s_add_i32 m0, s4, 0x2000
	s_add_i32 s68, s68, 2
	global_load_lds_dwordx4 v128, s[0:1]
	s_add_u32 s8, s8, 0x100
	s_addc_u32 s9, s9, 0
	s_add_u32 s66, s66, 0x100
	s_addc_u32 s67, s67, 0
	s_cmp_gt_u32 s68, 5
	s_waitcnt vmcnt(6)
	s_barrier
	s_setprio 1
	v_mfma_f32_16x16x32_bf16 v[44:47], v[210:213], v[170:173], v[44:47]
	v_mfma_f32_16x16x32_bf16 v[36:39], v[218:221], v[170:173], v[36:39]
	v_mfma_f32_16x16x32_bf16 v[28:31], v[210:213], v[178:181], v[28:31]
	v_mfma_f32_16x16x32_bf16 v[20:23], v[218:221], v[178:181], v[20:23]
	v_mfma_f32_16x16x32_bf16 v[12:15], v[210:213], v[194:197], v[12:15]
	v_mfma_f32_16x16x32_bf16 v[8:11], v[218:221], v[194:197], v[8:11]
	v_mfma_f32_16x16x32_bf16 v[4:7], v[210:213], v[202:205], v[4:7]
	v_mfma_f32_16x16x32_bf16 v[0:3], v[218:221], v[202:205], v[0:3]
	v_mfma_f32_16x16x32_bf16 v[44:47], v[214:217], v[174:177], v[44:47]
	v_mfma_f32_16x16x32_bf16 v[36:39], v[222:225], v[174:177], v[36:39]
	v_mfma_f32_16x16x32_bf16 v[28:31], v[214:217], v[188:191], v[28:31]
	v_mfma_f32_16x16x32_bf16 v[20:23], v[222:225], v[188:191], v[20:23]
	v_mfma_f32_16x16x32_bf16 v[12:15], v[214:217], v[198:201], v[12:15]
	v_mfma_f32_16x16x32_bf16 v[8:11], v[222:225], v[198:201], v[8:11]
	v_mfma_f32_16x16x32_bf16 v[4:7], v[214:217], v[206:209], v[4:7]
	v_mfma_f32_16x16x32_bf16 v[0:3], v[222:225], v[206:209], v[0:3]
	s_setprio 0
	s_cbranch_scc0 .Lrot_326
	s_barrier
	s_branch .Lpeel_done_326

; #define PG8_STAGE(bufoff, gbase, voff) do { _Pragma("unroll") for (int _i = 0; _i < 2; ++_i) \
;         __builtin_amdgcn_global_load_lds((const unsigned*)((const char*)(gbase) + (voff)[_i]), (LAS unsigned*)(lds + (bufoff) + ldsw + _i * 8192), 16, 0, 0); } while (0)
; #define PG8_LDA(dst, b, h) do { _Pragma("unroll") for (int m = 0; m < 4; ++m) _Pragma("unroll") for (int k = 0; k < 2; ++k) dst[m][k] = *(const LAS bf16x8*)(lds + PG8_SA(b, h) + aoff + m * 2048 + k * 1024); } while (0)
; #define PG8_LDB(dst, b, h) do { _Pragma("unroll") for (int n = 0; n < 2; ++n) _Pragma("unroll") for (int k = 0; k < 2; ++k) dst[n][k] = *(const LAS bf16x8*)(lds + PG8_SB(b, h) + boff + n * 2048 + k * 1024); } while (0)
; #define PG8_MMA(ai, bj, At, Bt) do { __builtin_amdgcn_s_setprio(1); _Pragma("unroll") for (int m = 0; m < 4; ++m) _Pragma("unroll") for (int n = 0; n < 2; ++n) _Pragma("unroll") for (int k = 0; k < 2; ++k) \
;         acc[ai][bj][m][n] = __builtin_amdgcn_mfma_f32_16x16x32_bf16(Bt[n][k], At[m][k], acc[ai][bj][m][n], 0, 0, 0); __builtin_amdgcn_s_setprio(0); } while (0)
; #define PG8_WAIT_V(n) asm volatile("s_waitcnt vmcnt(" #n ")" ::: "memory")
; #define PG8_WAIT_L(n) asm volatile("s_waitcnt lgkmcnt(" #n ")" ::: "memory")
; #define PG8_BAR __builtin_amdgcn_s_barrier()
; #define PG8_SCHED __builtin_amdgcn_sched_barrier(0)
; template <class Epi, class Sched>
; DI void gemm_phase(LAS unsigned char* lds, const Gemm g, const Sched& S, const Epi& E) {
;     ...
;             PG8_LDB(B0, 0, 0); PG8_SCHED; PG8_LDA(At, 0, 0); PG8_STAGE(PG8_SA(1, 1), a1 + hstep, voffA);
;             PG8_WAIT_L(8); PG8_BAR; PG8_WAIT_L(0); PG8_MMA(0, 0, At, B0); PG8_BAR; PG8_SCHED;
;             PG8_LDB(B1, 0, 1); PG8_STAGE(PG8_SB(0, 0), b2, voffB);
;             PG8_BAR; PG8_WAIT_L(0); PG8_MMA(0, 1, At, B1); PG8_BAR;
;             PG8_LDA(At, 0, 1); PG8_STAGE(PG8_SA(0, 0), a2, voffA);
;             PG8_BAR; PG8_WAIT_L(0); PG8_MMA(1, 0, At, B0); PG8_BAR; PG8_SCHED;
;             PG8_STAGE(PG8_SB(0, 1), b2 + hstep, voffB);
;             PG8_WAIT_V(6); PG8_BAR; PG8_MMA(1, 1, At, B1); PG8_BAR;
.LBB0_326:
	ds_read_b128 v[150:153], v141
	ds_read_b128 v[154:157], v141 offset:1024
	ds_read_b128 v[162:165], v141 offset:2048
	ds_read_b128 v[166:169], v141 offset:3072
	s_mov_b32 m0, s58
	ds_read_b128 v[170:173], v142
	ds_read_b128 v[174:177], v142 offset:1024
	ds_read_b128 v[178:181], v142 offset:2048
	ds_read_b128 v[188:191], v142 offset:3072
	ds_read_b128 v[194:197], v142 offset:4096
	ds_read_b128 v[198:201], v142 offset:5120
	ds_read_b128 v[202:205], v142 offset:6144
	global_load_lds_dwordx4 v132, s[8:9]
	s_mov_b32 m0, s59
	ds_read_b128 v[206:209], v142 offset:7168
	global_load_lds_dwordx4 v134, s[8:9]
	s_add_u32 s0, s8, 0xffea0080
	s_addc_u32 s1, s9, -1
	s_cmp_eq_u32 s68, 4
	s_cselect_b32 s39, s15, s1
	s_cselect_b32 s38, s17, s0
	s_cselect_b32 s37, s19, s67
	s_cselect_b32 s36, s18, s66
	s_waitcnt lgkmcnt(8)
	s_barrier
	s_waitcnt lgkmcnt(0)
	s_setprio 1
	v_mfma_f32_16x16x32_bf16 v[124:127], v[150:153], v[170:173], v[124:127]
	v_mfma_f32_16x16x32_bf16 v[120:123], v[162:165], v[170:173], v[120:123]
	v_mfma_f32_16x16x32_bf16 v[116:119], v[150:153], v[178:181], v[116:119]
	v_mfma_f32_16x16x32_bf16 v[112:115], v[162:165], v[178:181], v[112:115]
	v_mfma_f32_16x16x32_bf16 v[104:107], v[150:153], v[194:197], v[104:107]
	v_mfma_f32_16x16x32_bf16 v[96:99], v[162:165], v[194:197], v[96:99]
	v_mfma_f32_16x16x32_bf16 v[88:91], v[150:153], v[202:205], v[88:91]
	v_mfma_f32_16x16x32_bf16 v[80:83], v[162:165], v[202:205], v[80:83]
	v_mfma_f32_16x16x32_bf16 v[124:127], v[154:157], v[174:177], v[124:127]
	v_mfma_f32_16x16x32_bf16 v[120:123], v[166:169], v[174:177], v[120:123]
	v_mfma_f32_16x16x32_bf16 v[116:119], v[154:157], v[188:191], v[116:119]
	v_mfma_f32_16x16x32_bf16 v[112:115], v[166:169], v[188:191], v[112:115]
	v_mfma_f32_16x16x32_bf16 v[104:107], v[154:157], v[198:201], v[104:107]
	v_mfma_f32_16x16x32_bf16 v[96:99], v[166:169], v[198:201], v[96:99]
	v_mfma_f32_16x16x32_bf16 v[88:91], v[154:157], v[206:209], v[88:91]
	v_mfma_f32_16x16x32_bf16 v[80:83], v[166:169], v[206:209], v[80:83]
	s_setprio 0
	s_barrier
	s_mov_b32 m0, s60
	ds_read_b128 v[210:213], v143
	ds_read_b128 v[214:217], v143 offset:1024
	ds_read_b128 v[218:221], v143 offset:2048
	global_load_lds_dwordx4 v130, s[36:37]
	s_mov_b32 m0, s61
	ds_read_b128 v[222:225], v143 offset:3072
	global_load_lds_dwordx4 v128, s[36:37]
	s_barrier
	s_waitcnt lgkmcnt(0)
	s_setprio 1
	v_mfma_f32_16x16x32_bf16 v[108:111], v[210:213], v[170:173], v[108:111]
	v_mfma_f32_16x16x32_bf16 v[100:103], v[218:221], v[170:173], v[100:103]
	v_mfma_f32_16x16x32_bf16 v[92:95], v[210:213], v[178:181], v[92:95]
	v_mfma_f32_16x16x32_bf16 v[84:87], v[218:221], v[178:181], v[84:87]
	v_mfma_f32_16x16x32_bf16 v[76:79], v[210:213], v[194:197], v[76:79]
	v_mfma_f32_16x16x32_bf16 v[72:75], v[218:221], v[194:197], v[72:75]
	v_mfma_f32_16x16x32_bf16 v[68:71], v[210:213], v[202:205], v[68:71]
	v_mfma_f32_16x16x32_bf16 v[64:67], v[218:221], v[202:205], v[64:67]
	v_mfma_f32_16x16x32_bf16 v[108:111], v[214:217], v[174:177], v[108:111]
	v_mfma_f32_16x16x32_bf16 v[100:103], v[222:225], v[174:177], v[100:103]
	v_mfma_f32_16x16x32_bf16 v[92:95], v[214:217], v[188:191], v[92:95]
	v_mfma_f32_16x16x32_bf16 v[84:87], v[222:225], v[188:191], v[84:87]
	v_mfma_f32_16x16x32_bf16 v[76:79], v[214:217], v[198:201], v[76:79]
	v_mfma_f32_16x16x32_bf16 v[72:75], v[222:225], v[198:201], v[72:75]
	v_mfma_f32_16x16x32_bf16 v[68:71], v[214:217], v[206:209], v[68:71]
	v_mfma_f32_16x16x32_bf16 v[64:67], v[222:225], v[206:209], v[64:67]
	s_setprio 0
	s_mov_b32 m0, s42
	s_barrier
	ds_read_b128 v[170:173], v142 offset:16384
	ds_read_b128 v[174:177], v142 offset:17408
	ds_read_b128 v[178:181], v142 offset:18432
	ds_read_b128 v[188:191], v142 offset:19456
	ds_read_b128 v[194:197], v142 offset:20480
	ds_read_b128 v[198:201], v142 offset:21504
	ds_read_b128 v[202:205], v142 offset:22528
	global_load_lds_dwordx4 v130, s[38:39]
	s_mov_b32 m0, s43
	ds_read_b128 v[206:209], v142 offset:23552
	global_load_lds_dwordx4 v128, s[38:39]
	s_barrier
	s_waitcnt lgkmcnt(0)
	s_setprio 1
	v_mfma_f32_16x16x32_bf16 v[60:63], v[150:153], v[170:173], v[60:63]
	v_mfma_f32_16x16x32_bf16 v[56:59], v[162:165], v[170:173], v[56:59]
	v_mfma_f32_16x16x32_bf16 v[52:55], v[150:153], v[178:181], v[52:55]
	v_mfma_f32_16x16x32_bf16 v[48:51], v[162:165], v[178:181], v[48:51]
	v_mfma_f32_16x16x32_bf16 v[40:43], v[150:153], v[194:197], v[40:43]
	v_mfma_f32_16x16x32_bf16 v[32:35], v[162:165], v[194:197], v[32:35]
	v_mfma_f32_16x16x32_bf16 v[24:27], v[150:153], v[202:205], v[24:27]
	v_mfma_f32_16x16x32_bf16 v[16:19], v[162:165], v[202:205], v[16:19]
	v_mfma_f32_16x16x32_bf16 v[60:63], v[154:157], v[174:177], v[60:63]
	v_mfma_f32_16x16x32_bf16 v[56:59], v[166:169], v[174:177], v[56:59]
	v_mfma_f32_16x16x32_bf16 v[52:55], v[154:157], v[188:191], v[52:55]
	v_mfma_f32_16x16x32_bf16 v[48:51], v[166:169], v[188:191], v[48:51]
	v_mfma_f32_16x16x32_bf16 v[40:43], v[154:157], v[198:201], v[40:43]
	v_mfma_f32_16x16x32_bf16 v[32:35], v[166:169], v[198:201], v[32:35]
	v_mfma_f32_16x16x32_bf16 v[24:27], v[154:157], v[206:209], v[24:27]
	v_mfma_f32_16x16x32_bf16 v[16:19], v[166:169], v[206:209], v[16:19]
	s_setprio 0
	s_barrier
	s_add_u32 s0, s36, 0x160000
	s_addc_u32 s1, s37, 0
	s_mov_b32 m0, s62
	s_nop 0
	global_load_lds_dwordx4 v130, s[0:1]
	s_mov_b32 m0, s63
	s_nop 0
	global_load_lds_dwordx4 v128, s[0:1]
	s_waitcnt vmcnt(6)
	s_barrier
; #define PG8_STAGE(bufoff, gbase, voff) do { _Pragma("unroll") for (int _i = 0; _i < 2; ++_i) \
;         __builtin_amdgcn_global_load_lds((const unsigned*)((const char*)(gbase) + (voff)[_i]), (LAS unsigned*)(lds + (bufoff) + ldsw + _i * 8192), 16, 0, 0); } while (0)
; #define PG8_LDA(dst, b, h) do { _Pragma("unroll") for (int m = 0; m < 4; ++m) _Pragma("unroll") for (int k = 0; k < 2; ++k) dst[m][k] = *(const LAS bf16x8*)(lds + PG8_SA(b, h) + aoff + m * 2048 + k * 1024); } while (0)
; #define PG8_LDB(dst, b, h) do { _Pragma("unroll") for (int n = 0; n < 2; ++n) _Pragma("unroll") for (int k = 0; k < 2; ++k) dst[n][k] = *(const LAS bf16x8*)(lds + PG8_SB(b, h) + boff + n * 2048 + k * 1024); } while (0)
; #define PG8_MMA(ai, bj, At, Bt) do { __builtin_amdgcn_s_setprio(1); _Pragma("unroll") for (int m = 0; m < 4; ++m) _Pragma("unroll") for (int n = 0; n < 2; ++n) _Pragma("unroll") for (int k = 0; k < 2; ++k) \
;         acc[ai][bj][m][n] = __builtin_amdgcn_mfma_f32_16x16x32_bf16(Bt[n][k], At[m][k], acc[ai][bj][m][n], 0, 0, 0); __builtin_amdgcn_s_setprio(0); } while (0)
; #define PG8_WAIT_V(n) asm volatile("s_waitcnt vmcnt(" #n ")" ::: "memory")
; #define PG8_WAIT_L(n) asm volatile("s_waitcnt lgkmcnt(" #n ")" ::: "memory")
; #define PG8_BAR __builtin_amdgcn_s_barrier()
; #define PG8_SCHED __builtin_amdgcn_sched_barrier(0)
; template <class Epi, class Sched>
; DI void gemm_phase(LAS unsigned char* lds, const Gemm g, const Sched& S, const Epi& E) {
;     ...
;             PG8_WAIT_V(6); PG8_BAR; PG8_MMA(1, 1, At, B1); PG8_BAR;
;             PG8_LDB(B0, 1, 0); PG8_SCHED; PG8_LDA(At, 1, 0); PG8_STAGE(PG8_SA(0, 1), a2 + hstep, voffA);
;             PG8_WAIT_L(8); PG8_BAR; PG8_WAIT_L(0); PG8_MMA(0, 0, At, B0); PG8_BAR; PG8_SCHED;
;             PG8_LDB(B1, 1, 1); PG8_STAGE(PG8_SB(1, 0), b3, voffB);
	s_setprio 1
	v_mfma_f32_16x16x32_bf16 v[44:47], v[210:213], v[170:173], v[44:47]
	v_mfma_f32_16x16x32_bf16 v[36:39], v[218:221], v[170:173], v[36:39]
	v_mfma_f32_16x16x32_bf16 v[28:31], v[210:213], v[178:181], v[28:31]
	v_mfma_f32_16x16x32_bf16 v[20:23], v[218:221], v[178:181], v[20:23]
	v_mfma_f32_16x16x32_bf16 v[12:15], v[210:213], v[194:197], v[12:15]
	v_mfma_f32_16x16x32_bf16 v[8:11], v[218:221], v[194:197], v[8:11]
	v_mfma_f32_16x16x32_bf16 v[4:7], v[210:213], v[202:205], v[4:7]
	v_mfma_f32_16x16x32_bf16 v[0:3], v[218:221], v[202:205], v[0:3]
	v_mfma_f32_16x16x32_bf16 v[44:47], v[214:217], v[174:177], v[44:47]
	v_mfma_f32_16x16x32_bf16 v[36:39], v[222:225], v[174:177], v[36:39]
	v_mfma_f32_16x16x32_bf16 v[28:31], v[214:217], v[188:191], v[28:31]
	v_mfma_f32_16x16x32_bf16 v[20:23], v[222:225], v[188:191], v[20:23]
	v_mfma_f32_16x16x32_bf16 v[12:15], v[214:217], v[198:201], v[12:15]
	v_mfma_f32_16x16x32_bf16 v[8:11], v[222:225], v[198:201], v[8:11]
	v_mfma_f32_16x16x32_bf16 v[4:7], v[214:217], v[206:209], v[4:7]
	v_mfma_f32_16x16x32_bf16 v[0:3], v[222:225], v[206:209], v[0:3]
	s_setprio 0
	s_barrier
	ds_read_b128 v[150:153], v144
	ds_read_b128 v[154:157], v144 offset:1024
	ds_read_b128 v[162:165], v144 offset:2048
	ds_read_b128 v[166:169], v144 offset:3072
	s_add_u32 s0, s38, 0x160000
	s_addc_u32 s1, s39, 0
	s_mov_b32 m0, s44
	ds_read_b128 v[170:173], v142 offset:32768
	ds_read_b128 v[174:177], v142 offset:33792
	ds_read_b128 v[178:181], v142 offset:34816
	ds_read_b128 v[188:191], v142 offset:35840
	ds_read_b128 v[194:197], v142 offset:36864
	ds_read_b128 v[198:201], v142 offset:37888
	ds_read_b128 v[202:205], v142 offset:38912
	global_load_lds_dwordx4 v130, s[0:1]
	s_mov_b32 m0, s45
	ds_read_b128 v[206:209], v142 offset:39936
	global_load_lds_dwordx4 v128, s[0:1]
	s_waitcnt lgkmcnt(8)
	s_barrier
	s_waitcnt lgkmcnt(0)
	s_setprio 1
	v_mfma_f32_16x16x32_bf16 v[124:127], v[150:153], v[170:173], v[124:127]
	v_mfma_f32_16x16x32_bf16 v[120:123], v[162:165], v[170:173], v[120:123]
	v_mfma_f32_16x16x32_bf16 v[116:119], v[150:153], v[178:181], v[116:119]
	v_mfma_f32_16x16x32_bf16 v[112:115], v[162:165], v[178:181], v[112:115]
	v_mfma_f32_16x16x32_bf16 v[104:107], v[150:153], v[194:197], v[104:107]
	v_mfma_f32_16x16x32_bf16 v[96:99], v[162:165], v[194:197], v[96:99]
	v_mfma_f32_16x16x32_bf16 v[88:91], v[150:153], v[202:205], v[88:91]
	v_mfma_f32_16x16x32_bf16 v[80:83], v[162:165], v[202:205], v[80:83]
	v_mfma_f32_16x16x32_bf16 v[124:127], v[154:157], v[174:177], v[124:127]
	v_mfma_f32_16x16x32_bf16 v[120:123], v[166:169], v[174:177], v[120:123]
	v_mfma_f32_16x16x32_bf16 v[116:119], v[154:157], v[188:191], v[116:119]
	v_mfma_f32_16x16x32_bf16 v[112:115], v[166:169], v[188:191], v[112:115]
	v_mfma_f32_16x16x32_bf16 v[104:107], v[154:157], v[198:201], v[104:107]
	v_mfma_f32_16x16x32_bf16 v[96:99], v[166:169], v[198:201], v[96:99]
	v_mfma_f32_16x16x32_bf16 v[88:91], v[154:157], v[206:209], v[88:91]
	v_mfma_f32_16x16x32_bf16 v[80:83], v[166:169], v[206:209], v[80:83]
	s_setprio 0
	s_barrier
	s_add_i32 s4, 0, 0x1c000
	s_add_i32 s0, s64, s35
	v_add_u32_e32 v145, s4, v140
	s_add_i32 m0, s0, 0xffffff80
	ds_read_b128 v[210:213], v145
	ds_read_b128 v[214:217], v145 offset:1024
	ds_read_b128 v[218:221], v145 offset:2048
	global_load_lds_dwordx4 v130, s[36:37] offset:128
	s_add_i32 m0, s0, 0x1f80
	ds_read_b128 v[222:225], v145 offset:3072
	global_load_lds_dwordx4 v128, s[36:37] offset:128
	s_barrier
; #define PG8_STAGE(bufoff, gbase, voff) do { _Pragma("unroll") for (int _i = 0; _i < 2; ++_i) \
;         __builtin_amdgcn_global_load_lds((const unsigned*)((const char*)(gbase) + (voff)[_i]), (LAS unsigned*)(lds + (bufoff) + ldsw + _i * 8192), 16, 0, 0); } while (0)
; #define PG8_LDA(dst, b, h) do { _Pragma("unroll") for (int m = 0; m < 4; ++m) _Pragma("unroll") for (int k = 0; k < 2; ++k) dst[m][k] = *(const LAS bf16x8*)(lds + PG8_SA(b, h) + aoff + m * 2048 + k * 1024); } while (0)
; #define PG8_MMA(ai, bj, At, Bt) do { __builtin_amdgcn_s_setprio(1); _Pragma("unroll") for (int m = 0; m < 4; ++m) _Pragma("unroll") for (int n = 0; n < 2; ++n) _Pragma("unroll") for (int k = 0; k < 2; ++k) \
;         acc[ai][bj][m][n] = __builtin_amdgcn_mfma_f32_16x16x32_bf16(Bt[n][k], At[m][k], acc[ai][bj][m][n], 0, 0, 0); __builtin_amdgcn_s_setprio(0); } while (0)
; #define PG8_WAIT_V(n) asm volatile("s_waitcnt vmcnt(" #n ")" ::: "memory")
; #define PG8_WAIT_L(n) asm volatile("s_waitcnt lgkmcnt(" #n ")" ::: "memory")
; #define PG8_BAR __builtin_amdgcn_s_barrier()
; #define PG8_SCHED __builtin_amdgcn_sched_barrier(0)
; template <class Epi, class Sched>
; DI void gemm_phase(LAS unsigned char* lds, const Gemm g, const Sched& S, const Epi& E) {
;     ...
;             PG8_BAR; PG8_WAIT_L(0); PG8_MMA(0, 1, At, B1); PG8_BAR;
;             PG8_LDA(At, 1, 1); PG8_STAGE(PG8_SA(1, 0), a3, voffA);
;             PG8_BAR; PG8_WAIT_L(0); PG8_MMA(1, 0, At, B0); PG8_BAR; PG8_SCHED;
;             PG8_STAGE(PG8_SB(1, 1), b3 + hstep, voffB);
;             PG8_WAIT_V(6); PG8_BAR; PG8_MMA(1, 1, At, B1); PG8_BAR;
	s_waitcnt lgkmcnt(0)
	s_setprio 1
	v_mfma_f32_16x16x32_bf16 v[108:111], v[210:213], v[170:173], v[108:111]
	v_mfma_f32_16x16x32_bf16 v[100:103], v[218:221], v[170:173], v[100:103]
	v_mfma_f32_16x16x32_bf16 v[92:95], v[210:213], v[178:181], v[92:95]
	v_mfma_f32_16x16x32_bf16 v[84:87], v[218:221], v[178:181], v[84:87]
	v_mfma_f32_16x16x32_bf16 v[76:79], v[210:213], v[194:197], v[76:79]
	v_mfma_f32_16x16x32_bf16 v[72:75], v[218:221], v[194:197], v[72:75]
	v_mfma_f32_16x16x32_bf16 v[68:71], v[210:213], v[202:205], v[68:71]
	v_mfma_f32_16x16x32_bf16 v[64:67], v[218:221], v[202:205], v[64:67]
	v_mfma_f32_16x16x32_bf16 v[108:111], v[214:217], v[174:177], v[108:111]
	v_mfma_f32_16x16x32_bf16 v[100:103], v[222:225], v[174:177], v[100:103]
	v_mfma_f32_16x16x32_bf16 v[92:95], v[214:217], v[188:191], v[92:95]
	v_mfma_f32_16x16x32_bf16 v[84:87], v[222:225], v[188:191], v[84:87]
	v_mfma_f32_16x16x32_bf16 v[76:79], v[214:217], v[198:201], v[76:79]
	v_mfma_f32_16x16x32_bf16 v[72:75], v[222:225], v[198:201], v[72:75]
	v_mfma_f32_16x16x32_bf16 v[68:71], v[214:217], v[206:209], v[68:71]
	v_mfma_f32_16x16x32_bf16 v[64:67], v[222:225], v[206:209], v[64:67]
	s_setprio 0
	s_add_i32 m0, s56, 0xffffff80
	s_barrier
	ds_read_b128 v[170:173], v142 offset:49152
	ds_read_b128 v[174:177], v142 offset:50176
	ds_read_b128 v[178:181], v142 offset:51200
	ds_read_b128 v[188:191], v142 offset:52224
	ds_read_b128 v[194:197], v142 offset:53248
	ds_read_b128 v[198:201], v142 offset:54272
	ds_read_b128 v[202:205], v142 offset:55296
	global_load_lds_dwordx4 v130, s[38:39] offset:128
	s_add_i32 m0, s57, 0xffffff80
	ds_read_b128 v[206:209], v142 offset:56320
	global_load_lds_dwordx4 v128, s[38:39] offset:128
	s_barrier
	s_waitcnt lgkmcnt(0)
	s_setprio 1
	v_mfma_f32_16x16x32_bf16 v[60:63], v[150:153], v[170:173], v[60:63]
	v_mfma_f32_16x16x32_bf16 v[56:59], v[162:165], v[170:173], v[56:59]
	v_mfma_f32_16x16x32_bf16 v[52:55], v[150:153], v[178:181], v[52:55]
	v_mfma_f32_16x16x32_bf16 v[48:51], v[162:165], v[178:181], v[48:51]
	v_mfma_f32_16x16x32_bf16 v[40:43], v[150:153], v[194:197], v[40:43]
	v_mfma_f32_16x16x32_bf16 v[32:35], v[162:165], v[194:197], v[32:35]
	v_mfma_f32_16x16x32_bf16 v[24:27], v[150:153], v[202:205], v[24:27]
	v_mfma_f32_16x16x32_bf16 v[16:19], v[162:165], v[202:205], v[16:19]
	v_mfma_f32_16x16x32_bf16 v[60:63], v[154:157], v[174:177], v[60:63]
	v_mfma_f32_16x16x32_bf16 v[56:59], v[166:169], v[174:177], v[56:59]
	v_mfma_f32_16x16x32_bf16 v[52:55], v[154:157], v[188:191], v[52:55]
	v_mfma_f32_16x16x32_bf16 v[48:51], v[166:169], v[188:191], v[48:51]
	v_mfma_f32_16x16x32_bf16 v[40:43], v[154:157], v[198:201], v[40:43]
	v_mfma_f32_16x16x32_bf16 v[32:35], v[166:169], v[198:201], v[32:35]
	v_mfma_f32_16x16x32_bf16 v[24:27], v[154:157], v[206:209], v[24:27]
	v_mfma_f32_16x16x32_bf16 v[16:19], v[166:169], v[206:209], v[16:19]
	s_setprio 0
	s_barrier
	s_add_i32 s4, s4, s35
	s_mov_b32 m0, s4
	s_add_u32 s0, s36, 0x160080
	s_addc_u32 s1, s37, 0
	global_load_lds_dwordx4 v130, s[0:1]
	s_add_i32 m0, s4, 0x2000
	s_add_i32 s68, s68, 2
	global_load_lds_dwordx4 v128, s[0:1]
	s_add_u32 s8, s8, 0x100
	s_addc_u32 s9, s9, 0
	s_add_u32 s66, s66, 0x100
	s_addc_u32 s67, s67, 0
	s_cmp_gt_u32 s68, 5
	s_waitcnt vmcnt(6)
	s_barrier
	s_setprio 1
	v_mfma_f32_16x16x32_bf16 v[44:47], v[210:213], v[170:173], v[44:47]
	v_mfma_f32_16x16x32_bf16 v[36:39], v[218:221], v[170:173], v[36:39]
	v_mfma_f32_16x16x32_bf16 v[28:31], v[210:213], v[178:181], v[28:31]
	v_mfma_f32_16x16x32_bf16 v[20:23], v[218:221], v[178:181], v[20:23]
	v_mfma_f32_16x16x32_bf16 v[12:15], v[210:213], v[194:197], v[12:15]
	v_mfma_f32_16x16x32_bf16 v[8:11], v[218:221], v[194:197], v[8:11]
	v_mfma_f32_16x16x32_bf16 v[4:7], v[210:213], v[202:205], v[4:7]
	v_mfma_f32_16x16x32_bf16 v[0:3], v[218:221], v[202:205], v[0:3]
	v_mfma_f32_16x16x32_bf16 v[44:47], v[214:217], v[174:177], v[44:47]
	v_mfma_f32_16x16x32_bf16 v[36:39], v[222:225], v[174:177], v[36:39]
	v_mfma_f32_16x16x32_bf16 v[28:31], v[214:217], v[188:191], v[28:31]
	v_mfma_f32_16x16x32_bf16 v[20:23], v[222:225], v[188:191], v[20:23]
	v_mfma_f32_16x16x32_bf16 v[12:15], v[214:217], v[198:201], v[12:15]
	v_mfma_f32_16x16x32_bf16 v[8:11], v[222:225], v[198:201], v[8:11]
	v_mfma_f32_16x16x32_bf16 v[4:7], v[214:217], v[206:209], v[4:7]
	v_mfma_f32_16x16x32_bf16 v[0:3], v[222:225], v[206:209], v[0:3]
	s_setprio 0
	s_cbranch_scc0 .Lrot_326
	s_barrier

;     DI size_t aoff(const Unit& u, size_t tstep) const { return (size_t)u.pm * tstep; }
;     DI size_t boff(const Unit& u, size_t tstep) const { return (size_t)u.pn * tstep; }
;     DI bool next(int i, Unit& u) const { const long L = (long)i * G + c; if (L >= np) return false; u.pm = pmv; u.pn = (int)(L % nN); u.ks = (int)(L / nN); return true; }
;     DI size_t aoff(const Unit& u, size_t) const { return (size_t)u.ks * kbytes; }
;     DI size_t boff(const Unit& u, size_t tstep) const { return (size_t)u.pn * tstep + (size_t)u.ks * kbytes; }
;     DI bool next(int i, Unit& u) const { Unit t; if (!S.next(i / 3, t)) return false; u.pm = t.pm; u.pn = t.pn; u.ks = i % 3; return true; }
;     DI size_t aoff(const Unit& u, size_t tstep) const { return (u.ks < 2 ? offU : offOA) + (size_t)u.pm * tstep; }
; #define PG8_WAIT_V(n) asm volatile("s_waitcnt vmcnt(" #n ")" ::: "memory")
; template <class Epi, class Sched>
; DI void gemm_phase(LAS unsigned char* lds, const Gemm g, const Sched& S, const Epi& E) {
;     ...
;         const bool has_next = S.next(ui + 1, nxt);
;         const char* nA = has_next ? (const char*)g.A + S.aoff(nxt, tstep) : cA; const char* nB = has_next ? (const char*)g.Bt + S.boff(nxt, tstep) : cB;
;         for (int t = 0; t < nt; t += 2) {
;             if constexpr (Epi::HAS_MID) { if (t == E.mid_t(nt)) { int fr3 = fr, fq3 = fq; asm volatile("" : "+v"(fr3), "+v"(fq3)); E.mid(acc, cur, wr, wc, fr3, fq3); } }
;             const bool last = (t == nt - 2);
;             const char* a1 = cA + (size_t)(t + 1) * kstep;
;             const char* a2 = last ? nA : cA + (size_t)(t + 2) * kstep; const char* b2 = last ? nB : cB + (size_t)(t + 2) * kstep;
;             const char* a3 = a2 + kstep; const char* b3 = b2 + kstep;
;             PG8_LDB(B0, 0, 0); PG8_SCHED; PG8_LDA(At, 0, 0); PG8_STAGE(PG8_SA(1, 1), a1 + hstep, voffA);
;             PG8_WAIT_L(8); PG8_BAR; PG8_WAIT_L(0); PG8_MMA(0, 0, At, B0); PG8_BAR; PG8_SCHED;
;             PG8_LDB(B1, 0, 1); PG8_STAGE(PG8_SB(0, 0), b2, voffB);
;             PG8_BAR; PG8_WAIT_L(0); PG8_MMA(0, 1, At, B1); PG8_BAR;
;             PG8_LDA(At, 0, 1); PG8_STAGE(PG8_SA(0, 0), a2, voffA);
;             PG8_BAR; PG8_WAIT_L(0); PG8_MMA(1, 0, At, B0); PG8_BAR; PG8_SCHED;
;             PG8_STAGE(PG8_SB(0, 1), b2 + hstep, voffB);
;             PG8_WAIT_V(6); PG8_BAR; PG8_MMA(1, 1, At, B1); PG8_BAR;
.LBB0_526:
	s_ashr_i32 s51, s50, 31
	s_lshl_b64 s[0:1], s[50:51], 20
	s_add_u32 s52, s70, s0
	v_cmp_lt_i64_e32 vcc, s[12:13], v[142:143]
	s_addc_u32 s53, s71, s1
	s_and_b64 s[0:1], vcc, exec
	s_cselect_b32 s14, s53, s9
	s_cselect_b32 s15, s52, s8
	s_ashr_i32 s49, s48, 31
	s_lshl_b64 s[0:1], s[48:49], 20
	s_add_u32 s54, s72, s0
	s_addc_u32 s55, s73, s1
	s_and_b64 s[0:1], vcc, exec
	s_cselect_b32 s16, s55, s11
	s_cselect_b32 s17, s54, s10
	s_add_u32 s8, s8, 0x80080
	s_addc_u32 s9, s9, 0
	s_add_u32 s28, s10, 0x100
	v_mov_b32_e32 v0, 0
	s_addc_u32 s34, s11, 0
	s_mov_b32 s35, -2
	ds_read_b128 v[146:149], v164
	ds_read_b128 v[150:153], v164 offset:1024
	ds_read_b128 v[154:157], v164 offset:2048
	ds_read_b128 v[170:173], v164 offset:3072
	s_add_i32 m0, s59, 0xc000
	ds_read_b128 v[174:177], v165
	ds_read_b128 v[178:181], v165 offset:1024
	ds_read_b128 v[188:191], v165 offset:2048
	ds_read_b128 v[194:197], v165 offset:3072
	ds_read_b128 v[198:201], v165 offset:4096
	ds_read_b128 v[202:205], v165 offset:5120
	ds_read_b128 v[206:209], v165 offset:6144
	global_load_lds_dwordx4 v138, s[8:9]
	s_add_i32 m0, s59, 0xe000
	ds_read_b128 v[210:213], v165 offset:7168
	global_load_lds_dwordx4 v140, s[8:9]
	s_add_u32 s0, s8, 0xfff80080
	s_addc_u32 s1, s9, -1
	s_cmp_eq_u32 s35, 28
	s_cselect_b32 s13, s14, s1
	s_cselect_b32 s12, s15, s0
	s_cselect_b32 s11, s16, s34
	s_cselect_b32 s10, s17, s28
	s_waitcnt lgkmcnt(8)
	s_barrier
	s_waitcnt lgkmcnt(0)
	s_setprio 1
	v_mfma_f32_16x16x32_bf16 v[124:127], v[146:149], v[174:177], 0
	v_mfma_f32_16x16x32_bf16 v[120:123], v[154:157], v[174:177], 0
	v_mfma_f32_16x16x32_bf16 v[108:111], v[146:149], v[188:191], 0
	v_mfma_f32_16x16x32_bf16 v[104:107], v[154:157], v[188:191], 0
	v_mfma_f32_16x16x32_bf16 v[92:95], v[146:149], v[198:201], 0
	v_mfma_f32_16x16x32_bf16 v[88:91], v[154:157], v[198:201], 0
	v_mfma_f32_16x16x32_bf16 v[76:79], v[146:149], v[206:209], 0
	v_mfma_f32_16x16x32_bf16 v[72:75], v[154:157], v[206:209], 0
	v_mfma_f32_16x16x32_bf16 v[124:127], v[150:153], v[178:181], v[124:127]
	v_mfma_f32_16x16x32_bf16 v[120:123], v[170:173], v[178:181], v[120:123]
	v_mfma_f32_16x16x32_bf16 v[108:111], v[150:153], v[194:197], v[108:111]
	v_mfma_f32_16x16x32_bf16 v[104:107], v[170:173], v[194:197], v[104:107]
	v_mfma_f32_16x16x32_bf16 v[92:95], v[150:153], v[202:205], v[92:95]
	v_mfma_f32_16x16x32_bf16 v[88:91], v[170:173], v[202:205], v[88:91]
	v_mfma_f32_16x16x32_bf16 v[76:79], v[150:153], v[210:213], v[76:79]
	v_mfma_f32_16x16x32_bf16 v[72:75], v[170:173], v[210:213], v[72:75]
	s_setprio 0
	s_barrier
	s_add_i32 s0, s47, s74
	s_mov_b32 m0, s0
	ds_read_b128 v[214:217], v166
	ds_read_b128 v[218:221], v166 offset:1024
	ds_read_b128 v[222:225], v166 offset:2048
	global_load_lds_dwordx4 v130, s[10:11]
	s_add_i32 m0, s0, 0x2000
	ds_read_b128 v[226:229], v166 offset:3072
	global_load_lds_dwordx4 v134, s[10:11]
	s_barrier
	s_waitcnt lgkmcnt(0)
	s_setprio 1
	v_mfma_f32_16x16x32_bf16 v[116:119], v[214:217], v[174:177], 0
	v_mfma_f32_16x16x32_bf16 v[112:115], v[222:225], v[174:177], 0
	v_mfma_f32_16x16x32_bf16 v[100:103], v[214:217], v[188:191], 0
	v_mfma_f32_16x16x32_bf16 v[96:99], v[222:225], v[188:191], 0
	v_mfma_f32_16x16x32_bf16 v[84:87], v[214:217], v[198:201], 0
	v_mfma_f32_16x16x32_bf16 v[80:83], v[222:225], v[198:201], 0
	v_mfma_f32_16x16x32_bf16 v[68:71], v[214:217], v[206:209], 0
	v_mfma_f32_16x16x32_bf16 v[64:67], v[222:225], v[206:209], 0
	v_mfma_f32_16x16x32_bf16 v[116:119], v[218:221], v[178:181], v[116:119]
	v_mfma_f32_16x16x32_bf16 v[112:115], v[226:229], v[178:181], v[112:115]
	v_mfma_f32_16x16x32_bf16 v[100:103], v[218:221], v[194:197], v[100:103]
	v_mfma_f32_16x16x32_bf16 v[96:99], v[226:229], v[194:197], v[96:99]
	v_mfma_f32_16x16x32_bf16 v[84:87], v[218:221], v[202:205], v[84:87]
	v_mfma_f32_16x16x32_bf16 v[80:83], v[226:229], v[202:205], v[80:83]
	v_mfma_f32_16x16x32_bf16 v[68:71], v[218:221], v[210:213], v[68:71]
	v_mfma_f32_16x16x32_bf16 v[64:67], v[226:229], v[210:213], v[64:67]
	s_setprio 0
	s_mov_b32 m0, s59
	s_barrier
	ds_read_b128 v[174:177], v165 offset:16384
	ds_read_b128 v[178:181], v165 offset:17408
	ds_read_b128 v[188:191], v165 offset:18432
	ds_read_b128 v[194:197], v165 offset:19456
	ds_read_b128 v[198:201], v165 offset:20480
	ds_read_b128 v[202:205], v165 offset:21504
	ds_read_b128 v[206:209], v165 offset:22528
	global_load_lds_dwordx4 v128, s[12:13]
	s_mov_b32 m0, s75
	ds_read_b128 v[210:213], v165 offset:23552
	global_load_lds_dwordx4 v132, s[12:13]
	s_barrier
	s_waitcnt lgkmcnt(0)
	s_setprio 1
	v_mfma_f32_16x16x32_bf16 v[60:63], v[146:149], v[174:177], 0
	v_mfma_f32_16x16x32_bf16 v[56:59], v[154:157], v[174:177], 0
	v_mfma_f32_16x16x32_bf16 v[44:47], v[146:149], v[188:191], 0
	v_mfma_f32_16x16x32_bf16 v[40:43], v[154:157], v[188:191], 0
	v_mfma_f32_16x16x32_bf16 v[28:31], v[146:149], v[198:201], 0
	v_mfma_f32_16x16x32_bf16 v[24:27], v[154:157], v[198:201], 0
	v_mfma_f32_16x16x32_bf16 v[12:15], v[146:149], v[206:209], 0
	v_mfma_f32_16x16x32_bf16 v[8:11], v[154:157], v[206:209], 0
	v_mfma_f32_16x16x32_bf16 v[60:63], v[150:153], v[178:181], v[60:63]
	v_mfma_f32_16x16x32_bf16 v[56:59], v[170:173], v[178:181], v[56:59]
	v_mfma_f32_16x16x32_bf16 v[44:47], v[150:153], v[194:197], v[44:47]
	v_mfma_f32_16x16x32_bf16 v[40:43], v[170:173], v[194:197], v[40:43]
	v_mfma_f32_16x16x32_bf16 v[28:31], v[150:153], v[202:205], v[28:31]
	v_mfma_f32_16x16x32_bf16 v[24:27], v[170:173], v[202:205], v[24:27]
	v_mfma_f32_16x16x32_bf16 v[12:15], v[150:153], v[210:213], v[12:15]
	v_mfma_f32_16x16x32_bf16 v[8:11], v[170:173], v[210:213], v[8:11]
	s_setprio 0
	s_barrier
; #define PG8_STAGE(bufoff, gbase, voff) do { _Pragma("unroll") for (int _i = 0; _i < 2; ++_i) \
;         __builtin_amdgcn_global_load_lds((const unsigned*)((const char*)(gbase) + (voff)[_i]), (LAS unsigned*)(lds + (bufoff) + ldsw + _i * 8192), 16, 0, 0); } while (0)
; #define PG8_LDA(dst, b, h) do { _Pragma("unroll") for (int m = 0; m < 4; ++m) _Pragma("unroll") for (int k = 0; k < 2; ++k) dst[m][k] = *(const LAS bf16x8*)(lds + PG8_SA(b, h) + aoff + m * 2048 + k * 1024); } while (0)
; #define PG8_LDB(dst, b, h) do { _Pragma("unroll") for (int n = 0; n < 2; ++n) _Pragma("unroll") for (int k = 0; k < 2; ++k) dst[n][k] = *(const LAS bf16x8*)(lds + PG8_SB(b, h) + boff + n * 2048 + k * 1024); } while (0)
; #define PG8_MMA(ai, bj, At, Bt) do { __builtin_amdgcn_s_setprio(1); _Pragma("unroll") for (int m = 0; m < 4; ++m) _Pragma("unroll") for (int n = 0; n < 2; ++n) _Pragma("unroll") for (int k = 0; k < 2; ++k) \
;         acc[ai][bj][m][n] = __builtin_amdgcn_mfma_f32_16x16x32_bf16(Bt[n][k], At[m][k], acc[ai][bj][m][n], 0, 0, 0); __builtin_amdgcn_s_setprio(0); } while (0)
; #define PG8_WAIT_V(n) asm volatile("s_waitcnt vmcnt(" #n ")" ::: "memory")
; #define PG8_WAIT_L(n) asm volatile("s_waitcnt lgkmcnt(" #n ")" ::: "memory")
; #define PG8_BAR __builtin_amdgcn_s_barrier()
; #define PG8_SCHED __builtin_amdgcn_sched_barrier(0)
; template <class Epi, class Sched>
; DI void gemm_phase(LAS unsigned char* lds, const Gemm g, const Sched& S, const Epi& E) {
;     ...
;             PG8_STAGE(PG8_SB(0, 1), b2 + hstep, voffB);
;             PG8_WAIT_V(6); PG8_BAR; PG8_MMA(1, 1, At, B1); PG8_BAR;
;             PG8_LDB(B0, 1, 0); PG8_SCHED; PG8_LDA(At, 1, 0); PG8_STAGE(PG8_SA(0, 1), a2 + hstep, voffA);
;             PG8_WAIT_L(8); PG8_BAR; PG8_WAIT_L(0); PG8_MMA(0, 0, At, B0); PG8_BAR; PG8_SCHED;
;             PG8_LDB(B1, 1, 1); PG8_STAGE(PG8_SB(1, 0), b3, voffB);
	s_add_i32 s4, s87, s74
	s_mov_b32 m0, s4
	s_add_u32 s0, s10, 0x80000
	s_addc_u32 s1, s11, 0
	global_load_lds_dwordx4 v130, s[0:1]
	s_add_i32 m0, s4, 0x2000
	s_add_i32 s4, 0, 0x18000
	global_load_lds_dwordx4 v134, s[0:1]
	s_waitcnt vmcnt(6)
	s_barrier
	s_setprio 1
	v_mfma_f32_16x16x32_bf16 v[52:55], v[214:217], v[174:177], 0
	v_mfma_f32_16x16x32_bf16 v[48:51], v[222:225], v[174:177], 0
	v_mfma_f32_16x16x32_bf16 v[36:39], v[214:217], v[188:191], 0
	v_mfma_f32_16x16x32_bf16 v[32:35], v[222:225], v[188:191], 0
	v_mfma_f32_16x16x32_bf16 v[20:23], v[214:217], v[198:201], 0
	v_mfma_f32_16x16x32_bf16 v[16:19], v[222:225], v[198:201], 0
	v_mfma_f32_16x16x32_bf16 v[4:7], v[214:217], v[206:209], 0
	v_mfma_f32_16x16x32_bf16 v[0:3], v[222:225], v[206:209], 0
	v_mfma_f32_16x16x32_bf16 v[52:55], v[218:221], v[178:181], v[52:55]
	v_mfma_f32_16x16x32_bf16 v[48:51], v[226:229], v[178:181], v[48:51]
	v_mfma_f32_16x16x32_bf16 v[36:39], v[218:221], v[194:197], v[36:39]
	v_mfma_f32_16x16x32_bf16 v[32:35], v[226:229], v[194:197], v[32:35]
	v_mfma_f32_16x16x32_bf16 v[20:23], v[218:221], v[202:205], v[20:23]
	v_mfma_f32_16x16x32_bf16 v[16:19], v[226:229], v[202:205], v[16:19]
	v_mfma_f32_16x16x32_bf16 v[4:7], v[218:221], v[210:213], v[4:7]
	v_mfma_f32_16x16x32_bf16 v[0:3], v[226:229], v[210:213], v[0:3]
	s_setprio 0
	v_add_u32_e32 v158, s4, v163
	s_barrier
	ds_read_b128 v[146:149], v158
	ds_read_b128 v[150:153], v158 offset:1024
	ds_read_b128 v[154:157], v158 offset:2048
	ds_read_b128 v[170:173], v158 offset:3072
	s_add_u32 s0, s12, 0x80000
	s_addc_u32 s1, s13, 0
	s_mov_b32 m0, s76
	ds_read_b128 v[174:177], v165 offset:32768
	ds_read_b128 v[178:181], v165 offset:33792
	ds_read_b128 v[188:191], v165 offset:34816
	ds_read_b128 v[194:197], v165 offset:35840
	ds_read_b128 v[198:201], v165 offset:36864
	ds_read_b128 v[202:205], v165 offset:37888
	ds_read_b128 v[206:209], v165 offset:38912
	global_load_lds_dwordx4 v128, s[0:1]
	s_mov_b32 m0, s77
	ds_read_b128 v[210:213], v165 offset:39936
	global_load_lds_dwordx4 v132, s[0:1]
	s_waitcnt lgkmcnt(8)
	s_barrier
	s_waitcnt lgkmcnt(0)
	s_setprio 1
	v_mfma_f32_16x16x32_bf16 v[124:127], v[146:149], v[174:177], v[124:127]
	v_mfma_f32_16x16x32_bf16 v[120:123], v[154:157], v[174:177], v[120:123]
	v_mfma_f32_16x16x32_bf16 v[108:111], v[146:149], v[188:191], v[108:111]
	v_mfma_f32_16x16x32_bf16 v[104:107], v[154:157], v[188:191], v[104:107]
	v_mfma_f32_16x16x32_bf16 v[92:95], v[146:149], v[198:201], v[92:95]
	v_mfma_f32_16x16x32_bf16 v[88:91], v[154:157], v[198:201], v[88:91]
	v_mfma_f32_16x16x32_bf16 v[76:79], v[146:149], v[206:209], v[76:79]
	v_mfma_f32_16x16x32_bf16 v[72:75], v[154:157], v[206:209], v[72:75]
	v_mfma_f32_16x16x32_bf16 v[124:127], v[150:153], v[178:181], v[124:127]
	v_mfma_f32_16x16x32_bf16 v[120:123], v[170:173], v[178:181], v[120:123]
	v_mfma_f32_16x16x32_bf16 v[108:111], v[150:153], v[194:197], v[108:111]
	v_mfma_f32_16x16x32_bf16 v[104:107], v[170:173], v[194:197], v[104:107]
	v_mfma_f32_16x16x32_bf16 v[92:95], v[150:153], v[202:205], v[92:95]
	v_mfma_f32_16x16x32_bf16 v[88:91], v[170:173], v[202:205], v[88:91]
	v_mfma_f32_16x16x32_bf16 v[76:79], v[150:153], v[210:213], v[76:79]
	v_mfma_f32_16x16x32_bf16 v[72:75], v[170:173], v[210:213], v[72:75]
	s_setprio 0
	s_barrier
	s_add_i32 s5, 0, 0x1c000
	s_add_i32 s0, s4, s74
	v_add_u32_e32 v159, s5, v163
	s_add_i32 m0, s0, 0xffffff80
	ds_read_b128 v[214:217], v159
	ds_read_b128 v[218:221], v159 offset:1024
	ds_read_b128 v[222:225], v159 offset:2048
	global_load_lds_dwordx4 v130, s[10:11] offset:128
	s_add_i32 m0, s0, 0x1f80
	ds_read_b128 v[226:229], v159 offset:3072
	global_load_lds_dwordx4 v134, s[10:11] offset:128
	s_barrier
; #define PG8_STAGE(bufoff, gbase, voff) do { _Pragma("unroll") for (int _i = 0; _i < 2; ++_i) \
;         __builtin_amdgcn_global_load_lds((const unsigned*)((const char*)(gbase) + (voff)[_i]), (LAS unsigned*)(lds + (bufoff) + ldsw + _i * 8192), 16, 0, 0); } while (0)
; #define PG8_LDA(dst, b, h) do { _Pragma("unroll") for (int m = 0; m < 4; ++m) _Pragma("unroll") for (int k = 0; k < 2; ++k) dst[m][k] = *(const LAS bf16x8*)(lds + PG8_SA(b, h) + aoff + m * 2048 + k * 1024); } while (0)
; #define PG8_MMA(ai, bj, At, Bt) do { __builtin_amdgcn_s_setprio(1); _Pragma("unroll") for (int m = 0; m < 4; ++m) _Pragma("unroll") for (int n = 0; n < 2; ++n) _Pragma("unroll") for (int k = 0; k < 2; ++k) \
;         acc[ai][bj][m][n] = __builtin_amdgcn_mfma_f32_16x16x32_bf16(Bt[n][k], At[m][k], acc[ai][bj][m][n], 0, 0, 0); __builtin_amdgcn_s_setprio(0); } while (0)
; #define PG8_WAIT_V(n) asm volatile("s_waitcnt vmcnt(" #n ")" ::: "memory")
; #define PG8_WAIT_L(n) asm volatile("s_waitcnt lgkmcnt(" #n ")" ::: "memory")
; #define PG8_BAR __builtin_amdgcn_s_barrier()
; #define PG8_SCHED __builtin_amdgcn_sched_barrier(0)
; template <class Epi, class Sched>
; DI void gemm_phase(LAS unsigned char* lds, const Gemm g, const Sched& S, const Epi& E) {
;     ...
;             PG8_BAR; PG8_WAIT_L(0); PG8_MMA(0, 1, At, B1); PG8_BAR;
;             PG8_LDA(At, 1, 1); PG8_STAGE(PG8_SA(1, 0), a3, voffA);
;             PG8_BAR; PG8_WAIT_L(0); PG8_MMA(1, 0, At, B0); PG8_BAR; PG8_SCHED;
;             PG8_STAGE(PG8_SB(1, 1), b3 + hstep, voffB);
;             PG8_WAIT_V(6); PG8_BAR; PG8_MMA(1, 1, At, B1); PG8_BAR;
	s_waitcnt lgkmcnt(0)
	s_setprio 1
	v_mfma_f32_16x16x32_bf16 v[116:119], v[214:217], v[174:177], v[116:119]
	v_mfma_f32_16x16x32_bf16 v[112:115], v[222:225], v[174:177], v[112:115]
	v_mfma_f32_16x16x32_bf16 v[100:103], v[214:217], v[188:191], v[100:103]
	v_mfma_f32_16x16x32_bf16 v[96:99], v[222:225], v[188:191], v[96:99]
	v_mfma_f32_16x16x32_bf16 v[84:87], v[214:217], v[198:201], v[84:87]
	v_mfma_f32_16x16x32_bf16 v[80:83], v[222:225], v[198:201], v[80:83]
	v_mfma_f32_16x16x32_bf16 v[68:71], v[214:217], v[206:209], v[68:71]
	v_mfma_f32_16x16x32_bf16 v[64:67], v[222:225], v[206:209], v[64:67]
	v_mfma_f32_16x16x32_bf16 v[116:119], v[218:221], v[178:181], v[116:119]
	v_mfma_f32_16x16x32_bf16 v[112:115], v[226:229], v[178:181], v[112:115]
	v_mfma_f32_16x16x32_bf16 v[100:103], v[218:221], v[194:197], v[100:103]
	v_mfma_f32_16x16x32_bf16 v[96:99], v[226:229], v[194:197], v[96:99]
	v_mfma_f32_16x16x32_bf16 v[84:87], v[218:221], v[202:205], v[84:87]
	v_mfma_f32_16x16x32_bf16 v[80:83], v[226:229], v[202:205], v[80:83]
	v_mfma_f32_16x16x32_bf16 v[68:71], v[218:221], v[210:213], v[68:71]
	v_mfma_f32_16x16x32_bf16 v[64:67], v[226:229], v[210:213], v[64:67]
	s_setprio 0
	s_add_i32 m0, s97, 0xffffff80
	s_barrier
	ds_read_b128 v[174:177], v165 offset:49152
	ds_read_b128 v[178:181], v165 offset:50176
	ds_read_b128 v[188:191], v165 offset:51200
	ds_read_b128 v[194:197], v165 offset:52224
	ds_read_b128 v[198:201], v165 offset:53248
	ds_read_b128 v[202:205], v165 offset:54272
	ds_read_b128 v[206:209], v165 offset:55296
	global_load_lds_dwordx4 v128, s[12:13] offset:128
	s_add_i32 m0, s84, 0xffffff80
	ds_read_b128 v[210:213], v165 offset:56320
	global_load_lds_dwordx4 v132, s[12:13] offset:128
	s_barrier
	s_waitcnt lgkmcnt(0)
	s_setprio 1
	v_mfma_f32_16x16x32_bf16 v[60:63], v[146:149], v[174:177], v[60:63]
	v_mfma_f32_16x16x32_bf16 v[56:59], v[154:157], v[174:177], v[56:59]
	v_mfma_f32_16x16x32_bf16 v[44:47], v[146:149], v[188:191], v[44:47]
	v_mfma_f32_16x16x32_bf16 v[40:43], v[154:157], v[188:191], v[40:43]
	v_mfma_f32_16x16x32_bf16 v[28:31], v[146:149], v[198:201], v[28:31]
	v_mfma_f32_16x16x32_bf16 v[24:27], v[154:157], v[198:201], v[24:27]
	v_mfma_f32_16x16x32_bf16 v[12:15], v[146:149], v[206:209], v[12:15]
	v_mfma_f32_16x16x32_bf16 v[8:11], v[154:157], v[206:209], v[8:11]
	v_mfma_f32_16x16x32_bf16 v[60:63], v[150:153], v[178:181], v[60:63]
	v_mfma_f32_16x16x32_bf16 v[56:59], v[170:173], v[178:181], v[56:59]
	v_mfma_f32_16x16x32_bf16 v[44:47], v[150:153], v[194:197], v[44:47]
	v_mfma_f32_16x16x32_bf16 v[40:43], v[170:173], v[194:197], v[40:43]
	v_mfma_f32_16x16x32_bf16 v[28:31], v[150:153], v[202:205], v[28:31]
	v_mfma_f32_16x16x32_bf16 v[24:27], v[170:173], v[202:205], v[24:27]
	v_mfma_f32_16x16x32_bf16 v[12:15], v[150:153], v[210:213], v[12:15]
	v_mfma_f32_16x16x32_bf16 v[8:11], v[170:173], v[210:213], v[8:11]
	s_setprio 0
	s_barrier
	s_add_i32 s4, s5, s74
	s_mov_b32 m0, s4
	s_add_u32 s0, s10, 0x80080
	s_addc_u32 s1, s11, 0
	global_load_lds_dwordx4 v130, s[0:1]
	v_lshl_add_u64 v[146:147], s[0:1], 0, v[134:135]
	s_add_i32 m0, s4, 0x2000
	s_add_i32 s35, s35, 2
	global_load_lds_dwordx4 v134, s[0:1]
	s_add_u32 s8, s8, 0x100
	s_addc_u32 s9, s9, 0
	s_add_u32 s28, s28, 0x100
	s_addc_u32 s34, s34, 0
	s_cmp_gt_u32 s35, 29
	s_waitcnt vmcnt(6)
	s_barrier
	s_setprio 1
	v_mfma_f32_16x16x32_bf16 v[52:55], v[214:217], v[174:177], v[52:55]
	v_mfma_f32_16x16x32_bf16 v[48:51], v[222:225], v[174:177], v[48:51]
	v_mfma_f32_16x16x32_bf16 v[36:39], v[214:217], v[188:191], v[36:39]
	v_mfma_f32_16x16x32_bf16 v[32:35], v[222:225], v[188:191], v[32:35]
	v_mfma_f32_16x16x32_bf16 v[20:23], v[214:217], v[198:201], v[20:23]
	v_mfma_f32_16x16x32_bf16 v[16:19], v[222:225], v[198:201], v[16:19]
	v_mfma_f32_16x16x32_bf16 v[4:7], v[214:217], v[206:209], v[4:7]
	v_mfma_f32_16x16x32_bf16 v[0:3], v[222:225], v[206:209], v[0:3]
	v_mfma_f32_16x16x32_bf16 v[52:55], v[218:221], v[178:181], v[52:55]
	v_mfma_f32_16x16x32_bf16 v[48:51], v[226:229], v[178:181], v[48:51]
	v_mfma_f32_16x16x32_bf16 v[36:39], v[218:221], v[194:197], v[36:39]
	v_mfma_f32_16x16x32_bf16 v[32:35], v[226:229], v[194:197], v[32:35]
	v_mfma_f32_16x16x32_bf16 v[20:23], v[218:221], v[202:205], v[20:23]
	v_mfma_f32_16x16x32_bf16 v[16:19], v[226:229], v[202:205], v[16:19]
	v_mfma_f32_16x16x32_bf16 v[4:7], v[218:221], v[210:213], v[4:7]
	v_mfma_f32_16x16x32_bf16 v[0:3], v[226:229], v[210:213], v[0:3]
	s_setprio 0
	s_cbranch_scc0 .Lrot_527
	s_barrier
	s_branch .Lpeel_done_527

; #define PG8_STAGE(bufoff, gbase, voff) do { _Pragma("unroll") for (int _i = 0; _i < 2; ++_i) \
;         __builtin_amdgcn_global_load_lds((const unsigned*)((const char*)(gbase) + (voff)[_i]), (LAS unsigned*)(lds + (bufoff) + ldsw + _i * 8192), 16, 0, 0); } while (0)
; #define PG8_LDA(dst, b, h) do { _Pragma("unroll") for (int m = 0; m < 4; ++m) _Pragma("unroll") for (int k = 0; k < 2; ++k) dst[m][k] = *(const LAS bf16x8*)(lds + PG8_SA(b, h) + aoff + m * 2048 + k * 1024); } while (0)
; #define PG8_LDB(dst, b, h) do { _Pragma("unroll") for (int n = 0; n < 2; ++n) _Pragma("unroll") for (int k = 0; k < 2; ++k) dst[n][k] = *(const LAS bf16x8*)(lds + PG8_SB(b, h) + boff + n * 2048 + k * 1024); } while (0)
; #define PG8_MMA(ai, bj, At, Bt) do { __builtin_amdgcn_s_setprio(1); _Pragma("unroll") for (int m = 0; m < 4; ++m) _Pragma("unroll") for (int n = 0; n < 2; ++n) _Pragma("unroll") for (int k = 0; k < 2; ++k) \
;         acc[ai][bj][m][n] = __builtin_amdgcn_mfma_f32_16x16x32_bf16(Bt[n][k], At[m][k], acc[ai][bj][m][n], 0, 0, 0); __builtin_amdgcn_s_setprio(0); } while (0)
; #define PG8_WAIT_V(n) asm volatile("s_waitcnt vmcnt(" #n ")" ::: "memory")
; #define PG8_WAIT_L(n) asm volatile("s_waitcnt lgkmcnt(" #n ")" ::: "memory")
; #define PG8_BAR __builtin_amdgcn_s_barrier()
; #define PG8_SCHED __builtin_amdgcn_sched_barrier(0)
; template <class Epi, class Sched>
; DI void gemm_phase(LAS unsigned char* lds, const Gemm g, const Sched& S, const Epi& E) {
;     ...
;             PG8_LDB(B0, 0, 0); PG8_SCHED; PG8_LDA(At, 0, 0); PG8_STAGE(PG8_SA(1, 1), a1 + hstep, voffA);
;             PG8_WAIT_L(8); PG8_BAR; PG8_WAIT_L(0); PG8_MMA(0, 0, At, B0); PG8_BAR; PG8_SCHED;
;             PG8_LDB(B1, 0, 1); PG8_STAGE(PG8_SB(0, 0), b2, voffB);
;             PG8_BAR; PG8_WAIT_L(0); PG8_MMA(0, 1, At, B1); PG8_BAR;
;             PG8_LDA(At, 0, 1); PG8_STAGE(PG8_SA(0, 0), a2, voffA);
;             PG8_BAR; PG8_WAIT_L(0); PG8_MMA(1, 0, At, B0); PG8_BAR; PG8_SCHED;
;             PG8_STAGE(PG8_SB(0, 1), b2 + hstep, voffB);
;             PG8_WAIT_V(6); PG8_BAR; PG8_MMA(1, 1, At, B1); PG8_BAR;
.LBB0_527:
	ds_read_b128 v[146:149], v164
	ds_read_b128 v[150:153], v164 offset:1024
	ds_read_b128 v[154:157], v164 offset:2048
	ds_read_b128 v[170:173], v164 offset:3072
	s_add_i32 m0, s59, 0xc000
	ds_read_b128 v[174:177], v165
	ds_read_b128 v[178:181], v165 offset:1024
	ds_read_b128 v[188:191], v165 offset:2048
	ds_read_b128 v[194:197], v165 offset:3072
	ds_read_b128 v[198:201], v165 offset:4096
	ds_read_b128 v[202:205], v165 offset:5120
	ds_read_b128 v[206:209], v165 offset:6144
	global_load_lds_dwordx4 v138, s[8:9]
	s_add_i32 m0, s59, 0xe000
	ds_read_b128 v[210:213], v165 offset:7168
	global_load_lds_dwordx4 v140, s[8:9]
	s_add_u32 s0, s8, 0xfff80080
	s_addc_u32 s1, s9, -1
	s_cmp_eq_u32 s35, 28
	s_cselect_b32 s13, s14, s1
	s_cselect_b32 s12, s15, s0
	s_cselect_b32 s11, s16, s34
	s_cselect_b32 s10, s17, s28
	s_waitcnt lgkmcnt(8)
	s_barrier
	s_waitcnt lgkmcnt(0)
	s_setprio 1
	v_mfma_f32_16x16x32_bf16 v[124:127], v[146:149], v[174:177], v[124:127]
	v_mfma_f32_16x16x32_bf16 v[120:123], v[154:157], v[174:177], v[120:123]
	v_mfma_f32_16x16x32_bf16 v[108:111], v[146:149], v[188:191], v[108:111]
	v_mfma_f32_16x16x32_bf16 v[104:107], v[154:157], v[188:191], v[104:107]
	v_mfma_f32_16x16x32_bf16 v[92:95], v[146:149], v[198:201], v[92:95]
	v_mfma_f32_16x16x32_bf16 v[88:91], v[154:157], v[198:201], v[88:91]
	v_mfma_f32_16x16x32_bf16 v[76:79], v[146:149], v[206:209], v[76:79]
	v_mfma_f32_16x16x32_bf16 v[72:75], v[154:157], v[206:209], v[72:75]
	v_mfma_f32_16x16x32_bf16 v[124:127], v[150:153], v[178:181], v[124:127]
	v_mfma_f32_16x16x32_bf16 v[120:123], v[170:173], v[178:181], v[120:123]
	v_mfma_f32_16x16x32_bf16 v[108:111], v[150:153], v[194:197], v[108:111]
	v_mfma_f32_16x16x32_bf16 v[104:107], v[170:173], v[194:197], v[104:107]
	v_mfma_f32_16x16x32_bf16 v[92:95], v[150:153], v[202:205], v[92:95]
	v_mfma_f32_16x16x32_bf16 v[88:91], v[170:173], v[202:205], v[88:91]
	v_mfma_f32_16x16x32_bf16 v[76:79], v[150:153], v[210:213], v[76:79]
	v_mfma_f32_16x16x32_bf16 v[72:75], v[170:173], v[210:213], v[72:75]
	s_setprio 0
	s_barrier
	s_add_i32 s0, s47, s74
	s_mov_b32 m0, s0
	ds_read_b128 v[214:217], v166
	ds_read_b128 v[218:221], v166 offset:1024
	ds_read_b128 v[222:225], v166 offset:2048
	global_load_lds_dwordx4 v130, s[10:11]
	s_add_i32 m0, s0, 0x2000
	ds_read_b128 v[226:229], v166 offset:3072
	global_load_lds_dwordx4 v134, s[10:11]
	s_barrier
	s_waitcnt lgkmcnt(0)
	s_setprio 1
	v_mfma_f32_16x16x32_bf16 v[116:119], v[214:217], v[174:177], v[116:119]
	v_mfma_f32_16x16x32_bf16 v[112:115], v[222:225], v[174:177], v[112:115]
	v_mfma_f32_16x16x32_bf16 v[100:103], v[214:217], v[188:191], v[100:103]
	v_mfma_f32_16x16x32_bf16 v[96:99], v[222:225], v[188:191], v[96:99]
	v_mfma_f32_16x16x32_bf16 v[84:87], v[214:217], v[198:201], v[84:87]
	v_mfma_f32_16x16x32_bf16 v[80:83], v[222:225], v[198:201], v[80:83]
	v_mfma_f32_16x16x32_bf16 v[68:71], v[214:217], v[206:209], v[68:71]
	v_mfma_f32_16x16x32_bf16 v[64:67], v[222:225], v[206:209], v[64:67]
	v_mfma_f32_16x16x32_bf16 v[116:119], v[218:221], v[178:181], v[116:119]
	v_mfma_f32_16x16x32_bf16 v[112:115], v[226:229], v[178:181], v[112:115]
	v_mfma_f32_16x16x32_bf16 v[100:103], v[218:221], v[194:197], v[100:103]
	v_mfma_f32_16x16x32_bf16 v[96:99], v[226:229], v[194:197], v[96:99]
	v_mfma_f32_16x16x32_bf16 v[84:87], v[218:221], v[202:205], v[84:87]
	v_mfma_f32_16x16x32_bf16 v[80:83], v[226:229], v[202:205], v[80:83]
	v_mfma_f32_16x16x32_bf16 v[68:71], v[218:221], v[210:213], v[68:71]
	v_mfma_f32_16x16x32_bf16 v[64:67], v[226:229], v[210:213], v[64:67]
	s_setprio 0
	s_mov_b32 m0, s59
	s_barrier
	ds_read_b128 v[174:177], v165 offset:16384
	ds_read_b128 v[178:181], v165 offset:17408
	ds_read_b128 v[188:191], v165 offset:18432
	ds_read_b128 v[194:197], v165 offset:19456
	ds_read_b128 v[198:201], v165 offset:20480
	ds_read_b128 v[202:205], v165 offset:21504
	ds_read_b128 v[206:209], v165 offset:22528
	global_load_lds_dwordx4 v128, s[12:13]
	s_mov_b32 m0, s75
	ds_read_b128 v[210:213], v165 offset:23552
	global_load_lds_dwordx4 v132, s[12:13]
	s_barrier
	s_waitcnt lgkmcnt(0)
	s_setprio 1
	v_mfma_f32_16x16x32_bf16 v[60:63], v[146:149], v[174:177], v[60:63]
	v_mfma_f32_16x16x32_bf16 v[56:59], v[154:157], v[174:177], v[56:59]
	v_mfma_f32_16x16x32_bf16 v[44:47], v[146:149], v[188:191], v[44:47]
	v_mfma_f32_16x16x32_bf16 v[40:43], v[154:157], v[188:191], v[40:43]
	v_mfma_f32_16x16x32_bf16 v[28:31], v[146:149], v[198:201], v[28:31]
	v_mfma_f32_16x16x32_bf16 v[24:27], v[154:157], v[198:201], v[24:27]
	v_mfma_f32_16x16x32_bf16 v[12:15], v[146:149], v[206:209], v[12:15]
	v_mfma_f32_16x16x32_bf16 v[8:11], v[154:157], v[206:209], v[8:11]
	v_mfma_f32_16x16x32_bf16 v[60:63], v[150:153], v[178:181], v[60:63]
	v_mfma_f32_16x16x32_bf16 v[56:59], v[170:173], v[178:181], v[56:59]
	v_mfma_f32_16x16x32_bf16 v[44:47], v[150:153], v[194:197], v[44:47]
	v_mfma_f32_16x16x32_bf16 v[40:43], v[170:173], v[194:197], v[40:43]
	v_mfma_f32_16x16x32_bf16 v[28:31], v[150:153], v[202:205], v[28:31]
	v_mfma_f32_16x16x32_bf16 v[24:27], v[170:173], v[202:205], v[24:27]
	v_mfma_f32_16x16x32_bf16 v[12:15], v[150:153], v[210:213], v[12:15]
	v_mfma_f32_16x16x32_bf16 v[8:11], v[170:173], v[210:213], v[8:11]
	s_setprio 0
	s_barrier
	s_add_i32 s4, s87, s74
	s_mov_b32 m0, s4
	s_add_u32 s0, s10, 0x80000
	s_addc_u32 s1, s11, 0
	global_load_lds_dwordx4 v130, s[0:1]
	s_add_i32 m0, s4, 0x2000
	s_add_i32 s4, 0, 0x18000
	global_load_lds_dwordx4 v134, s[0:1]
	s_waitcnt vmcnt(6)
	s_barrier
; #define PG8_STAGE(bufoff, gbase, voff) do { _Pragma("unroll") for (int _i = 0; _i < 2; ++_i) \
;         __builtin_amdgcn_global_load_lds((const unsigned*)((const char*)(gbase) + (voff)[_i]), (LAS unsigned*)(lds + (bufoff) + ldsw + _i * 8192), 16, 0, 0); } while (0)
; #define PG8_LDA(dst, b, h) do { _Pragma("unroll") for (int m = 0; m < 4; ++m) _Pragma("unroll") for (int k = 0; k < 2; ++k) dst[m][k] = *(const LAS bf16x8*)(lds + PG8_SA(b, h) + aoff + m * 2048 + k * 1024); } while (0)
; #define PG8_LDB(dst, b, h) do { _Pragma("unroll") for (int n = 0; n < 2; ++n) _Pragma("unroll") for (int k = 0; k < 2; ++k) dst[n][k] = *(const LAS bf16x8*)(lds + PG8_SB(b, h) + boff + n * 2048 + k * 1024); } while (0)
; #define PG8_MMA(ai, bj, At, Bt) do { __builtin_amdgcn_s_setprio(1); _Pragma("unroll") for (int m = 0; m < 4; ++m) _Pragma("unroll") for (int n = 0; n < 2; ++n) _Pragma("unroll") for (int k = 0; k < 2; ++k) \
;         acc[ai][bj][m][n] = __builtin_amdgcn_mfma_f32_16x16x32_bf16(Bt[n][k], At[m][k], acc[ai][bj][m][n], 0, 0, 0); __builtin_amdgcn_s_setprio(0); } while (0)
; #define PG8_WAIT_V(n) asm volatile("s_waitcnt vmcnt(" #n ")" ::: "memory")
; #define PG8_WAIT_L(n) asm volatile("s_waitcnt lgkmcnt(" #n ")" ::: "memory")
; #define PG8_BAR __builtin_amdgcn_s_barrier()
; #define PG8_SCHED __builtin_amdgcn_sched_barrier(0)
; template <class Epi, class Sched>
; DI void gemm_phase(LAS unsigned char* lds, const Gemm g, const Sched& S, const Epi& E) {
;     ...
;             PG8_WAIT_V(6); PG8_BAR; PG8_MMA(1, 1, At, B1); PG8_BAR;
;             PG8_LDB(B0, 1, 0); PG8_SCHED; PG8_LDA(At, 1, 0); PG8_STAGE(PG8_SA(0, 1), a2 + hstep, voffA);
;             PG8_WAIT_L(8); PG8_BAR; PG8_WAIT_L(0); PG8_MMA(0, 0, At, B0); PG8_BAR; PG8_SCHED;
;             PG8_LDB(B1, 1, 1); PG8_STAGE(PG8_SB(1, 0), b3, voffB);
	s_setprio 1
	v_mfma_f32_16x16x32_bf16 v[52:55], v[214:217], v[174:177], v[52:55]
	v_mfma_f32_16x16x32_bf16 v[48:51], v[222:225], v[174:177], v[48:51]
	v_mfma_f32_16x16x32_bf16 v[36:39], v[214:217], v[188:191], v[36:39]
	v_mfma_f32_16x16x32_bf16 v[32:35], v[222:225], v[188:191], v[32:35]
	v_mfma_f32_16x16x32_bf16 v[20:23], v[214:217], v[198:201], v[20:23]
	v_mfma_f32_16x16x32_bf16 v[16:19], v[222:225], v[198:201], v[16:19]
	v_mfma_f32_16x16x32_bf16 v[4:7], v[214:217], v[206:209], v[4:7]
	v_mfma_f32_16x16x32_bf16 v[0:3], v[222:225], v[206:209], v[0:3]
	v_mfma_f32_16x16x32_bf16 v[52:55], v[218:221], v[178:181], v[52:55]
	v_mfma_f32_16x16x32_bf16 v[48:51], v[226:229], v[178:181], v[48:51]
	v_mfma_f32_16x16x32_bf16 v[36:39], v[218:221], v[194:197], v[36:39]
	v_mfma_f32_16x16x32_bf16 v[32:35], v[226:229], v[194:197], v[32:35]
	v_mfma_f32_16x16x32_bf16 v[20:23], v[218:221], v[202:205], v[20:23]
	v_mfma_f32_16x16x32_bf16 v[16:19], v[226:229], v[202:205], v[16:19]
	v_mfma_f32_16x16x32_bf16 v[4:7], v[218:221], v[210:213], v[4:7]
	v_mfma_f32_16x16x32_bf16 v[0:3], v[226:229], v[210:213], v[0:3]
	s_setprio 0
	s_barrier
	ds_read_b128 v[146:149], v158
	ds_read_b128 v[150:153], v158 offset:1024
	ds_read_b128 v[154:157], v158 offset:2048
	ds_read_b128 v[170:173], v158 offset:3072
	s_add_u32 s0, s12, 0x80000
	s_addc_u32 s1, s13, 0
	s_mov_b32 m0, s76
	ds_read_b128 v[174:177], v165 offset:32768
	ds_read_b128 v[178:181], v165 offset:33792
	ds_read_b128 v[188:191], v165 offset:34816
	ds_read_b128 v[194:197], v165 offset:35840
	ds_read_b128 v[198:201], v165 offset:36864
	ds_read_b128 v[202:205], v165 offset:37888
	ds_read_b128 v[206:209], v165 offset:38912
	global_load_lds_dwordx4 v128, s[0:1]
	s_mov_b32 m0, s77
	ds_read_b128 v[210:213], v165 offset:39936
	global_load_lds_dwordx4 v132, s[0:1]
	s_waitcnt lgkmcnt(8)
	s_barrier
	s_waitcnt lgkmcnt(0)
	s_setprio 1
	v_mfma_f32_16x16x32_bf16 v[124:127], v[146:149], v[174:177], v[124:127]
	v_mfma_f32_16x16x32_bf16 v[120:123], v[154:157], v[174:177], v[120:123]
	v_mfma_f32_16x16x32_bf16 v[108:111], v[146:149], v[188:191], v[108:111]
	v_mfma_f32_16x16x32_bf16 v[104:107], v[154:157], v[188:191], v[104:107]
	v_mfma_f32_16x16x32_bf16 v[92:95], v[146:149], v[198:201], v[92:95]
	v_mfma_f32_16x16x32_bf16 v[88:91], v[154:157], v[198:201], v[88:91]
	v_mfma_f32_16x16x32_bf16 v[76:79], v[146:149], v[206:209], v[76:79]
	v_mfma_f32_16x16x32_bf16 v[72:75], v[154:157], v[206:209], v[72:75]
	v_mfma_f32_16x16x32_bf16 v[124:127], v[150:153], v[178:181], v[124:127]
	v_mfma_f32_16x16x32_bf16 v[120:123], v[170:173], v[178:181], v[120:123]
	v_mfma_f32_16x16x32_bf16 v[108:111], v[150:153], v[194:197], v[108:111]
	v_mfma_f32_16x16x32_bf16 v[104:107], v[170:173], v[194:197], v[104:107]
	v_mfma_f32_16x16x32_bf16 v[92:95], v[150:153], v[202:205], v[92:95]
	v_mfma_f32_16x16x32_bf16 v[88:91], v[170:173], v[202:205], v[88:91]
	v_mfma_f32_16x16x32_bf16 v[76:79], v[150:153], v[210:213], v[76:79]
	v_mfma_f32_16x16x32_bf16 v[72:75], v[170:173], v[210:213], v[72:75]
	s_setprio 0
	s_barrier
	s_add_i32 s5, 0, 0x1c000
	s_add_i32 s0, s4, s74
	s_add_i32 m0, s0, 0xffffff80
	ds_read_b128 v[214:217], v159
	ds_read_b128 v[218:221], v159 offset:1024
	ds_read_b128 v[222:225], v159 offset:2048
	global_load_lds_dwordx4 v130, s[10:11] offset:128
	s_add_i32 m0, s0, 0x1f80
	ds_read_b128 v[226:229], v159 offset:3072
	global_load_lds_dwordx4 v134, s[10:11] offset:128
	s_barrier
; #define PG8_STAGE(bufoff, gbase, voff) do { _Pragma("unroll") for (int _i = 0; _i < 2; ++_i) \
;         __builtin_amdgcn_global_load_lds((const unsigned*)((const char*)(gbase) + (voff)[_i]), (LAS unsigned*)(lds + (bufoff) + ldsw + _i * 8192), 16, 0, 0); } while (0)
; #define PG8_LDA(dst, b, h) do { _Pragma("unroll") for (int m = 0; m < 4; ++m) _Pragma("unroll") for (int k = 0; k < 2; ++k) dst[m][k] = *(const LAS bf16x8*)(lds + PG8_SA(b, h) + aoff + m * 2048 + k * 1024); } while (0)
; #define PG8_MMA(ai, bj, At, Bt) do { __builtin_amdgcn_s_setprio(1); _Pragma("unroll") for (int m = 0; m < 4; ++m) _Pragma("unroll") for (int n = 0; n < 2; ++n) _Pragma("unroll") for (int k = 0; k < 2; ++k) \
;         acc[ai][bj][m][n] = __builtin_amdgcn_mfma_f32_16x16x32_bf16(Bt[n][k], At[m][k], acc[ai][bj][m][n], 0, 0, 0); __builtin_amdgcn_s_setprio(0); } while (0)
; #define PG8_WAIT_V(n) asm volatile("s_waitcnt vmcnt(" #n ")" ::: "memory")
; #define PG8_WAIT_L(n) asm volatile("s_waitcnt lgkmcnt(" #n ")" ::: "memory")
; #define PG8_BAR __builtin_amdgcn_s_barrier()
; #define PG8_SCHED __builtin_amdgcn_sched_barrier(0)
; template <class Epi, class Sched>
; DI void gemm_phase(LAS unsigned char* lds, const Gemm g, const Sched& S, const Epi& E) {
;     ...
;             PG8_BAR; PG8_WAIT_L(0); PG8_MMA(0, 1, At, B1); PG8_BAR;
;             PG8_LDA(At, 1, 1); PG8_STAGE(PG8_SA(1, 0), a3, voffA);
;             PG8_BAR; PG8_WAIT_L(0); PG8_MMA(1, 0, At, B0); PG8_BAR; PG8_SCHED;
;             PG8_STAGE(PG8_SB(1, 1), b3 + hstep, voffB);
;             PG8_WAIT_V(6); PG8_BAR; PG8_MMA(1, 1, At, B1); PG8_BAR;
	s_waitcnt lgkmcnt(0)
	s_setprio 1
	v_mfma_f32_16x16x32_bf16 v[116:119], v[214:217], v[174:177], v[116:119]
	v_mfma_f32_16x16x32_bf16 v[112:115], v[222:225], v[174:177], v[112:115]
	v_mfma_f32_16x16x32_bf16 v[100:103], v[214:217], v[188:191], v[100:103]
	v_mfma_f32_16x16x32_bf16 v[96:99], v[222:225], v[188:191], v[96:99]
	v_mfma_f32_16x16x32_bf16 v[84:87], v[214:217], v[198:201], v[84:87]
	v_mfma_f32_16x16x32_bf16 v[80:83], v[222:225], v[198:201], v[80:83]
	v_mfma_f32_16x16x32_bf16 v[68:71], v[214:217], v[206:209], v[68:71]
	v_mfma_f32_16x16x32_bf16 v[64:67], v[222:225], v[206:209], v[64:67]
	v_mfma_f32_16x16x32_bf16 v[116:119], v[218:221], v[178:181], v[116:119]
	v_mfma_f32_16x16x32_bf16 v[112:115], v[226:229], v[178:181], v[112:115]
	v_mfma_f32_16x16x32_bf16 v[100:103], v[218:221], v[194:197], v[100:103]
	v_mfma_f32_16x16x32_bf16 v[96:99], v[226:229], v[194:197], v[96:99]
	v_mfma_f32_16x16x32_bf16 v[84:87], v[218:221], v[202:205], v[84:87]
	v_mfma_f32_16x16x32_bf16 v[80:83], v[226:229], v[202:205], v[80:83]
	v_mfma_f32_16x16x32_bf16 v[68:71], v[218:221], v[210:213], v[68:71]
	v_mfma_f32_16x16x32_bf16 v[64:67], v[226:229], v[210:213], v[64:67]
	s_setprio 0
	s_add_i32 m0, s97, 0xffffff80
	s_barrier
	ds_read_b128 v[174:177], v165 offset:49152
	ds_read_b128 v[178:181], v165 offset:50176
	ds_read_b128 v[188:191], v165 offset:51200
	ds_read_b128 v[194:197], v165 offset:52224
	ds_read_b128 v[198:201], v165 offset:53248
	ds_read_b128 v[202:205], v165 offset:54272
	ds_read_b128 v[206:209], v165 offset:55296
	global_load_lds_dwordx4 v128, s[12:13] offset:128
	s_add_i32 m0, s84, 0xffffff80
	ds_read_b128 v[210:213], v165 offset:56320
	global_load_lds_dwordx4 v132, s[12:13] offset:128
	s_barrier
	s_waitcnt lgkmcnt(0)
	s_setprio 1
	v_mfma_f32_16x16x32_bf16 v[60:63], v[146:149], v[174:177], v[60:63]
	v_mfma_f32_16x16x32_bf16 v[56:59], v[154:157], v[174:177], v[56:59]
	v_mfma_f32_16x16x32_bf16 v[44:47], v[146:149], v[188:191], v[44:47]
	v_mfma_f32_16x16x32_bf16 v[40:43], v[154:157], v[188:191], v[40:43]
	v_mfma_f32_16x16x32_bf16 v[28:31], v[146:149], v[198:201], v[28:31]
	v_mfma_f32_16x16x32_bf16 v[24:27], v[154:157], v[198:201], v[24:27]
	v_mfma_f32_16x16x32_bf16 v[12:15], v[146:149], v[206:209], v[12:15]
	v_mfma_f32_16x16x32_bf16 v[8:11], v[154:157], v[206:209], v[8:11]
	v_mfma_f32_16x16x32_bf16 v[60:63], v[150:153], v[178:181], v[60:63]
	v_mfma_f32_16x16x32_bf16 v[56:59], v[170:173], v[178:181], v[56:59]
	v_mfma_f32_16x16x32_bf16 v[44:47], v[150:153], v[194:197], v[44:47]
	v_mfma_f32_16x16x32_bf16 v[40:43], v[170:173], v[194:197], v[40:43]
	v_mfma_f32_16x16x32_bf16 v[28:31], v[150:153], v[202:205], v[28:31]
	v_mfma_f32_16x16x32_bf16 v[24:27], v[170:173], v[202:205], v[24:27]
	v_mfma_f32_16x16x32_bf16 v[12:15], v[150:153], v[210:213], v[12:15]
	v_mfma_f32_16x16x32_bf16 v[8:11], v[170:173], v[210:213], v[8:11]
	s_setprio 0
	s_barrier
	s_add_i32 s4, s5, s74
	s_mov_b32 m0, s4
	s_add_u32 s0, s10, 0x80080
	s_addc_u32 s1, s11, 0
	global_load_lds_dwordx4 v130, s[0:1]
	v_lshl_add_u64 v[146:147], s[0:1], 0, v[134:135]
	s_add_i32 m0, s4, 0x2000
	s_add_i32 s35, s35, 2
	global_load_lds_dwordx4 v134, s[0:1]
	s_add_u32 s8, s8, 0x100
	s_addc_u32 s9, s9, 0
	s_add_u32 s28, s28, 0x100
	s_addc_u32 s34, s34, 0
	s_cmp_gt_u32 s35, 29
	s_waitcnt vmcnt(6)
	s_barrier
	s_setprio 1
	v_mfma_f32_16x16x32_bf16 v[52:55], v[214:217], v[174:177], v[52:55]
	v_mfma_f32_16x16x32_bf16 v[48:51], v[222:225], v[174:177], v[48:51]
	v_mfma_f32_16x16x32_bf16 v[36:39], v[214:217], v[188:191], v[36:39]
	v_mfma_f32_16x16x32_bf16 v[32:35], v[222:225], v[188:191], v[32:35]
	v_mfma_f32_16x16x32_bf16 v[20:23], v[214:217], v[198:201], v[20:23]
	v_mfma_f32_16x16x32_bf16 v[16:19], v[222:225], v[198:201], v[16:19]
	v_mfma_f32_16x16x32_bf16 v[4:7], v[214:217], v[206:209], v[4:7]
	v_mfma_f32_16x16x32_bf16 v[0:3], v[222:225], v[206:209], v[0:3]
	v_mfma_f32_16x16x32_bf16 v[52:55], v[218:221], v[178:181], v[52:55]
	v_mfma_f32_16x16x32_bf16 v[48:51], v[226:229], v[178:181], v[48:51]
	v_mfma_f32_16x16x32_bf16 v[36:39], v[218:221], v[194:197], v[36:39]
	v_mfma_f32_16x16x32_bf16 v[32:35], v[226:229], v[194:197], v[32:35]
	v_mfma_f32_16x16x32_bf16 v[20:23], v[218:221], v[202:205], v[20:23]
	v_mfma_f32_16x16x32_bf16 v[16:19], v[226:229], v[202:205], v[16:19]
	v_mfma_f32_16x16x32_bf16 v[4:7], v[218:221], v[210:213], v[4:7]
	v_mfma_f32_16x16x32_bf16 v[0:3], v[226:229], v[210:213], v[0:3]
	s_setprio 0
	s_cbranch_scc0 .Lrot_527
	s_barrier

;     DI size_t aoff(const Unit& u, size_t tstep) const { return (size_t)u.pm * tstep; }
;     DI size_t boff(const Unit& u, size_t tstep) const { return (size_t)u.pn * tstep; }
;     DI bool next(int i, Unit& u) const { const long L = (long)i * G + c; if (L >= np) return false; u.pm = pmv; u.pn = (int)(L % nN); u.ks = (int)(L / nN); return true; }
;     DI size_t aoff(const Unit& u, size_t) const { return (size_t)u.ks * kbytes; }
;     DI size_t boff(const Unit& u, size_t tstep) const { return (size_t)u.pn * tstep + (size_t)u.ks * kbytes; }
;     DI bool next(int i, Unit& u) const { Unit t; if (!S.next(i / 3, t)) return false; u.pm = t.pm; u.pn = t.pn; u.ks = i % 3; return true; }
;     DI size_t aoff(const Unit& u, size_t tstep) const { return (u.ks < 2 ? offU : offOA) + (size_t)u.pm * tstep; }
; #define PG8_WAIT_V(n) asm volatile("s_waitcnt vmcnt(" #n ")" ::: "memory")
; template <class Epi, class Sched>
; DI void gemm_phase(LAS unsigned char* lds, const Gemm g, const Sched& S, const Epi& E) {
;     ...
;         const bool has_next = S.next(ui + 1, nxt);
;         const char* nA = has_next ? (const char*)g.A + S.aoff(nxt, tstep) : cA; const char* nB = has_next ? (const char*)g.Bt + S.boff(nxt, tstep) : cB;
;         for (int t = 0; t < nt; t += 2) {
;             if constexpr (Epi::HAS_MID) { if (t == E.mid_t(nt)) { int fr3 = fr, fq3 = fq; asm volatile("" : "+v"(fr3), "+v"(fq3)); E.mid(acc, cur, wr, wc, fr3, fq3); } }
;             const bool last = (t == nt - 2);
;             const char* a1 = cA + (size_t)(t + 1) * kstep;
;             const char* a2 = last ? nA : cA + (size_t)(t + 2) * kstep; const char* b2 = last ? nB : cB + (size_t)(t + 2) * kstep;
;             const char* a3 = a2 + kstep; const char* b3 = b2 + kstep;
;             PG8_LDB(B0, 0, 0); PG8_SCHED; PG8_LDA(At, 0, 0); PG8_STAGE(PG8_SA(1, 1), a1 + hstep, voffA);
;             PG8_WAIT_L(8); PG8_BAR; PG8_WAIT_L(0); PG8_MMA(0, 0, At, B0); PG8_BAR; PG8_SCHED;
;             PG8_LDB(B1, 0, 1); PG8_STAGE(PG8_SB(0, 0), b2, voffB);
;             PG8_BAR; PG8_WAIT_L(0); PG8_MMA(0, 1, At, B1); PG8_BAR;
;             PG8_LDA(At, 0, 1); PG8_STAGE(PG8_SA(0, 0), a2, voffA);
;             PG8_BAR; PG8_WAIT_L(0); PG8_MMA(1, 0, At, B0); PG8_BAR; PG8_SCHED;
;             PG8_STAGE(PG8_SB(0, 1), b2 + hstep, voffB);
;             PG8_WAIT_V(6); PG8_BAR; PG8_MMA(1, 1, At, B1); PG8_BAR;
.LBB0_937:
	s_add_u32 s8, s38, 0x30080
	s_addc_u32 s9, s39, 0
	s_add_u32 s35, s36, 0x100
	v_mov_b32_e32 v0, 0
	s_addc_u32 s40, s37, 0
	s_mov_b32 s41, -2
	ds_read_b128 v[144:147], v165
	ds_read_b128 v[168:171], v165 offset:1024
	ds_read_b128 v[172:175], v165 offset:2048
	ds_read_b128 v[176:179], v165 offset:3072
	s_add_i32 m0, s51, 0xc000
	ds_read_b128 v[180:183], v166
	ds_read_b128 v[188:191], v166 offset:1024
	ds_read_b128 v[194:197], v166 offset:2048
	ds_read_b128 v[198:201], v166 offset:3072
	ds_read_b128 v[202:205], v166 offset:4096
	ds_read_b128 v[206:209], v166 offset:5120
	ds_read_b128 v[210:213], v166 offset:6144
	global_load_lds_dwordx4 v136, s[8:9]
	s_add_i32 m0, s51, 0xe000
	ds_read_b128 v[214:217], v166 offset:7168
	global_load_lds_dwordx4 v138, s[8:9]
	s_add_u32 s0, s8, 0xfffd0080
	s_addc_u32 s1, s9, -1
	s_cmp_eq_u32 s41, 8
	s_cselect_b32 s39, s31, s1
	s_cselect_b32 s38, s30, s0
	s_cselect_b32 s37, s11, s40
	s_cselect_b32 s36, s10, s35
	s_waitcnt lgkmcnt(8)
	s_barrier
	s_waitcnt lgkmcnt(0)
	s_setprio 1
	v_mfma_f32_16x16x32_bf16 v[124:127], v[144:147], v[180:183], 0
	v_mfma_f32_16x16x32_bf16 v[120:123], v[172:175], v[180:183], 0
	v_mfma_f32_16x16x32_bf16 v[108:111], v[144:147], v[194:197], 0
	v_mfma_f32_16x16x32_bf16 v[104:107], v[172:175], v[194:197], 0
	v_mfma_f32_16x16x32_bf16 v[92:95], v[144:147], v[202:205], 0
	v_mfma_f32_16x16x32_bf16 v[88:91], v[172:175], v[202:205], 0
	v_mfma_f32_16x16x32_bf16 v[76:79], v[144:147], v[210:213], 0
	v_mfma_f32_16x16x32_bf16 v[72:75], v[172:175], v[210:213], 0
	v_mfma_f32_16x16x32_bf16 v[124:127], v[168:171], v[188:191], v[124:127]
	v_mfma_f32_16x16x32_bf16 v[120:123], v[176:179], v[188:191], v[120:123]
	v_mfma_f32_16x16x32_bf16 v[108:111], v[168:171], v[198:201], v[108:111]
	v_mfma_f32_16x16x32_bf16 v[104:107], v[176:179], v[198:201], v[104:107]
	v_mfma_f32_16x16x32_bf16 v[92:95], v[168:171], v[206:209], v[92:95]
	v_mfma_f32_16x16x32_bf16 v[88:91], v[176:179], v[206:209], v[88:91]
	v_mfma_f32_16x16x32_bf16 v[76:79], v[168:171], v[214:217], v[76:79]
	v_mfma_f32_16x16x32_bf16 v[72:75], v[176:179], v[214:217], v[72:75]
	s_setprio 0
	s_barrier
	s_add_i32 s0, s61, s50
	s_mov_b32 m0, s0
	ds_read_b128 v[218:221], v167
	ds_read_b128 v[222:225], v167 offset:1024
	ds_read_b128 v[226:229], v167 offset:2048
	global_load_lds_dwordx4 v130, s[36:37]
	s_add_i32 m0, s0, 0x2000
	ds_read_b128 v[230:233], v167 offset:3072
	global_load_lds_dwordx4 v134, s[36:37]
	s_barrier
	s_waitcnt lgkmcnt(0)
	s_setprio 1
	v_mfma_f32_16x16x32_bf16 v[116:119], v[218:221], v[180:183], 0
	v_mfma_f32_16x16x32_bf16 v[112:115], v[226:229], v[180:183], 0
	v_mfma_f32_16x16x32_bf16 v[100:103], v[218:221], v[194:197], 0
	v_mfma_f32_16x16x32_bf16 v[96:99], v[226:229], v[194:197], 0
	v_mfma_f32_16x16x32_bf16 v[84:87], v[218:221], v[202:205], 0
	v_mfma_f32_16x16x32_bf16 v[80:83], v[226:229], v[202:205], 0
	v_mfma_f32_16x16x32_bf16 v[68:71], v[218:221], v[210:213], 0
	v_mfma_f32_16x16x32_bf16 v[64:67], v[226:229], v[210:213], 0
	v_mfma_f32_16x16x32_bf16 v[116:119], v[222:225], v[188:191], v[116:119]
	v_mfma_f32_16x16x32_bf16 v[112:115], v[230:233], v[188:191], v[112:115]
	v_mfma_f32_16x16x32_bf16 v[100:103], v[222:225], v[198:201], v[100:103]
	v_mfma_f32_16x16x32_bf16 v[96:99], v[230:233], v[198:201], v[96:99]
	v_mfma_f32_16x16x32_bf16 v[84:87], v[222:225], v[206:209], v[84:87]
	v_mfma_f32_16x16x32_bf16 v[80:83], v[230:233], v[206:209], v[80:83]
	v_mfma_f32_16x16x32_bf16 v[68:71], v[222:225], v[214:217], v[68:71]
	v_mfma_f32_16x16x32_bf16 v[64:67], v[230:233], v[214:217], v[64:67]
	s_setprio 0
	s_mov_b32 m0, s51
	s_barrier
	ds_read_b128 v[180:183], v166 offset:16384
	ds_read_b128 v[188:191], v166 offset:17408
	ds_read_b128 v[194:197], v166 offset:18432
	ds_read_b128 v[198:201], v166 offset:19456
	ds_read_b128 v[202:205], v166 offset:20480
	ds_read_b128 v[206:209], v166 offset:21504
	ds_read_b128 v[210:213], v166 offset:22528
	global_load_lds_dwordx4 v128, s[38:39]
	s_mov_b32 m0, s52
	ds_read_b128 v[214:217], v166 offset:23552
	global_load_lds_dwordx4 v132, s[38:39]
	s_barrier
	s_waitcnt lgkmcnt(0)
	s_setprio 1
	v_mfma_f32_16x16x32_bf16 v[60:63], v[144:147], v[180:183], 0
	v_mfma_f32_16x16x32_bf16 v[56:59], v[172:175], v[180:183], 0
	v_mfma_f32_16x16x32_bf16 v[44:47], v[144:147], v[194:197], 0
	v_mfma_f32_16x16x32_bf16 v[40:43], v[172:175], v[194:197], 0
	v_mfma_f32_16x16x32_bf16 v[28:31], v[144:147], v[202:205], 0
	v_mfma_f32_16x16x32_bf16 v[24:27], v[172:175], v[202:205], 0
	v_mfma_f32_16x16x32_bf16 v[12:15], v[144:147], v[210:213], 0
	v_mfma_f32_16x16x32_bf16 v[8:11], v[172:175], v[210:213], 0
	v_mfma_f32_16x16x32_bf16 v[60:63], v[168:171], v[188:191], v[60:63]
	v_mfma_f32_16x16x32_bf16 v[56:59], v[176:179], v[188:191], v[56:59]
	v_mfma_f32_16x16x32_bf16 v[44:47], v[168:171], v[198:201], v[44:47]
	v_mfma_f32_16x16x32_bf16 v[40:43], v[176:179], v[198:201], v[40:43]
	v_mfma_f32_16x16x32_bf16 v[28:31], v[168:171], v[206:209], v[28:31]
	v_mfma_f32_16x16x32_bf16 v[24:27], v[176:179], v[206:209], v[24:27]
	v_mfma_f32_16x16x32_bf16 v[12:15], v[168:171], v[214:217], v[12:15]
	v_mfma_f32_16x16x32_bf16 v[8:11], v[176:179], v[214:217], v[8:11]
	s_setprio 0
	s_barrier
	s_add_i32 s4, s62, s50
	s_mov_b32 m0, s4
	s_add_u32 s0, s36, 0x30000
	s_addc_u32 s1, s37, 0
	global_load_lds_dwordx4 v130, s[0:1]
	s_add_i32 m0, s4, 0x2000
	s_add_i32 s4, 0, 0x18000
	global_load_lds_dwordx4 v134, s[0:1]
	s_waitcnt vmcnt(6)
	s_barrier
; #define PG8_STAGE(bufoff, gbase, voff) do { _Pragma("unroll") for (int _i = 0; _i < 2; ++_i) \
;         __builtin_amdgcn_global_load_lds((const unsigned*)((const char*)(gbase) + (voff)[_i]), (LAS unsigned*)(lds + (bufoff) + ldsw + _i * 8192), 16, 0, 0); } while (0)
; #define PG8_LDA(dst, b, h) do { _Pragma("unroll") for (int m = 0; m < 4; ++m) _Pragma("unroll") for (int k = 0; k < 2; ++k) dst[m][k] = *(const LAS bf16x8*)(lds + PG8_SA(b, h) + aoff + m * 2048 + k * 1024); } while (0)
; #define PG8_LDB(dst, b, h) do { _Pragma("unroll") for (int n = 0; n < 2; ++n) _Pragma("unroll") for (int k = 0; k < 2; ++k) dst[n][k] = *(const LAS bf16x8*)(lds + PG8_SB(b, h) + boff + n * 2048 + k * 1024); } while (0)
; #define PG8_MMA(ai, bj, At, Bt) do { __builtin_amdgcn_s_setprio(1); _Pragma("unroll") for (int m = 0; m < 4; ++m) _Pragma("unroll") for (int n = 0; n < 2; ++n) _Pragma("unroll") for (int k = 0; k < 2; ++k) \
;         acc[ai][bj][m][n] = __builtin_amdgcn_mfma_f32_16x16x32_bf16(Bt[n][k], At[m][k], acc[ai][bj][m][n], 0, 0, 0); __builtin_amdgcn_s_setprio(0); } while (0)
; #define PG8_WAIT_V(n) asm volatile("s_waitcnt vmcnt(" #n ")" ::: "memory")
; #define PG8_WAIT_L(n) asm volatile("s_waitcnt lgkmcnt(" #n ")" ::: "memory")
; #define PG8_BAR __builtin_amdgcn_s_barrier()
; #define PG8_SCHED __builtin_amdgcn_sched_barrier(0)
; template <class Epi, class Sched>
; DI void gemm_phase(LAS unsigned char* lds, const Gemm g, const Sched& S, const Epi& E) {
;     ...
;             PG8_WAIT_V(6); PG8_BAR; PG8_MMA(1, 1, At, B1); PG8_BAR;
;             PG8_LDB(B0, 1, 0); PG8_SCHED; PG8_LDA(At, 1, 0); PG8_STAGE(PG8_SA(0, 1), a2 + hstep, voffA);
;             PG8_WAIT_L(8); PG8_BAR; PG8_WAIT_L(0); PG8_MMA(0, 0, At, B0); PG8_BAR; PG8_SCHED;
;             PG8_LDB(B1, 1, 1); PG8_STAGE(PG8_SB(1, 0), b3, voffB);
	s_setprio 1
	v_mfma_f32_16x16x32_bf16 v[52:55], v[218:221], v[180:183], 0
	v_mfma_f32_16x16x32_bf16 v[48:51], v[226:229], v[180:183], 0
	v_mfma_f32_16x16x32_bf16 v[36:39], v[218:221], v[194:197], 0
	v_mfma_f32_16x16x32_bf16 v[32:35], v[226:229], v[194:197], 0
	v_mfma_f32_16x16x32_bf16 v[20:23], v[218:221], v[202:205], 0
	v_mfma_f32_16x16x32_bf16 v[16:19], v[226:229], v[202:205], 0
	v_mfma_f32_16x16x32_bf16 v[4:7], v[218:221], v[210:213], 0
	v_mfma_f32_16x16x32_bf16 v[0:3], v[226:229], v[210:213], 0
	v_mfma_f32_16x16x32_bf16 v[52:55], v[222:225], v[188:191], v[52:55]
	v_mfma_f32_16x16x32_bf16 v[48:51], v[230:233], v[188:191], v[48:51]
	v_mfma_f32_16x16x32_bf16 v[36:39], v[222:225], v[198:201], v[36:39]
	v_mfma_f32_16x16x32_bf16 v[32:35], v[230:233], v[198:201], v[32:35]
	v_mfma_f32_16x16x32_bf16 v[20:23], v[222:225], v[206:209], v[20:23]
	v_mfma_f32_16x16x32_bf16 v[16:19], v[230:233], v[206:209], v[16:19]
	v_mfma_f32_16x16x32_bf16 v[4:7], v[222:225], v[214:217], v[4:7]
	v_mfma_f32_16x16x32_bf16 v[0:3], v[230:233], v[214:217], v[0:3]
	s_setprio 0
	v_add_u32_e32 v148, s4, v164
	s_barrier
	ds_read_b128 v[144:147], v148
	ds_read_b128 v[168:171], v148 offset:1024
	ds_read_b128 v[172:175], v148 offset:2048
	ds_read_b128 v[176:179], v148 offset:3072
	s_add_u32 s0, s38, 0x30000
	s_addc_u32 s1, s39, 0
	s_mov_b32 m0, s53
	ds_read_b128 v[180:183], v166 offset:32768
	ds_read_b128 v[188:191], v166 offset:33792
	ds_read_b128 v[194:197], v166 offset:34816
	ds_read_b128 v[198:201], v166 offset:35840
	ds_read_b128 v[202:205], v166 offset:36864
	ds_read_b128 v[206:209], v166 offset:37888
	ds_read_b128 v[210:213], v166 offset:38912
	global_load_lds_dwordx4 v128, s[0:1]
	s_mov_b32 m0, s54
	ds_read_b128 v[214:217], v166 offset:39936
	global_load_lds_dwordx4 v132, s[0:1]
	s_waitcnt lgkmcnt(8)
	s_barrier
	s_waitcnt lgkmcnt(0)
	s_setprio 1
	v_mfma_f32_16x16x32_bf16 v[124:127], v[144:147], v[180:183], v[124:127]
	v_mfma_f32_16x16x32_bf16 v[120:123], v[172:175], v[180:183], v[120:123]
	v_mfma_f32_16x16x32_bf16 v[108:111], v[144:147], v[194:197], v[108:111]
	v_mfma_f32_16x16x32_bf16 v[104:107], v[172:175], v[194:197], v[104:107]
	v_mfma_f32_16x16x32_bf16 v[92:95], v[144:147], v[202:205], v[92:95]
	v_mfma_f32_16x16x32_bf16 v[88:91], v[172:175], v[202:205], v[88:91]
	v_mfma_f32_16x16x32_bf16 v[76:79], v[144:147], v[210:213], v[76:79]
	v_mfma_f32_16x16x32_bf16 v[72:75], v[172:175], v[210:213], v[72:75]
	v_mfma_f32_16x16x32_bf16 v[124:127], v[168:171], v[188:191], v[124:127]
	v_mfma_f32_16x16x32_bf16 v[120:123], v[176:179], v[188:191], v[120:123]
	v_mfma_f32_16x16x32_bf16 v[108:111], v[168:171], v[198:201], v[108:111]
	v_mfma_f32_16x16x32_bf16 v[104:107], v[176:179], v[198:201], v[104:107]
	v_mfma_f32_16x16x32_bf16 v[92:95], v[168:171], v[206:209], v[92:95]
	v_mfma_f32_16x16x32_bf16 v[88:91], v[176:179], v[206:209], v[88:91]
	v_mfma_f32_16x16x32_bf16 v[76:79], v[168:171], v[214:217], v[76:79]
	v_mfma_f32_16x16x32_bf16 v[72:75], v[176:179], v[214:217], v[72:75]
	s_setprio 0
	s_barrier
	s_add_i32 s5, 0, 0x1c000
	s_add_i32 s0, s4, s50
	v_add_u32_e32 v149, s5, v164
	s_add_i32 m0, s0, 0xffffff80
	ds_read_b128 v[218:221], v149
	ds_read_b128 v[222:225], v149 offset:1024
	ds_read_b128 v[226:229], v149 offset:2048
	global_load_lds_dwordx4 v130, s[36:37] offset:128
	s_add_i32 m0, s0, 0x1f80
	ds_read_b128 v[230:233], v149 offset:3072
	global_load_lds_dwordx4 v134, s[36:37] offset:128
	s_barrier
; #define PG8_STAGE(bufoff, gbase, voff) do { _Pragma("unroll") for (int _i = 0; _i < 2; ++_i) \
;         __builtin_amdgcn_global_load_lds((const unsigned*)((const char*)(gbase) + (voff)[_i]), (LAS unsigned*)(lds + (bufoff) + ldsw + _i * 8192), 16, 0, 0); } while (0)
; #define PG8_LDA(dst, b, h) do { _Pragma("unroll") for (int m = 0; m < 4; ++m) _Pragma("unroll") for (int k = 0; k < 2; ++k) dst[m][k] = *(const LAS bf16x8*)(lds + PG8_SA(b, h) + aoff + m * 2048 + k * 1024); } while (0)
; #define PG8_MMA(ai, bj, At, Bt) do { __builtin_amdgcn_s_setprio(1); _Pragma("unroll") for (int m = 0; m < 4; ++m) _Pragma("unroll") for (int n = 0; n < 2; ++n) _Pragma("unroll") for (int k = 0; k < 2; ++k) \
;         acc[ai][bj][m][n] = __builtin_amdgcn_mfma_f32_16x16x32_bf16(Bt[n][k], At[m][k], acc[ai][bj][m][n], 0, 0, 0); __builtin_amdgcn_s_setprio(0); } while (0)
; #define PG8_WAIT_V(n) asm volatile("s_waitcnt vmcnt(" #n ")" ::: "memory")
; #define PG8_WAIT_L(n) asm volatile("s_waitcnt lgkmcnt(" #n ")" ::: "memory")
; #define PG8_BAR __builtin_amdgcn_s_barrier()
; #define PG8_SCHED __builtin_amdgcn_sched_barrier(0)
; template <class Epi, class Sched>
; DI void gemm_phase(LAS unsigned char* lds, const Gemm g, const Sched& S, const Epi& E) {
;     ...
;             PG8_BAR; PG8_WAIT_L(0); PG8_MMA(0, 1, At, B1); PG8_BAR;
;             PG8_LDA(At, 1, 1); PG8_STAGE(PG8_SA(1, 0), a3, voffA);
;             PG8_BAR; PG8_WAIT_L(0); PG8_MMA(1, 0, At, B0); PG8_BAR; PG8_SCHED;
;             PG8_STAGE(PG8_SB(1, 1), b3 + hstep, voffB);
;             PG8_WAIT_V(6); PG8_BAR; PG8_MMA(1, 1, At, B1); PG8_BAR;
	s_waitcnt lgkmcnt(0)
	s_setprio 1
	v_mfma_f32_16x16x32_bf16 v[116:119], v[218:221], v[180:183], v[116:119]
	v_mfma_f32_16x16x32_bf16 v[112:115], v[226:229], v[180:183], v[112:115]
	v_mfma_f32_16x16x32_bf16 v[100:103], v[218:221], v[194:197], v[100:103]
	v_mfma_f32_16x16x32_bf16 v[96:99], v[226:229], v[194:197], v[96:99]
	v_mfma_f32_16x16x32_bf16 v[84:87], v[218:221], v[202:205], v[84:87]
	v_mfma_f32_16x16x32_bf16 v[80:83], v[226:229], v[202:205], v[80:83]
	v_mfma_f32_16x16x32_bf16 v[68:71], v[218:221], v[210:213], v[68:71]
	v_mfma_f32_16x16x32_bf16 v[64:67], v[226:229], v[210:213], v[64:67]
	v_mfma_f32_16x16x32_bf16 v[116:119], v[222:225], v[188:191], v[116:119]
	v_mfma_f32_16x16x32_bf16 v[112:115], v[230:233], v[188:191], v[112:115]
	v_mfma_f32_16x16x32_bf16 v[100:103], v[222:225], v[198:201], v[100:103]
	v_mfma_f32_16x16x32_bf16 v[96:99], v[230:233], v[198:201], v[96:99]
	v_mfma_f32_16x16x32_bf16 v[84:87], v[222:225], v[206:209], v[84:87]
	v_mfma_f32_16x16x32_bf16 v[80:83], v[230:233], v[206:209], v[80:83]
	v_mfma_f32_16x16x32_bf16 v[68:71], v[222:225], v[214:217], v[68:71]
	v_mfma_f32_16x16x32_bf16 v[64:67], v[230:233], v[214:217], v[64:67]
	s_setprio 0
	s_add_i32 m0, s57, 0xffffff80
	s_barrier
	ds_read_b128 v[180:183], v166 offset:49152
	ds_read_b128 v[188:191], v166 offset:50176
	ds_read_b128 v[194:197], v166 offset:51200
	ds_read_b128 v[198:201], v166 offset:52224
	ds_read_b128 v[202:205], v166 offset:53248
	ds_read_b128 v[206:209], v166 offset:54272
	ds_read_b128 v[210:213], v166 offset:55296
	global_load_lds_dwordx4 v128, s[38:39] offset:128
	s_add_i32 m0, s58, 0xffffff80
	ds_read_b128 v[214:217], v166 offset:56320
	global_load_lds_dwordx4 v132, s[38:39] offset:128
	s_barrier
	s_waitcnt lgkmcnt(0)
	s_setprio 1
	v_mfma_f32_16x16x32_bf16 v[60:63], v[144:147], v[180:183], v[60:63]
	v_mfma_f32_16x16x32_bf16 v[56:59], v[172:175], v[180:183], v[56:59]
	v_mfma_f32_16x16x32_bf16 v[44:47], v[144:147], v[194:197], v[44:47]
	v_mfma_f32_16x16x32_bf16 v[40:43], v[172:175], v[194:197], v[40:43]
	v_mfma_f32_16x16x32_bf16 v[28:31], v[144:147], v[202:205], v[28:31]
	v_mfma_f32_16x16x32_bf16 v[24:27], v[172:175], v[202:205], v[24:27]
	v_mfma_f32_16x16x32_bf16 v[12:15], v[144:147], v[210:213], v[12:15]
	v_mfma_f32_16x16x32_bf16 v[8:11], v[172:175], v[210:213], v[8:11]
	v_mfma_f32_16x16x32_bf16 v[60:63], v[168:171], v[188:191], v[60:63]
	v_mfma_f32_16x16x32_bf16 v[56:59], v[176:179], v[188:191], v[56:59]
	v_mfma_f32_16x16x32_bf16 v[44:47], v[168:171], v[198:201], v[44:47]
	v_mfma_f32_16x16x32_bf16 v[40:43], v[176:179], v[198:201], v[40:43]
	v_mfma_f32_16x16x32_bf16 v[28:31], v[168:171], v[206:209], v[28:31]
	v_mfma_f32_16x16x32_bf16 v[24:27], v[176:179], v[206:209], v[24:27]
	v_mfma_f32_16x16x32_bf16 v[12:15], v[168:171], v[214:217], v[12:15]
	v_mfma_f32_16x16x32_bf16 v[8:11], v[176:179], v[214:217], v[8:11]
	s_setprio 0
	s_barrier
	s_add_i32 s4, s5, s50
	s_mov_b32 m0, s4
	s_add_u32 s0, s36, 0x30080
	s_addc_u32 s1, s37, 0
	global_load_lds_dwordx4 v130, s[0:1]
	s_add_i32 m0, s4, 0x2000
	s_add_i32 s41, s41, 2
	global_load_lds_dwordx4 v134, s[0:1]
	s_add_u32 s8, s8, 0x100
	s_addc_u32 s9, s9, 0
	s_add_u32 s35, s35, 0x100
	s_addc_u32 s40, s40, 0
	s_cmp_gt_u32 s41, 9
	s_waitcnt vmcnt(6)
	s_barrier
	s_setprio 1
	v_mfma_f32_16x16x32_bf16 v[52:55], v[218:221], v[180:183], v[52:55]
	v_mfma_f32_16x16x32_bf16 v[48:51], v[226:229], v[180:183], v[48:51]
	v_mfma_f32_16x16x32_bf16 v[36:39], v[218:221], v[194:197], v[36:39]
	v_mfma_f32_16x16x32_bf16 v[32:35], v[226:229], v[194:197], v[32:35]
	v_mfma_f32_16x16x32_bf16 v[20:23], v[218:221], v[202:205], v[20:23]
	v_mfma_f32_16x16x32_bf16 v[16:19], v[226:229], v[202:205], v[16:19]
	v_mfma_f32_16x16x32_bf16 v[4:7], v[218:221], v[210:213], v[4:7]
	v_mfma_f32_16x16x32_bf16 v[0:3], v[226:229], v[210:213], v[0:3]
	v_mfma_f32_16x16x32_bf16 v[52:55], v[222:225], v[188:191], v[52:55]
	v_mfma_f32_16x16x32_bf16 v[48:51], v[230:233], v[188:191], v[48:51]
	v_mfma_f32_16x16x32_bf16 v[36:39], v[222:225], v[198:201], v[36:39]
	v_mfma_f32_16x16x32_bf16 v[32:35], v[230:233], v[198:201], v[32:35]
	v_mfma_f32_16x16x32_bf16 v[20:23], v[222:225], v[206:209], v[20:23]
	v_mfma_f32_16x16x32_bf16 v[16:19], v[230:233], v[206:209], v[16:19]
	v_mfma_f32_16x16x32_bf16 v[4:7], v[222:225], v[214:217], v[4:7]
	v_mfma_f32_16x16x32_bf16 v[0:3], v[230:233], v[214:217], v[0:3]
	s_setprio 0
	s_cbranch_scc0 .Lrot_938
	s_barrier
	s_branch .Lpeel_done_938

; #define PG8_STAGE(bufoff, gbase, voff) do { _Pragma("unroll") for (int _i = 0; _i < 2; ++_i) \
;         __builtin_amdgcn_global_load_lds((const unsigned*)((const char*)(gbase) + (voff)[_i]), (LAS unsigned*)(lds + (bufoff) + ldsw + _i * 8192), 16, 0, 0); } while (0)
; #define PG8_LDA(dst, b, h) do { _Pragma("unroll") for (int m = 0; m < 4; ++m) _Pragma("unroll") for (int k = 0; k < 2; ++k) dst[m][k] = *(const LAS bf16x8*)(lds + PG8_SA(b, h) + aoff + m * 2048 + k * 1024); } while (0)
; #define PG8_LDB(dst, b, h) do { _Pragma("unroll") for (int n = 0; n < 2; ++n) _Pragma("unroll") for (int k = 0; k < 2; ++k) dst[n][k] = *(const LAS bf16x8*)(lds + PG8_SB(b, h) + boff + n * 2048 + k * 1024); } while (0)
; #define PG8_MMA(ai, bj, At, Bt) do { __builtin_amdgcn_s_setprio(1); _Pragma("unroll") for (int m = 0; m < 4; ++m) _Pragma("unroll") for (int n = 0; n < 2; ++n) _Pragma("unroll") for (int k = 0; k < 2; ++k) \
;         acc[ai][bj][m][n] = __builtin_amdgcn_mfma_f32_16x16x32_bf16(Bt[n][k], At[m][k], acc[ai][bj][m][n], 0, 0, 0); __builtin_amdgcn_s_setprio(0); } while (0)
; #define PG8_WAIT_V(n) asm volatile("s_waitcnt vmcnt(" #n ")" ::: "memory")
; #define PG8_WAIT_L(n) asm volatile("s_waitcnt lgkmcnt(" #n ")" ::: "memory")
; #define PG8_BAR __builtin_amdgcn_s_barrier()
; #define PG8_SCHED __builtin_amdgcn_sched_barrier(0)
; template <class Epi, class Sched>
; DI void gemm_phase(LAS unsigned char* lds, const Gemm g, const Sched& S, const Epi& E) {
;     ...
;             PG8_LDB(B0, 0, 0); PG8_SCHED; PG8_LDA(At, 0, 0); PG8_STAGE(PG8_SA(1, 1), a1 + hstep, voffA);
;             PG8_WAIT_L(8); PG8_BAR; PG8_WAIT_L(0); PG8_MMA(0, 0, At, B0); PG8_BAR; PG8_SCHED;
;             PG8_LDB(B1, 0, 1); PG8_STAGE(PG8_SB(0, 0), b2, voffB);
;             PG8_BAR; PG8_WAIT_L(0); PG8_MMA(0, 1, At, B1); PG8_BAR;
;             PG8_LDA(At, 0, 1); PG8_STAGE(PG8_SA(0, 0), a2, voffA);
;             PG8_BAR; PG8_WAIT_L(0); PG8_MMA(1, 0, At, B0); PG8_BAR; PG8_SCHED;
;             PG8_STAGE(PG8_SB(0, 1), b2 + hstep, voffB);
;             PG8_WAIT_V(6); PG8_BAR; PG8_MMA(1, 1, At, B1); PG8_BAR;
.LBB0_938:
	ds_read_b128 v[144:147], v165
	ds_read_b128 v[168:171], v165 offset:1024
	ds_read_b128 v[172:175], v165 offset:2048
	ds_read_b128 v[176:179], v165 offset:3072
	s_add_i32 m0, s51, 0xc000
	ds_read_b128 v[180:183], v166
	ds_read_b128 v[188:191], v166 offset:1024
	ds_read_b128 v[194:197], v166 offset:2048
	ds_read_b128 v[198:201], v166 offset:3072
	ds_read_b128 v[202:205], v166 offset:4096
	ds_read_b128 v[206:209], v166 offset:5120
	ds_read_b128 v[210:213], v166 offset:6144
	global_load_lds_dwordx4 v136, s[8:9]
	s_add_i32 m0, s51, 0xe000
	ds_read_b128 v[214:217], v166 offset:7168
	global_load_lds_dwordx4 v138, s[8:9]
	s_add_u32 s0, s8, 0xfffd0080
	s_addc_u32 s1, s9, -1
	s_cmp_eq_u32 s41, 8
	s_cselect_b32 s39, s31, s1
	s_cselect_b32 s38, s30, s0
	s_cselect_b32 s37, s11, s40
	s_cselect_b32 s36, s10, s35
	s_waitcnt lgkmcnt(8)
	s_barrier
	s_waitcnt lgkmcnt(0)
	s_setprio 1
	v_mfma_f32_16x16x32_bf16 v[124:127], v[144:147], v[180:183], v[124:127]
	v_mfma_f32_16x16x32_bf16 v[120:123], v[172:175], v[180:183], v[120:123]
	v_mfma_f32_16x16x32_bf16 v[108:111], v[144:147], v[194:197], v[108:111]
	v_mfma_f32_16x16x32_bf16 v[104:107], v[172:175], v[194:197], v[104:107]
	v_mfma_f32_16x16x32_bf16 v[92:95], v[144:147], v[202:205], v[92:95]
	v_mfma_f32_16x16x32_bf16 v[88:91], v[172:175], v[202:205], v[88:91]
	v_mfma_f32_16x16x32_bf16 v[76:79], v[144:147], v[210:213], v[76:79]
	v_mfma_f32_16x16x32_bf16 v[72:75], v[172:175], v[210:213], v[72:75]
	v_mfma_f32_16x16x32_bf16 v[124:127], v[168:171], v[188:191], v[124:127]
	v_mfma_f32_16x16x32_bf16 v[120:123], v[176:179], v[188:191], v[120:123]
	v_mfma_f32_16x16x32_bf16 v[108:111], v[168:171], v[198:201], v[108:111]
	v_mfma_f32_16x16x32_bf16 v[104:107], v[176:179], v[198:201], v[104:107]
	v_mfma_f32_16x16x32_bf16 v[92:95], v[168:171], v[206:209], v[92:95]
	v_mfma_f32_16x16x32_bf16 v[88:91], v[176:179], v[206:209], v[88:91]
	v_mfma_f32_16x16x32_bf16 v[76:79], v[168:171], v[214:217], v[76:79]
	v_mfma_f32_16x16x32_bf16 v[72:75], v[176:179], v[214:217], v[72:75]
	s_setprio 0
	s_barrier
	s_add_i32 s0, s61, s50
	s_mov_b32 m0, s0
	ds_read_b128 v[218:221], v167
	ds_read_b128 v[222:225], v167 offset:1024
	ds_read_b128 v[226:229], v167 offset:2048
	global_load_lds_dwordx4 v130, s[36:37]
	s_add_i32 m0, s0, 0x2000
	ds_read_b128 v[230:233], v167 offset:3072
	global_load_lds_dwordx4 v134, s[36:37]
	s_barrier
	s_waitcnt lgkmcnt(0)
	s_setprio 1
	v_mfma_f32_16x16x32_bf16 v[116:119], v[218:221], v[180:183], v[116:119]
	v_mfma_f32_16x16x32_bf16 v[112:115], v[226:229], v[180:183], v[112:115]
	v_mfma_f32_16x16x32_bf16 v[100:103], v[218:221], v[194:197], v[100:103]
	v_mfma_f32_16x16x32_bf16 v[96:99], v[226:229], v[194:197], v[96:99]
	v_mfma_f32_16x16x32_bf16 v[84:87], v[218:221], v[202:205], v[84:87]
	v_mfma_f32_16x16x32_bf16 v[80:83], v[226:229], v[202:205], v[80:83]
	v_mfma_f32_16x16x32_bf16 v[68:71], v[218:221], v[210:213], v[68:71]
	v_mfma_f32_16x16x32_bf16 v[64:67], v[226:229], v[210:213], v[64:67]
	v_mfma_f32_16x16x32_bf16 v[116:119], v[222:225], v[188:191], v[116:119]
	v_mfma_f32_16x16x32_bf16 v[112:115], v[230:233], v[188:191], v[112:115]
	v_mfma_f32_16x16x32_bf16 v[100:103], v[222:225], v[198:201], v[100:103]
	v_mfma_f32_16x16x32_bf16 v[96:99], v[230:233], v[198:201], v[96:99]
	v_mfma_f32_16x16x32_bf16 v[84:87], v[222:225], v[206:209], v[84:87]
	v_mfma_f32_16x16x32_bf16 v[80:83], v[230:233], v[206:209], v[80:83]
	v_mfma_f32_16x16x32_bf16 v[68:71], v[222:225], v[214:217], v[68:71]
	v_mfma_f32_16x16x32_bf16 v[64:67], v[230:233], v[214:217], v[64:67]
	s_setprio 0
	s_mov_b32 m0, s51
	s_barrier
	ds_read_b128 v[180:183], v166 offset:16384
	ds_read_b128 v[188:191], v166 offset:17408
	ds_read_b128 v[194:197], v166 offset:18432
	ds_read_b128 v[198:201], v166 offset:19456
	ds_read_b128 v[202:205], v166 offset:20480
	ds_read_b128 v[206:209], v166 offset:21504
	ds_read_b128 v[210:213], v166 offset:22528
	global_load_lds_dwordx4 v128, s[38:39]
	s_mov_b32 m0, s52
	ds_read_b128 v[214:217], v166 offset:23552
	global_load_lds_dwordx4 v132, s[38:39]
	s_barrier
	s_waitcnt lgkmcnt(0)
	s_setprio 1
	v_mfma_f32_16x16x32_bf16 v[60:63], v[144:147], v[180:183], v[60:63]
	v_mfma_f32_16x16x32_bf16 v[56:59], v[172:175], v[180:183], v[56:59]
	v_mfma_f32_16x16x32_bf16 v[44:47], v[144:147], v[194:197], v[44:47]
	v_mfma_f32_16x16x32_bf16 v[40:43], v[172:175], v[194:197], v[40:43]
	v_mfma_f32_16x16x32_bf16 v[28:31], v[144:147], v[202:205], v[28:31]
	v_mfma_f32_16x16x32_bf16 v[24:27], v[172:175], v[202:205], v[24:27]
	v_mfma_f32_16x16x32_bf16 v[12:15], v[144:147], v[210:213], v[12:15]
	v_mfma_f32_16x16x32_bf16 v[8:11], v[172:175], v[210:213], v[8:11]
	v_mfma_f32_16x16x32_bf16 v[60:63], v[168:171], v[188:191], v[60:63]
	v_mfma_f32_16x16x32_bf16 v[56:59], v[176:179], v[188:191], v[56:59]
	v_mfma_f32_16x16x32_bf16 v[44:47], v[168:171], v[198:201], v[44:47]
	v_mfma_f32_16x16x32_bf16 v[40:43], v[176:179], v[198:201], v[40:43]
	v_mfma_f32_16x16x32_bf16 v[28:31], v[168:171], v[206:209], v[28:31]
	v_mfma_f32_16x16x32_bf16 v[24:27], v[176:179], v[206:209], v[24:27]
	v_mfma_f32_16x16x32_bf16 v[12:15], v[168:171], v[214:217], v[12:15]
	v_mfma_f32_16x16x32_bf16 v[8:11], v[176:179], v[214:217], v[8:11]
	s_setprio 0
	s_barrier
	s_add_i32 s4, s62, s50
	s_mov_b32 m0, s4
	s_add_u32 s0, s36, 0x30000
	s_addc_u32 s1, s37, 0
	global_load_lds_dwordx4 v130, s[0:1]
	s_add_i32 m0, s4, 0x2000
	s_add_i32 s4, 0, 0x18000
	global_load_lds_dwordx4 v134, s[0:1]
	s_waitcnt vmcnt(6)
	s_barrier
; #define PG8_STAGE(bufoff, gbase, voff) do { _Pragma("unroll") for (int _i = 0; _i < 2; ++_i) \
;         __builtin_amdgcn_global_load_lds((const unsigned*)((const char*)(gbase) + (voff)[_i]), (LAS unsigned*)(lds + (bufoff) + ldsw + _i * 8192), 16, 0, 0); } while (0)
; #define PG8_LDA(dst, b, h) do { _Pragma("unroll") for (int m = 0; m < 4; ++m) _Pragma("unroll") for (int k = 0; k < 2; ++k) dst[m][k] = *(const LAS bf16x8*)(lds + PG8_SA(b, h) + aoff + m * 2048 + k * 1024); } while (0)
; #define PG8_LDB(dst, b, h) do { _Pragma("unroll") for (int n = 0; n < 2; ++n) _Pragma("unroll") for (int k = 0; k < 2; ++k) dst[n][k] = *(const LAS bf16x8*)(lds + PG8_SB(b, h) + boff + n * 2048 + k * 1024); } while (0)
; #define PG8_MMA(ai, bj, At, Bt) do { __builtin_amdgcn_s_setprio(1); _Pragma("unroll") for (int m = 0; m < 4; ++m) _Pragma("unroll") for (int n = 0; n < 2; ++n) _Pragma("unroll") for (int k = 0; k < 2; ++k) \
;         acc[ai][bj][m][n] = __builtin_amdgcn_mfma_f32_16x16x32_bf16(Bt[n][k], At[m][k], acc[ai][bj][m][n], 0, 0, 0); __builtin_amdgcn_s_setprio(0); } while (0)
; #define PG8_WAIT_V(n) asm volatile("s_waitcnt vmcnt(" #n ")" ::: "memory")
; #define PG8_WAIT_L(n) asm volatile("s_waitcnt lgkmcnt(" #n ")" ::: "memory")
; #define PG8_BAR __builtin_amdgcn_s_barrier()
; #define PG8_SCHED __builtin_amdgcn_sched_barrier(0)
; template <class Epi, class Sched>
; DI void gemm_phase(LAS unsigned char* lds, const Gemm g, const Sched& S, const Epi& E) {
;     ...
;             PG8_WAIT_V(6); PG8_BAR; PG8_MMA(1, 1, At, B1); PG8_BAR;
;             PG8_LDB(B0, 1, 0); PG8_SCHED; PG8_LDA(At, 1, 0); PG8_STAGE(PG8_SA(0, 1), a2 + hstep, voffA);
;             PG8_WAIT_L(8); PG8_BAR; PG8_WAIT_L(0); PG8_MMA(0, 0, At, B0); PG8_BAR; PG8_SCHED;
;             PG8_LDB(B1, 1, 1); PG8_STAGE(PG8_SB(1, 0), b3, voffB);
	s_setprio 1
	v_mfma_f32_16x16x32_bf16 v[52:55], v[218:221], v[180:183], v[52:55]
	v_mfma_f32_16x16x32_bf16 v[48:51], v[226:229], v[180:183], v[48:51]
	v_mfma_f32_16x16x32_bf16 v[36:39], v[218:221], v[194:197], v[36:39]
	v_mfma_f32_16x16x32_bf16 v[32:35], v[226:229], v[194:197], v[32:35]
	v_mfma_f32_16x16x32_bf16 v[20:23], v[218:221], v[202:205], v[20:23]
	v_mfma_f32_16x16x32_bf16 v[16:19], v[226:229], v[202:205], v[16:19]
	v_mfma_f32_16x16x32_bf16 v[4:7], v[218:221], v[210:213], v[4:7]
	v_mfma_f32_16x16x32_bf16 v[0:3], v[226:229], v[210:213], v[0:3]
	v_mfma_f32_16x16x32_bf16 v[52:55], v[222:225], v[188:191], v[52:55]
	v_mfma_f32_16x16x32_bf16 v[48:51], v[230:233], v[188:191], v[48:51]
	v_mfma_f32_16x16x32_bf16 v[36:39], v[222:225], v[198:201], v[36:39]
	v_mfma_f32_16x16x32_bf16 v[32:35], v[230:233], v[198:201], v[32:35]
	v_mfma_f32_16x16x32_bf16 v[20:23], v[222:225], v[206:209], v[20:23]
	v_mfma_f32_16x16x32_bf16 v[16:19], v[230:233], v[206:209], v[16:19]
	v_mfma_f32_16x16x32_bf16 v[4:7], v[222:225], v[214:217], v[4:7]
	v_mfma_f32_16x16x32_bf16 v[0:3], v[230:233], v[214:217], v[0:3]
	s_setprio 0
	s_barrier
	ds_read_b128 v[144:147], v148
	ds_read_b128 v[168:171], v148 offset:1024
	ds_read_b128 v[172:175], v148 offset:2048
	ds_read_b128 v[176:179], v148 offset:3072
	s_add_u32 s0, s38, 0x30000
	s_addc_u32 s1, s39, 0
	s_mov_b32 m0, s53
	ds_read_b128 v[180:183], v166 offset:32768
	ds_read_b128 v[188:191], v166 offset:33792
	ds_read_b128 v[194:197], v166 offset:34816
	ds_read_b128 v[198:201], v166 offset:35840
	ds_read_b128 v[202:205], v166 offset:36864
	ds_read_b128 v[206:209], v166 offset:37888
	ds_read_b128 v[210:213], v166 offset:38912
	global_load_lds_dwordx4 v128, s[0:1]
	s_mov_b32 m0, s54
	ds_read_b128 v[214:217], v166 offset:39936
	global_load_lds_dwordx4 v132, s[0:1]
	s_waitcnt lgkmcnt(8)
	s_barrier
	s_waitcnt lgkmcnt(0)
	s_setprio 1
	v_mfma_f32_16x16x32_bf16 v[124:127], v[144:147], v[180:183], v[124:127]
	v_mfma_f32_16x16x32_bf16 v[120:123], v[172:175], v[180:183], v[120:123]
	v_mfma_f32_16x16x32_bf16 v[108:111], v[144:147], v[194:197], v[108:111]
	v_mfma_f32_16x16x32_bf16 v[104:107], v[172:175], v[194:197], v[104:107]
	v_mfma_f32_16x16x32_bf16 v[92:95], v[144:147], v[202:205], v[92:95]
	v_mfma_f32_16x16x32_bf16 v[88:91], v[172:175], v[202:205], v[88:91]
	v_mfma_f32_16x16x32_bf16 v[76:79], v[144:147], v[210:213], v[76:79]
	v_mfma_f32_16x16x32_bf16 v[72:75], v[172:175], v[210:213], v[72:75]
	v_mfma_f32_16x16x32_bf16 v[124:127], v[168:171], v[188:191], v[124:127]
	v_mfma_f32_16x16x32_bf16 v[120:123], v[176:179], v[188:191], v[120:123]
	v_mfma_f32_16x16x32_bf16 v[108:111], v[168:171], v[198:201], v[108:111]
	v_mfma_f32_16x16x32_bf16 v[104:107], v[176:179], v[198:201], v[104:107]
	v_mfma_f32_16x16x32_bf16 v[92:95], v[168:171], v[206:209], v[92:95]
	v_mfma_f32_16x16x32_bf16 v[88:91], v[176:179], v[206:209], v[88:91]
	v_mfma_f32_16x16x32_bf16 v[76:79], v[168:171], v[214:217], v[76:79]
	v_mfma_f32_16x16x32_bf16 v[72:75], v[176:179], v[214:217], v[72:75]
	s_setprio 0
	s_barrier
	s_add_i32 s5, 0, 0x1c000
	s_add_i32 s0, s4, s50
	s_add_i32 m0, s0, 0xffffff80
	ds_read_b128 v[218:221], v149
	ds_read_b128 v[222:225], v149 offset:1024
	ds_read_b128 v[226:229], v149 offset:2048
	global_load_lds_dwordx4 v130, s[36:37] offset:128
	s_add_i32 m0, s0, 0x1f80
	ds_read_b128 v[230:233], v149 offset:3072
	global_load_lds_dwordx4 v134, s[36:37] offset:128
	s_barrier
; #define PG8_STAGE(bufoff, gbase, voff) do { _Pragma("unroll") for (int _i = 0; _i < 2; ++_i) \
;         __builtin_amdgcn_global_load_lds((const unsigned*)((const char*)(gbase) + (voff)[_i]), (LAS unsigned*)(lds + (bufoff) + ldsw + _i * 8192), 16, 0, 0); } while (0)
; #define PG8_LDA(dst, b, h) do { _Pragma("unroll") for (int m = 0; m < 4; ++m) _Pragma("unroll") for (int k = 0; k < 2; ++k) dst[m][k] = *(const LAS bf16x8*)(lds + PG8_SA(b, h) + aoff + m * 2048 + k * 1024); } while (0)
; #define PG8_MMA(ai, bj, At, Bt) do { __builtin_amdgcn_s_setprio(1); _Pragma("unroll") for (int m = 0; m < 4; ++m) _Pragma("unroll") for (int n = 0; n < 2; ++n) _Pragma("unroll") for (int k = 0; k < 2; ++k) \
;         acc[ai][bj][m][n] = __builtin_amdgcn_mfma_f32_16x16x32_bf16(Bt[n][k], At[m][k], acc[ai][bj][m][n], 0, 0, 0); __builtin_amdgcn_s_setprio(0); } while (0)
; #define PG8_WAIT_V(n) asm volatile("s_waitcnt vmcnt(" #n ")" ::: "memory")
; #define PG8_WAIT_L(n) asm volatile("s_waitcnt lgkmcnt(" #n ")" ::: "memory")
; #define PG8_BAR __builtin_amdgcn_s_barrier()
; #define PG8_SCHED __builtin_amdgcn_sched_barrier(0)
; template <class Epi, class Sched>
; DI void gemm_phase(LAS unsigned char* lds, const Gemm g, const Sched& S, const Epi& E) {
;     ...
;             PG8_BAR; PG8_WAIT_L(0); PG8_MMA(0, 1, At, B1); PG8_BAR;
;             PG8_LDA(At, 1, 1); PG8_STAGE(PG8_SA(1, 0), a3, voffA);
;             PG8_BAR; PG8_WAIT_L(0); PG8_MMA(1, 0, At, B0); PG8_BAR; PG8_SCHED;
;             PG8_STAGE(PG8_SB(1, 1), b3 + hstep, voffB);
;             PG8_WAIT_V(6); PG8_BAR; PG8_MMA(1, 1, At, B1); PG8_BAR;
	s_waitcnt lgkmcnt(0)
	s_setprio 1
	v_mfma_f32_16x16x32_bf16 v[116:119], v[218:221], v[180:183], v[116:119]
	v_mfma_f32_16x16x32_bf16 v[112:115], v[226:229], v[180:183], v[112:115]
	v_mfma_f32_16x16x32_bf16 v[100:103], v[218:221], v[194:197], v[100:103]
	v_mfma_f32_16x16x32_bf16 v[96:99], v[226:229], v[194:197], v[96:99]
	v_mfma_f32_16x16x32_bf16 v[84:87], v[218:221], v[202:205], v[84:87]
	v_mfma_f32_16x16x32_bf16 v[80:83], v[226:229], v[202:205], v[80:83]
	v_mfma_f32_16x16x32_bf16 v[68:71], v[218:221], v[210:213], v[68:71]
	v_mfma_f32_16x16x32_bf16 v[64:67], v[226:229], v[210:213], v[64:67]
	v_mfma_f32_16x16x32_bf16 v[116:119], v[222:225], v[188:191], v[116:119]
	v_mfma_f32_16x16x32_bf16 v[112:115], v[230:233], v[188:191], v[112:115]
	v_mfma_f32_16x16x32_bf16 v[100:103], v[222:225], v[198:201], v[100:103]
	v_mfma_f32_16x16x32_bf16 v[96:99], v[230:233], v[198:201], v[96:99]
	v_mfma_f32_16x16x32_bf16 v[84:87], v[222:225], v[206:209], v[84:87]
	v_mfma_f32_16x16x32_bf16 v[80:83], v[230:233], v[206:209], v[80:83]
	v_mfma_f32_16x16x32_bf16 v[68:71], v[222:225], v[214:217], v[68:71]
	v_mfma_f32_16x16x32_bf16 v[64:67], v[230:233], v[214:217], v[64:67]
	s_setprio 0
	s_add_i32 m0, s57, 0xffffff80
	s_barrier
	ds_read_b128 v[180:183], v166 offset:49152
	ds_read_b128 v[188:191], v166 offset:50176
	ds_read_b128 v[194:197], v166 offset:51200
	ds_read_b128 v[198:201], v166 offset:52224
	ds_read_b128 v[202:205], v166 offset:53248
	ds_read_b128 v[206:209], v166 offset:54272
	ds_read_b128 v[210:213], v166 offset:55296
	global_load_lds_dwordx4 v128, s[38:39] offset:128
	s_add_i32 m0, s58, 0xffffff80
	ds_read_b128 v[214:217], v166 offset:56320
	global_load_lds_dwordx4 v132, s[38:39] offset:128
	s_barrier
	s_waitcnt lgkmcnt(0)
	s_setprio 1
	v_mfma_f32_16x16x32_bf16 v[60:63], v[144:147], v[180:183], v[60:63]
	v_mfma_f32_16x16x32_bf16 v[56:59], v[172:175], v[180:183], v[56:59]
	v_mfma_f32_16x16x32_bf16 v[44:47], v[144:147], v[194:197], v[44:47]
	v_mfma_f32_16x16x32_bf16 v[40:43], v[172:175], v[194:197], v[40:43]
	v_mfma_f32_16x16x32_bf16 v[28:31], v[144:147], v[202:205], v[28:31]
	v_mfma_f32_16x16x32_bf16 v[24:27], v[172:175], v[202:205], v[24:27]
	v_mfma_f32_16x16x32_bf16 v[12:15], v[144:147], v[210:213], v[12:15]
	v_mfma_f32_16x16x32_bf16 v[8:11], v[172:175], v[210:213], v[8:11]
	v_mfma_f32_16x16x32_bf16 v[60:63], v[168:171], v[188:191], v[60:63]
	v_mfma_f32_16x16x32_bf16 v[56:59], v[176:179], v[188:191], v[56:59]
	v_mfma_f32_16x16x32_bf16 v[44:47], v[168:171], v[198:201], v[44:47]
	v_mfma_f32_16x16x32_bf16 v[40:43], v[176:179], v[198:201], v[40:43]
	v_mfma_f32_16x16x32_bf16 v[28:31], v[168:171], v[206:209], v[28:31]
	v_mfma_f32_16x16x32_bf16 v[24:27], v[176:179], v[206:209], v[24:27]
	v_mfma_f32_16x16x32_bf16 v[12:15], v[168:171], v[214:217], v[12:15]
	v_mfma_f32_16x16x32_bf16 v[8:11], v[176:179], v[214:217], v[8:11]
	s_setprio 0
	s_barrier
	s_add_i32 s4, s5, s50
	s_mov_b32 m0, s4
	s_add_u32 s0, s36, 0x30080
	s_addc_u32 s1, s37, 0
	global_load_lds_dwordx4 v130, s[0:1]
	s_add_i32 m0, s4, 0x2000
	s_add_i32 s41, s41, 2
	global_load_lds_dwordx4 v134, s[0:1]
	s_add_u32 s8, s8, 0x100
	s_addc_u32 s9, s9, 0
	s_add_u32 s35, s35, 0x100
	s_addc_u32 s40, s40, 0
	s_cmp_gt_u32 s41, 9
	s_waitcnt vmcnt(6)
	s_barrier
	s_setprio 1
	v_mfma_f32_16x16x32_bf16 v[52:55], v[218:221], v[180:183], v[52:55]
	v_mfma_f32_16x16x32_bf16 v[48:51], v[226:229], v[180:183], v[48:51]
	v_mfma_f32_16x16x32_bf16 v[36:39], v[218:221], v[194:197], v[36:39]
	v_mfma_f32_16x16x32_bf16 v[32:35], v[226:229], v[194:197], v[32:35]
	v_mfma_f32_16x16x32_bf16 v[20:23], v[218:221], v[202:205], v[20:23]
	v_mfma_f32_16x16x32_bf16 v[16:19], v[226:229], v[202:205], v[16:19]
	v_mfma_f32_16x16x32_bf16 v[4:7], v[218:221], v[210:213], v[4:7]
	v_mfma_f32_16x16x32_bf16 v[0:3], v[226:229], v[210:213], v[0:3]
	v_mfma_f32_16x16x32_bf16 v[52:55], v[222:225], v[188:191], v[52:55]
	v_mfma_f32_16x16x32_bf16 v[48:51], v[230:233], v[188:191], v[48:51]
	v_mfma_f32_16x16x32_bf16 v[36:39], v[222:225], v[198:201], v[36:39]
	v_mfma_f32_16x16x32_bf16 v[32:35], v[230:233], v[198:201], v[32:35]
	v_mfma_f32_16x16x32_bf16 v[20:23], v[222:225], v[206:209], v[20:23]
	v_mfma_f32_16x16x32_bf16 v[16:19], v[230:233], v[206:209], v[16:19]
	v_mfma_f32_16x16x32_bf16 v[4:7], v[222:225], v[214:217], v[4:7]
	v_mfma_f32_16x16x32_bf16 v[0:3], v[230:233], v[214:217], v[0:3]
	s_setprio 0
	s_cbranch_scc0 .Lrot_938
	s_barrier

;     DI size_t aoff(const Unit& u, size_t tstep) const { return (size_t)u.pm * tstep; }
;     DI size_t boff(const Unit& u, size_t tstep) const { return (size_t)u.pn * tstep; }
;     DI bool next(int i, Unit& u) const { const long L = (long)i * G + c; if (L >= np) return false; u.pm = pmv; u.pn = (int)(L % nN); u.ks = (int)(L / nN); return true; }
;     DI size_t aoff(const Unit& u, size_t) const { return (size_t)u.ks * kbytes; }
;     DI size_t boff(const Unit& u, size_t tstep) const { return (size_t)u.pn * tstep + (size_t)u.ks * kbytes; }
;     DI bool next(int i, Unit& u) const { Unit t; if (!S.next(i / 3, t)) return false; u.pm = t.pm; u.pn = t.pn; u.ks = i % 3; return true; }
;     DI size_t aoff(const Unit& u, size_t tstep) const { return (u.ks < 2 ? offU : offOA) + (size_t)u.pm * tstep; }
; #define PG8_WAIT_V(n) asm volatile("s_waitcnt vmcnt(" #n ")" ::: "memory")
; template <class Epi, class Sched>
; DI void gemm_phase(LAS unsigned char* lds, const Gemm g, const Sched& S, const Epi& E) {
;     ...
;         const bool has_next = S.next(ui + 1, nxt);
;         const char* nA = has_next ? (const char*)g.A + S.aoff(nxt, tstep) : cA; const char* nB = has_next ? (const char*)g.Bt + S.boff(nxt, tstep) : cB;
;         for (int t = 0; t < nt; t += 2) {
;             if constexpr (Epi::HAS_MID) { if (t == E.mid_t(nt)) { int fr3 = fr, fq3 = fq; asm volatile("" : "+v"(fr3), "+v"(fq3)); E.mid(acc, cur, wr, wc, fr3, fq3); } }
;             const bool last = (t == nt - 2);
;             const char* a1 = cA + (size_t)(t + 1) * kstep;
;             const char* a2 = last ? nA : cA + (size_t)(t + 2) * kstep; const char* b2 = last ? nB : cB + (size_t)(t + 2) * kstep;
;             const char* a3 = a2 + kstep; const char* b3 = b2 + kstep;
;             PG8_LDB(B0, 0, 0); PG8_SCHED; PG8_LDA(At, 0, 0); PG8_STAGE(PG8_SA(1, 1), a1 + hstep, voffA);
;             PG8_WAIT_L(8); PG8_BAR; PG8_WAIT_L(0); PG8_MMA(0, 0, At, B0); PG8_BAR; PG8_SCHED;
;             PG8_LDB(B1, 0, 1); PG8_STAGE(PG8_SB(0, 0), b2, voffB);
;             PG8_BAR; PG8_WAIT_L(0); PG8_MMA(0, 1, At, B1); PG8_BAR;
;             PG8_LDA(At, 0, 1); PG8_STAGE(PG8_SA(0, 0), a2, voffA);
;             PG8_BAR; PG8_WAIT_L(0); PG8_MMA(1, 0, At, B0); PG8_BAR; PG8_SCHED;
;             PG8_STAGE(PG8_SB(0, 1), b2 + hstep, voffB);
;             PG8_WAIT_V(6); PG8_BAR; PG8_MMA(1, 1, At, B1); PG8_BAR;
.LBB0_983:
	s_ashr_i32 s31, s30, 31
	s_lshl_b64 s[0:1], s[30:31], 18
	v_cmp_lt_i64_e32 vcc, s[36:37], v[142:143]
	s_add_u32 s36, s51, s0
	s_addc_u32 s37, s52, s1
	s_and_b64 s[0:1], vcc, exec
	s_cselect_b32 s9, s37, s43
	s_cselect_b32 s31, s36, s42
	s_ashr_i32 s29, s28, 31
	s_lshl_b64 s[0:1], s[28:29], 18
	s_add_u32 s38, s53, s0
	s_addc_u32 s39, s54, s1
	s_and_b64 s[0:1], vcc, exec
	s_cselect_b32 s29, s39, s45
	s_cselect_b32 s34, s38, s44
	s_add_u32 s42, s42, 0x20080
	s_addc_u32 s43, s43, 0
	s_add_u32 s35, s44, 0x100
	v_mov_b32_e32 v0, 0
	s_addc_u32 s41, s45, 0
	s_mov_b32 s79, -2
	ds_read_b128 v[146:149], v156
	ds_read_b128 v[150:153], v156 offset:1024
	ds_read_b128 v[160:163], v156 offset:2048
	ds_read_b128 v[164:167], v156 offset:3072
	s_add_i32 m0, s55, 0xc000
	ds_read_b128 v[168:171], v158
	ds_read_b128 v[172:175], v158 offset:1024
	ds_read_b128 v[176:179], v158 offset:2048
	ds_read_b128 v[180:183], v158 offset:3072
	ds_read_b128 v[188:191], v158 offset:4096
	ds_read_b128 v[194:197], v158 offset:5120
	ds_read_b128 v[198:201], v158 offset:6144
	global_load_lds_dwordx4 v138, s[42:43]
	s_add_i32 m0, s55, 0xe000
	ds_read_b128 v[202:205], v158 offset:7168
	global_load_lds_dwordx4 v140, s[42:43]
	s_add_u32 s0, s42, 0xfffe0080
	s_addc_u32 s1, s43, -1
	s_cmp_eq_u32 s79, 4
	s_cselect_b32 s47, s9, s1
	s_cselect_b32 s46, s31, s0
	s_cselect_b32 s45, s29, s41
	s_cselect_b32 s44, s34, s35
	s_waitcnt lgkmcnt(8)
	s_barrier
	s_waitcnt lgkmcnt(0)
	s_setprio 1
	v_mfma_f32_16x16x32_bf16 v[124:127], v[146:149], v[168:171], 0
	v_mfma_f32_16x16x32_bf16 v[120:123], v[160:163], v[168:171], 0
	v_mfma_f32_16x16x32_bf16 v[108:111], v[146:149], v[176:179], 0
	v_mfma_f32_16x16x32_bf16 v[104:107], v[160:163], v[176:179], 0
	v_mfma_f32_16x16x32_bf16 v[92:95], v[146:149], v[188:191], 0
	v_mfma_f32_16x16x32_bf16 v[88:91], v[160:163], v[188:191], 0
	v_mfma_f32_16x16x32_bf16 v[76:79], v[146:149], v[198:201], 0
	v_mfma_f32_16x16x32_bf16 v[72:75], v[160:163], v[198:201], 0
	v_mfma_f32_16x16x32_bf16 v[124:127], v[150:153], v[172:175], v[124:127]
	v_mfma_f32_16x16x32_bf16 v[120:123], v[164:167], v[172:175], v[120:123]
	v_mfma_f32_16x16x32_bf16 v[108:111], v[150:153], v[180:183], v[108:111]
	v_mfma_f32_16x16x32_bf16 v[104:107], v[164:167], v[180:183], v[104:107]
	v_mfma_f32_16x16x32_bf16 v[92:95], v[150:153], v[194:197], v[92:95]
	v_mfma_f32_16x16x32_bf16 v[88:91], v[164:167], v[194:197], v[88:91]
	v_mfma_f32_16x16x32_bf16 v[76:79], v[150:153], v[202:205], v[76:79]
	v_mfma_f32_16x16x32_bf16 v[72:75], v[164:167], v[202:205], v[72:75]
	s_setprio 0
	s_barrier
	s_add_i32 s0, s66, s50
	s_mov_b32 m0, s0
	ds_read_b128 v[206:209], v159
	ds_read_b128 v[210:213], v159 offset:1024
	ds_read_b128 v[214:217], v159 offset:2048
	global_load_lds_dwordx4 v130, s[44:45]
	s_add_i32 m0, s0, 0x2000
	ds_read_b128 v[218:221], v159 offset:3072
	global_load_lds_dwordx4 v134, s[44:45]
	s_barrier
	s_waitcnt lgkmcnt(0)
	s_setprio 1
	v_mfma_f32_16x16x32_bf16 v[116:119], v[206:209], v[168:171], 0
	v_mfma_f32_16x16x32_bf16 v[112:115], v[214:217], v[168:171], 0
	v_mfma_f32_16x16x32_bf16 v[100:103], v[206:209], v[176:179], 0
	v_mfma_f32_16x16x32_bf16 v[96:99], v[214:217], v[176:179], 0
	v_mfma_f32_16x16x32_bf16 v[84:87], v[206:209], v[188:191], 0
	v_mfma_f32_16x16x32_bf16 v[80:83], v[214:217], v[188:191], 0
	v_mfma_f32_16x16x32_bf16 v[68:71], v[206:209], v[198:201], 0
	v_mfma_f32_16x16x32_bf16 v[64:67], v[214:217], v[198:201], 0
	v_mfma_f32_16x16x32_bf16 v[116:119], v[210:213], v[172:175], v[116:119]
	v_mfma_f32_16x16x32_bf16 v[112:115], v[218:221], v[172:175], v[112:115]
	v_mfma_f32_16x16x32_bf16 v[100:103], v[210:213], v[180:183], v[100:103]
	v_mfma_f32_16x16x32_bf16 v[96:99], v[218:221], v[180:183], v[96:99]
	v_mfma_f32_16x16x32_bf16 v[84:87], v[210:213], v[194:197], v[84:87]
	v_mfma_f32_16x16x32_bf16 v[80:83], v[218:221], v[194:197], v[80:83]
	v_mfma_f32_16x16x32_bf16 v[68:71], v[210:213], v[202:205], v[68:71]
	v_mfma_f32_16x16x32_bf16 v[64:67], v[218:221], v[202:205], v[64:67]
	s_setprio 0
	s_mov_b32 m0, s55
	s_barrier
	ds_read_b128 v[168:171], v158 offset:16384
	ds_read_b128 v[172:175], v158 offset:17408
	ds_read_b128 v[176:179], v158 offset:18432
	ds_read_b128 v[180:183], v158 offset:19456
	ds_read_b128 v[188:191], v158 offset:20480
	ds_read_b128 v[194:197], v158 offset:21504
	ds_read_b128 v[198:201], v158 offset:22528
	global_load_lds_dwordx4 v128, s[46:47]
	s_mov_b32 m0, s56
	ds_read_b128 v[202:205], v158 offset:23552
	global_load_lds_dwordx4 v132, s[46:47]
	s_barrier
	s_waitcnt lgkmcnt(0)
	s_setprio 1
	v_mfma_f32_16x16x32_bf16 v[60:63], v[146:149], v[168:171], 0
	v_mfma_f32_16x16x32_bf16 v[56:59], v[160:163], v[168:171], 0
	v_mfma_f32_16x16x32_bf16 v[44:47], v[146:149], v[176:179], 0
	v_mfma_f32_16x16x32_bf16 v[40:43], v[160:163], v[176:179], 0
	v_mfma_f32_16x16x32_bf16 v[28:31], v[146:149], v[188:191], 0
	v_mfma_f32_16x16x32_bf16 v[24:27], v[160:163], v[188:191], 0
	v_mfma_f32_16x16x32_bf16 v[12:15], v[146:149], v[198:201], 0
	v_mfma_f32_16x16x32_bf16 v[8:11], v[160:163], v[198:201], 0
	v_mfma_f32_16x16x32_bf16 v[60:63], v[150:153], v[172:175], v[60:63]
	v_mfma_f32_16x16x32_bf16 v[56:59], v[164:167], v[172:175], v[56:59]
	v_mfma_f32_16x16x32_bf16 v[44:47], v[150:153], v[180:183], v[44:47]
	v_mfma_f32_16x16x32_bf16 v[40:43], v[164:167], v[180:183], v[40:43]
	v_mfma_f32_16x16x32_bf16 v[28:31], v[150:153], v[194:197], v[28:31]
	v_mfma_f32_16x16x32_bf16 v[24:27], v[164:167], v[194:197], v[24:27]
	v_mfma_f32_16x16x32_bf16 v[12:15], v[150:153], v[202:205], v[12:15]
	v_mfma_f32_16x16x32_bf16 v[8:11], v[164:167], v[202:205], v[8:11]
	s_setprio 0
	s_barrier
; #define PG8_STAGE(bufoff, gbase, voff) do { _Pragma("unroll") for (int _i = 0; _i < 2; ++_i) \
;         __builtin_amdgcn_global_load_lds((const unsigned*)((const char*)(gbase) + (voff)[_i]), (LAS unsigned*)(lds + (bufoff) + ldsw + _i * 8192), 16, 0, 0); } while (0)
; #define PG8_LDA(dst, b, h) do { _Pragma("unroll") for (int m = 0; m < 4; ++m) _Pragma("unroll") for (int k = 0; k < 2; ++k) dst[m][k] = *(const LAS bf16x8*)(lds + PG8_SA(b, h) + aoff + m * 2048 + k * 1024); } while (0)
; #define PG8_LDB(dst, b, h) do { _Pragma("unroll") for (int n = 0; n < 2; ++n) _Pragma("unroll") for (int k = 0; k < 2; ++k) dst[n][k] = *(const LAS bf16x8*)(lds + PG8_SB(b, h) + boff + n * 2048 + k * 1024); } while (0)
; #define PG8_MMA(ai, bj, At, Bt) do { __builtin_amdgcn_s_setprio(1); _Pragma("unroll") for (int m = 0; m < 4; ++m) _Pragma("unroll") for (int n = 0; n < 2; ++n) _Pragma("unroll") for (int k = 0; k < 2; ++k) \
;         acc[ai][bj][m][n] = __builtin_amdgcn_mfma_f32_16x16x32_bf16(Bt[n][k], At[m][k], acc[ai][bj][m][n], 0, 0, 0); __builtin_amdgcn_s_setprio(0); } while (0)
; #define PG8_WAIT_V(n) asm volatile("s_waitcnt vmcnt(" #n ")" ::: "memory")
; #define PG8_WAIT_L(n) asm volatile("s_waitcnt lgkmcnt(" #n ")" ::: "memory")
; #define PG8_BAR __builtin_amdgcn_s_barrier()
; #define PG8_SCHED __builtin_amdgcn_sched_barrier(0)
; template <class Epi, class Sched>
; DI void gemm_phase(LAS unsigned char* lds, const Gemm g, const Sched& S, const Epi& E) {
;     ...
;             PG8_STAGE(PG8_SB(0, 1), b2 + hstep, voffB);
;             PG8_WAIT_V(6); PG8_BAR; PG8_MMA(1, 1, At, B1); PG8_BAR;
;             PG8_LDB(B0, 1, 0); PG8_SCHED; PG8_LDA(At, 1, 0); PG8_STAGE(PG8_SA(0, 1), a2 + hstep, voffA);
;             PG8_WAIT_L(8); PG8_BAR; PG8_WAIT_L(0); PG8_MMA(0, 0, At, B0); PG8_BAR; PG8_SCHED;
;             PG8_LDB(B1, 1, 1); PG8_STAGE(PG8_SB(1, 0), b3, voffB);
	s_add_i32 s4, s67, s50
	s_mov_b32 m0, s4
	s_add_u32 s0, s44, 0x20000
	s_addc_u32 s1, s45, 0
	global_load_lds_dwordx4 v130, s[0:1]
	s_add_i32 m0, s4, 0x2000
	s_add_i32 s4, 0, 0x18000
	global_load_lds_dwordx4 v134, s[0:1]
	s_waitcnt vmcnt(6)
	s_barrier
	s_setprio 1
	v_mfma_f32_16x16x32_bf16 v[52:55], v[206:209], v[168:171], 0
	v_mfma_f32_16x16x32_bf16 v[48:51], v[214:217], v[168:171], 0
	v_mfma_f32_16x16x32_bf16 v[36:39], v[206:209], v[176:179], 0
	v_mfma_f32_16x16x32_bf16 v[32:35], v[214:217], v[176:179], 0
	v_mfma_f32_16x16x32_bf16 v[20:23], v[206:209], v[188:191], 0
	v_mfma_f32_16x16x32_bf16 v[16:19], v[214:217], v[188:191], 0
	v_mfma_f32_16x16x32_bf16 v[4:7], v[206:209], v[198:201], 0
	v_mfma_f32_16x16x32_bf16 v[0:3], v[214:217], v[198:201], 0
	v_mfma_f32_16x16x32_bf16 v[52:55], v[210:213], v[172:175], v[52:55]
	v_mfma_f32_16x16x32_bf16 v[48:51], v[218:221], v[172:175], v[48:51]
	v_mfma_f32_16x16x32_bf16 v[36:39], v[210:213], v[180:183], v[36:39]
	v_mfma_f32_16x16x32_bf16 v[32:35], v[218:221], v[180:183], v[32:35]
	v_mfma_f32_16x16x32_bf16 v[20:23], v[210:213], v[194:197], v[20:23]
	v_mfma_f32_16x16x32_bf16 v[16:19], v[218:221], v[194:197], v[16:19]
	v_mfma_f32_16x16x32_bf16 v[4:7], v[210:213], v[202:205], v[4:7]
	v_mfma_f32_16x16x32_bf16 v[0:3], v[218:221], v[202:205], v[0:3]
	s_setprio 0
	v_add_u32_e32 v222, s4, v157
	s_barrier
	ds_read_b128 v[146:149], v222
	ds_read_b128 v[150:153], v222 offset:1024
	ds_read_b128 v[160:163], v222 offset:2048
	ds_read_b128 v[164:167], v222 offset:3072
	s_add_u32 s0, s46, 0x20000
	s_addc_u32 s1, s47, 0
	s_mov_b32 m0, s57
	ds_read_b128 v[168:171], v158 offset:32768
	ds_read_b128 v[172:175], v158 offset:33792
	ds_read_b128 v[176:179], v158 offset:34816
	ds_read_b128 v[180:183], v158 offset:35840
	ds_read_b128 v[188:191], v158 offset:36864
	ds_read_b128 v[194:197], v158 offset:37888
	ds_read_b128 v[198:201], v158 offset:38912
	global_load_lds_dwordx4 v128, s[0:1]
	s_mov_b32 m0, s58
	ds_read_b128 v[202:205], v158 offset:39936
	global_load_lds_dwordx4 v132, s[0:1]
	s_waitcnt lgkmcnt(8)
	s_barrier
	s_waitcnt lgkmcnt(0)
	s_setprio 1
	v_mfma_f32_16x16x32_bf16 v[124:127], v[146:149], v[168:171], v[124:127]
	v_mfma_f32_16x16x32_bf16 v[120:123], v[160:163], v[168:171], v[120:123]
	v_mfma_f32_16x16x32_bf16 v[108:111], v[146:149], v[176:179], v[108:111]
	v_mfma_f32_16x16x32_bf16 v[104:107], v[160:163], v[176:179], v[104:107]
	v_mfma_f32_16x16x32_bf16 v[92:95], v[146:149], v[188:191], v[92:95]
	v_mfma_f32_16x16x32_bf16 v[88:91], v[160:163], v[188:191], v[88:91]
	v_mfma_f32_16x16x32_bf16 v[76:79], v[146:149], v[198:201], v[76:79]
	v_mfma_f32_16x16x32_bf16 v[72:75], v[160:163], v[198:201], v[72:75]
	v_mfma_f32_16x16x32_bf16 v[124:127], v[150:153], v[172:175], v[124:127]
	v_mfma_f32_16x16x32_bf16 v[120:123], v[164:167], v[172:175], v[120:123]
	v_mfma_f32_16x16x32_bf16 v[108:111], v[150:153], v[180:183], v[108:111]
	v_mfma_f32_16x16x32_bf16 v[104:107], v[164:167], v[180:183], v[104:107]
	v_mfma_f32_16x16x32_bf16 v[92:95], v[150:153], v[194:197], v[92:95]
	v_mfma_f32_16x16x32_bf16 v[88:91], v[164:167], v[194:197], v[88:91]
	v_mfma_f32_16x16x32_bf16 v[76:79], v[150:153], v[202:205], v[76:79]
	v_mfma_f32_16x16x32_bf16 v[72:75], v[164:167], v[202:205], v[72:75]
	s_setprio 0
	s_barrier
	s_add_i32 s5, 0, 0x1c000
	s_add_i32 s0, s4, s50
	v_add_u32_e32 v223, s5, v157
	s_add_i32 m0, s0, 0xffffff80
	ds_read_b128 v[206:209], v223
	ds_read_b128 v[210:213], v223 offset:1024
	ds_read_b128 v[214:217], v223 offset:2048
	global_load_lds_dwordx4 v130, s[44:45] offset:128
	s_add_i32 m0, s0, 0x1f80
	ds_read_b128 v[218:221], v223 offset:3072
	global_load_lds_dwordx4 v134, s[44:45] offset:128
	s_barrier
; #define PG8_STAGE(bufoff, gbase, voff) do { _Pragma("unroll") for (int _i = 0; _i < 2; ++_i) \
;         __builtin_amdgcn_global_load_lds((const unsigned*)((const char*)(gbase) + (voff)[_i]), (LAS unsigned*)(lds + (bufoff) + ldsw + _i * 8192), 16, 0, 0); } while (0)
; #define PG8_LDA(dst, b, h) do { _Pragma("unroll") for (int m = 0; m < 4; ++m) _Pragma("unroll") for (int k = 0; k < 2; ++k) dst[m][k] = *(const LAS bf16x8*)(lds + PG8_SA(b, h) + aoff + m * 2048 + k * 1024); } while (0)
; #define PG8_MMA(ai, bj, At, Bt) do { __builtin_amdgcn_s_setprio(1); _Pragma("unroll") for (int m = 0; m < 4; ++m) _Pragma("unroll") for (int n = 0; n < 2; ++n) _Pragma("unroll") for (int k = 0; k < 2; ++k) \
;         acc[ai][bj][m][n] = __builtin_amdgcn_mfma_f32_16x16x32_bf16(Bt[n][k], At[m][k], acc[ai][bj][m][n], 0, 0, 0); __builtin_amdgcn_s_setprio(0); } while (0)
; #define PG8_WAIT_V(n) asm volatile("s_waitcnt vmcnt(" #n ")" ::: "memory")
; #define PG8_WAIT_L(n) asm volatile("s_waitcnt lgkmcnt(" #n ")" ::: "memory")
; #define PG8_BAR __builtin_amdgcn_s_barrier()
; #define PG8_SCHED __builtin_amdgcn_sched_barrier(0)
; template <class Epi, class Sched>
; DI void gemm_phase(LAS unsigned char* lds, const Gemm g, const Sched& S, const Epi& E) {
;     ...
;             PG8_BAR; PG8_WAIT_L(0); PG8_MMA(0, 1, At, B1); PG8_BAR;
;             PG8_LDA(At, 1, 1); PG8_STAGE(PG8_SA(1, 0), a3, voffA);
;             PG8_BAR; PG8_WAIT_L(0); PG8_MMA(1, 0, At, B0); PG8_BAR; PG8_SCHED;
;             PG8_STAGE(PG8_SB(1, 1), b3 + hstep, voffB);
;             PG8_WAIT_V(6); PG8_BAR; PG8_MMA(1, 1, At, B1); PG8_BAR;
	s_waitcnt lgkmcnt(0)
	s_setprio 1
	v_mfma_f32_16x16x32_bf16 v[116:119], v[206:209], v[168:171], v[116:119]
	v_mfma_f32_16x16x32_bf16 v[112:115], v[214:217], v[168:171], v[112:115]
	v_mfma_f32_16x16x32_bf16 v[100:103], v[206:209], v[176:179], v[100:103]
	v_mfma_f32_16x16x32_bf16 v[96:99], v[214:217], v[176:179], v[96:99]
	v_mfma_f32_16x16x32_bf16 v[84:87], v[206:209], v[188:191], v[84:87]
	v_mfma_f32_16x16x32_bf16 v[80:83], v[214:217], v[188:191], v[80:83]
	v_mfma_f32_16x16x32_bf16 v[68:71], v[206:209], v[198:201], v[68:71]
	v_mfma_f32_16x16x32_bf16 v[64:67], v[214:217], v[198:201], v[64:67]
	v_mfma_f32_16x16x32_bf16 v[116:119], v[210:213], v[172:175], v[116:119]
	v_mfma_f32_16x16x32_bf16 v[112:115], v[218:221], v[172:175], v[112:115]
	v_mfma_f32_16x16x32_bf16 v[100:103], v[210:213], v[180:183], v[100:103]
	v_mfma_f32_16x16x32_bf16 v[96:99], v[218:221], v[180:183], v[96:99]
	v_mfma_f32_16x16x32_bf16 v[84:87], v[210:213], v[194:197], v[84:87]
	v_mfma_f32_16x16x32_bf16 v[80:83], v[218:221], v[194:197], v[80:83]
	v_mfma_f32_16x16x32_bf16 v[68:71], v[210:213], v[202:205], v[68:71]
	v_mfma_f32_16x16x32_bf16 v[64:67], v[218:221], v[202:205], v[64:67]
	s_setprio 0
	s_add_i32 m0, s62, 0xffffff80
	s_barrier
	ds_read_b128 v[168:171], v158 offset:49152
	ds_read_b128 v[172:175], v158 offset:50176
	ds_read_b128 v[176:179], v158 offset:51200
	ds_read_b128 v[180:183], v158 offset:52224
	ds_read_b128 v[188:191], v158 offset:53248
	ds_read_b128 v[194:197], v158 offset:54272
	ds_read_b128 v[198:201], v158 offset:55296
	global_load_lds_dwordx4 v128, s[46:47] offset:128
	s_add_i32 m0, s63, 0xffffff80
	ds_read_b128 v[202:205], v158 offset:56320
	global_load_lds_dwordx4 v132, s[46:47] offset:128
	s_barrier
	s_waitcnt lgkmcnt(0)
	s_setprio 1
	v_mfma_f32_16x16x32_bf16 v[60:63], v[146:149], v[168:171], v[60:63]
	v_mfma_f32_16x16x32_bf16 v[56:59], v[160:163], v[168:171], v[56:59]
	v_mfma_f32_16x16x32_bf16 v[44:47], v[146:149], v[176:179], v[44:47]
	v_mfma_f32_16x16x32_bf16 v[40:43], v[160:163], v[176:179], v[40:43]
	v_mfma_f32_16x16x32_bf16 v[28:31], v[146:149], v[188:191], v[28:31]
	v_mfma_f32_16x16x32_bf16 v[24:27], v[160:163], v[188:191], v[24:27]
	v_mfma_f32_16x16x32_bf16 v[12:15], v[146:149], v[198:201], v[12:15]
	v_mfma_f32_16x16x32_bf16 v[8:11], v[160:163], v[198:201], v[8:11]
	v_mfma_f32_16x16x32_bf16 v[60:63], v[150:153], v[172:175], v[60:63]
	v_mfma_f32_16x16x32_bf16 v[56:59], v[164:167], v[172:175], v[56:59]
	v_mfma_f32_16x16x32_bf16 v[44:47], v[150:153], v[180:183], v[44:47]
	v_mfma_f32_16x16x32_bf16 v[40:43], v[164:167], v[180:183], v[40:43]
	v_mfma_f32_16x16x32_bf16 v[28:31], v[150:153], v[194:197], v[28:31]
	v_mfma_f32_16x16x32_bf16 v[24:27], v[164:167], v[194:197], v[24:27]
	v_mfma_f32_16x16x32_bf16 v[12:15], v[150:153], v[202:205], v[12:15]
	v_mfma_f32_16x16x32_bf16 v[8:11], v[164:167], v[202:205], v[8:11]
	s_setprio 0
	s_barrier
	s_add_i32 s4, s5, s50
	s_mov_b32 m0, s4
	s_add_u32 s0, s44, 0x20080
	s_addc_u32 s1, s45, 0
	global_load_lds_dwordx4 v130, s[0:1]
	v_lshl_add_u64 v[146:147], s[0:1], 0, v[134:135]
	s_add_i32 m0, s4, 0x2000
	s_add_i32 s79, s79, 2
	global_load_lds_dwordx4 v134, s[0:1]
	s_add_u32 s42, s42, 0x100
	s_addc_u32 s43, s43, 0
	s_add_u32 s35, s35, 0x100
	s_addc_u32 s41, s41, 0
	s_cmp_gt_u32 s79, 5
	s_waitcnt vmcnt(6)
	s_barrier
	s_setprio 1
	v_mfma_f32_16x16x32_bf16 v[52:55], v[206:209], v[168:171], v[52:55]
	v_mfma_f32_16x16x32_bf16 v[48:51], v[214:217], v[168:171], v[48:51]
	v_mfma_f32_16x16x32_bf16 v[36:39], v[206:209], v[176:179], v[36:39]
	v_mfma_f32_16x16x32_bf16 v[32:35], v[214:217], v[176:179], v[32:35]
	v_mfma_f32_16x16x32_bf16 v[20:23], v[206:209], v[188:191], v[20:23]
	v_mfma_f32_16x16x32_bf16 v[16:19], v[214:217], v[188:191], v[16:19]
	v_mfma_f32_16x16x32_bf16 v[4:7], v[206:209], v[198:201], v[4:7]
	v_mfma_f32_16x16x32_bf16 v[0:3], v[214:217], v[198:201], v[0:3]
	v_mfma_f32_16x16x32_bf16 v[52:55], v[210:213], v[172:175], v[52:55]
	v_mfma_f32_16x16x32_bf16 v[48:51], v[218:221], v[172:175], v[48:51]
	v_mfma_f32_16x16x32_bf16 v[36:39], v[210:213], v[180:183], v[36:39]
	v_mfma_f32_16x16x32_bf16 v[32:35], v[218:221], v[180:183], v[32:35]
	v_mfma_f32_16x16x32_bf16 v[20:23], v[210:213], v[194:197], v[20:23]
	v_mfma_f32_16x16x32_bf16 v[16:19], v[218:221], v[194:197], v[16:19]
	v_mfma_f32_16x16x32_bf16 v[4:7], v[210:213], v[202:205], v[4:7]
	v_mfma_f32_16x16x32_bf16 v[0:3], v[218:221], v[202:205], v[0:3]
	s_setprio 0
	s_cbranch_scc0 .Lrot_984
	s_barrier
	s_branch .Lpeel_done_984

; #define PG8_STAGE(bufoff, gbase, voff) do { _Pragma("unroll") for (int _i = 0; _i < 2; ++_i) \
;         __builtin_amdgcn_global_load_lds((const unsigned*)((const char*)(gbase) + (voff)[_i]), (LAS unsigned*)(lds + (bufoff) + ldsw + _i * 8192), 16, 0, 0); } while (0)
; #define PG8_LDA(dst, b, h) do { _Pragma("unroll") for (int m = 0; m < 4; ++m) _Pragma("unroll") for (int k = 0; k < 2; ++k) dst[m][k] = *(const LAS bf16x8*)(lds + PG8_SA(b, h) + aoff + m * 2048 + k * 1024); } while (0)
; #define PG8_LDB(dst, b, h) do { _Pragma("unroll") for (int n = 0; n < 2; ++n) _Pragma("unroll") for (int k = 0; k < 2; ++k) dst[n][k] = *(const LAS bf16x8*)(lds + PG8_SB(b, h) + boff + n * 2048 + k * 1024); } while (0)
; #define PG8_MMA(ai, bj, At, Bt) do { __builtin_amdgcn_s_setprio(1); _Pragma("unroll") for (int m = 0; m < 4; ++m) _Pragma("unroll") for (int n = 0; n < 2; ++n) _Pragma("unroll") for (int k = 0; k < 2; ++k) \
;         acc[ai][bj][m][n] = __builtin_amdgcn_mfma_f32_16x16x32_bf16(Bt[n][k], At[m][k], acc[ai][bj][m][n], 0, 0, 0); __builtin_amdgcn_s_setprio(0); } while (0)
; #define PG8_WAIT_V(n) asm volatile("s_waitcnt vmcnt(" #n ")" ::: "memory")
; #define PG8_WAIT_L(n) asm volatile("s_waitcnt lgkmcnt(" #n ")" ::: "memory")
; #define PG8_BAR __builtin_amdgcn_s_barrier()
; #define PG8_SCHED __builtin_amdgcn_sched_barrier(0)
; template <class Epi, class Sched>
; DI void gemm_phase(LAS unsigned char* lds, const Gemm g, const Sched& S, const Epi& E) {
;     ...
;             PG8_LDB(B0, 0, 0); PG8_SCHED; PG8_LDA(At, 0, 0); PG8_STAGE(PG8_SA(1, 1), a1 + hstep, voffA);
;             PG8_WAIT_L(8); PG8_BAR; PG8_WAIT_L(0); PG8_MMA(0, 0, At, B0); PG8_BAR; PG8_SCHED;
;             PG8_LDB(B1, 0, 1); PG8_STAGE(PG8_SB(0, 0), b2, voffB);
;             PG8_BAR; PG8_WAIT_L(0); PG8_MMA(0, 1, At, B1); PG8_BAR;
;             PG8_LDA(At, 0, 1); PG8_STAGE(PG8_SA(0, 0), a2, voffA);
;             PG8_BAR; PG8_WAIT_L(0); PG8_MMA(1, 0, At, B0); PG8_BAR; PG8_SCHED;
;             PG8_STAGE(PG8_SB(0, 1), b2 + hstep, voffB);
;             PG8_WAIT_V(6); PG8_BAR; PG8_MMA(1, 1, At, B1); PG8_BAR;
.LBB0_984:
	ds_read_b128 v[146:149], v156
	ds_read_b128 v[150:153], v156 offset:1024
	ds_read_b128 v[160:163], v156 offset:2048
	ds_read_b128 v[164:167], v156 offset:3072
	s_add_i32 m0, s55, 0xc000
	ds_read_b128 v[168:171], v158
	ds_read_b128 v[172:175], v158 offset:1024
	ds_read_b128 v[176:179], v158 offset:2048
	ds_read_b128 v[180:183], v158 offset:3072
	ds_read_b128 v[188:191], v158 offset:4096
	ds_read_b128 v[194:197], v158 offset:5120
	ds_read_b128 v[198:201], v158 offset:6144
	global_load_lds_dwordx4 v138, s[42:43]
	s_add_i32 m0, s55, 0xe000
	ds_read_b128 v[202:205], v158 offset:7168
	global_load_lds_dwordx4 v140, s[42:43]
	s_add_u32 s0, s42, 0xfffe0080
	s_addc_u32 s1, s43, -1
	s_cmp_eq_u32 s79, 4
	s_cselect_b32 s47, s9, s1
	s_cselect_b32 s46, s31, s0
	s_cselect_b32 s45, s29, s41
	s_cselect_b32 s44, s34, s35
	s_waitcnt lgkmcnt(8)
	s_barrier
	s_waitcnt lgkmcnt(0)
	s_setprio 1
	v_mfma_f32_16x16x32_bf16 v[124:127], v[146:149], v[168:171], v[124:127]
	v_mfma_f32_16x16x32_bf16 v[120:123], v[160:163], v[168:171], v[120:123]
	v_mfma_f32_16x16x32_bf16 v[108:111], v[146:149], v[176:179], v[108:111]
	v_mfma_f32_16x16x32_bf16 v[104:107], v[160:163], v[176:179], v[104:107]
	v_mfma_f32_16x16x32_bf16 v[92:95], v[146:149], v[188:191], v[92:95]
	v_mfma_f32_16x16x32_bf16 v[88:91], v[160:163], v[188:191], v[88:91]
	v_mfma_f32_16x16x32_bf16 v[76:79], v[146:149], v[198:201], v[76:79]
	v_mfma_f32_16x16x32_bf16 v[72:75], v[160:163], v[198:201], v[72:75]
	v_mfma_f32_16x16x32_bf16 v[124:127], v[150:153], v[172:175], v[124:127]
	v_mfma_f32_16x16x32_bf16 v[120:123], v[164:167], v[172:175], v[120:123]
	v_mfma_f32_16x16x32_bf16 v[108:111], v[150:153], v[180:183], v[108:111]
	v_mfma_f32_16x16x32_bf16 v[104:107], v[164:167], v[180:183], v[104:107]
	v_mfma_f32_16x16x32_bf16 v[92:95], v[150:153], v[194:197], v[92:95]
	v_mfma_f32_16x16x32_bf16 v[88:91], v[164:167], v[194:197], v[88:91]
	v_mfma_f32_16x16x32_bf16 v[76:79], v[150:153], v[202:205], v[76:79]
	v_mfma_f32_16x16x32_bf16 v[72:75], v[164:167], v[202:205], v[72:75]
	s_setprio 0
	s_barrier
	s_add_i32 s0, s66, s50
	s_mov_b32 m0, s0
	ds_read_b128 v[206:209], v159
	ds_read_b128 v[210:213], v159 offset:1024
	ds_read_b128 v[214:217], v159 offset:2048
	global_load_lds_dwordx4 v130, s[44:45]
	s_add_i32 m0, s0, 0x2000
	ds_read_b128 v[218:221], v159 offset:3072
	global_load_lds_dwordx4 v134, s[44:45]
	s_barrier
	s_waitcnt lgkmcnt(0)
	s_setprio 1
	v_mfma_f32_16x16x32_bf16 v[116:119], v[206:209], v[168:171], v[116:119]
	v_mfma_f32_16x16x32_bf16 v[112:115], v[214:217], v[168:171], v[112:115]
	v_mfma_f32_16x16x32_bf16 v[100:103], v[206:209], v[176:179], v[100:103]
	v_mfma_f32_16x16x32_bf16 v[96:99], v[214:217], v[176:179], v[96:99]
	v_mfma_f32_16x16x32_bf16 v[84:87], v[206:209], v[188:191], v[84:87]
	v_mfma_f32_16x16x32_bf16 v[80:83], v[214:217], v[188:191], v[80:83]
	v_mfma_f32_16x16x32_bf16 v[68:71], v[206:209], v[198:201], v[68:71]
	v_mfma_f32_16x16x32_bf16 v[64:67], v[214:217], v[198:201], v[64:67]
	v_mfma_f32_16x16x32_bf16 v[116:119], v[210:213], v[172:175], v[116:119]
	v_mfma_f32_16x16x32_bf16 v[112:115], v[218:221], v[172:175], v[112:115]
	v_mfma_f32_16x16x32_bf16 v[100:103], v[210:213], v[180:183], v[100:103]
	v_mfma_f32_16x16x32_bf16 v[96:99], v[218:221], v[180:183], v[96:99]
	v_mfma_f32_16x16x32_bf16 v[84:87], v[210:213], v[194:197], v[84:87]
	v_mfma_f32_16x16x32_bf16 v[80:83], v[218:221], v[194:197], v[80:83]
	v_mfma_f32_16x16x32_bf16 v[68:71], v[210:213], v[202:205], v[68:71]
	v_mfma_f32_16x16x32_bf16 v[64:67], v[218:221], v[202:205], v[64:67]
	s_setprio 0
	s_mov_b32 m0, s55
	s_barrier
	ds_read_b128 v[168:171], v158 offset:16384
	ds_read_b128 v[172:175], v158 offset:17408
	ds_read_b128 v[176:179], v158 offset:18432
	ds_read_b128 v[180:183], v158 offset:19456
	ds_read_b128 v[188:191], v158 offset:20480
	ds_read_b128 v[194:197], v158 offset:21504
	ds_read_b128 v[198:201], v158 offset:22528
	global_load_lds_dwordx4 v128, s[46:47]
	s_mov_b32 m0, s56
	ds_read_b128 v[202:205], v158 offset:23552
	global_load_lds_dwordx4 v132, s[46:47]
	s_barrier
	s_waitcnt lgkmcnt(0)
	s_setprio 1
	v_mfma_f32_16x16x32_bf16 v[60:63], v[146:149], v[168:171], v[60:63]
	v_mfma_f32_16x16x32_bf16 v[56:59], v[160:163], v[168:171], v[56:59]
	v_mfma_f32_16x16x32_bf16 v[44:47], v[146:149], v[176:179], v[44:47]
	v_mfma_f32_16x16x32_bf16 v[40:43], v[160:163], v[176:179], v[40:43]
	v_mfma_f32_16x16x32_bf16 v[28:31], v[146:149], v[188:191], v[28:31]
	v_mfma_f32_16x16x32_bf16 v[24:27], v[160:163], v[188:191], v[24:27]
	v_mfma_f32_16x16x32_bf16 v[12:15], v[146:149], v[198:201], v[12:15]
	v_mfma_f32_16x16x32_bf16 v[8:11], v[160:163], v[198:201], v[8:11]
	v_mfma_f32_16x16x32_bf16 v[60:63], v[150:153], v[172:175], v[60:63]
	v_mfma_f32_16x16x32_bf16 v[56:59], v[164:167], v[172:175], v[56:59]
	v_mfma_f32_16x16x32_bf16 v[44:47], v[150:153], v[180:183], v[44:47]
	v_mfma_f32_16x16x32_bf16 v[40:43], v[164:167], v[180:183], v[40:43]
	v_mfma_f32_16x16x32_bf16 v[28:31], v[150:153], v[194:197], v[28:31]
	v_mfma_f32_16x16x32_bf16 v[24:27], v[164:167], v[194:197], v[24:27]
	v_mfma_f32_16x16x32_bf16 v[12:15], v[150:153], v[202:205], v[12:15]
	v_mfma_f32_16x16x32_bf16 v[8:11], v[164:167], v[202:205], v[8:11]
	s_setprio 0
	s_barrier
	s_add_i32 s4, s67, s50
	s_mov_b32 m0, s4
	s_add_u32 s0, s44, 0x20000
	s_addc_u32 s1, s45, 0
	global_load_lds_dwordx4 v130, s[0:1]
	s_add_i32 m0, s4, 0x2000
	s_add_i32 s4, 0, 0x18000
	global_load_lds_dwordx4 v134, s[0:1]
	s_waitcnt vmcnt(6)
	s_barrier
; #define PG8_STAGE(bufoff, gbase, voff) do { _Pragma("unroll") for (int _i = 0; _i < 2; ++_i) \
;         __builtin_amdgcn_global_load_lds((const unsigned*)((const char*)(gbase) + (voff)[_i]), (LAS unsigned*)(lds + (bufoff) + ldsw + _i * 8192), 16, 0, 0); } while (0)
; #define PG8_LDA(dst, b, h) do { _Pragma("unroll") for (int m = 0; m < 4; ++m) _Pragma("unroll") for (int k = 0; k < 2; ++k) dst[m][k] = *(const LAS bf16x8*)(lds + PG8_SA(b, h) + aoff + m * 2048 + k * 1024); } while (0)
; #define PG8_LDB(dst, b, h) do { _Pragma("unroll") for (int n = 0; n < 2; ++n) _Pragma("unroll") for (int k = 0; k < 2; ++k) dst[n][k] = *(const LAS bf16x8*)(lds + PG8_SB(b, h) + boff + n * 2048 + k * 1024); } while (0)
; #define PG8_MMA(ai, bj, At, Bt) do { __builtin_amdgcn_s_setprio(1); _Pragma("unroll") for (int m = 0; m < 4; ++m) _Pragma("unroll") for (int n = 0; n < 2; ++n) _Pragma("unroll") for (int k = 0; k < 2; ++k) \
;         acc[ai][bj][m][n] = __builtin_amdgcn_mfma_f32_16x16x32_bf16(Bt[n][k], At[m][k], acc[ai][bj][m][n], 0, 0, 0); __builtin_amdgcn_s_setprio(0); } while (0)
; #define PG8_WAIT_V(n) asm volatile("s_waitcnt vmcnt(" #n ")" ::: "memory")
; #define PG8_WAIT_L(n) asm volatile("s_waitcnt lgkmcnt(" #n ")" ::: "memory")
; #define PG8_BAR __builtin_amdgcn_s_barrier()
; #define PG8_SCHED __builtin_amdgcn_sched_barrier(0)
; template <class Epi, class Sched>
; DI void gemm_phase(LAS unsigned char* lds, const Gemm g, const Sched& S, const Epi& E) {
;     ...
;             PG8_WAIT_V(6); PG8_BAR; PG8_MMA(1, 1, At, B1); PG8_BAR;
;             PG8_LDB(B0, 1, 0); PG8_SCHED; PG8_LDA(At, 1, 0); PG8_STAGE(PG8_SA(0, 1), a2 + hstep, voffA);
;             PG8_WAIT_L(8); PG8_BAR; PG8_WAIT_L(0); PG8_MMA(0, 0, At, B0); PG8_BAR; PG8_SCHED;
;             PG8_LDB(B1, 1, 1); PG8_STAGE(PG8_SB(1, 0), b3, voffB);
	s_setprio 1
	v_mfma_f32_16x16x32_bf16 v[52:55], v[206:209], v[168:171], v[52:55]
	v_mfma_f32_16x16x32_bf16 v[48:51], v[214:217], v[168:171], v[48:51]
	v_mfma_f32_16x16x32_bf16 v[36:39], v[206:209], v[176:179], v[36:39]
	v_mfma_f32_16x16x32_bf16 v[32:35], v[214:217], v[176:179], v[32:35]
	v_mfma_f32_16x16x32_bf16 v[20:23], v[206:209], v[188:191], v[20:23]
	v_mfma_f32_16x16x32_bf16 v[16:19], v[214:217], v[188:191], v[16:19]
	v_mfma_f32_16x16x32_bf16 v[4:7], v[206:209], v[198:201], v[4:7]
	v_mfma_f32_16x16x32_bf16 v[0:3], v[214:217], v[198:201], v[0:3]
	v_mfma_f32_16x16x32_bf16 v[52:55], v[210:213], v[172:175], v[52:55]
	v_mfma_f32_16x16x32_bf16 v[48:51], v[218:221], v[172:175], v[48:51]
	v_mfma_f32_16x16x32_bf16 v[36:39], v[210:213], v[180:183], v[36:39]
	v_mfma_f32_16x16x32_bf16 v[32:35], v[218:221], v[180:183], v[32:35]
	v_mfma_f32_16x16x32_bf16 v[20:23], v[210:213], v[194:197], v[20:23]
	v_mfma_f32_16x16x32_bf16 v[16:19], v[218:221], v[194:197], v[16:19]
	v_mfma_f32_16x16x32_bf16 v[4:7], v[210:213], v[202:205], v[4:7]
	v_mfma_f32_16x16x32_bf16 v[0:3], v[218:221], v[202:205], v[0:3]
	s_setprio 0
	s_barrier
	ds_read_b128 v[146:149], v222
	ds_read_b128 v[150:153], v222 offset:1024
	ds_read_b128 v[160:163], v222 offset:2048
	ds_read_b128 v[164:167], v222 offset:3072
	s_add_u32 s0, s46, 0x20000
	s_addc_u32 s1, s47, 0
	s_mov_b32 m0, s57
	ds_read_b128 v[168:171], v158 offset:32768
	ds_read_b128 v[172:175], v158 offset:33792
	ds_read_b128 v[176:179], v158 offset:34816
	ds_read_b128 v[180:183], v158 offset:35840
	ds_read_b128 v[188:191], v158 offset:36864
	ds_read_b128 v[194:197], v158 offset:37888
	ds_read_b128 v[198:201], v158 offset:38912
	global_load_lds_dwordx4 v128, s[0:1]
	s_mov_b32 m0, s58
	ds_read_b128 v[202:205], v158 offset:39936
	global_load_lds_dwordx4 v132, s[0:1]
	s_waitcnt lgkmcnt(8)
	s_barrier
	s_waitcnt lgkmcnt(0)
	s_setprio 1
	v_mfma_f32_16x16x32_bf16 v[124:127], v[146:149], v[168:171], v[124:127]
	v_mfma_f32_16x16x32_bf16 v[120:123], v[160:163], v[168:171], v[120:123]
	v_mfma_f32_16x16x32_bf16 v[108:111], v[146:149], v[176:179], v[108:111]
	v_mfma_f32_16x16x32_bf16 v[104:107], v[160:163], v[176:179], v[104:107]
	v_mfma_f32_16x16x32_bf16 v[92:95], v[146:149], v[188:191], v[92:95]
	v_mfma_f32_16x16x32_bf16 v[88:91], v[160:163], v[188:191], v[88:91]
	v_mfma_f32_16x16x32_bf16 v[76:79], v[146:149], v[198:201], v[76:79]
	v_mfma_f32_16x16x32_bf16 v[72:75], v[160:163], v[198:201], v[72:75]
	v_mfma_f32_16x16x32_bf16 v[124:127], v[150:153], v[172:175], v[124:127]
	v_mfma_f32_16x16x32_bf16 v[120:123], v[164:167], v[172:175], v[120:123]
	v_mfma_f32_16x16x32_bf16 v[108:111], v[150:153], v[180:183], v[108:111]
	v_mfma_f32_16x16x32_bf16 v[104:107], v[164:167], v[180:183], v[104:107]
	v_mfma_f32_16x16x32_bf16 v[92:95], v[150:153], v[194:197], v[92:95]
	v_mfma_f32_16x16x32_bf16 v[88:91], v[164:167], v[194:197], v[88:91]
	v_mfma_f32_16x16x32_bf16 v[76:79], v[150:153], v[202:205], v[76:79]
	v_mfma_f32_16x16x32_bf16 v[72:75], v[164:167], v[202:205], v[72:75]
	s_setprio 0
	s_barrier
	s_add_i32 s5, 0, 0x1c000
	s_add_i32 s0, s4, s50
	s_add_i32 m0, s0, 0xffffff80
	ds_read_b128 v[206:209], v223
	ds_read_b128 v[210:213], v223 offset:1024
	ds_read_b128 v[214:217], v223 offset:2048
	global_load_lds_dwordx4 v130, s[44:45] offset:128
	s_add_i32 m0, s0, 0x1f80
	ds_read_b128 v[218:221], v223 offset:3072
	global_load_lds_dwordx4 v134, s[44:45] offset:128
	s_barrier
; #define PG8_STAGE(bufoff, gbase, voff) do { _Pragma("unroll") for (int _i = 0; _i < 2; ++_i) \
;         __builtin_amdgcn_global_load_lds((const unsigned*)((const char*)(gbase) + (voff)[_i]), (LAS unsigned*)(lds + (bufoff) + ldsw + _i * 8192), 16, 0, 0); } while (0)
; #define PG8_LDA(dst, b, h) do { _Pragma("unroll") for (int m = 0; m < 4; ++m) _Pragma("unroll") for (int k = 0; k < 2; ++k) dst[m][k] = *(const LAS bf16x8*)(lds + PG8_SA(b, h) + aoff + m * 2048 + k * 1024); } while (0)
; #define PG8_LDB(dst, b, h) do { _Pragma("unroll") for (int n = 0; n < 2; ++n) _Pragma("unroll") for (int k = 0; k < 2; ++k) dst[n][k] = *(const LAS bf16x8*)(lds + PG8_SB(b, h) + boff + n * 2048 + k * 1024); } while (0)
; #define PG8_MMA(ai, bj, At, Bt) do { __builtin_amdgcn_s_setprio(1); _Pragma("unroll") for (int m = 0; m < 4; ++m) _Pragma("unroll") for (int n = 0; n < 2; ++n) _Pragma("unroll") for (int k = 0; k < 2; ++k) \
;         acc[ai][bj][m][n] = __builtin_amdgcn_mfma_f32_16x16x32_bf16(Bt[n][k], At[m][k], acc[ai][bj][m][n], 0, 0, 0); __builtin_amdgcn_s_setprio(0); } while (0)
; #define PG8_WAIT_V(n) asm volatile("s_waitcnt vmcnt(" #n ")" ::: "memory")
; #define PG8_WAIT_L(n) asm volatile("s_waitcnt lgkmcnt(" #n ")" ::: "memory")
; #define PG8_BAR __builtin_amdgcn_s_barrier()
; #define PG8_SCHED __builtin_amdgcn_sched_barrier(0)
; template <class Epi, class Sched>
; DI void gemm_phase(LAS unsigned char* lds, const Gemm g, const Sched& S, const Epi& E) {
;     ...
;             PG8_LDB(B0, 1, 0); PG8_SCHED; PG8_LDA(At, 1, 0); PG8_STAGE(PG8_SA(0, 1), a2 + hstep, voffA);
;             PG8_WAIT_L(8); PG8_BAR; PG8_WAIT_L(0); PG8_MMA(0, 0, At, B0); PG8_BAR; PG8_SCHED;
;             PG8_LDB(B1, 1, 1); PG8_STAGE(PG8_SB(1, 0), b3, voffB);
;             PG8_BAR; PG8_WAIT_L(0); PG8_MMA(0, 1, At, B1); PG8_BAR;
;             PG8_LDA(At, 1, 1); PG8_STAGE(PG8_SA(1, 0), a3, voffA);
;             PG8_BAR; PG8_WAIT_L(0); PG8_MMA(1, 0, At, B0); PG8_BAR; PG8_SCHED;
;             PG8_STAGE(PG8_SB(1, 1), b3 + hstep, voffB);
;             PG8_WAIT_V(6); PG8_BAR; PG8_MMA(1, 1, At, B1); PG8_BAR;
	s_waitcnt lgkmcnt(0)
	s_setprio 1
	v_mfma_f32_16x16x32_bf16 v[116:119], v[206:209], v[168:171], v[116:119]
	v_mfma_f32_16x16x32_bf16 v[112:115], v[214:217], v[168:171], v[112:115]
	v_mfma_f32_16x16x32_bf16 v[100:103], v[206:209], v[176:179], v[100:103]
	v_mfma_f32_16x16x32_bf16 v[96:99], v[214:217], v[176:179], v[96:99]
	v_mfma_f32_16x16x32_bf16 v[84:87], v[206:209], v[188:191], v[84:87]
	v_mfma_f32_16x16x32_bf16 v[80:83], v[214:217], v[188:191], v[80:83]
	v_mfma_f32_16x16x32_bf16 v[68:71], v[206:209], v[198:201], v[68:71]
	v_mfma_f32_16x16x32_bf16 v[64:67], v[214:217], v[198:201], v[64:67]
	v_mfma_f32_16x16x32_bf16 v[116:119], v[210:213], v[172:175], v[116:119]
	v_mfma_f32_16x16x32_bf16 v[112:115], v[218:221], v[172:175], v[112:115]
	v_mfma_f32_16x16x32_bf16 v[100:103], v[210:213], v[180:183], v[100:103]
	v_mfma_f32_16x16x32_bf16 v[96:99], v[218:221], v[180:183], v[96:99]
	v_mfma_f32_16x16x32_bf16 v[84:87], v[210:213], v[194:197], v[84:87]
	v_mfma_f32_16x16x32_bf16 v[80:83], v[218:221], v[194:197], v[80:83]
	v_mfma_f32_16x16x32_bf16 v[68:71], v[210:213], v[202:205], v[68:71]
	v_mfma_f32_16x16x32_bf16 v[64:67], v[218:221], v[202:205], v[64:67]
	s_setprio 0
	s_add_i32 m0, s62, 0xffffff80
	s_barrier
	ds_read_b128 v[168:171], v158 offset:49152
	ds_read_b128 v[172:175], v158 offset:50176
	ds_read_b128 v[176:179], v158 offset:51200
	ds_read_b128 v[180:183], v158 offset:52224
	ds_read_b128 v[188:191], v158 offset:53248
	ds_read_b128 v[194:197], v158 offset:54272
	ds_read_b128 v[198:201], v158 offset:55296
	global_load_lds_dwordx4 v128, s[46:47] offset:128
	s_add_i32 m0, s63, 0xffffff80
	ds_read_b128 v[202:205], v158 offset:56320
	global_load_lds_dwordx4 v132, s[46:47] offset:128
	s_barrier
	s_waitcnt lgkmcnt(0)
	s_setprio 1
	v_mfma_f32_16x16x32_bf16 v[60:63], v[146:149], v[168:171], v[60:63]
	v_mfma_f32_16x16x32_bf16 v[56:59], v[160:163], v[168:171], v[56:59]
	v_mfma_f32_16x16x32_bf16 v[44:47], v[146:149], v[176:179], v[44:47]
	v_mfma_f32_16x16x32_bf16 v[40:43], v[160:163], v[176:179], v[40:43]
	v_mfma_f32_16x16x32_bf16 v[28:31], v[146:149], v[188:191], v[28:31]
	v_mfma_f32_16x16x32_bf16 v[24:27], v[160:163], v[188:191], v[24:27]
	v_mfma_f32_16x16x32_bf16 v[12:15], v[146:149], v[198:201], v[12:15]
	v_mfma_f32_16x16x32_bf16 v[8:11], v[160:163], v[198:201], v[8:11]
	v_mfma_f32_16x16x32_bf16 v[60:63], v[150:153], v[172:175], v[60:63]
	v_mfma_f32_16x16x32_bf16 v[56:59], v[164:167], v[172:175], v[56:59]
	v_mfma_f32_16x16x32_bf16 v[44:47], v[150:153], v[180:183], v[44:47]
	v_mfma_f32_16x16x32_bf16 v[40:43], v[164:167], v[180:183], v[40:43]
	v_mfma_f32_16x16x32_bf16 v[28:31], v[150:153], v[194:197], v[28:31]
	v_mfma_f32_16x16x32_bf16 v[24:27], v[164:167], v[194:197], v[24:27]
	v_mfma_f32_16x16x32_bf16 v[12:15], v[150:153], v[202:205], v[12:15]
	v_mfma_f32_16x16x32_bf16 v[8:11], v[164:167], v[202:205], v[8:11]
	s_setprio 0
	s_barrier
	s_add_i32 s4, s5, s50
	s_mov_b32 m0, s4
	s_add_u32 s0, s44, 0x20080
	s_addc_u32 s1, s45, 0
	global_load_lds_dwordx4 v130, s[0:1]
	v_lshl_add_u64 v[146:147], s[0:1], 0, v[134:135]
	s_add_i32 m0, s4, 0x2000
	s_add_i32 s79, s79, 2
	global_load_lds_dwordx4 v134, s[0:1]
	s_add_u32 s42, s42, 0x100
	s_addc_u32 s43, s43, 0
	s_add_u32 s35, s35, 0x100
	s_addc_u32 s41, s41, 0
	s_cmp_gt_u32 s79, 5
	s_waitcnt vmcnt(6)
	s_barrier
	s_setprio 1
	v_mfma_f32_16x16x32_bf16 v[52:55], v[206:209], v[168:171], v[52:55]
	v_mfma_f32_16x16x32_bf16 v[48:51], v[214:217], v[168:171], v[48:51]
	v_mfma_f32_16x16x32_bf16 v[36:39], v[206:209], v[176:179], v[36:39]
	v_mfma_f32_16x16x32_bf16 v[32:35], v[214:217], v[176:179], v[32:35]
	v_mfma_f32_16x16x32_bf16 v[20:23], v[206:209], v[188:191], v[20:23]
	v_mfma_f32_16x16x32_bf16 v[16:19], v[214:217], v[188:191], v[16:19]
	v_mfma_f32_16x16x32_bf16 v[4:7], v[206:209], v[198:201], v[4:7]
	v_mfma_f32_16x16x32_bf16 v[0:3], v[214:217], v[198:201], v[0:3]
	v_mfma_f32_16x16x32_bf16 v[52:55], v[210:213], v[172:175], v[52:55]
	v_mfma_f32_16x16x32_bf16 v[48:51], v[218:221], v[172:175], v[48:51]
	v_mfma_f32_16x16x32_bf16 v[36:39], v[210:213], v[180:183], v[36:39]
	v_mfma_f32_16x16x32_bf16 v[32:35], v[218:221], v[180:183], v[32:35]
	v_mfma_f32_16x16x32_bf16 v[20:23], v[210:213], v[194:197], v[20:23]
	v_mfma_f32_16x16x32_bf16 v[16:19], v[218:221], v[194:197], v[16:19]
	v_mfma_f32_16x16x32_bf16 v[4:7], v[210:213], v[202:205], v[4:7]
	v_mfma_f32_16x16x32_bf16 v[0:3], v[218:221], v[202:205], v[0:3]
	s_setprio 0
	s_cbranch_scc0 .Lrot_984
	s_barrier

; #define PG8_STAGE(bufoff, gbase, voff) do { _Pragma("unroll") for (int _i = 0; _i < 2; ++_i) \
;         __builtin_amdgcn_global_load_lds((const unsigned*)((const char*)(gbase) + (voff)[_i]), (LAS unsigned*)(lds + (bufoff) + ldsw + _i * 8192), 16, 0, 0); } while (0)
; #define PG8_LDA(dst, b, h) do { _Pragma("unroll") for (int m = 0; m < 4; ++m) _Pragma("unroll") for (int k = 0; k < 2; ++k) dst[m][k] = *(const LAS bf16x8*)(lds + PG8_SA(b, h) + aoff + m * 2048 + k * 1024); } while (0)
; #define PG8_LDB(dst, b, h) do { _Pragma("unroll") for (int n = 0; n < 2; ++n) _Pragma("unroll") for (int k = 0; k < 2; ++k) dst[n][k] = *(const LAS bf16x8*)(lds + PG8_SB(b, h) + boff + n * 2048 + k * 1024); } while (0)
; #define PG8_MMA(ai, bj, At, Bt) do { __builtin_amdgcn_s_setprio(1); _Pragma("unroll") for (int m = 0; m < 4; ++m) _Pragma("unroll") for (int n = 0; n < 2; ++n) _Pragma("unroll") for (int k = 0; k < 2; ++k) \
;         acc[ai][bj][m][n] = __builtin_amdgcn_mfma_f32_16x16x32_bf16(Bt[n][k], At[m][k], acc[ai][bj][m][n], 0, 0, 0); __builtin_amdgcn_s_setprio(0); } while (0)
; #define PG8_WAIT_V(n) asm volatile("s_waitcnt vmcnt(" #n ")" ::: "memory")
; #define PG8_WAIT_L(n) asm volatile("s_waitcnt lgkmcnt(" #n ")" ::: "memory")
; #define PG8_BAR __builtin_amdgcn_s_barrier()
; #define PG8_SCHED __builtin_amdgcn_sched_barrier(0)
; template <class Epi, class Sched>
; DI void gemm_phase(LAS unsigned char* lds, const Gemm g, const Sched& S, const Epi& E) {
;     ...
;             const char* a1 = cA + (size_t)(t + 1) * kstep;
;             const char* a2 = last ? nA : cA + (size_t)(t + 2) * kstep; const char* b2 = last ? nB : cB + (size_t)(t + 2) * kstep;
;             const char* a3 = a2 + kstep; const char* b3 = b2 + kstep;
;             PG8_LDB(B0, 0, 0); PG8_SCHED; PG8_LDA(At, 0, 0); PG8_STAGE(PG8_SA(1, 1), a1 + hstep, voffA);
;             PG8_WAIT_L(8); PG8_BAR; PG8_WAIT_L(0); PG8_MMA(0, 0, At, B0); PG8_BAR; PG8_SCHED;
;             PG8_LDB(B1, 0, 1); PG8_STAGE(PG8_SB(0, 0), b2, voffB);
;             PG8_BAR; PG8_WAIT_L(0); PG8_MMA(0, 1, At, B1); PG8_BAR;
;             PG8_LDA(At, 0, 1); PG8_STAGE(PG8_SA(0, 0), a2, voffA);
;             PG8_BAR; PG8_WAIT_L(0); PG8_MMA(1, 0, At, B0); PG8_BAR; PG8_SCHED;
;             PG8_STAGE(PG8_SB(0, 1), b2 + hstep, voffB);
;             PG8_WAIT_V(6); PG8_BAR; PG8_MMA(1, 1, At, B1); PG8_BAR;
.LBB0_1347:
	v_add_u32_e32 v1, s63, v202
	s_add_u32 s0, s40, s44
	ds_read_b128 v[132:135], v1
	ds_read_b128 v[136:139], v1 offset:1024
	ds_read_b128 v[140:143], v1 offset:2048
	ds_read_b128 v[144:147], v1 offset:3072
	s_addc_u32 s1, s41, s45
	s_add_u32 s0, s0, 0x100
	s_addc_u32 s1, s1, 0
	s_add_u32 s4, s79, s44
	s_addc_u32 s5, s80, s45
	s_cmpk_eq_i32 s44, 0xf00
	s_cselect_b32 s49, s70, s1
	s_cselect_b32 s48, s71, s0
	s_cselect_b32 s47, s37, s5
	s_cselect_b32 s46, s36, s4
	v_lshl_add_u64 v[2:3], v[188:189], 0, s[44:45]
	s_add_i32 m0, s53, 0xc000
	ds_read_b128 v[148:151], v203
	ds_read_b128 v[152:155], v203 offset:1024
	ds_read_b128 v[156:159], v203 offset:2048
	ds_read_b128 v[160:163], v203 offset:3072
	ds_read_b128 v[164:167], v203 offset:4096
	ds_read_b128 v[208:211], v203 offset:5120
	ds_read_b128 v[212:215], v203 offset:6144
	ds_read_b128 v[216:219], v203 offset:7168
	global_load_lds_dwordx4 v[2:3], off
	v_lshl_add_u64 v[2:3], v[190:191], 0, s[44:45]
	s_add_i32 m0, s53, 0xe000
	s_nop 0
	global_load_lds_dwordx4 v[2:3], off
	s_waitcnt lgkmcnt(8)
	s_barrier
	s_waitcnt lgkmcnt(0)
	s_setprio 1
	v_mfma_f32_16x16x32_bf16 v[128:131], v[132:135], v[148:151], v[128:131]
	v_mfma_f32_16x16x32_bf16 v[124:127], v[140:143], v[148:151], v[124:127]
	v_mfma_f32_16x16x32_bf16 v[112:115], v[132:135], v[156:159], v[112:115]
	v_mfma_f32_16x16x32_bf16 v[108:111], v[140:143], v[156:159], v[108:111]
	v_mfma_f32_16x16x32_bf16 v[96:99], v[132:135], v[164:167], v[96:99]
	v_mfma_f32_16x16x32_bf16 v[92:95], v[140:143], v[164:167], v[92:95]
	v_mfma_f32_16x16x32_bf16 v[80:83], v[132:135], v[212:215], v[80:83]
	v_mfma_f32_16x16x32_bf16 v[76:79], v[140:143], v[212:215], v[76:79]
	v_mfma_f32_16x16x32_bf16 v[128:131], v[136:139], v[152:155], v[128:131]
	v_mfma_f32_16x16x32_bf16 v[124:127], v[144:147], v[152:155], v[124:127]
	v_mfma_f32_16x16x32_bf16 v[112:115], v[136:139], v[160:163], v[112:115]
	v_mfma_f32_16x16x32_bf16 v[108:111], v[144:147], v[160:163], v[108:111]
	v_mfma_f32_16x16x32_bf16 v[96:99], v[136:139], v[208:211], v[96:99]
	v_mfma_f32_16x16x32_bf16 v[92:95], v[144:147], v[208:211], v[92:95]
	v_mfma_f32_16x16x32_bf16 v[80:83], v[136:139], v[216:219], v[80:83]
	v_mfma_f32_16x16x32_bf16 v[76:79], v[144:147], v[216:219], v[76:79]
	s_setprio 0
	s_barrier
	s_add_i32 s0, s63, s51
	v_add_u32_e32 v1, s64, v202
	s_mov_b32 m0, s0
	ds_read_b128 v[220:223], v1
	ds_read_b128 v[224:227], v1 offset:1024
	ds_read_b128 v[228:231], v1 offset:2048
	global_load_lds_dwordx4 v172, s[46:47]
	s_add_i32 m0, s0, 0x2000
	ds_read_b128 v[232:235], v1 offset:3072
	global_load_lds_dwordx4 v174, s[46:47]
	s_barrier
	s_waitcnt lgkmcnt(0)
	s_setprio 1
	v_mfma_f32_16x16x32_bf16 v[120:123], v[220:223], v[148:151], v[120:123]
	v_mfma_f32_16x16x32_bf16 v[116:119], v[228:231], v[148:151], v[116:119]
	v_mfma_f32_16x16x32_bf16 v[104:107], v[220:223], v[156:159], v[104:107]
	v_mfma_f32_16x16x32_bf16 v[100:103], v[228:231], v[156:159], v[100:103]
	v_mfma_f32_16x16x32_bf16 v[88:91], v[220:223], v[164:167], v[88:91]
	v_mfma_f32_16x16x32_bf16 v[84:87], v[228:231], v[164:167], v[84:87]
	v_mfma_f32_16x16x32_bf16 v[72:75], v[220:223], v[212:215], v[72:75]
	v_mfma_f32_16x16x32_bf16 v[68:71], v[228:231], v[212:215], v[68:71]
	v_mfma_f32_16x16x32_bf16 v[120:123], v[224:227], v[152:155], v[120:123]
	v_mfma_f32_16x16x32_bf16 v[116:119], v[232:235], v[152:155], v[116:119]
	v_mfma_f32_16x16x32_bf16 v[104:107], v[224:227], v[160:163], v[104:107]
	v_mfma_f32_16x16x32_bf16 v[100:103], v[232:235], v[160:163], v[100:103]
	v_mfma_f32_16x16x32_bf16 v[88:91], v[224:227], v[208:211], v[88:91]
	v_mfma_f32_16x16x32_bf16 v[84:87], v[232:235], v[208:211], v[84:87]
	v_mfma_f32_16x16x32_bf16 v[72:75], v[224:227], v[216:219], v[72:75]
	v_mfma_f32_16x16x32_bf16 v[68:71], v[232:235], v[216:219], v[68:71]
	s_setprio 0
	s_mov_b32 m0, s53
	s_barrier
	ds_read_b128 v[148:151], v203 offset:16384
	ds_read_b128 v[152:155], v203 offset:17408
	ds_read_b128 v[156:159], v203 offset:18432
	ds_read_b128 v[160:163], v203 offset:19456
	ds_read_b128 v[164:167], v203 offset:20480
	ds_read_b128 v[208:211], v203 offset:21504
	ds_read_b128 v[212:215], v203 offset:22528
	global_load_lds_dwordx4 v168, s[48:49]
	s_mov_b32 m0, s54
	ds_read_b128 v[216:219], v203 offset:23552
	global_load_lds_dwordx4 v170, s[48:49]
	s_barrier
	s_waitcnt lgkmcnt(0)
	s_setprio 1
	v_mfma_f32_16x16x32_bf16 v[64:67], v[132:135], v[148:151], v[64:67]
	v_mfma_f32_16x16x32_bf16 v[60:63], v[140:143], v[148:151], v[60:63]
	v_mfma_f32_16x16x32_bf16 v[48:51], v[132:135], v[156:159], v[48:51]
	v_mfma_f32_16x16x32_bf16 v[44:47], v[140:143], v[156:159], v[44:47]
	v_mfma_f32_16x16x32_bf16 v[32:35], v[132:135], v[164:167], v[32:35]
	v_mfma_f32_16x16x32_bf16 v[28:31], v[140:143], v[164:167], v[28:31]
	v_mfma_f32_16x16x32_bf16 v[16:19], v[132:135], v[212:215], v[16:19]
	v_mfma_f32_16x16x32_bf16 v[12:15], v[140:143], v[212:215], v[12:15]
	v_mfma_f32_16x16x32_bf16 v[64:67], v[136:139], v[152:155], v[64:67]
	v_mfma_f32_16x16x32_bf16 v[60:63], v[144:147], v[152:155], v[60:63]
	v_mfma_f32_16x16x32_bf16 v[48:51], v[136:139], v[160:163], v[48:51]
	v_mfma_f32_16x16x32_bf16 v[44:47], v[144:147], v[160:163], v[44:47]
	v_mfma_f32_16x16x32_bf16 v[32:35], v[136:139], v[208:211], v[32:35]
	v_mfma_f32_16x16x32_bf16 v[28:31], v[144:147], v[208:211], v[28:31]
	v_mfma_f32_16x16x32_bf16 v[16:19], v[136:139], v[216:219], v[16:19]
	v_mfma_f32_16x16x32_bf16 v[12:15], v[144:147], v[216:219], v[12:15]
	s_setprio 0
	s_barrier
	s_add_i32 s4, s64, s51
	s_mov_b32 m0, s4
	s_add_u32 s0, s46, 0x80000
	s_addc_u32 s1, s47, 0
	global_load_lds_dwordx4 v172, s[0:1]
	s_add_i32 m0, s4, 0x2000
	s_add_i32 s4, 0, 0x18000
	global_load_lds_dwordx4 v174, s[0:1]
	s_waitcnt vmcnt(6)
	s_barrier
; #define PG8_STAGE(bufoff, gbase, voff) do { _Pragma("unroll") for (int _i = 0; _i < 2; ++_i) \
;         __builtin_amdgcn_global_load_lds((const unsigned*)((const char*)(gbase) + (voff)[_i]), (LAS unsigned*)(lds + (bufoff) + ldsw + _i * 8192), 16, 0, 0); } while (0)
; #define PG8_LDA(dst, b, h) do { _Pragma("unroll") for (int m = 0; m < 4; ++m) _Pragma("unroll") for (int k = 0; k < 2; ++k) dst[m][k] = *(const LAS bf16x8*)(lds + PG8_SA(b, h) + aoff + m * 2048 + k * 1024); } while (0)
; #define PG8_LDB(dst, b, h) do { _Pragma("unroll") for (int n = 0; n < 2; ++n) _Pragma("unroll") for (int k = 0; k < 2; ++k) dst[n][k] = *(const LAS bf16x8*)(lds + PG8_SB(b, h) + boff + n * 2048 + k * 1024); } while (0)
; #define PG8_MMA(ai, bj, At, Bt) do { __builtin_amdgcn_s_setprio(1); _Pragma("unroll") for (int m = 0; m < 4; ++m) _Pragma("unroll") for (int n = 0; n < 2; ++n) _Pragma("unroll") for (int k = 0; k < 2; ++k) \
;         acc[ai][bj][m][n] = __builtin_amdgcn_mfma_f32_16x16x32_bf16(Bt[n][k], At[m][k], acc[ai][bj][m][n], 0, 0, 0); __builtin_amdgcn_s_setprio(0); } while (0)
; #define PG8_WAIT_V(n) asm volatile("s_waitcnt vmcnt(" #n ")" ::: "memory")
; #define PG8_WAIT_L(n) asm volatile("s_waitcnt lgkmcnt(" #n ")" ::: "memory")
; #define PG8_BAR __builtin_amdgcn_s_barrier()
; #define PG8_SCHED __builtin_amdgcn_sched_barrier(0)
; template <class Epi, class Sched>
; DI void gemm_phase(LAS unsigned char* lds, const Gemm g, const Sched& S, const Epi& E) {
;     ...
;             PG8_WAIT_V(6); PG8_BAR; PG8_MMA(1, 1, At, B1); PG8_BAR;
;             PG8_LDB(B0, 1, 0); PG8_SCHED; PG8_LDA(At, 1, 0); PG8_STAGE(PG8_SA(0, 1), a2 + hstep, voffA);
;             PG8_WAIT_L(8); PG8_BAR; PG8_WAIT_L(0); PG8_MMA(0, 0, At, B0); PG8_BAR; PG8_SCHED;
	s_setprio 1
	v_mfma_f32_16x16x32_bf16 v[56:59], v[220:223], v[148:151], v[56:59]
	v_mfma_f32_16x16x32_bf16 v[52:55], v[228:231], v[148:151], v[52:55]
	v_mfma_f32_16x16x32_bf16 v[40:43], v[220:223], v[156:159], v[40:43]
	v_mfma_f32_16x16x32_bf16 v[36:39], v[228:231], v[156:159], v[36:39]
	v_mfma_f32_16x16x32_bf16 v[24:27], v[220:223], v[164:167], v[24:27]
	v_mfma_f32_16x16x32_bf16 v[20:23], v[228:231], v[164:167], v[20:23]
	v_mfma_f32_16x16x32_bf16 v[8:11], v[220:223], v[212:215], v[8:11]
	v_mfma_f32_16x16x32_bf16 v[2:5], v[228:231], v[212:215], v[4:7]
	v_mfma_f32_16x16x32_bf16 v[56:59], v[224:227], v[152:155], v[56:59]
	v_mfma_f32_16x16x32_bf16 v[52:55], v[232:235], v[152:155], v[52:55]
	v_mfma_f32_16x16x32_bf16 v[40:43], v[224:227], v[160:163], v[40:43]
	v_mfma_f32_16x16x32_bf16 v[36:39], v[232:235], v[160:163], v[36:39]
	v_mfma_f32_16x16x32_bf16 v[24:27], v[224:227], v[208:211], v[24:27]
	v_mfma_f32_16x16x32_bf16 v[20:23], v[232:235], v[208:211], v[20:23]
	v_mfma_f32_16x16x32_bf16 v[8:11], v[224:227], v[216:219], v[8:11]
	v_mfma_f32_16x16x32_bf16 v[2:5], v[232:235], v[216:219], v[2:5]
	s_setprio 0
	v_add_u32_e32 v1, s4, v202
	s_barrier
	ds_read_b128 v[132:135], v1
	ds_read_b128 v[136:139], v1 offset:1024
	ds_read_b128 v[140:143], v1 offset:2048
	ds_read_b128 v[144:147], v1 offset:3072
	s_add_u32 s0, s48, 0x80000
	s_addc_u32 s1, s49, 0
	s_mov_b32 m0, s55
	ds_read_b128 v[148:151], v203 offset:32768
	ds_read_b128 v[152:155], v203 offset:33792
	ds_read_b128 v[156:159], v203 offset:34816
	ds_read_b128 v[160:163], v203 offset:35840
	ds_read_b128 v[164:167], v203 offset:36864
	ds_read_b128 v[208:211], v203 offset:37888
	ds_read_b128 v[212:215], v203 offset:38912
	global_load_lds_dwordx4 v168, s[0:1]
	s_mov_b32 m0, s56
	ds_read_b128 v[216:219], v203 offset:39936
	global_load_lds_dwordx4 v170, s[0:1]
	s_waitcnt lgkmcnt(8)
	s_barrier
	s_waitcnt lgkmcnt(0)
	s_setprio 1
	v_mfma_f32_16x16x32_bf16 v[128:131], v[132:135], v[148:151], v[128:131]
	v_mfma_f32_16x16x32_bf16 v[124:127], v[140:143], v[148:151], v[124:127]
	v_mfma_f32_16x16x32_bf16 v[112:115], v[132:135], v[156:159], v[112:115]
	v_mfma_f32_16x16x32_bf16 v[108:111], v[140:143], v[156:159], v[108:111]
	v_mfma_f32_16x16x32_bf16 v[96:99], v[132:135], v[164:167], v[96:99]
	v_mfma_f32_16x16x32_bf16 v[92:95], v[140:143], v[164:167], v[92:95]
	v_mfma_f32_16x16x32_bf16 v[80:83], v[132:135], v[212:215], v[80:83]
	v_mfma_f32_16x16x32_bf16 v[76:79], v[140:143], v[212:215], v[76:79]
	v_mfma_f32_16x16x32_bf16 v[128:131], v[136:139], v[152:155], v[128:131]
	v_mfma_f32_16x16x32_bf16 v[124:127], v[144:147], v[152:155], v[124:127]
	v_mfma_f32_16x16x32_bf16 v[112:115], v[136:139], v[160:163], v[112:115]
	v_mfma_f32_16x16x32_bf16 v[108:111], v[144:147], v[160:163], v[108:111]
	v_mfma_f32_16x16x32_bf16 v[96:99], v[136:139], v[208:211], v[96:99]
	v_mfma_f32_16x16x32_bf16 v[92:95], v[144:147], v[208:211], v[92:95]
	v_mfma_f32_16x16x32_bf16 v[80:83], v[136:139], v[216:219], v[80:83]
	v_mfma_f32_16x16x32_bf16 v[76:79], v[144:147], v[216:219], v[76:79]
	s_setprio 0
	s_barrier
	s_add_i32 s5, 0, 0x1c000
	s_add_i32 s0, s4, s51
	v_add_u32_e32 v1, s5, v202
	s_add_i32 m0, s0, 0xffffff80
	ds_read_b128 v[220:223], v1
	ds_read_b128 v[224:227], v1 offset:1024
	ds_read_b128 v[228:231], v1 offset:2048
	global_load_lds_dwordx4 v172, s[46:47] offset:128
	s_add_i32 m0, s0, 0x1f80
	ds_read_b128 v[232:235], v1 offset:3072
	global_load_lds_dwordx4 v174, s[46:47] offset:128
	s_barrier
; #define PG8_STAGE(bufoff, gbase, voff) do { _Pragma("unroll") for (int _i = 0; _i < 2; ++_i) \
;         __builtin_amdgcn_global_load_lds((const unsigned*)((const char*)(gbase) + (voff)[_i]), (LAS unsigned*)(lds + (bufoff) + ldsw + _i * 8192), 16, 0, 0); } while (0)
; #define PG8_LDA(dst, b, h) do { _Pragma("unroll") for (int m = 0; m < 4; ++m) _Pragma("unroll") for (int k = 0; k < 2; ++k) dst[m][k] = *(const LAS bf16x8*)(lds + PG8_SA(b, h) + aoff + m * 2048 + k * 1024); } while (0)
; #define PG8_LDB(dst, b, h) do { _Pragma("unroll") for (int n = 0; n < 2; ++n) _Pragma("unroll") for (int k = 0; k < 2; ++k) dst[n][k] = *(const LAS bf16x8*)(lds + PG8_SB(b, h) + boff + n * 2048 + k * 1024); } while (0)
; #define PG8_MMA(ai, bj, At, Bt) do { __builtin_amdgcn_s_setprio(1); _Pragma("unroll") for (int m = 0; m < 4; ++m) _Pragma("unroll") for (int n = 0; n < 2; ++n) _Pragma("unroll") for (int k = 0; k < 2; ++k) \
;         acc[ai][bj][m][n] = __builtin_amdgcn_mfma_f32_16x16x32_bf16(Bt[n][k], At[m][k], acc[ai][bj][m][n], 0, 0, 0); __builtin_amdgcn_s_setprio(0); } while (0)
; #define PG8_WAIT_V(n) asm volatile("s_waitcnt vmcnt(" #n ")" ::: "memory")
; #define PG8_WAIT_L(n) asm volatile("s_waitcnt lgkmcnt(" #n ")" ::: "memory")
; #define PG8_BAR __builtin_amdgcn_s_barrier()
; #define PG8_SCHED __builtin_amdgcn_sched_barrier(0)
; template <class Epi, class Sched>
; DI void gemm_phase(LAS unsigned char* lds, const Gemm g, const Sched& S, const Epi& E) {
;     ...
;             PG8_WAIT_L(8); PG8_BAR; PG8_WAIT_L(0); PG8_MMA(0, 0, At, B0); PG8_BAR; PG8_SCHED;
;             PG8_LDB(B1, 1, 1); PG8_STAGE(PG8_SB(1, 0), b3, voffB);
;             PG8_BAR; PG8_WAIT_L(0); PG8_MMA(0, 1, At, B1); PG8_BAR;
;             PG8_LDA(At, 1, 1); PG8_STAGE(PG8_SA(1, 0), a3, voffA);
;             PG8_BAR; PG8_WAIT_L(0); PG8_MMA(1, 0, At, B0); PG8_BAR; PG8_SCHED;
;             PG8_STAGE(PG8_SB(1, 1), b3 + hstep, voffB);
;             PG8_WAIT_V(6); PG8_BAR; PG8_MMA(1, 1, At, B1); PG8_BAR;
	s_waitcnt lgkmcnt(0)
	s_setprio 1
	v_mfma_f32_16x16x32_bf16 v[120:123], v[220:223], v[148:151], v[120:123]
	v_mfma_f32_16x16x32_bf16 v[116:119], v[228:231], v[148:151], v[116:119]
	v_mfma_f32_16x16x32_bf16 v[104:107], v[220:223], v[156:159], v[104:107]
	v_mfma_f32_16x16x32_bf16 v[100:103], v[228:231], v[156:159], v[100:103]
	v_mfma_f32_16x16x32_bf16 v[88:91], v[220:223], v[164:167], v[88:91]
	v_mfma_f32_16x16x32_bf16 v[84:87], v[228:231], v[164:167], v[84:87]
	v_mfma_f32_16x16x32_bf16 v[72:75], v[220:223], v[212:215], v[72:75]
	v_mfma_f32_16x16x32_bf16 v[68:71], v[228:231], v[212:215], v[68:71]
	v_mfma_f32_16x16x32_bf16 v[120:123], v[224:227], v[152:155], v[120:123]
	v_mfma_f32_16x16x32_bf16 v[116:119], v[232:235], v[152:155], v[116:119]
	v_mfma_f32_16x16x32_bf16 v[104:107], v[224:227], v[160:163], v[104:107]
	v_mfma_f32_16x16x32_bf16 v[100:103], v[232:235], v[160:163], v[100:103]
	v_mfma_f32_16x16x32_bf16 v[88:91], v[224:227], v[208:211], v[88:91]
	v_mfma_f32_16x16x32_bf16 v[84:87], v[232:235], v[208:211], v[84:87]
	v_mfma_f32_16x16x32_bf16 v[72:75], v[224:227], v[216:219], v[72:75]
	v_mfma_f32_16x16x32_bf16 v[68:71], v[232:235], v[216:219], v[68:71]
	s_setprio 0
	s_add_i32 m0, s59, 0xffffff80
	s_barrier
	ds_read_b128 v[148:151], v203 offset:49152
	ds_read_b128 v[152:155], v203 offset:50176
	ds_read_b128 v[156:159], v203 offset:51200
	ds_read_b128 v[160:163], v203 offset:52224
	ds_read_b128 v[164:167], v203 offset:53248
	ds_read_b128 v[208:211], v203 offset:54272
	ds_read_b128 v[212:215], v203 offset:55296
	global_load_lds_dwordx4 v168, s[48:49] offset:128
	s_add_i32 m0, s60, 0xffffff80
	ds_read_b128 v[216:219], v203 offset:56320
	global_load_lds_dwordx4 v170, s[48:49] offset:128
	s_barrier
	s_waitcnt lgkmcnt(0)
	s_setprio 1
	v_mfma_f32_16x16x32_bf16 v[64:67], v[132:135], v[148:151], v[64:67]
	v_mfma_f32_16x16x32_bf16 v[60:63], v[140:143], v[148:151], v[60:63]
	v_mfma_f32_16x16x32_bf16 v[48:51], v[132:135], v[156:159], v[48:51]
	v_mfma_f32_16x16x32_bf16 v[44:47], v[140:143], v[156:159], v[44:47]
	v_mfma_f32_16x16x32_bf16 v[32:35], v[132:135], v[164:167], v[32:35]
	v_mfma_f32_16x16x32_bf16 v[28:31], v[140:143], v[164:167], v[28:31]
	v_mfma_f32_16x16x32_bf16 v[16:19], v[132:135], v[212:215], v[16:19]
	v_mfma_f32_16x16x32_bf16 v[12:15], v[140:143], v[212:215], v[12:15]
	v_mfma_f32_16x16x32_bf16 v[64:67], v[136:139], v[152:155], v[64:67]
	v_mfma_f32_16x16x32_bf16 v[60:63], v[144:147], v[152:155], v[60:63]
	v_mfma_f32_16x16x32_bf16 v[48:51], v[136:139], v[160:163], v[48:51]
	v_mfma_f32_16x16x32_bf16 v[44:47], v[144:147], v[160:163], v[44:47]
	v_mfma_f32_16x16x32_bf16 v[32:35], v[136:139], v[208:211], v[32:35]
	v_mfma_f32_16x16x32_bf16 v[28:31], v[144:147], v[208:211], v[28:31]
	v_mfma_f32_16x16x32_bf16 v[16:19], v[136:139], v[216:219], v[16:19]
	v_mfma_f32_16x16x32_bf16 v[12:15], v[144:147], v[216:219], v[12:15]
	s_setprio 0
	s_barrier
	s_add_i32 s4, s5, s51
	s_mov_b32 m0, s4
	s_add_u32 s0, s46, 0x80080
	s_addc_u32 s1, s47, 0
	global_load_lds_dwordx4 v172, s[0:1]
	s_add_i32 m0, s4, 0x2000
	s_nop 0
	global_load_lds_dwordx4 v174, s[0:1]
	s_waitcnt vmcnt(6)
	s_barrier
	s_setprio 1
	v_mfma_f32_16x16x32_bf16 v[56:59], v[220:223], v[148:151], v[56:59]
	v_mfma_f32_16x16x32_bf16 v[52:55], v[228:231], v[148:151], v[52:55]
	v_mfma_f32_16x16x32_bf16 v[40:43], v[220:223], v[156:159], v[40:43]
	v_mfma_f32_16x16x32_bf16 v[36:39], v[228:231], v[156:159], v[36:39]
	v_mfma_f32_16x16x32_bf16 v[24:27], v[220:223], v[164:167], v[24:27]
	v_mfma_f32_16x16x32_bf16 v[20:23], v[228:231], v[164:167], v[20:23]
	v_mfma_f32_16x16x32_bf16 v[6:9], v[220:223], v[212:215], v[8:11]
	v_mfma_f32_16x16x32_bf16 v[2:5], v[228:231], v[212:215], v[2:5]
	v_mfma_f32_16x16x32_bf16 v[56:59], v[224:227], v[152:155], v[56:59]
	v_mfma_f32_16x16x32_bf16 v[52:55], v[232:235], v[152:155], v[52:55]
	v_mfma_f32_16x16x32_bf16 v[40:43], v[224:227], v[160:163], v[40:43]
	v_mfma_f32_16x16x32_bf16 v[36:39], v[232:235], v[160:163], v[36:39]
	v_mfma_f32_16x16x32_bf16 v[24:27], v[224:227], v[208:211], v[24:27]
	v_mfma_f32_16x16x32_bf16 v[20:23], v[232:235], v[208:211], v[20:23]
	v_mfma_f32_16x16x32_bf16 v[8:11], v[224:227], v[216:219], v[6:9]
	v_mfma_f32_16x16x32_bf16 v[4:7], v[232:235], v[216:219], v[2:5]
	s_setprio 0
	s_add_i32 s81, s81, 2
	s_add_u32 s44, s44, 0x100
	s_addc_u32 s45, s45, 0
	s_cmp_gt_u32 s81, 29
	s_barrier
	s_cbranch_scc1 .LBB0_1351

;     DI size_t aoff(const Unit& u, size_t tstep) const { return (size_t)u.pm * tstep; }
;     DI size_t boff(const Unit& u, size_t tstep) const { return (size_t)u.pn * tstep; }
;     DI bool next(int i, Unit& u) const { const long L = (long)i * G + c; if (L >= np) return false; u.pm = pmv; u.pn = (int)(L % nN); u.ks = (int)(L / nN); return true; }
;     DI size_t aoff(const Unit& u, size_t) const { return (size_t)u.ks * kbytes; }
;     DI size_t boff(const Unit& u, size_t tstep) const { return (size_t)u.pn * tstep + (size_t)u.ks * kbytes; }
;     DI bool next(int i, Unit& u) const { Unit t; if (!S.next(i / 3, t)) return false; u.pm = t.pm; u.pn = t.pn; u.ks = i % 3; return true; }
;     DI size_t aoff(const Unit& u, size_t tstep) const { return (u.ks < 2 ? offU : offOA) + (size_t)u.pm * tstep; }
; #define PG8_LDA(dst, b, h) do { _Pragma("unroll") for (int m = 0; m < 4; ++m) _Pragma("unroll") for (int k = 0; k < 2; ++k) dst[m][k] = *(const LAS bf16x8*)(lds + PG8_SA(b, h) + aoff + m * 2048 + k * 1024); } while (0)
; template <class Epi, class Sched>
; DI void gemm_phase(LAS unsigned char* lds, const Gemm g, const Sched& S, const Epi& E) {
;     ...
;         const bool has_next = S.next(ui + 1, nxt);
;         const char* nA = has_next ? (const char*)g.A + S.aoff(nxt, tstep) : cA; const char* nB = has_next ? (const char*)g.Bt + S.boff(nxt, tstep) : cB;
;         for (int t = 0; t < nt; t += 2) {
;             if constexpr (Epi::HAS_MID) { if (t == E.mid_t(nt)) { int fr3 = fr, fq3 = fq; asm volatile("" : "+v"(fr3), "+v"(fq3)); E.mid(acc, cur, wr, wc, fr3, fq3); } }
;             const bool last = (t == nt - 2);
;             const char* a1 = cA + (size_t)(t + 1) * kstep;
;             const char* a2 = last ? nA : cA + (size_t)(t + 2) * kstep; const char* b2 = last ? nB : cB + (size_t)(t + 2) * kstep;
;             const char* a3 = a2 + kstep; const char* b3 = b2 + kstep;
;             PG8_LDB(B0, 0, 0); PG8_SCHED; PG8_LDA(At, 0, 0); PG8_STAGE(PG8_SA(1, 1), a1 + hstep, voffA);
;             PG8_WAIT_L(8); PG8_BAR; PG8_WAIT_L(0); PG8_MMA(0, 0, At, B0); PG8_BAR; PG8_SCHED;
;             PG8_LDB(B1, 0, 1); PG8_STAGE(PG8_SB(0, 0), b2, voffB);
;             PG8_BAR; PG8_WAIT_L(0); PG8_MMA(0, 1, At, B1); PG8_BAR;
;             PG8_LDA(At, 0, 1); PG8_STAGE(PG8_SA(0, 0), a2, voffA);
;             PG8_BAR; PG8_WAIT_L(0); PG8_MMA(1, 0, At, B0); PG8_BAR; PG8_SCHED;
.LBB0_1507:
	s_ashr_i32 s37, s36, 31
	s_lshl_b64 s[0:1], s[36:37], 20
	v_cmp_lt_i64_e32 vcc, s[38:39], v[140:141]
	s_add_u32 s38, s13, s0
	s_addc_u32 s39, s50, s1
	s_and_b64 s[0:1], vcc, exec
	s_cselect_b32 s34, s39, s45
	s_cselect_b32 s35, s38, s44
	s_ashr_i32 s31, s30, 31
	s_lshl_b64 s[0:1], s[30:31], 20
	s_add_u32 s40, s55, s0
	s_addc_u32 s41, s56, s1
	s_and_b64 s[0:1], vcc, exec
	s_cselect_b32 s31, s41, s47
	s_cselect_b32 s37, s40, s46
	s_add_u32 s44, s44, 0x80080
	s_addc_u32 s45, s45, 0
	s_add_u32 s43, s46, 0x100
	v_mov_b32_e32 v0, 0
	s_addc_u32 s68, s47, 0
	s_mov_b32 s69, -2
	s_waitcnt lgkmcnt(0)
	ds_read_b128 v[144:147], v150
	ds_read_b128 v[154:157], v150 offset:1024
	ds_read_b128 v[158:161], v150 offset:2048
	ds_read_b128 v[162:165], v150 offset:3072
	s_add_i32 m0, s52, 0xc000
	ds_read_b128 v[166:169], v151
	ds_read_b128 v[170:173], v151 offset:1024
	ds_read_b128 v[174:177], v151 offset:2048
	ds_read_b128 v[178:181], v151 offset:3072
	ds_read_b128 v[188:191], v151 offset:4096
	ds_read_b128 v[206:209], v151 offset:5120
	ds_read_b128 v[210:213], v151 offset:6144
	global_load_lds_dwordx4 v136, s[44:45]
	s_add_i32 m0, s52, 0xe000
	ds_read_b128 v[214:217], v151 offset:7168
	global_load_lds_dwordx4 v138, s[44:45]
	s_add_u32 s0, s44, 0xfff80080
	s_addc_u32 s1, s45, -1
	s_cmp_eq_u32 s69, 28
	s_cselect_b32 s49, s34, s1
	s_cselect_b32 s48, s35, s0
	s_cselect_b32 s47, s31, s68
	s_cselect_b32 s46, s37, s43
	s_waitcnt lgkmcnt(8)
	s_barrier
	s_waitcnt lgkmcnt(0)
	s_setprio 1
	v_mfma_f32_16x16x32_bf16 v[124:127], v[144:147], v[166:169], 0
	v_mfma_f32_16x16x32_bf16 v[120:123], v[158:161], v[166:169], 0
	v_mfma_f32_16x16x32_bf16 v[108:111], v[144:147], v[174:177], 0
	v_mfma_f32_16x16x32_bf16 v[104:107], v[158:161], v[174:177], 0
	v_mfma_f32_16x16x32_bf16 v[92:95], v[144:147], v[188:191], 0
	v_mfma_f32_16x16x32_bf16 v[88:91], v[158:161], v[188:191], 0
	v_mfma_f32_16x16x32_bf16 v[76:79], v[144:147], v[210:213], 0
	v_mfma_f32_16x16x32_bf16 v[72:75], v[158:161], v[210:213], 0
	v_mfma_f32_16x16x32_bf16 v[124:127], v[154:157], v[170:173], v[124:127]
	v_mfma_f32_16x16x32_bf16 v[120:123], v[162:165], v[170:173], v[120:123]
	v_mfma_f32_16x16x32_bf16 v[108:111], v[154:157], v[178:181], v[108:111]
	v_mfma_f32_16x16x32_bf16 v[104:107], v[162:165], v[178:181], v[104:107]
	v_mfma_f32_16x16x32_bf16 v[92:95], v[154:157], v[206:209], v[92:95]
	v_mfma_f32_16x16x32_bf16 v[88:91], v[162:165], v[206:209], v[88:91]
	v_mfma_f32_16x16x32_bf16 v[76:79], v[154:157], v[214:217], v[76:79]
	v_mfma_f32_16x16x32_bf16 v[72:75], v[162:165], v[214:217], v[72:75]
	s_setprio 0
	s_barrier
	s_add_i32 s0, s65, s51
	s_mov_b32 m0, s0
	ds_read_b128 v[218:221], v152
	ds_read_b128 v[222:225], v152 offset:1024
	ds_read_b128 v[226:229], v152 offset:2048
	global_load_lds_dwordx4 v132, s[46:47]
	s_add_i32 m0, s0, 0x2000
	ds_read_b128 v[230:233], v152 offset:3072
	global_load_lds_dwordx4 v134, s[46:47]
	s_barrier
	s_waitcnt lgkmcnt(0)
	s_setprio 1
	v_mfma_f32_16x16x32_bf16 v[116:119], v[218:221], v[166:169], 0
	v_mfma_f32_16x16x32_bf16 v[112:115], v[226:229], v[166:169], 0
	v_mfma_f32_16x16x32_bf16 v[100:103], v[218:221], v[174:177], 0
	v_mfma_f32_16x16x32_bf16 v[96:99], v[226:229], v[174:177], 0
	v_mfma_f32_16x16x32_bf16 v[84:87], v[218:221], v[188:191], 0
	v_mfma_f32_16x16x32_bf16 v[80:83], v[226:229], v[188:191], 0
	v_mfma_f32_16x16x32_bf16 v[68:71], v[218:221], v[210:213], 0
	v_mfma_f32_16x16x32_bf16 v[64:67], v[226:229], v[210:213], 0
	v_mfma_f32_16x16x32_bf16 v[116:119], v[222:225], v[170:173], v[116:119]
	v_mfma_f32_16x16x32_bf16 v[112:115], v[230:233], v[170:173], v[112:115]
	v_mfma_f32_16x16x32_bf16 v[100:103], v[222:225], v[178:181], v[100:103]
	v_mfma_f32_16x16x32_bf16 v[96:99], v[230:233], v[178:181], v[96:99]
	v_mfma_f32_16x16x32_bf16 v[84:87], v[222:225], v[206:209], v[84:87]
	v_mfma_f32_16x16x32_bf16 v[80:83], v[230:233], v[206:209], v[80:83]
	v_mfma_f32_16x16x32_bf16 v[68:71], v[222:225], v[214:217], v[68:71]
	v_mfma_f32_16x16x32_bf16 v[64:67], v[230:233], v[214:217], v[64:67]
	s_setprio 0
	s_mov_b32 m0, s52
	s_barrier
	ds_read_b128 v[166:169], v151 offset:16384
	ds_read_b128 v[170:173], v151 offset:17408
	ds_read_b128 v[174:177], v151 offset:18432
	ds_read_b128 v[178:181], v151 offset:19456
	ds_read_b128 v[188:191], v151 offset:20480
	ds_read_b128 v[206:209], v151 offset:21504
	ds_read_b128 v[210:213], v151 offset:22528
	global_load_lds_dwordx4 v128, s[48:49]
	s_mov_b32 m0, s53
	ds_read_b128 v[214:217], v151 offset:23552
	global_load_lds_dwordx4 v130, s[48:49]
	s_barrier
	s_waitcnt lgkmcnt(0)
	s_setprio 1
	v_mfma_f32_16x16x32_bf16 v[60:63], v[144:147], v[166:169], 0
	v_mfma_f32_16x16x32_bf16 v[56:59], v[158:161], v[166:169], 0
	v_mfma_f32_16x16x32_bf16 v[44:47], v[144:147], v[174:177], 0
	v_mfma_f32_16x16x32_bf16 v[40:43], v[158:161], v[174:177], 0
	v_mfma_f32_16x16x32_bf16 v[28:31], v[144:147], v[188:191], 0
	v_mfma_f32_16x16x32_bf16 v[24:27], v[158:161], v[188:191], 0
	v_mfma_f32_16x16x32_bf16 v[12:15], v[144:147], v[210:213], 0
	v_mfma_f32_16x16x32_bf16 v[8:11], v[158:161], v[210:213], 0
	v_mfma_f32_16x16x32_bf16 v[60:63], v[154:157], v[170:173], v[60:63]
	v_mfma_f32_16x16x32_bf16 v[56:59], v[162:165], v[170:173], v[56:59]
	v_mfma_f32_16x16x32_bf16 v[44:47], v[154:157], v[178:181], v[44:47]
	v_mfma_f32_16x16x32_bf16 v[40:43], v[162:165], v[178:181], v[40:43]
	v_mfma_f32_16x16x32_bf16 v[28:31], v[154:157], v[206:209], v[28:31]
	v_mfma_f32_16x16x32_bf16 v[24:27], v[162:165], v[206:209], v[24:27]
	v_mfma_f32_16x16x32_bf16 v[12:15], v[154:157], v[214:217], v[12:15]
	v_mfma_f32_16x16x32_bf16 v[8:11], v[162:165], v[214:217], v[8:11]
	s_setprio 0
	s_barrier
; #define PG8_STAGE(bufoff, gbase, voff) do { _Pragma("unroll") for (int _i = 0; _i < 2; ++_i) \
;         __builtin_amdgcn_global_load_lds((const unsigned*)((const char*)(gbase) + (voff)[_i]), (LAS unsigned*)(lds + (bufoff) + ldsw + _i * 8192), 16, 0, 0); } while (0)
; #define PG8_LDA(dst, b, h) do { _Pragma("unroll") for (int m = 0; m < 4; ++m) _Pragma("unroll") for (int k = 0; k < 2; ++k) dst[m][k] = *(const LAS bf16x8*)(lds + PG8_SA(b, h) + aoff + m * 2048 + k * 1024); } while (0)
; #define PG8_LDB(dst, b, h) do { _Pragma("unroll") for (int n = 0; n < 2; ++n) _Pragma("unroll") for (int k = 0; k < 2; ++k) dst[n][k] = *(const LAS bf16x8*)(lds + PG8_SB(b, h) + boff + n * 2048 + k * 1024); } while (0)
; #define PG8_MMA(ai, bj, At, Bt) do { __builtin_amdgcn_s_setprio(1); _Pragma("unroll") for (int m = 0; m < 4; ++m) _Pragma("unroll") for (int n = 0; n < 2; ++n) _Pragma("unroll") for (int k = 0; k < 2; ++k) \
;         acc[ai][bj][m][n] = __builtin_amdgcn_mfma_f32_16x16x32_bf16(Bt[n][k], At[m][k], acc[ai][bj][m][n], 0, 0, 0); __builtin_amdgcn_s_setprio(0); } while (0)
; #define PG8_WAIT_V(n) asm volatile("s_waitcnt vmcnt(" #n ")" ::: "memory")
; #define PG8_WAIT_L(n) asm volatile("s_waitcnt lgkmcnt(" #n ")" ::: "memory")
; #define PG8_BAR __builtin_amdgcn_s_barrier()
; #define PG8_SCHED __builtin_amdgcn_sched_barrier(0)
; template <class Epi, class Sched>
; DI void gemm_phase(LAS unsigned char* lds, const Gemm g, const Sched& S, const Epi& E) {
;     ...
;             PG8_STAGE(PG8_SB(0, 1), b2 + hstep, voffB);
;             PG8_WAIT_V(6); PG8_BAR; PG8_MMA(1, 1, At, B1); PG8_BAR;
;             PG8_LDB(B0, 1, 0); PG8_SCHED; PG8_LDA(At, 1, 0); PG8_STAGE(PG8_SA(0, 1), a2 + hstep, voffA);
;             PG8_WAIT_L(8); PG8_BAR; PG8_WAIT_L(0); PG8_MMA(0, 0, At, B0); PG8_BAR; PG8_SCHED;
	s_add_i32 s4, s66, s51
	s_mov_b32 m0, s4
	s_add_u32 s0, s46, 0x80000
	s_addc_u32 s1, s47, 0
	global_load_lds_dwordx4 v132, s[0:1]
	s_add_i32 m0, s4, 0x2000
	s_add_i32 s4, 0, 0x18000
	global_load_lds_dwordx4 v134, s[0:1]
	s_waitcnt vmcnt(6)
	s_barrier
	s_setprio 1
	v_mfma_f32_16x16x32_bf16 v[52:55], v[218:221], v[166:169], 0
	v_mfma_f32_16x16x32_bf16 v[48:51], v[226:229], v[166:169], 0
	v_mfma_f32_16x16x32_bf16 v[36:39], v[218:221], v[174:177], 0
	v_mfma_f32_16x16x32_bf16 v[32:35], v[226:229], v[174:177], 0
	v_mfma_f32_16x16x32_bf16 v[20:23], v[218:221], v[188:191], 0
	v_mfma_f32_16x16x32_bf16 v[16:19], v[226:229], v[188:191], 0
	v_mfma_f32_16x16x32_bf16 v[4:7], v[218:221], v[210:213], 0
	v_mfma_f32_16x16x32_bf16 v[0:3], v[226:229], v[210:213], 0
	v_mfma_f32_16x16x32_bf16 v[52:55], v[222:225], v[170:173], v[52:55]
	v_mfma_f32_16x16x32_bf16 v[48:51], v[230:233], v[170:173], v[48:51]
	v_mfma_f32_16x16x32_bf16 v[36:39], v[222:225], v[178:181], v[36:39]
	v_mfma_f32_16x16x32_bf16 v[32:35], v[230:233], v[178:181], v[32:35]
	v_mfma_f32_16x16x32_bf16 v[20:23], v[222:225], v[206:209], v[20:23]
	v_mfma_f32_16x16x32_bf16 v[16:19], v[230:233], v[206:209], v[16:19]
	v_mfma_f32_16x16x32_bf16 v[4:7], v[222:225], v[214:217], v[4:7]
	v_mfma_f32_16x16x32_bf16 v[0:3], v[230:233], v[214:217], v[0:3]
	s_setprio 0
	v_add_u32_e32 v162, s4, v149
	s_barrier
	ds_read_b128 v[144:147], v162
	ds_read_b128 v[154:157], v162 offset:1024
	ds_read_b128 v[158:161], v162 offset:2048
	ds_read_b128 v[162:165], v162 offset:3072
	s_add_u32 s0, s48, 0x80000
	s_addc_u32 s1, s49, 0
	s_mov_b32 m0, s58
	ds_read_b128 v[166:169], v151 offset:32768
	ds_read_b128 v[170:173], v151 offset:33792
	ds_read_b128 v[174:177], v151 offset:34816
	ds_read_b128 v[178:181], v151 offset:35840
	ds_read_b128 v[188:191], v151 offset:36864
	ds_read_b128 v[206:209], v151 offset:37888
	ds_read_b128 v[210:213], v151 offset:38912
	global_load_lds_dwordx4 v128, s[0:1]
	s_mov_b32 m0, s59
	ds_read_b128 v[214:217], v151 offset:39936
	global_load_lds_dwordx4 v130, s[0:1]
	s_waitcnt lgkmcnt(8)
	s_barrier
	s_waitcnt lgkmcnt(0)
	s_setprio 1
	v_mfma_f32_16x16x32_bf16 v[124:127], v[144:147], v[166:169], v[124:127]
	v_mfma_f32_16x16x32_bf16 v[120:123], v[158:161], v[166:169], v[120:123]
	v_mfma_f32_16x16x32_bf16 v[108:111], v[144:147], v[174:177], v[108:111]
	v_mfma_f32_16x16x32_bf16 v[104:107], v[158:161], v[174:177], v[104:107]
	v_mfma_f32_16x16x32_bf16 v[92:95], v[144:147], v[188:191], v[92:95]
	v_mfma_f32_16x16x32_bf16 v[88:91], v[158:161], v[188:191], v[88:91]
	v_mfma_f32_16x16x32_bf16 v[76:79], v[144:147], v[210:213], v[76:79]
	v_mfma_f32_16x16x32_bf16 v[72:75], v[158:161], v[210:213], v[72:75]
	v_mfma_f32_16x16x32_bf16 v[124:127], v[154:157], v[170:173], v[124:127]
	v_mfma_f32_16x16x32_bf16 v[120:123], v[162:165], v[170:173], v[120:123]
	v_mfma_f32_16x16x32_bf16 v[108:111], v[154:157], v[178:181], v[108:111]
	v_mfma_f32_16x16x32_bf16 v[104:107], v[162:165], v[178:181], v[104:107]
	v_mfma_f32_16x16x32_bf16 v[92:95], v[154:157], v[206:209], v[92:95]
	v_mfma_f32_16x16x32_bf16 v[88:91], v[162:165], v[206:209], v[88:91]
	v_mfma_f32_16x16x32_bf16 v[76:79], v[154:157], v[214:217], v[76:79]
	v_mfma_f32_16x16x32_bf16 v[72:75], v[162:165], v[214:217], v[72:75]
	s_setprio 0
	s_barrier
	s_add_i32 s5, 0, 0x1c000
	s_add_i32 s0, s4, s51
	v_add_u32_e32 v201, s5, v149
	s_add_i32 m0, s0, 0xffffff80
	ds_read_b128 v[218:221], v201
	ds_read_b128 v[222:225], v201 offset:1024
	ds_read_b128 v[226:229], v201 offset:2048
	global_load_lds_dwordx4 v132, s[46:47] offset:128
	s_add_i32 m0, s0, 0x1f80
	ds_read_b128 v[230:233], v201 offset:3072
	global_load_lds_dwordx4 v134, s[46:47] offset:128
	s_barrier
; #define PG8_STAGE(bufoff, gbase, voff) do { _Pragma("unroll") for (int _i = 0; _i < 2; ++_i) \
;         __builtin_amdgcn_global_load_lds((const unsigned*)((const char*)(gbase) + (voff)[_i]), (LAS unsigned*)(lds + (bufoff) + ldsw + _i * 8192), 16, 0, 0); } while (0)
; #define PG8_LDA(dst, b, h) do { _Pragma("unroll") for (int m = 0; m < 4; ++m) _Pragma("unroll") for (int k = 0; k < 2; ++k) dst[m][k] = *(const LAS bf16x8*)(lds + PG8_SA(b, h) + aoff + m * 2048 + k * 1024); } while (0)
; #define PG8_LDB(dst, b, h) do { _Pragma("unroll") for (int n = 0; n < 2; ++n) _Pragma("unroll") for (int k = 0; k < 2; ++k) dst[n][k] = *(const LAS bf16x8*)(lds + PG8_SB(b, h) + boff + n * 2048 + k * 1024); } while (0)
; #define PG8_MMA(ai, bj, At, Bt) do { __builtin_amdgcn_s_setprio(1); _Pragma("unroll") for (int m = 0; m < 4; ++m) _Pragma("unroll") for (int n = 0; n < 2; ++n) _Pragma("unroll") for (int k = 0; k < 2; ++k) \
;         acc[ai][bj][m][n] = __builtin_amdgcn_mfma_f32_16x16x32_bf16(Bt[n][k], At[m][k], acc[ai][bj][m][n], 0, 0, 0); __builtin_amdgcn_s_setprio(0); } while (0)
; #define PG8_WAIT_V(n) asm volatile("s_waitcnt vmcnt(" #n ")" ::: "memory")
; #define PG8_WAIT_L(n) asm volatile("s_waitcnt lgkmcnt(" #n ")" ::: "memory")
; #define PG8_BAR __builtin_amdgcn_s_barrier()
; #define PG8_SCHED __builtin_amdgcn_sched_barrier(0)
; template <class Epi, class Sched>
; DI void gemm_phase(LAS unsigned char* lds, const Gemm g, const Sched& S, const Epi& E) {
;     ...
;             PG8_WAIT_L(8); PG8_BAR; PG8_WAIT_L(0); PG8_MMA(0, 0, At, B0); PG8_BAR; PG8_SCHED;
;             PG8_LDB(B1, 1, 1); PG8_STAGE(PG8_SB(1, 0), b3, voffB);
;             PG8_BAR; PG8_WAIT_L(0); PG8_MMA(0, 1, At, B1); PG8_BAR;
;             PG8_LDA(At, 1, 1); PG8_STAGE(PG8_SA(1, 0), a3, voffA);
;             PG8_BAR; PG8_WAIT_L(0); PG8_MMA(1, 0, At, B0); PG8_BAR; PG8_SCHED;
;             PG8_STAGE(PG8_SB(1, 1), b3 + hstep, voffB);
;             PG8_WAIT_V(6); PG8_BAR; PG8_MMA(1, 1, At, B1); PG8_BAR;
	s_waitcnt lgkmcnt(0)
	s_setprio 1
	v_mfma_f32_16x16x32_bf16 v[116:119], v[218:221], v[166:169], v[116:119]
	v_mfma_f32_16x16x32_bf16 v[112:115], v[226:229], v[166:169], v[112:115]
	v_mfma_f32_16x16x32_bf16 v[100:103], v[218:221], v[174:177], v[100:103]
	v_mfma_f32_16x16x32_bf16 v[96:99], v[226:229], v[174:177], v[96:99]
	v_mfma_f32_16x16x32_bf16 v[84:87], v[218:221], v[188:191], v[84:87]
	v_mfma_f32_16x16x32_bf16 v[80:83], v[226:229], v[188:191], v[80:83]
	v_mfma_f32_16x16x32_bf16 v[68:71], v[218:221], v[210:213], v[68:71]
	v_mfma_f32_16x16x32_bf16 v[64:67], v[226:229], v[210:213], v[64:67]
	v_mfma_f32_16x16x32_bf16 v[116:119], v[222:225], v[170:173], v[116:119]
	v_mfma_f32_16x16x32_bf16 v[112:115], v[230:233], v[170:173], v[112:115]
	v_mfma_f32_16x16x32_bf16 v[100:103], v[222:225], v[178:181], v[100:103]
	v_mfma_f32_16x16x32_bf16 v[96:99], v[230:233], v[178:181], v[96:99]
	v_mfma_f32_16x16x32_bf16 v[84:87], v[222:225], v[206:209], v[84:87]
	v_mfma_f32_16x16x32_bf16 v[80:83], v[230:233], v[206:209], v[80:83]
	v_mfma_f32_16x16x32_bf16 v[68:71], v[222:225], v[214:217], v[68:71]
	v_mfma_f32_16x16x32_bf16 v[64:67], v[230:233], v[214:217], v[64:67]
	s_setprio 0
	s_add_i32 m0, s63, 0xffffff80
	s_barrier
	ds_read_b128 v[166:169], v151 offset:49152
	ds_read_b128 v[170:173], v151 offset:50176
	ds_read_b128 v[174:177], v151 offset:51200
	ds_read_b128 v[178:181], v151 offset:52224
	ds_read_b128 v[188:191], v151 offset:53248
	ds_read_b128 v[206:209], v151 offset:54272
	ds_read_b128 v[210:213], v151 offset:55296
	global_load_lds_dwordx4 v128, s[48:49] offset:128
	s_add_i32 m0, s64, 0xffffff80
	ds_read_b128 v[214:217], v151 offset:56320
	global_load_lds_dwordx4 v130, s[48:49] offset:128
	s_barrier
	s_waitcnt lgkmcnt(0)
	s_setprio 1
	v_mfma_f32_16x16x32_bf16 v[60:63], v[144:147], v[166:169], v[60:63]
	v_mfma_f32_16x16x32_bf16 v[56:59], v[158:161], v[166:169], v[56:59]
	v_mfma_f32_16x16x32_bf16 v[44:47], v[144:147], v[174:177], v[44:47]
	v_mfma_f32_16x16x32_bf16 v[40:43], v[158:161], v[174:177], v[40:43]
	v_mfma_f32_16x16x32_bf16 v[28:31], v[144:147], v[188:191], v[28:31]
	v_mfma_f32_16x16x32_bf16 v[24:27], v[158:161], v[188:191], v[24:27]
	v_mfma_f32_16x16x32_bf16 v[12:15], v[144:147], v[210:213], v[12:15]
	v_mfma_f32_16x16x32_bf16 v[8:11], v[158:161], v[210:213], v[8:11]
	v_mfma_f32_16x16x32_bf16 v[60:63], v[154:157], v[170:173], v[60:63]
	v_mfma_f32_16x16x32_bf16 v[56:59], v[162:165], v[170:173], v[56:59]
	v_mfma_f32_16x16x32_bf16 v[44:47], v[154:157], v[178:181], v[44:47]
	v_mfma_f32_16x16x32_bf16 v[40:43], v[162:165], v[178:181], v[40:43]
	v_mfma_f32_16x16x32_bf16 v[28:31], v[154:157], v[206:209], v[28:31]
	v_mfma_f32_16x16x32_bf16 v[24:27], v[162:165], v[206:209], v[24:27]
	v_mfma_f32_16x16x32_bf16 v[12:15], v[154:157], v[214:217], v[12:15]
	v_mfma_f32_16x16x32_bf16 v[8:11], v[162:165], v[214:217], v[8:11]
	s_setprio 0
	s_barrier
	s_add_i32 s4, s5, s51
	s_mov_b32 m0, s4
	s_add_u32 s0, s46, 0x80080
	s_addc_u32 s1, s47, 0
	global_load_lds_dwordx4 v132, s[0:1]
	s_add_i32 m0, s4, 0x2000
	s_add_i32 s69, s69, 2
	global_load_lds_dwordx4 v134, s[0:1]
	s_add_u32 s44, s44, 0x100
	s_addc_u32 s45, s45, 0
	s_add_u32 s43, s43, 0x100
	s_addc_u32 s68, s68, 0
	s_cmp_gt_u32 s69, 29
	s_waitcnt vmcnt(6)
	s_barrier
	s_setprio 1
	v_mfma_f32_16x16x32_bf16 v[52:55], v[218:221], v[166:169], v[52:55]
	v_mfma_f32_16x16x32_bf16 v[48:51], v[226:229], v[166:169], v[48:51]
	v_mfma_f32_16x16x32_bf16 v[36:39], v[218:221], v[174:177], v[36:39]
	v_mfma_f32_16x16x32_bf16 v[32:35], v[226:229], v[174:177], v[32:35]
	v_mfma_f32_16x16x32_bf16 v[20:23], v[218:221], v[188:191], v[20:23]
	v_mfma_f32_16x16x32_bf16 v[16:19], v[226:229], v[188:191], v[16:19]
	v_mfma_f32_16x16x32_bf16 v[4:7], v[218:221], v[210:213], v[4:7]
	v_mfma_f32_16x16x32_bf16 v[0:3], v[226:229], v[210:213], v[0:3]
	v_mfma_f32_16x16x32_bf16 v[52:55], v[222:225], v[170:173], v[52:55]
	v_mfma_f32_16x16x32_bf16 v[48:51], v[230:233], v[170:173], v[48:51]
	v_mfma_f32_16x16x32_bf16 v[36:39], v[222:225], v[178:181], v[36:39]
	v_mfma_f32_16x16x32_bf16 v[32:35], v[230:233], v[178:181], v[32:35]
	v_mfma_f32_16x16x32_bf16 v[20:23], v[222:225], v[206:209], v[20:23]
	v_mfma_f32_16x16x32_bf16 v[16:19], v[230:233], v[206:209], v[16:19]
	v_mfma_f32_16x16x32_bf16 v[4:7], v[222:225], v[214:217], v[4:7]
	v_mfma_f32_16x16x32_bf16 v[0:3], v[230:233], v[214:217], v[0:3]
	s_setprio 0
	s_cbranch_scc0 .Lrot_1508
	s_barrier
	s_branch .Lpeel_done_1508

; #define PG8_STAGE(bufoff, gbase, voff) do { _Pragma("unroll") for (int _i = 0; _i < 2; ++_i) \
;         __builtin_amdgcn_global_load_lds((const unsigned*)((const char*)(gbase) + (voff)[_i]), (LAS unsigned*)(lds + (bufoff) + ldsw + _i * 8192), 16, 0, 0); } while (0)
; #define PG8_LDA(dst, b, h) do { _Pragma("unroll") for (int m = 0; m < 4; ++m) _Pragma("unroll") for (int k = 0; k < 2; ++k) dst[m][k] = *(const LAS bf16x8*)(lds + PG8_SA(b, h) + aoff + m * 2048 + k * 1024); } while (0)
; #define PG8_LDB(dst, b, h) do { _Pragma("unroll") for (int n = 0; n < 2; ++n) _Pragma("unroll") for (int k = 0; k < 2; ++k) dst[n][k] = *(const LAS bf16x8*)(lds + PG8_SB(b, h) + boff + n * 2048 + k * 1024); } while (0)
; #define PG8_MMA(ai, bj, At, Bt) do { __builtin_amdgcn_s_setprio(1); _Pragma("unroll") for (int m = 0; m < 4; ++m) _Pragma("unroll") for (int n = 0; n < 2; ++n) _Pragma("unroll") for (int k = 0; k < 2; ++k) \
;         acc[ai][bj][m][n] = __builtin_amdgcn_mfma_f32_16x16x32_bf16(Bt[n][k], At[m][k], acc[ai][bj][m][n], 0, 0, 0); __builtin_amdgcn_s_setprio(0); } while (0)
; #define PG8_WAIT_V(n) asm volatile("s_waitcnt vmcnt(" #n ")" ::: "memory")
; #define PG8_WAIT_L(n) asm volatile("s_waitcnt lgkmcnt(" #n ")" ::: "memory")
; #define PG8_BAR __builtin_amdgcn_s_barrier()
; #define PG8_SCHED __builtin_amdgcn_sched_barrier(0)
; template <class Epi, class Sched>
; DI void gemm_phase(LAS unsigned char* lds, const Gemm g, const Sched& S, const Epi& E) {
;     ...
;             PG8_LDB(B0, 0, 0); PG8_SCHED; PG8_LDA(At, 0, 0); PG8_STAGE(PG8_SA(1, 1), a1 + hstep, voffA);
;             PG8_WAIT_L(8); PG8_BAR; PG8_WAIT_L(0); PG8_MMA(0, 0, At, B0); PG8_BAR; PG8_SCHED;
;             PG8_LDB(B1, 0, 1); PG8_STAGE(PG8_SB(0, 0), b2, voffB);
;             PG8_BAR; PG8_WAIT_L(0); PG8_MMA(0, 1, At, B1); PG8_BAR;
;             PG8_LDA(At, 0, 1); PG8_STAGE(PG8_SA(0, 0), a2, voffA);
;             PG8_BAR; PG8_WAIT_L(0); PG8_MMA(1, 0, At, B0); PG8_BAR; PG8_SCHED;
;             PG8_STAGE(PG8_SB(0, 1), b2 + hstep, voffB);
;             PG8_WAIT_V(6); PG8_BAR; PG8_MMA(1, 1, At, B1); PG8_BAR;
.LBB0_1508:
	ds_read_b128 v[144:147], v150
	ds_read_b128 v[154:157], v150 offset:1024
	ds_read_b128 v[158:161], v150 offset:2048
	ds_read_b128 v[162:165], v150 offset:3072
	s_add_i32 m0, s52, 0xc000
	ds_read_b128 v[166:169], v151
	ds_read_b128 v[170:173], v151 offset:1024
	ds_read_b128 v[174:177], v151 offset:2048
	ds_read_b128 v[178:181], v151 offset:3072
	ds_read_b128 v[188:191], v151 offset:4096
	ds_read_b128 v[206:209], v151 offset:5120
	ds_read_b128 v[210:213], v151 offset:6144
	global_load_lds_dwordx4 v136, s[44:45]
	s_add_i32 m0, s52, 0xe000
	ds_read_b128 v[214:217], v151 offset:7168
	global_load_lds_dwordx4 v138, s[44:45]
	s_add_u32 s0, s44, 0xfff80080
	s_addc_u32 s1, s45, -1
	s_cmp_eq_u32 s69, 28
	s_cselect_b32 s49, s34, s1
	s_cselect_b32 s48, s35, s0
	s_cselect_b32 s47, s31, s68
	s_cselect_b32 s46, s37, s43
	s_waitcnt lgkmcnt(8)
	s_barrier
	s_waitcnt lgkmcnt(0)
	s_setprio 1
	v_mfma_f32_16x16x32_bf16 v[124:127], v[144:147], v[166:169], v[124:127]
	v_mfma_f32_16x16x32_bf16 v[120:123], v[158:161], v[166:169], v[120:123]
	v_mfma_f32_16x16x32_bf16 v[108:111], v[144:147], v[174:177], v[108:111]
	v_mfma_f32_16x16x32_bf16 v[104:107], v[158:161], v[174:177], v[104:107]
	v_mfma_f32_16x16x32_bf16 v[92:95], v[144:147], v[188:191], v[92:95]
	v_mfma_f32_16x16x32_bf16 v[88:91], v[158:161], v[188:191], v[88:91]
	v_mfma_f32_16x16x32_bf16 v[76:79], v[144:147], v[210:213], v[76:79]
	v_mfma_f32_16x16x32_bf16 v[72:75], v[158:161], v[210:213], v[72:75]
	v_mfma_f32_16x16x32_bf16 v[124:127], v[154:157], v[170:173], v[124:127]
	v_mfma_f32_16x16x32_bf16 v[120:123], v[162:165], v[170:173], v[120:123]
	v_mfma_f32_16x16x32_bf16 v[108:111], v[154:157], v[178:181], v[108:111]
	v_mfma_f32_16x16x32_bf16 v[104:107], v[162:165], v[178:181], v[104:107]
	v_mfma_f32_16x16x32_bf16 v[92:95], v[154:157], v[206:209], v[92:95]
	v_mfma_f32_16x16x32_bf16 v[88:91], v[162:165], v[206:209], v[88:91]
	v_mfma_f32_16x16x32_bf16 v[76:79], v[154:157], v[214:217], v[76:79]
	v_mfma_f32_16x16x32_bf16 v[72:75], v[162:165], v[214:217], v[72:75]
	s_setprio 0
	s_barrier
	s_add_i32 s0, s65, s51
	s_mov_b32 m0, s0
	ds_read_b128 v[218:221], v152
	ds_read_b128 v[222:225], v152 offset:1024
	ds_read_b128 v[226:229], v152 offset:2048
	global_load_lds_dwordx4 v132, s[46:47]
	s_add_i32 m0, s0, 0x2000
	ds_read_b128 v[230:233], v152 offset:3072
	global_load_lds_dwordx4 v134, s[46:47]
	s_barrier
	s_waitcnt lgkmcnt(0)
	s_setprio 1
	v_mfma_f32_16x16x32_bf16 v[116:119], v[218:221], v[166:169], v[116:119]
	v_mfma_f32_16x16x32_bf16 v[112:115], v[226:229], v[166:169], v[112:115]
	v_mfma_f32_16x16x32_bf16 v[100:103], v[218:221], v[174:177], v[100:103]
	v_mfma_f32_16x16x32_bf16 v[96:99], v[226:229], v[174:177], v[96:99]
	v_mfma_f32_16x16x32_bf16 v[84:87], v[218:221], v[188:191], v[84:87]
	v_mfma_f32_16x16x32_bf16 v[80:83], v[226:229], v[188:191], v[80:83]
	v_mfma_f32_16x16x32_bf16 v[68:71], v[218:221], v[210:213], v[68:71]
	v_mfma_f32_16x16x32_bf16 v[64:67], v[226:229], v[210:213], v[64:67]
	v_mfma_f32_16x16x32_bf16 v[116:119], v[222:225], v[170:173], v[116:119]
	v_mfma_f32_16x16x32_bf16 v[112:115], v[230:233], v[170:173], v[112:115]
	v_mfma_f32_16x16x32_bf16 v[100:103], v[222:225], v[178:181], v[100:103]
	v_mfma_f32_16x16x32_bf16 v[96:99], v[230:233], v[178:181], v[96:99]
	v_mfma_f32_16x16x32_bf16 v[84:87], v[222:225], v[206:209], v[84:87]
	v_mfma_f32_16x16x32_bf16 v[80:83], v[230:233], v[206:209], v[80:83]
	v_mfma_f32_16x16x32_bf16 v[68:71], v[222:225], v[214:217], v[68:71]
	v_mfma_f32_16x16x32_bf16 v[64:67], v[230:233], v[214:217], v[64:67]
	s_setprio 0
	s_mov_b32 m0, s52
	s_barrier
	ds_read_b128 v[166:169], v151 offset:16384
	ds_read_b128 v[170:173], v151 offset:17408
	ds_read_b128 v[174:177], v151 offset:18432
	ds_read_b128 v[178:181], v151 offset:19456
	ds_read_b128 v[188:191], v151 offset:20480
	ds_read_b128 v[206:209], v151 offset:21504
	ds_read_b128 v[210:213], v151 offset:22528
	global_load_lds_dwordx4 v128, s[48:49]
	s_mov_b32 m0, s53
	ds_read_b128 v[214:217], v151 offset:23552
	global_load_lds_dwordx4 v130, s[48:49]
	s_barrier
	s_waitcnt lgkmcnt(0)
	s_setprio 1
	v_mfma_f32_16x16x32_bf16 v[60:63], v[144:147], v[166:169], v[60:63]
	v_mfma_f32_16x16x32_bf16 v[56:59], v[158:161], v[166:169], v[56:59]
	v_mfma_f32_16x16x32_bf16 v[44:47], v[144:147], v[174:177], v[44:47]
	v_mfma_f32_16x16x32_bf16 v[40:43], v[158:161], v[174:177], v[40:43]
	v_mfma_f32_16x16x32_bf16 v[28:31], v[144:147], v[188:191], v[28:31]
	v_mfma_f32_16x16x32_bf16 v[24:27], v[158:161], v[188:191], v[24:27]
	v_mfma_f32_16x16x32_bf16 v[12:15], v[144:147], v[210:213], v[12:15]
	v_mfma_f32_16x16x32_bf16 v[8:11], v[158:161], v[210:213], v[8:11]
	v_mfma_f32_16x16x32_bf16 v[60:63], v[154:157], v[170:173], v[60:63]
	v_mfma_f32_16x16x32_bf16 v[56:59], v[162:165], v[170:173], v[56:59]
	v_mfma_f32_16x16x32_bf16 v[44:47], v[154:157], v[178:181], v[44:47]
	v_mfma_f32_16x16x32_bf16 v[40:43], v[162:165], v[178:181], v[40:43]
	v_mfma_f32_16x16x32_bf16 v[28:31], v[154:157], v[206:209], v[28:31]
	v_mfma_f32_16x16x32_bf16 v[24:27], v[162:165], v[206:209], v[24:27]
	v_mfma_f32_16x16x32_bf16 v[12:15], v[154:157], v[214:217], v[12:15]
	v_mfma_f32_16x16x32_bf16 v[8:11], v[162:165], v[214:217], v[8:11]
	s_setprio 0
	s_barrier
	s_add_i32 s4, s66, s51
	s_mov_b32 m0, s4
	s_add_u32 s0, s46, 0x80000
	s_addc_u32 s1, s47, 0
	global_load_lds_dwordx4 v132, s[0:1]
	s_add_i32 m0, s4, 0x2000
	s_add_i32 s4, 0, 0x18000
	global_load_lds_dwordx4 v134, s[0:1]
	s_waitcnt vmcnt(6)
	s_barrier
; #define PG8_STAGE(bufoff, gbase, voff) do { _Pragma("unroll") for (int _i = 0; _i < 2; ++_i) \
;         __builtin_amdgcn_global_load_lds((const unsigned*)((const char*)(gbase) + (voff)[_i]), (LAS unsigned*)(lds + (bufoff) + ldsw + _i * 8192), 16, 0, 0); } while (0)
; #define PG8_LDA(dst, b, h) do { _Pragma("unroll") for (int m = 0; m < 4; ++m) _Pragma("unroll") for (int k = 0; k < 2; ++k) dst[m][k] = *(const LAS bf16x8*)(lds + PG8_SA(b, h) + aoff + m * 2048 + k * 1024); } while (0)
; #define PG8_LDB(dst, b, h) do { _Pragma("unroll") for (int n = 0; n < 2; ++n) _Pragma("unroll") for (int k = 0; k < 2; ++k) dst[n][k] = *(const LAS bf16x8*)(lds + PG8_SB(b, h) + boff + n * 2048 + k * 1024); } while (0)
; #define PG8_MMA(ai, bj, At, Bt) do { __builtin_amdgcn_s_setprio(1); _Pragma("unroll") for (int m = 0; m < 4; ++m) _Pragma("unroll") for (int n = 0; n < 2; ++n) _Pragma("unroll") for (int k = 0; k < 2; ++k) \
;         acc[ai][bj][m][n] = __builtin_amdgcn_mfma_f32_16x16x32_bf16(Bt[n][k], At[m][k], acc[ai][bj][m][n], 0, 0, 0); __builtin_amdgcn_s_setprio(0); } while (0)
; #define PG8_WAIT_V(n) asm volatile("s_waitcnt vmcnt(" #n ")" ::: "memory")
; #define PG8_WAIT_L(n) asm volatile("s_waitcnt lgkmcnt(" #n ")" ::: "memory")
; #define PG8_BAR __builtin_amdgcn_s_barrier()
; #define PG8_SCHED __builtin_amdgcn_sched_barrier(0)
; template <class Epi, class Sched>
; DI void gemm_phase(LAS unsigned char* lds, const Gemm g, const Sched& S, const Epi& E) {
;     ...
;             PG8_WAIT_V(6); PG8_BAR; PG8_MMA(1, 1, At, B1); PG8_BAR;
;             PG8_LDB(B0, 1, 0); PG8_SCHED; PG8_LDA(At, 1, 0); PG8_STAGE(PG8_SA(0, 1), a2 + hstep, voffA);
;             PG8_WAIT_L(8); PG8_BAR; PG8_WAIT_L(0); PG8_MMA(0, 0, At, B0); PG8_BAR; PG8_SCHED;
	s_setprio 1
	v_mfma_f32_16x16x32_bf16 v[52:55], v[218:221], v[166:169], v[52:55]
	v_mfma_f32_16x16x32_bf16 v[48:51], v[226:229], v[166:169], v[48:51]
	v_mfma_f32_16x16x32_bf16 v[36:39], v[218:221], v[174:177], v[36:39]
	v_mfma_f32_16x16x32_bf16 v[32:35], v[226:229], v[174:177], v[32:35]
	v_mfma_f32_16x16x32_bf16 v[20:23], v[218:221], v[188:191], v[20:23]
	v_mfma_f32_16x16x32_bf16 v[16:19], v[226:229], v[188:191], v[16:19]
	v_mfma_f32_16x16x32_bf16 v[4:7], v[218:221], v[210:213], v[4:7]
	v_mfma_f32_16x16x32_bf16 v[0:3], v[226:229], v[210:213], v[0:3]
	v_mfma_f32_16x16x32_bf16 v[52:55], v[222:225], v[170:173], v[52:55]
	v_mfma_f32_16x16x32_bf16 v[48:51], v[230:233], v[170:173], v[48:51]
	v_mfma_f32_16x16x32_bf16 v[36:39], v[222:225], v[178:181], v[36:39]
	v_mfma_f32_16x16x32_bf16 v[32:35], v[230:233], v[178:181], v[32:35]
	v_mfma_f32_16x16x32_bf16 v[20:23], v[222:225], v[206:209], v[20:23]
	v_mfma_f32_16x16x32_bf16 v[16:19], v[230:233], v[206:209], v[16:19]
	v_mfma_f32_16x16x32_bf16 v[4:7], v[222:225], v[214:217], v[4:7]
	v_mfma_f32_16x16x32_bf16 v[0:3], v[230:233], v[214:217], v[0:3]
	s_setprio 0
	v_add_u32_e32 v162, s4, v149
	s_barrier
	ds_read_b128 v[144:147], v162
	ds_read_b128 v[154:157], v162 offset:1024
	ds_read_b128 v[158:161], v162 offset:2048
	ds_read_b128 v[162:165], v162 offset:3072
	s_add_u32 s0, s48, 0x80000
	s_addc_u32 s1, s49, 0
	s_mov_b32 m0, s58
	ds_read_b128 v[166:169], v151 offset:32768
	ds_read_b128 v[170:173], v151 offset:33792
	ds_read_b128 v[174:177], v151 offset:34816
	ds_read_b128 v[178:181], v151 offset:35840
	ds_read_b128 v[188:191], v151 offset:36864
	ds_read_b128 v[206:209], v151 offset:37888
	ds_read_b128 v[210:213], v151 offset:38912
	global_load_lds_dwordx4 v128, s[0:1]
	s_mov_b32 m0, s59
	ds_read_b128 v[214:217], v151 offset:39936
	global_load_lds_dwordx4 v130, s[0:1]
	s_waitcnt lgkmcnt(8)
	s_barrier
	s_waitcnt lgkmcnt(0)
	s_setprio 1
	v_mfma_f32_16x16x32_bf16 v[124:127], v[144:147], v[166:169], v[124:127]
	v_mfma_f32_16x16x32_bf16 v[120:123], v[158:161], v[166:169], v[120:123]
	v_mfma_f32_16x16x32_bf16 v[108:111], v[144:147], v[174:177], v[108:111]
	v_mfma_f32_16x16x32_bf16 v[104:107], v[158:161], v[174:177], v[104:107]
	v_mfma_f32_16x16x32_bf16 v[92:95], v[144:147], v[188:191], v[92:95]
	v_mfma_f32_16x16x32_bf16 v[88:91], v[158:161], v[188:191], v[88:91]
	v_mfma_f32_16x16x32_bf16 v[76:79], v[144:147], v[210:213], v[76:79]
	v_mfma_f32_16x16x32_bf16 v[72:75], v[158:161], v[210:213], v[72:75]
	v_mfma_f32_16x16x32_bf16 v[124:127], v[154:157], v[170:173], v[124:127]
	v_mfma_f32_16x16x32_bf16 v[120:123], v[162:165], v[170:173], v[120:123]
	v_mfma_f32_16x16x32_bf16 v[108:111], v[154:157], v[178:181], v[108:111]
	v_mfma_f32_16x16x32_bf16 v[104:107], v[162:165], v[178:181], v[104:107]
	v_mfma_f32_16x16x32_bf16 v[92:95], v[154:157], v[206:209], v[92:95]
	v_mfma_f32_16x16x32_bf16 v[88:91], v[162:165], v[206:209], v[88:91]
	v_mfma_f32_16x16x32_bf16 v[76:79], v[154:157], v[214:217], v[76:79]
	v_mfma_f32_16x16x32_bf16 v[72:75], v[162:165], v[214:217], v[72:75]
	s_setprio 0
	s_barrier
	s_add_i32 s5, 0, 0x1c000
	s_add_i32 s0, s4, s51
	v_add_u32_e32 v201, s5, v149
	s_add_i32 m0, s0, 0xffffff80
	ds_read_b128 v[218:221], v201
	ds_read_b128 v[222:225], v201 offset:1024
	ds_read_b128 v[226:229], v201 offset:2048
	global_load_lds_dwordx4 v132, s[46:47] offset:128
	s_add_i32 m0, s0, 0x1f80
	ds_read_b128 v[230:233], v201 offset:3072
	global_load_lds_dwordx4 v134, s[46:47] offset:128
	s_barrier
; #define PG8_STAGE(bufoff, gbase, voff) do { _Pragma("unroll") for (int _i = 0; _i < 2; ++_i) \
;         __builtin_amdgcn_global_load_lds((const unsigned*)((const char*)(gbase) + (voff)[_i]), (LAS unsigned*)(lds + (bufoff) + ldsw + _i * 8192), 16, 0, 0); } while (0)
; #define PG8_LDA(dst, b, h) do { _Pragma("unroll") for (int m = 0; m < 4; ++m) _Pragma("unroll") for (int k = 0; k < 2; ++k) dst[m][k] = *(const LAS bf16x8*)(lds + PG8_SA(b, h) + aoff + m * 2048 + k * 1024); } while (0)
; #define PG8_LDB(dst, b, h) do { _Pragma("unroll") for (int n = 0; n < 2; ++n) _Pragma("unroll") for (int k = 0; k < 2; ++k) dst[n][k] = *(const LAS bf16x8*)(lds + PG8_SB(b, h) + boff + n * 2048 + k * 1024); } while (0)
; #define PG8_MMA(ai, bj, At, Bt) do { __builtin_amdgcn_s_setprio(1); _Pragma("unroll") for (int m = 0; m < 4; ++m) _Pragma("unroll") for (int n = 0; n < 2; ++n) _Pragma("unroll") for (int k = 0; k < 2; ++k) \
;         acc[ai][bj][m][n] = __builtin_amdgcn_mfma_f32_16x16x32_bf16(Bt[n][k], At[m][k], acc[ai][bj][m][n], 0, 0, 0); __builtin_amdgcn_s_setprio(0); } while (0)
; #define PG8_WAIT_V(n) asm volatile("s_waitcnt vmcnt(" #n ")" ::: "memory")
; #define PG8_WAIT_L(n) asm volatile("s_waitcnt lgkmcnt(" #n ")" ::: "memory")
; #define PG8_BAR __builtin_amdgcn_s_barrier()
; #define PG8_SCHED __builtin_amdgcn_sched_barrier(0)
; template <class Epi, class Sched>
; DI void gemm_phase(LAS unsigned char* lds, const Gemm g, const Sched& S, const Epi& E) {
;     ...
;             PG8_WAIT_L(8); PG8_BAR; PG8_WAIT_L(0); PG8_MMA(0, 0, At, B0); PG8_BAR; PG8_SCHED;
;             PG8_LDB(B1, 1, 1); PG8_STAGE(PG8_SB(1, 0), b3, voffB);
;             PG8_BAR; PG8_WAIT_L(0); PG8_MMA(0, 1, At, B1); PG8_BAR;
;             PG8_LDA(At, 1, 1); PG8_STAGE(PG8_SA(1, 0), a3, voffA);
;             PG8_BAR; PG8_WAIT_L(0); PG8_MMA(1, 0, At, B0); PG8_BAR; PG8_SCHED;
;             PG8_STAGE(PG8_SB(1, 1), b3 + hstep, voffB);
;             PG8_WAIT_V(6); PG8_BAR; PG8_MMA(1, 1, At, B1); PG8_BAR;
	s_waitcnt lgkmcnt(0)
	s_setprio 1
	v_mfma_f32_16x16x32_bf16 v[116:119], v[218:221], v[166:169], v[116:119]
	v_mfma_f32_16x16x32_bf16 v[112:115], v[226:229], v[166:169], v[112:115]
	v_mfma_f32_16x16x32_bf16 v[100:103], v[218:221], v[174:177], v[100:103]
	v_mfma_f32_16x16x32_bf16 v[96:99], v[226:229], v[174:177], v[96:99]
	v_mfma_f32_16x16x32_bf16 v[84:87], v[218:221], v[188:191], v[84:87]
	v_mfma_f32_16x16x32_bf16 v[80:83], v[226:229], v[188:191], v[80:83]
	v_mfma_f32_16x16x32_bf16 v[68:71], v[218:221], v[210:213], v[68:71]
	v_mfma_f32_16x16x32_bf16 v[64:67], v[226:229], v[210:213], v[64:67]
	v_mfma_f32_16x16x32_bf16 v[116:119], v[222:225], v[170:173], v[116:119]
	v_mfma_f32_16x16x32_bf16 v[112:115], v[230:233], v[170:173], v[112:115]
	v_mfma_f32_16x16x32_bf16 v[100:103], v[222:225], v[178:181], v[100:103]
	v_mfma_f32_16x16x32_bf16 v[96:99], v[230:233], v[178:181], v[96:99]
	v_mfma_f32_16x16x32_bf16 v[84:87], v[222:225], v[206:209], v[84:87]
	v_mfma_f32_16x16x32_bf16 v[80:83], v[230:233], v[206:209], v[80:83]
	v_mfma_f32_16x16x32_bf16 v[68:71], v[222:225], v[214:217], v[68:71]
	v_mfma_f32_16x16x32_bf16 v[64:67], v[230:233], v[214:217], v[64:67]
	s_setprio 0
	s_add_i32 m0, s63, 0xffffff80
	s_barrier
	ds_read_b128 v[166:169], v151 offset:49152
	ds_read_b128 v[170:173], v151 offset:50176
	ds_read_b128 v[174:177], v151 offset:51200
	ds_read_b128 v[178:181], v151 offset:52224
	ds_read_b128 v[188:191], v151 offset:53248
	ds_read_b128 v[206:209], v151 offset:54272
	ds_read_b128 v[210:213], v151 offset:55296
	global_load_lds_dwordx4 v128, s[48:49] offset:128
	s_add_i32 m0, s64, 0xffffff80
	ds_read_b128 v[214:217], v151 offset:56320
	global_load_lds_dwordx4 v130, s[48:49] offset:128
	s_barrier
	s_waitcnt lgkmcnt(0)
	s_setprio 1
	v_mfma_f32_16x16x32_bf16 v[60:63], v[144:147], v[166:169], v[60:63]
	v_mfma_f32_16x16x32_bf16 v[56:59], v[158:161], v[166:169], v[56:59]
	v_mfma_f32_16x16x32_bf16 v[44:47], v[144:147], v[174:177], v[44:47]
	v_mfma_f32_16x16x32_bf16 v[40:43], v[158:161], v[174:177], v[40:43]
	v_mfma_f32_16x16x32_bf16 v[28:31], v[144:147], v[188:191], v[28:31]
	v_mfma_f32_16x16x32_bf16 v[24:27], v[158:161], v[188:191], v[24:27]
	v_mfma_f32_16x16x32_bf16 v[12:15], v[144:147], v[210:213], v[12:15]
	v_mfma_f32_16x16x32_bf16 v[8:11], v[158:161], v[210:213], v[8:11]
	v_mfma_f32_16x16x32_bf16 v[60:63], v[154:157], v[170:173], v[60:63]
	v_mfma_f32_16x16x32_bf16 v[56:59], v[162:165], v[170:173], v[56:59]
	v_mfma_f32_16x16x32_bf16 v[44:47], v[154:157], v[178:181], v[44:47]
	v_mfma_f32_16x16x32_bf16 v[40:43], v[162:165], v[178:181], v[40:43]
	v_mfma_f32_16x16x32_bf16 v[28:31], v[154:157], v[206:209], v[28:31]
	v_mfma_f32_16x16x32_bf16 v[24:27], v[162:165], v[206:209], v[24:27]
	v_mfma_f32_16x16x32_bf16 v[12:15], v[154:157], v[214:217], v[12:15]
	v_mfma_f32_16x16x32_bf16 v[8:11], v[162:165], v[214:217], v[8:11]
	s_setprio 0
	s_barrier
	s_add_i32 s4, s5, s51
	s_mov_b32 m0, s4
	s_add_u32 s0, s46, 0x80080
	s_addc_u32 s1, s47, 0
	global_load_lds_dwordx4 v132, s[0:1]
	s_add_i32 m0, s4, 0x2000
	s_add_i32 s69, s69, 2
	global_load_lds_dwordx4 v134, s[0:1]
	s_add_u32 s44, s44, 0x100
	s_addc_u32 s45, s45, 0
	s_add_u32 s43, s43, 0x100
	s_addc_u32 s68, s68, 0
	s_cmp_gt_u32 s69, 29
	s_waitcnt vmcnt(6)
	s_barrier
	s_setprio 1
	v_mfma_f32_16x16x32_bf16 v[52:55], v[218:221], v[166:169], v[52:55]
	v_mfma_f32_16x16x32_bf16 v[48:51], v[226:229], v[166:169], v[48:51]
	v_mfma_f32_16x16x32_bf16 v[36:39], v[218:221], v[174:177], v[36:39]
	v_mfma_f32_16x16x32_bf16 v[32:35], v[226:229], v[174:177], v[32:35]
	v_mfma_f32_16x16x32_bf16 v[20:23], v[218:221], v[188:191], v[20:23]
	v_mfma_f32_16x16x32_bf16 v[16:19], v[226:229], v[188:191], v[16:19]
	v_mfma_f32_16x16x32_bf16 v[4:7], v[218:221], v[210:213], v[4:7]
	v_mfma_f32_16x16x32_bf16 v[0:3], v[226:229], v[210:213], v[0:3]
	v_mfma_f32_16x16x32_bf16 v[52:55], v[222:225], v[170:173], v[52:55]
	v_mfma_f32_16x16x32_bf16 v[48:51], v[230:233], v[170:173], v[48:51]
	v_mfma_f32_16x16x32_bf16 v[36:39], v[222:225], v[178:181], v[36:39]
	v_mfma_f32_16x16x32_bf16 v[32:35], v[230:233], v[178:181], v[32:35]
	v_mfma_f32_16x16x32_bf16 v[20:23], v[222:225], v[206:209], v[20:23]
	v_mfma_f32_16x16x32_bf16 v[16:19], v[230:233], v[206:209], v[16:19]
	v_mfma_f32_16x16x32_bf16 v[4:7], v[222:225], v[214:217], v[4:7]
	v_mfma_f32_16x16x32_bf16 v[0:3], v[230:233], v[214:217], v[0:3]
	s_setprio 0
	s_cbranch_scc0 .Lrot_1508
	s_barrier

;     DI size_t aoff(const Unit& u, size_t tstep) const { return (size_t)u.pm * tstep; }
;     DI size_t boff(const Unit& u, size_t tstep) const { return (size_t)u.pn * tstep; }
;     DI bool next(int i, Unit& u) const { const long L = (long)i * G + c; if (L >= np) return false; u.pm = pmv; u.pn = (int)(L % nN); u.ks = (int)(L / nN); return true; }
;     DI size_t aoff(const Unit& u, size_t) const { return (size_t)u.ks * kbytes; }
;     DI size_t boff(const Unit& u, size_t tstep) const { return (size_t)u.pn * tstep + (size_t)u.ks * kbytes; }
;     DI bool next(int i, Unit& u) const { Unit t; if (!S.next(i / 3, t)) return false; u.pm = t.pm; u.pn = t.pn; u.ks = i % 3; return true; }
;     DI size_t aoff(const Unit& u, size_t tstep) const { return (u.ks < 2 ? offU : offOA) + (size_t)u.pm * tstep; }
; #define PG8_LDA(dst, b, h) do { _Pragma("unroll") for (int m = 0; m < 4; ++m) _Pragma("unroll") for (int k = 0; k < 2; ++k) dst[m][k] = *(const LAS bf16x8*)(lds + PG8_SA(b, h) + aoff + m * 2048 + k * 1024); } while (0)
; template <class Epi, class Sched>
; DI void gemm_phase(LAS unsigned char* lds, const Gemm g, const Sched& S, const Epi& E) {
;     ...
;         const bool has_next = S.next(ui + 1, nxt);
;         const char* nA = has_next ? (const char*)g.A + S.aoff(nxt, tstep) : cA; const char* nB = has_next ? (const char*)g.Bt + S.boff(nxt, tstep) : cB;
;         for (int t = 0; t < nt; t += 2) {
;             if constexpr (Epi::HAS_MID) { if (t == E.mid_t(nt)) { int fr3 = fr, fq3 = fq; asm volatile("" : "+v"(fr3), "+v"(fq3)); E.mid(acc, cur, wr, wc, fr3, fq3); } }
;             const bool last = (t == nt - 2);
;             const char* a1 = cA + (size_t)(t + 1) * kstep;
;             const char* a2 = last ? nA : cA + (size_t)(t + 2) * kstep; const char* b2 = last ? nB : cB + (size_t)(t + 2) * kstep;
;             const char* a3 = a2 + kstep; const char* b3 = b2 + kstep;
;             PG8_LDB(B0, 0, 0); PG8_SCHED; PG8_LDA(At, 0, 0); PG8_STAGE(PG8_SA(1, 1), a1 + hstep, voffA);
;             PG8_WAIT_L(8); PG8_BAR; PG8_WAIT_L(0); PG8_MMA(0, 0, At, B0); PG8_BAR; PG8_SCHED;
;             PG8_LDB(B1, 0, 1); PG8_STAGE(PG8_SB(0, 0), b2, voffB);
;             PG8_BAR; PG8_WAIT_L(0); PG8_MMA(0, 1, At, B1); PG8_BAR;
;             PG8_LDA(At, 0, 1); PG8_STAGE(PG8_SA(0, 0), a2, voffA);
;             PG8_BAR; PG8_WAIT_L(0); PG8_MMA(1, 0, At, B0); PG8_BAR; PG8_SCHED;
.LBB0_1667:
	s_ashr_i32 s29, s28, 31
	s_lshl_b64 s[0:1], s[28:29], 20
	s_add_u32 s30, s45, s0
	v_cmp_lt_i64_e32 vcc, s[8:9], v[140:141]
	s_addc_u32 s31, s46, s1
	s_and_b64 s[0:1], vcc, exec
	s_cselect_b32 s29, s31, s43
	s_cselect_b32 s35, s30, s42
	s_ashr_i32 s19, s18, 31
	s_lshl_b64 s[0:1], s[18:19], 20
	s_add_u32 s36, s47, s0
	s_addc_u32 s37, s48, s1
	s_and_b64 s[0:1], vcc, exec
	s_cselect_b32 s19, s37, s41
	s_cselect_b32 s65, s36, s40
	s_add_u32 s8, s42, 0x80080
	s_addc_u32 s9, s43, 0
	s_add_u32 s66, s40, 0x100
	v_mov_b32_e32 v8, 0
	s_addc_u32 s67, s41, 0
	s_mov_b32 s68, -2
	ds_read_b128 v[144:147], v149
	ds_read_b128 v[156:159], v149 offset:1024
	ds_read_b128 v[160:163], v149 offset:2048
	ds_read_b128 v[164:167], v149 offset:3072
	s_add_i32 m0, s39, 0xc000
	ds_read_b128 v[168:171], v150
	ds_read_b128 v[172:175], v150 offset:1024
	ds_read_b128 v[176:179], v150 offset:2048
	ds_read_b128 v[180:183], v150 offset:3072
	ds_read_b128 v[188:191], v150 offset:4096
	ds_read_b128 v[206:209], v150 offset:5120
	ds_read_b128 v[210:213], v150 offset:6144
	global_load_lds_dwordx4 v136, s[8:9]
	s_add_i32 m0, s39, 0xe000
	ds_read_b128 v[214:217], v150 offset:7168
	global_load_lds_dwordx4 v138, s[8:9]
	s_add_u32 s0, s8, 0xfff80080
	s_addc_u32 s1, s9, -1
	s_cmp_eq_u32 s68, 28
	s_cselect_b32 s43, s29, s1
	s_cselect_b32 s42, s35, s0
	s_cselect_b32 s41, s19, s67
	s_cselect_b32 s40, s65, s66
	s_waitcnt lgkmcnt(8)
	s_barrier
	s_waitcnt lgkmcnt(0)
	s_setprio 1
	v_mfma_f32_16x16x32_bf16 v[116:119], v[144:147], v[168:171], 0
	v_mfma_f32_16x16x32_bf16 v[112:115], v[160:163], v[168:171], 0
	v_mfma_f32_16x16x32_bf16 v[100:103], v[144:147], v[176:179], 0
	v_mfma_f32_16x16x32_bf16 v[96:99], v[160:163], v[176:179], 0
	v_mfma_f32_16x16x32_bf16 v[84:87], v[144:147], v[188:191], 0
	v_mfma_f32_16x16x32_bf16 v[80:83], v[160:163], v[188:191], 0
	v_mfma_f32_16x16x32_bf16 v[68:71], v[144:147], v[210:213], 0
	v_mfma_f32_16x16x32_bf16 v[64:67], v[160:163], v[210:213], 0
	v_mfma_f32_16x16x32_bf16 v[116:119], v[156:159], v[172:175], v[116:119]
	v_mfma_f32_16x16x32_bf16 v[112:115], v[164:167], v[172:175], v[112:115]
	v_mfma_f32_16x16x32_bf16 v[100:103], v[156:159], v[180:183], v[100:103]
	v_mfma_f32_16x16x32_bf16 v[96:99], v[164:167], v[180:183], v[96:99]
	v_mfma_f32_16x16x32_bf16 v[84:87], v[156:159], v[206:209], v[84:87]
	v_mfma_f32_16x16x32_bf16 v[80:83], v[164:167], v[206:209], v[80:83]
	v_mfma_f32_16x16x32_bf16 v[68:71], v[156:159], v[214:217], v[68:71]
	v_mfma_f32_16x16x32_bf16 v[64:67], v[164:167], v[214:217], v[64:67]
	s_setprio 0
	s_barrier
	s_add_i32 s0, s61, s50
	s_mov_b32 m0, s0
	ds_read_b128 v[218:221], v151
	ds_read_b128 v[222:225], v151 offset:1024
	ds_read_b128 v[226:229], v151 offset:2048
	global_load_lds_dwordx4 v130, s[40:41]
	s_add_i32 m0, s0, 0x2000
	ds_read_b128 v[230:233], v151 offset:3072
	global_load_lds_dwordx4 v134, s[40:41]
	s_barrier
	s_waitcnt lgkmcnt(0)
	s_setprio 1
	v_mfma_f32_16x16x32_bf16 v[124:127], v[218:221], v[168:171], 0
	v_mfma_f32_16x16x32_bf16 v[120:123], v[226:229], v[168:171], 0
	v_mfma_f32_16x16x32_bf16 v[108:111], v[218:221], v[176:179], 0
	v_mfma_f32_16x16x32_bf16 v[104:107], v[226:229], v[176:179], 0
	v_mfma_f32_16x16x32_bf16 v[92:95], v[218:221], v[188:191], 0
	v_mfma_f32_16x16x32_bf16 v[88:91], v[226:229], v[188:191], 0
	v_mfma_f32_16x16x32_bf16 v[76:79], v[218:221], v[210:213], 0
	v_mfma_f32_16x16x32_bf16 v[72:75], v[226:229], v[210:213], 0
	v_mfma_f32_16x16x32_bf16 v[124:127], v[222:225], v[172:175], v[124:127]
	v_mfma_f32_16x16x32_bf16 v[120:123], v[230:233], v[172:175], v[120:123]
	v_mfma_f32_16x16x32_bf16 v[108:111], v[222:225], v[180:183], v[108:111]
	v_mfma_f32_16x16x32_bf16 v[104:107], v[230:233], v[180:183], v[104:107]
	v_mfma_f32_16x16x32_bf16 v[92:95], v[222:225], v[206:209], v[92:95]
	v_mfma_f32_16x16x32_bf16 v[88:91], v[230:233], v[206:209], v[88:91]
	v_mfma_f32_16x16x32_bf16 v[76:79], v[222:225], v[214:217], v[76:79]
	v_mfma_f32_16x16x32_bf16 v[72:75], v[230:233], v[214:217], v[72:75]
	s_setprio 0
	s_mov_b32 m0, s39
	s_barrier
	ds_read_b128 v[168:171], v150 offset:16384
	ds_read_b128 v[172:175], v150 offset:17408
	ds_read_b128 v[176:179], v150 offset:18432
	ds_read_b128 v[180:183], v150 offset:19456
	ds_read_b128 v[188:191], v150 offset:20480
	ds_read_b128 v[206:209], v150 offset:21504
	ds_read_b128 v[210:213], v150 offset:22528
	global_load_lds_dwordx4 v128, s[42:43]
	s_mov_b32 m0, s51
	ds_read_b128 v[214:217], v150 offset:23552
	global_load_lds_dwordx4 v132, s[42:43]
	s_barrier
	s_waitcnt lgkmcnt(0)
	s_setprio 1
	v_mfma_f32_16x16x32_bf16 v[52:55], v[144:147], v[168:171], 0
	v_mfma_f32_16x16x32_bf16 v[48:51], v[160:163], v[168:171], 0
	v_mfma_f32_16x16x32_bf16 v[36:39], v[144:147], v[176:179], 0
	v_mfma_f32_16x16x32_bf16 v[32:35], v[160:163], v[176:179], 0
	v_mfma_f32_16x16x32_bf16 v[20:23], v[144:147], v[188:191], 0
	v_mfma_f32_16x16x32_bf16 v[16:19], v[160:163], v[188:191], 0
	v_mfma_f32_16x16x32_bf16 v[4:7], v[144:147], v[210:213], 0
	v_mfma_f32_16x16x32_bf16 v[0:3], v[160:163], v[210:213], 0
	v_mfma_f32_16x16x32_bf16 v[52:55], v[156:159], v[172:175], v[52:55]
	v_mfma_f32_16x16x32_bf16 v[48:51], v[164:167], v[172:175], v[48:51]
	v_mfma_f32_16x16x32_bf16 v[36:39], v[156:159], v[180:183], v[36:39]
	v_mfma_f32_16x16x32_bf16 v[32:35], v[164:167], v[180:183], v[32:35]
	v_mfma_f32_16x16x32_bf16 v[20:23], v[156:159], v[206:209], v[20:23]
	v_mfma_f32_16x16x32_bf16 v[16:19], v[164:167], v[206:209], v[16:19]
	v_mfma_f32_16x16x32_bf16 v[4:7], v[156:159], v[214:217], v[4:7]
	v_mfma_f32_16x16x32_bf16 v[0:3], v[164:167], v[214:217], v[0:3]
	s_setprio 0
	s_barrier
; #define PG8_STAGE(bufoff, gbase, voff) do { _Pragma("unroll") for (int _i = 0; _i < 2; ++_i) \
;         __builtin_amdgcn_global_load_lds((const unsigned*)((const char*)(gbase) + (voff)[_i]), (LAS unsigned*)(lds + (bufoff) + ldsw + _i * 8192), 16, 0, 0); } while (0)
; #define PG8_LDA(dst, b, h) do { _Pragma("unroll") for (int m = 0; m < 4; ++m) _Pragma("unroll") for (int k = 0; k < 2; ++k) dst[m][k] = *(const LAS bf16x8*)(lds + PG8_SA(b, h) + aoff + m * 2048 + k * 1024); } while (0)
; #define PG8_LDB(dst, b, h) do { _Pragma("unroll") for (int n = 0; n < 2; ++n) _Pragma("unroll") for (int k = 0; k < 2; ++k) dst[n][k] = *(const LAS bf16x8*)(lds + PG8_SB(b, h) + boff + n * 2048 + k * 1024); } while (0)
; #define PG8_MMA(ai, bj, At, Bt) do { __builtin_amdgcn_s_setprio(1); _Pragma("unroll") for (int m = 0; m < 4; ++m) _Pragma("unroll") for (int n = 0; n < 2; ++n) _Pragma("unroll") for (int k = 0; k < 2; ++k) \
;         acc[ai][bj][m][n] = __builtin_amdgcn_mfma_f32_16x16x32_bf16(Bt[n][k], At[m][k], acc[ai][bj][m][n], 0, 0, 0); __builtin_amdgcn_s_setprio(0); } while (0)
; #define PG8_WAIT_V(n) asm volatile("s_waitcnt vmcnt(" #n ")" ::: "memory")
; #define PG8_WAIT_L(n) asm volatile("s_waitcnt lgkmcnt(" #n ")" ::: "memory")
; #define PG8_BAR __builtin_amdgcn_s_barrier()
; #define PG8_SCHED __builtin_amdgcn_sched_barrier(0)
; template <class Epi, class Sched>
; DI void gemm_phase(LAS unsigned char* lds, const Gemm g, const Sched& S, const Epi& E) {
;     ...
;             PG8_STAGE(PG8_SB(0, 1), b2 + hstep, voffB);
;             PG8_WAIT_V(6); PG8_BAR; PG8_MMA(1, 1, At, B1); PG8_BAR;
;             PG8_LDB(B0, 1, 0); PG8_SCHED; PG8_LDA(At, 1, 0); PG8_STAGE(PG8_SA(0, 1), a2 + hstep, voffA);
;             PG8_WAIT_L(8); PG8_BAR; PG8_WAIT_L(0); PG8_MMA(0, 0, At, B0); PG8_BAR; PG8_SCHED;
	s_add_i32 s4, s62, s50
	s_mov_b32 m0, s4
	s_add_u32 s0, s40, 0x80000
	s_addc_u32 s1, s41, 0
	global_load_lds_dwordx4 v130, s[0:1]
	s_add_i32 m0, s4, 0x2000
	s_add_i32 s4, 0, 0x18000
	global_load_lds_dwordx4 v134, s[0:1]
	s_waitcnt vmcnt(6)
	s_barrier
	s_setprio 1
	v_mfma_f32_16x16x32_bf16 v[60:63], v[218:221], v[168:171], 0
	v_mfma_f32_16x16x32_bf16 v[56:59], v[226:229], v[168:171], 0
	v_mfma_f32_16x16x32_bf16 v[44:47], v[218:221], v[176:179], 0
	v_mfma_f32_16x16x32_bf16 v[40:43], v[226:229], v[176:179], 0
	v_mfma_f32_16x16x32_bf16 v[28:31], v[218:221], v[188:191], 0
	v_mfma_f32_16x16x32_bf16 v[24:27], v[226:229], v[188:191], 0
	v_mfma_f32_16x16x32_bf16 v[12:15], v[218:221], v[210:213], 0
	v_mfma_f32_16x16x32_bf16 v[8:11], v[226:229], v[210:213], 0
	v_mfma_f32_16x16x32_bf16 v[60:63], v[222:225], v[172:175], v[60:63]
	v_mfma_f32_16x16x32_bf16 v[56:59], v[230:233], v[172:175], v[56:59]
	v_mfma_f32_16x16x32_bf16 v[44:47], v[222:225], v[180:183], v[44:47]
	v_mfma_f32_16x16x32_bf16 v[40:43], v[230:233], v[180:183], v[40:43]
	v_mfma_f32_16x16x32_bf16 v[28:31], v[222:225], v[206:209], v[28:31]
	v_mfma_f32_16x16x32_bf16 v[24:27], v[230:233], v[206:209], v[24:27]
	v_mfma_f32_16x16x32_bf16 v[12:15], v[222:225], v[214:217], v[12:15]
	v_mfma_f32_16x16x32_bf16 v[8:11], v[230:233], v[214:217], v[8:11]
	s_setprio 0
	v_add_u32_e32 v202, s4, v148
	s_barrier
	ds_read_b128 v[144:147], v202
	ds_read_b128 v[156:159], v202 offset:1024
	ds_read_b128 v[160:163], v202 offset:2048
	ds_read_b128 v[164:167], v202 offset:3072
	s_add_u32 s0, s42, 0x80000
	s_addc_u32 s1, s43, 0
	s_mov_b32 m0, s52
	ds_read_b128 v[168:171], v150 offset:32768
	ds_read_b128 v[172:175], v150 offset:33792
	ds_read_b128 v[176:179], v150 offset:34816
	ds_read_b128 v[180:183], v150 offset:35840
	ds_read_b128 v[188:191], v150 offset:36864
	ds_read_b128 v[206:209], v150 offset:37888
	ds_read_b128 v[210:213], v150 offset:38912
	global_load_lds_dwordx4 v128, s[0:1]
	s_mov_b32 m0, s53
	ds_read_b128 v[214:217], v150 offset:39936
	global_load_lds_dwordx4 v132, s[0:1]
	s_waitcnt lgkmcnt(8)
	s_barrier
	s_waitcnt lgkmcnt(0)
	s_setprio 1
	v_mfma_f32_16x16x32_bf16 v[116:119], v[144:147], v[168:171], v[116:119]
	v_mfma_f32_16x16x32_bf16 v[112:115], v[160:163], v[168:171], v[112:115]
	v_mfma_f32_16x16x32_bf16 v[100:103], v[144:147], v[176:179], v[100:103]
	v_mfma_f32_16x16x32_bf16 v[96:99], v[160:163], v[176:179], v[96:99]
	v_mfma_f32_16x16x32_bf16 v[84:87], v[144:147], v[188:191], v[84:87]
	v_mfma_f32_16x16x32_bf16 v[80:83], v[160:163], v[188:191], v[80:83]
	v_mfma_f32_16x16x32_bf16 v[68:71], v[144:147], v[210:213], v[68:71]
	v_mfma_f32_16x16x32_bf16 v[64:67], v[160:163], v[210:213], v[64:67]
	v_mfma_f32_16x16x32_bf16 v[116:119], v[156:159], v[172:175], v[116:119]
	v_mfma_f32_16x16x32_bf16 v[112:115], v[164:167], v[172:175], v[112:115]
	v_mfma_f32_16x16x32_bf16 v[100:103], v[156:159], v[180:183], v[100:103]
	v_mfma_f32_16x16x32_bf16 v[96:99], v[164:167], v[180:183], v[96:99]
	v_mfma_f32_16x16x32_bf16 v[84:87], v[156:159], v[206:209], v[84:87]
	v_mfma_f32_16x16x32_bf16 v[80:83], v[164:167], v[206:209], v[80:83]
	v_mfma_f32_16x16x32_bf16 v[68:71], v[156:159], v[214:217], v[68:71]
	v_mfma_f32_16x16x32_bf16 v[64:67], v[164:167], v[214:217], v[64:67]
	s_setprio 0
	s_barrier
	s_add_i32 s5, 0, 0x1c000
	s_add_i32 s0, s4, s50
	v_add_u32_e32 v203, s5, v148
	s_add_i32 m0, s0, 0xffffff80
	ds_read_b128 v[218:221], v203
	ds_read_b128 v[222:225], v203 offset:1024
	ds_read_b128 v[226:229], v203 offset:2048
	global_load_lds_dwordx4 v130, s[40:41] offset:128
	s_add_i32 m0, s0, 0x1f80
	ds_read_b128 v[230:233], v203 offset:3072
	global_load_lds_dwordx4 v134, s[40:41] offset:128
	s_barrier
; #define PG8_STAGE(bufoff, gbase, voff) do { _Pragma("unroll") for (int _i = 0; _i < 2; ++_i) \
;         __builtin_amdgcn_global_load_lds((const unsigned*)((const char*)(gbase) + (voff)[_i]), (LAS unsigned*)(lds + (bufoff) + ldsw + _i * 8192), 16, 0, 0); } while (0)
; #define PG8_LDA(dst, b, h) do { _Pragma("unroll") for (int m = 0; m < 4; ++m) _Pragma("unroll") for (int k = 0; k < 2; ++k) dst[m][k] = *(const LAS bf16x8*)(lds + PG8_SA(b, h) + aoff + m * 2048 + k * 1024); } while (0)
; #define PG8_LDB(dst, b, h) do { _Pragma("unroll") for (int n = 0; n < 2; ++n) _Pragma("unroll") for (int k = 0; k < 2; ++k) dst[n][k] = *(const LAS bf16x8*)(lds + PG8_SB(b, h) + boff + n * 2048 + k * 1024); } while (0)
; #define PG8_MMA(ai, bj, At, Bt) do { __builtin_amdgcn_s_setprio(1); _Pragma("unroll") for (int m = 0; m < 4; ++m) _Pragma("unroll") for (int n = 0; n < 2; ++n) _Pragma("unroll") for (int k = 0; k < 2; ++k) \
;         acc[ai][bj][m][n] = __builtin_amdgcn_mfma_f32_16x16x32_bf16(Bt[n][k], At[m][k], acc[ai][bj][m][n], 0, 0, 0); __builtin_amdgcn_s_setprio(0); } while (0)
; #define PG8_WAIT_V(n) asm volatile("s_waitcnt vmcnt(" #n ")" ::: "memory")
; #define PG8_WAIT_L(n) asm volatile("s_waitcnt lgkmcnt(" #n ")" ::: "memory")
; #define PG8_BAR __builtin_amdgcn_s_barrier()
; #define PG8_SCHED __builtin_amdgcn_sched_barrier(0)
; template <class Epi, class Sched>
; DI void gemm_phase(LAS unsigned char* lds, const Gemm g, const Sched& S, const Epi& E) {
;     ...
;             PG8_WAIT_L(8); PG8_BAR; PG8_WAIT_L(0); PG8_MMA(0, 0, At, B0); PG8_BAR; PG8_SCHED;
;             PG8_LDB(B1, 1, 1); PG8_STAGE(PG8_SB(1, 0), b3, voffB);
;             PG8_BAR; PG8_WAIT_L(0); PG8_MMA(0, 1, At, B1); PG8_BAR;
;             PG8_LDA(At, 1, 1); PG8_STAGE(PG8_SA(1, 0), a3, voffA);
;             PG8_BAR; PG8_WAIT_L(0); PG8_MMA(1, 0, At, B0); PG8_BAR; PG8_SCHED;
;             PG8_STAGE(PG8_SB(1, 1), b3 + hstep, voffB);
;             PG8_WAIT_V(6); PG8_BAR; PG8_MMA(1, 1, At, B1); PG8_BAR;
	s_waitcnt lgkmcnt(0)
	s_setprio 1
	v_mfma_f32_16x16x32_bf16 v[124:127], v[218:221], v[168:171], v[124:127]
	v_mfma_f32_16x16x32_bf16 v[120:123], v[226:229], v[168:171], v[120:123]
	v_mfma_f32_16x16x32_bf16 v[108:111], v[218:221], v[176:179], v[108:111]
	v_mfma_f32_16x16x32_bf16 v[104:107], v[226:229], v[176:179], v[104:107]
	v_mfma_f32_16x16x32_bf16 v[92:95], v[218:221], v[188:191], v[92:95]
	v_mfma_f32_16x16x32_bf16 v[88:91], v[226:229], v[188:191], v[88:91]
	v_mfma_f32_16x16x32_bf16 v[76:79], v[218:221], v[210:213], v[76:79]
	v_mfma_f32_16x16x32_bf16 v[72:75], v[226:229], v[210:213], v[72:75]
	v_mfma_f32_16x16x32_bf16 v[124:127], v[222:225], v[172:175], v[124:127]
	v_mfma_f32_16x16x32_bf16 v[120:123], v[230:233], v[172:175], v[120:123]
	v_mfma_f32_16x16x32_bf16 v[108:111], v[222:225], v[180:183], v[108:111]
	v_mfma_f32_16x16x32_bf16 v[104:107], v[230:233], v[180:183], v[104:107]
	v_mfma_f32_16x16x32_bf16 v[92:95], v[222:225], v[206:209], v[92:95]
	v_mfma_f32_16x16x32_bf16 v[88:91], v[230:233], v[206:209], v[88:91]
	v_mfma_f32_16x16x32_bf16 v[76:79], v[222:225], v[214:217], v[76:79]
	v_mfma_f32_16x16x32_bf16 v[72:75], v[230:233], v[214:217], v[72:75]
	s_setprio 0
	s_add_i32 m0, s57, 0xffffff80
	s_barrier
	ds_read_b128 v[168:171], v150 offset:49152
	ds_read_b128 v[172:175], v150 offset:50176
	ds_read_b128 v[176:179], v150 offset:51200
	ds_read_b128 v[180:183], v150 offset:52224
	ds_read_b128 v[188:191], v150 offset:53248
	ds_read_b128 v[206:209], v150 offset:54272
	ds_read_b128 v[210:213], v150 offset:55296
	global_load_lds_dwordx4 v128, s[42:43] offset:128
	s_add_i32 m0, s58, 0xffffff80
	ds_read_b128 v[214:217], v150 offset:56320
	global_load_lds_dwordx4 v132, s[42:43] offset:128
	s_barrier
	s_waitcnt lgkmcnt(0)
	s_setprio 1
	v_mfma_f32_16x16x32_bf16 v[52:55], v[144:147], v[168:171], v[52:55]
	v_mfma_f32_16x16x32_bf16 v[48:51], v[160:163], v[168:171], v[48:51]
	v_mfma_f32_16x16x32_bf16 v[36:39], v[144:147], v[176:179], v[36:39]
	v_mfma_f32_16x16x32_bf16 v[32:35], v[160:163], v[176:179], v[32:35]
	v_mfma_f32_16x16x32_bf16 v[20:23], v[144:147], v[188:191], v[20:23]
	v_mfma_f32_16x16x32_bf16 v[16:19], v[160:163], v[188:191], v[16:19]
	v_mfma_f32_16x16x32_bf16 v[4:7], v[144:147], v[210:213], v[4:7]
	v_mfma_f32_16x16x32_bf16 v[0:3], v[160:163], v[210:213], v[0:3]
	v_mfma_f32_16x16x32_bf16 v[52:55], v[156:159], v[172:175], v[52:55]
	v_mfma_f32_16x16x32_bf16 v[48:51], v[164:167], v[172:175], v[48:51]
	v_mfma_f32_16x16x32_bf16 v[36:39], v[156:159], v[180:183], v[36:39]
	v_mfma_f32_16x16x32_bf16 v[32:35], v[164:167], v[180:183], v[32:35]
	v_mfma_f32_16x16x32_bf16 v[20:23], v[156:159], v[206:209], v[20:23]
	v_mfma_f32_16x16x32_bf16 v[16:19], v[164:167], v[206:209], v[16:19]
	v_mfma_f32_16x16x32_bf16 v[4:7], v[156:159], v[214:217], v[4:7]
	v_mfma_f32_16x16x32_bf16 v[0:3], v[164:167], v[214:217], v[0:3]
	s_setprio 0
	s_barrier
	s_add_i32 s4, s5, s50
	s_mov_b32 m0, s4
	s_add_u32 s0, s40, 0x80080
	s_addc_u32 s1, s41, 0
	global_load_lds_dwordx4 v130, s[0:1]
	s_add_i32 m0, s4, 0x2000
	s_add_i32 s68, s68, 2
	global_load_lds_dwordx4 v134, s[0:1]
	s_add_u32 s8, s8, 0x100
	s_addc_u32 s9, s9, 0
	s_add_u32 s66, s66, 0x100
	s_addc_u32 s67, s67, 0
	s_cmp_gt_u32 s68, 29
	s_waitcnt vmcnt(6)
	s_barrier
	s_setprio 1
	v_mfma_f32_16x16x32_bf16 v[60:63], v[218:221], v[168:171], v[60:63]
	v_mfma_f32_16x16x32_bf16 v[56:59], v[226:229], v[168:171], v[56:59]
	v_mfma_f32_16x16x32_bf16 v[44:47], v[218:221], v[176:179], v[44:47]
	v_mfma_f32_16x16x32_bf16 v[40:43], v[226:229], v[176:179], v[40:43]
	v_mfma_f32_16x16x32_bf16 v[28:31], v[218:221], v[188:191], v[28:31]
	v_mfma_f32_16x16x32_bf16 v[24:27], v[226:229], v[188:191], v[24:27]
	v_mfma_f32_16x16x32_bf16 v[12:15], v[218:221], v[210:213], v[12:15]
	v_mfma_f32_16x16x32_bf16 v[8:11], v[226:229], v[210:213], v[8:11]
	v_mfma_f32_16x16x32_bf16 v[60:63], v[222:225], v[172:175], v[60:63]
	v_mfma_f32_16x16x32_bf16 v[56:59], v[230:233], v[172:175], v[56:59]
	v_mfma_f32_16x16x32_bf16 v[44:47], v[222:225], v[180:183], v[44:47]
	v_mfma_f32_16x16x32_bf16 v[40:43], v[230:233], v[180:183], v[40:43]
	v_mfma_f32_16x16x32_bf16 v[28:31], v[222:225], v[206:209], v[28:31]
	v_mfma_f32_16x16x32_bf16 v[24:27], v[230:233], v[206:209], v[24:27]
	v_mfma_f32_16x16x32_bf16 v[12:15], v[222:225], v[214:217], v[12:15]
	v_mfma_f32_16x16x32_bf16 v[8:11], v[230:233], v[214:217], v[8:11]
	s_setprio 0
	s_cbranch_scc0 .Lrot_1668
	s_barrier
	s_branch .Lpeel_done_1668

; #define PG8_STAGE(bufoff, gbase, voff) do { _Pragma("unroll") for (int _i = 0; _i < 2; ++_i) \
;         __builtin_amdgcn_global_load_lds((const unsigned*)((const char*)(gbase) + (voff)[_i]), (LAS unsigned*)(lds + (bufoff) + ldsw + _i * 8192), 16, 0, 0); } while (0)
; #define PG8_LDA(dst, b, h) do { _Pragma("unroll") for (int m = 0; m < 4; ++m) _Pragma("unroll") for (int k = 0; k < 2; ++k) dst[m][k] = *(const LAS bf16x8*)(lds + PG8_SA(b, h) + aoff + m * 2048 + k * 1024); } while (0)
; #define PG8_LDB(dst, b, h) do { _Pragma("unroll") for (int n = 0; n < 2; ++n) _Pragma("unroll") for (int k = 0; k < 2; ++k) dst[n][k] = *(const LAS bf16x8*)(lds + PG8_SB(b, h) + boff + n * 2048 + k * 1024); } while (0)
; #define PG8_MMA(ai, bj, At, Bt) do { __builtin_amdgcn_s_setprio(1); _Pragma("unroll") for (int m = 0; m < 4; ++m) _Pragma("unroll") for (int n = 0; n < 2; ++n) _Pragma("unroll") for (int k = 0; k < 2; ++k) \
;         acc[ai][bj][m][n] = __builtin_amdgcn_mfma_f32_16x16x32_bf16(Bt[n][k], At[m][k], acc[ai][bj][m][n], 0, 0, 0); __builtin_amdgcn_s_setprio(0); } while (0)
; #define PG8_WAIT_V(n) asm volatile("s_waitcnt vmcnt(" #n ")" ::: "memory")
; #define PG8_WAIT_L(n) asm volatile("s_waitcnt lgkmcnt(" #n ")" ::: "memory")
; #define PG8_BAR __builtin_amdgcn_s_barrier()
; #define PG8_SCHED __builtin_amdgcn_sched_barrier(0)
; template <class Epi, class Sched>
; DI void gemm_phase(LAS unsigned char* lds, const Gemm g, const Sched& S, const Epi& E) {
;     ...
;             PG8_LDB(B0, 0, 0); PG8_SCHED; PG8_LDA(At, 0, 0); PG8_STAGE(PG8_SA(1, 1), a1 + hstep, voffA);
;             PG8_WAIT_L(8); PG8_BAR; PG8_WAIT_L(0); PG8_MMA(0, 0, At, B0); PG8_BAR; PG8_SCHED;
;             PG8_LDB(B1, 0, 1); PG8_STAGE(PG8_SB(0, 0), b2, voffB);
;             PG8_BAR; PG8_WAIT_L(0); PG8_MMA(0, 1, At, B1); PG8_BAR;
;             PG8_LDA(At, 0, 1); PG8_STAGE(PG8_SA(0, 0), a2, voffA);
;             PG8_BAR; PG8_WAIT_L(0); PG8_MMA(1, 0, At, B0); PG8_BAR; PG8_SCHED;
;             PG8_STAGE(PG8_SB(0, 1), b2 + hstep, voffB);
;             PG8_WAIT_V(6); PG8_BAR; PG8_MMA(1, 1, At, B1); PG8_BAR;
.LBB0_1668:
	ds_read_b128 v[144:147], v149
	ds_read_b128 v[156:159], v149 offset:1024
	ds_read_b128 v[160:163], v149 offset:2048
	ds_read_b128 v[164:167], v149 offset:3072
	s_add_i32 m0, s39, 0xc000
	ds_read_b128 v[168:171], v150
	ds_read_b128 v[172:175], v150 offset:1024
	ds_read_b128 v[176:179], v150 offset:2048
	ds_read_b128 v[180:183], v150 offset:3072
	ds_read_b128 v[188:191], v150 offset:4096
	ds_read_b128 v[206:209], v150 offset:5120
	ds_read_b128 v[210:213], v150 offset:6144
	global_load_lds_dwordx4 v136, s[8:9]
	s_add_i32 m0, s39, 0xe000
	ds_read_b128 v[214:217], v150 offset:7168
	global_load_lds_dwordx4 v138, s[8:9]
	s_add_u32 s0, s8, 0xfff80080
	s_addc_u32 s1, s9, -1
	s_cmp_eq_u32 s68, 28
	s_cselect_b32 s43, s29, s1
	s_cselect_b32 s42, s35, s0
	s_cselect_b32 s41, s19, s67
	s_cselect_b32 s40, s65, s66
	s_waitcnt lgkmcnt(8)
	s_barrier
	s_waitcnt lgkmcnt(0)
	s_setprio 1
	v_mfma_f32_16x16x32_bf16 v[116:119], v[144:147], v[168:171], v[116:119]
	v_mfma_f32_16x16x32_bf16 v[112:115], v[160:163], v[168:171], v[112:115]
	v_mfma_f32_16x16x32_bf16 v[100:103], v[144:147], v[176:179], v[100:103]
	v_mfma_f32_16x16x32_bf16 v[96:99], v[160:163], v[176:179], v[96:99]
	v_mfma_f32_16x16x32_bf16 v[84:87], v[144:147], v[188:191], v[84:87]
	v_mfma_f32_16x16x32_bf16 v[80:83], v[160:163], v[188:191], v[80:83]
	v_mfma_f32_16x16x32_bf16 v[68:71], v[144:147], v[210:213], v[68:71]
	v_mfma_f32_16x16x32_bf16 v[64:67], v[160:163], v[210:213], v[64:67]
	v_mfma_f32_16x16x32_bf16 v[116:119], v[156:159], v[172:175], v[116:119]
	v_mfma_f32_16x16x32_bf16 v[112:115], v[164:167], v[172:175], v[112:115]
	v_mfma_f32_16x16x32_bf16 v[100:103], v[156:159], v[180:183], v[100:103]
	v_mfma_f32_16x16x32_bf16 v[96:99], v[164:167], v[180:183], v[96:99]
	v_mfma_f32_16x16x32_bf16 v[84:87], v[156:159], v[206:209], v[84:87]
	v_mfma_f32_16x16x32_bf16 v[80:83], v[164:167], v[206:209], v[80:83]
	v_mfma_f32_16x16x32_bf16 v[68:71], v[156:159], v[214:217], v[68:71]
	v_mfma_f32_16x16x32_bf16 v[64:67], v[164:167], v[214:217], v[64:67]
	s_setprio 0
	s_barrier
	s_add_i32 s0, s61, s50
	s_mov_b32 m0, s0
	ds_read_b128 v[218:221], v151
	ds_read_b128 v[222:225], v151 offset:1024
	ds_read_b128 v[226:229], v151 offset:2048
	global_load_lds_dwordx4 v130, s[40:41]
	s_add_i32 m0, s0, 0x2000
	ds_read_b128 v[230:233], v151 offset:3072
	global_load_lds_dwordx4 v134, s[40:41]
	s_barrier
	s_waitcnt lgkmcnt(0)
	s_setprio 1
	v_mfma_f32_16x16x32_bf16 v[124:127], v[218:221], v[168:171], v[124:127]
	v_mfma_f32_16x16x32_bf16 v[120:123], v[226:229], v[168:171], v[120:123]
	v_mfma_f32_16x16x32_bf16 v[108:111], v[218:221], v[176:179], v[108:111]
	v_mfma_f32_16x16x32_bf16 v[104:107], v[226:229], v[176:179], v[104:107]
	v_mfma_f32_16x16x32_bf16 v[92:95], v[218:221], v[188:191], v[92:95]
	v_mfma_f32_16x16x32_bf16 v[88:91], v[226:229], v[188:191], v[88:91]
	v_mfma_f32_16x16x32_bf16 v[76:79], v[218:221], v[210:213], v[76:79]
	v_mfma_f32_16x16x32_bf16 v[72:75], v[226:229], v[210:213], v[72:75]
	v_mfma_f32_16x16x32_bf16 v[124:127], v[222:225], v[172:175], v[124:127]
	v_mfma_f32_16x16x32_bf16 v[120:123], v[230:233], v[172:175], v[120:123]
	v_mfma_f32_16x16x32_bf16 v[108:111], v[222:225], v[180:183], v[108:111]
	v_mfma_f32_16x16x32_bf16 v[104:107], v[230:233], v[180:183], v[104:107]
	v_mfma_f32_16x16x32_bf16 v[92:95], v[222:225], v[206:209], v[92:95]
	v_mfma_f32_16x16x32_bf16 v[88:91], v[230:233], v[206:209], v[88:91]
	v_mfma_f32_16x16x32_bf16 v[76:79], v[222:225], v[214:217], v[76:79]
	v_mfma_f32_16x16x32_bf16 v[72:75], v[230:233], v[214:217], v[72:75]
	s_setprio 0
	s_mov_b32 m0, s39
	s_barrier
	ds_read_b128 v[168:171], v150 offset:16384
	ds_read_b128 v[172:175], v150 offset:17408
	ds_read_b128 v[176:179], v150 offset:18432
	ds_read_b128 v[180:183], v150 offset:19456
	ds_read_b128 v[188:191], v150 offset:20480
	ds_read_b128 v[206:209], v150 offset:21504
	ds_read_b128 v[210:213], v150 offset:22528
	global_load_lds_dwordx4 v128, s[42:43]
	s_mov_b32 m0, s51
	ds_read_b128 v[214:217], v150 offset:23552
	global_load_lds_dwordx4 v132, s[42:43]
	s_barrier
	s_waitcnt lgkmcnt(0)
	s_setprio 1
	v_mfma_f32_16x16x32_bf16 v[52:55], v[144:147], v[168:171], v[52:55]
	v_mfma_f32_16x16x32_bf16 v[48:51], v[160:163], v[168:171], v[48:51]
	v_mfma_f32_16x16x32_bf16 v[36:39], v[144:147], v[176:179], v[36:39]
	v_mfma_f32_16x16x32_bf16 v[32:35], v[160:163], v[176:179], v[32:35]
	v_mfma_f32_16x16x32_bf16 v[20:23], v[144:147], v[188:191], v[20:23]
	v_mfma_f32_16x16x32_bf16 v[16:19], v[160:163], v[188:191], v[16:19]
	v_mfma_f32_16x16x32_bf16 v[4:7], v[144:147], v[210:213], v[4:7]
	v_mfma_f32_16x16x32_bf16 v[0:3], v[160:163], v[210:213], v[0:3]
	v_mfma_f32_16x16x32_bf16 v[52:55], v[156:159], v[172:175], v[52:55]
	v_mfma_f32_16x16x32_bf16 v[48:51], v[164:167], v[172:175], v[48:51]
	v_mfma_f32_16x16x32_bf16 v[36:39], v[156:159], v[180:183], v[36:39]
	v_mfma_f32_16x16x32_bf16 v[32:35], v[164:167], v[180:183], v[32:35]
	v_mfma_f32_16x16x32_bf16 v[20:23], v[156:159], v[206:209], v[20:23]
	v_mfma_f32_16x16x32_bf16 v[16:19], v[164:167], v[206:209], v[16:19]
	v_mfma_f32_16x16x32_bf16 v[4:7], v[156:159], v[214:217], v[4:7]
	v_mfma_f32_16x16x32_bf16 v[0:3], v[164:167], v[214:217], v[0:3]
	s_setprio 0
	s_barrier
	s_add_i32 s4, s62, s50
	s_mov_b32 m0, s4
	s_add_u32 s0, s40, 0x80000
	s_addc_u32 s1, s41, 0
	global_load_lds_dwordx4 v130, s[0:1]
	s_add_i32 m0, s4, 0x2000
	s_add_i32 s4, 0, 0x18000
	global_load_lds_dwordx4 v134, s[0:1]
	s_waitcnt vmcnt(6)
	s_barrier
; #define PG8_STAGE(bufoff, gbase, voff) do { _Pragma("unroll") for (int _i = 0; _i < 2; ++_i) \
;         __builtin_amdgcn_global_load_lds((const unsigned*)((const char*)(gbase) + (voff)[_i]), (LAS unsigned*)(lds + (bufoff) + ldsw + _i * 8192), 16, 0, 0); } while (0)
; #define PG8_LDA(dst, b, h) do { _Pragma("unroll") for (int m = 0; m < 4; ++m) _Pragma("unroll") for (int k = 0; k < 2; ++k) dst[m][k] = *(const LAS bf16x8*)(lds + PG8_SA(b, h) + aoff + m * 2048 + k * 1024); } while (0)
; #define PG8_LDB(dst, b, h) do { _Pragma("unroll") for (int n = 0; n < 2; ++n) _Pragma("unroll") for (int k = 0; k < 2; ++k) dst[n][k] = *(const LAS bf16x8*)(lds + PG8_SB(b, h) + boff + n * 2048 + k * 1024); } while (0)
; #define PG8_MMA(ai, bj, At, Bt) do { __builtin_amdgcn_s_setprio(1); _Pragma("unroll") for (int m = 0; m < 4; ++m) _Pragma("unroll") for (int n = 0; n < 2; ++n) _Pragma("unroll") for (int k = 0; k < 2; ++k) \
;         acc[ai][bj][m][n] = __builtin_amdgcn_mfma_f32_16x16x32_bf16(Bt[n][k], At[m][k], acc[ai][bj][m][n], 0, 0, 0); __builtin_amdgcn_s_setprio(0); } while (0)
; #define PG8_WAIT_V(n) asm volatile("s_waitcnt vmcnt(" #n ")" ::: "memory")
; #define PG8_WAIT_L(n) asm volatile("s_waitcnt lgkmcnt(" #n ")" ::: "memory")
; #define PG8_BAR __builtin_amdgcn_s_barrier()
; #define PG8_SCHED __builtin_amdgcn_sched_barrier(0)
; template <class Epi, class Sched>
; DI void gemm_phase(LAS unsigned char* lds, const Gemm g, const Sched& S, const Epi& E) {
;     ...
;             PG8_WAIT_V(6); PG8_BAR; PG8_MMA(1, 1, At, B1); PG8_BAR;
;             PG8_LDB(B0, 1, 0); PG8_SCHED; PG8_LDA(At, 1, 0); PG8_STAGE(PG8_SA(0, 1), a2 + hstep, voffA);
;             PG8_WAIT_L(8); PG8_BAR; PG8_WAIT_L(0); PG8_MMA(0, 0, At, B0); PG8_BAR; PG8_SCHED;
	s_setprio 1
	v_mfma_f32_16x16x32_bf16 v[60:63], v[218:221], v[168:171], v[60:63]
	v_mfma_f32_16x16x32_bf16 v[56:59], v[226:229], v[168:171], v[56:59]
	v_mfma_f32_16x16x32_bf16 v[44:47], v[218:221], v[176:179], v[44:47]
	v_mfma_f32_16x16x32_bf16 v[40:43], v[226:229], v[176:179], v[40:43]
	v_mfma_f32_16x16x32_bf16 v[28:31], v[218:221], v[188:191], v[28:31]
	v_mfma_f32_16x16x32_bf16 v[24:27], v[226:229], v[188:191], v[24:27]
	v_mfma_f32_16x16x32_bf16 v[12:15], v[218:221], v[210:213], v[12:15]
	v_mfma_f32_16x16x32_bf16 v[8:11], v[226:229], v[210:213], v[8:11]
	v_mfma_f32_16x16x32_bf16 v[60:63], v[222:225], v[172:175], v[60:63]
	v_mfma_f32_16x16x32_bf16 v[56:59], v[230:233], v[172:175], v[56:59]
	v_mfma_f32_16x16x32_bf16 v[44:47], v[222:225], v[180:183], v[44:47]
	v_mfma_f32_16x16x32_bf16 v[40:43], v[230:233], v[180:183], v[40:43]
	v_mfma_f32_16x16x32_bf16 v[28:31], v[222:225], v[206:209], v[28:31]
	v_mfma_f32_16x16x32_bf16 v[24:27], v[230:233], v[206:209], v[24:27]
	v_mfma_f32_16x16x32_bf16 v[12:15], v[222:225], v[214:217], v[12:15]
	v_mfma_f32_16x16x32_bf16 v[8:11], v[230:233], v[214:217], v[8:11]
	s_setprio 0
	s_barrier
	ds_read_b128 v[144:147], v202
	ds_read_b128 v[156:159], v202 offset:1024
	ds_read_b128 v[160:163], v202 offset:2048
	ds_read_b128 v[164:167], v202 offset:3072
	s_add_u32 s0, s42, 0x80000
	s_addc_u32 s1, s43, 0
	s_mov_b32 m0, s52
	ds_read_b128 v[168:171], v150 offset:32768
	ds_read_b128 v[172:175], v150 offset:33792
	ds_read_b128 v[176:179], v150 offset:34816
	ds_read_b128 v[180:183], v150 offset:35840
	ds_read_b128 v[188:191], v150 offset:36864
	ds_read_b128 v[206:209], v150 offset:37888
	ds_read_b128 v[210:213], v150 offset:38912
	global_load_lds_dwordx4 v128, s[0:1]
	s_mov_b32 m0, s53
	ds_read_b128 v[214:217], v150 offset:39936
	global_load_lds_dwordx4 v132, s[0:1]
	s_waitcnt lgkmcnt(8)
	s_barrier
	s_waitcnt lgkmcnt(0)
	s_setprio 1
	v_mfma_f32_16x16x32_bf16 v[116:119], v[144:147], v[168:171], v[116:119]
	v_mfma_f32_16x16x32_bf16 v[112:115], v[160:163], v[168:171], v[112:115]
	v_mfma_f32_16x16x32_bf16 v[100:103], v[144:147], v[176:179], v[100:103]
	v_mfma_f32_16x16x32_bf16 v[96:99], v[160:163], v[176:179], v[96:99]
	v_mfma_f32_16x16x32_bf16 v[84:87], v[144:147], v[188:191], v[84:87]
	v_mfma_f32_16x16x32_bf16 v[80:83], v[160:163], v[188:191], v[80:83]
	v_mfma_f32_16x16x32_bf16 v[68:71], v[144:147], v[210:213], v[68:71]
	v_mfma_f32_16x16x32_bf16 v[64:67], v[160:163], v[210:213], v[64:67]
	v_mfma_f32_16x16x32_bf16 v[116:119], v[156:159], v[172:175], v[116:119]
	v_mfma_f32_16x16x32_bf16 v[112:115], v[164:167], v[172:175], v[112:115]
	v_mfma_f32_16x16x32_bf16 v[100:103], v[156:159], v[180:183], v[100:103]
	v_mfma_f32_16x16x32_bf16 v[96:99], v[164:167], v[180:183], v[96:99]
	v_mfma_f32_16x16x32_bf16 v[84:87], v[156:159], v[206:209], v[84:87]
	v_mfma_f32_16x16x32_bf16 v[80:83], v[164:167], v[206:209], v[80:83]
	v_mfma_f32_16x16x32_bf16 v[68:71], v[156:159], v[214:217], v[68:71]
	v_mfma_f32_16x16x32_bf16 v[64:67], v[164:167], v[214:217], v[64:67]
	s_setprio 0
	s_barrier
	s_add_i32 s5, 0, 0x1c000
	s_add_i32 s0, s4, s50
	s_add_i32 m0, s0, 0xffffff80
	ds_read_b128 v[218:221], v203
	ds_read_b128 v[222:225], v203 offset:1024
	ds_read_b128 v[226:229], v203 offset:2048
	global_load_lds_dwordx4 v130, s[40:41] offset:128
	s_add_i32 m0, s0, 0x1f80
	ds_read_b128 v[230:233], v203 offset:3072
	global_load_lds_dwordx4 v134, s[40:41] offset:128
	s_barrier
; #define PG8_STAGE(bufoff, gbase, voff) do { _Pragma("unroll") for (int _i = 0; _i < 2; ++_i) \
;         __builtin_amdgcn_global_load_lds((const unsigned*)((const char*)(gbase) + (voff)[_i]), (LAS unsigned*)(lds + (bufoff) + ldsw + _i * 8192), 16, 0, 0); } while (0)
; #define PG8_LDA(dst, b, h) do { _Pragma("unroll") for (int m = 0; m < 4; ++m) _Pragma("unroll") for (int k = 0; k < 2; ++k) dst[m][k] = *(const LAS bf16x8*)(lds + PG8_SA(b, h) + aoff + m * 2048 + k * 1024); } while (0)
; #define PG8_LDB(dst, b, h) do { _Pragma("unroll") for (int n = 0; n < 2; ++n) _Pragma("unroll") for (int k = 0; k < 2; ++k) dst[n][k] = *(const LAS bf16x8*)(lds + PG8_SB(b, h) + boff + n * 2048 + k * 1024); } while (0)
; #define PG8_MMA(ai, bj, At, Bt) do { __builtin_amdgcn_s_setprio(1); _Pragma("unroll") for (int m = 0; m < 4; ++m) _Pragma("unroll") for (int n = 0; n < 2; ++n) _Pragma("unroll") for (int k = 0; k < 2; ++k) \
;         acc[ai][bj][m][n] = __builtin_amdgcn_mfma_f32_16x16x32_bf16(Bt[n][k], At[m][k], acc[ai][bj][m][n], 0, 0, 0); __builtin_amdgcn_s_setprio(0); } while (0)
; #define PG8_WAIT_V(n) asm volatile("s_waitcnt vmcnt(" #n ")" ::: "memory")
; #define PG8_WAIT_L(n) asm volatile("s_waitcnt lgkmcnt(" #n ")" ::: "memory")
; #define PG8_BAR __builtin_amdgcn_s_barrier()
; #define PG8_SCHED __builtin_amdgcn_sched_barrier(0)
; template <class Epi, class Sched>
; DI void gemm_phase(LAS unsigned char* lds, const Gemm g, const Sched& S, const Epi& E) {
;     ...
;             PG8_WAIT_L(8); PG8_BAR; PG8_WAIT_L(0); PG8_MMA(0, 0, At, B0); PG8_BAR; PG8_SCHED;
;             PG8_LDB(B1, 1, 1); PG8_STAGE(PG8_SB(1, 0), b3, voffB);
;             PG8_BAR; PG8_WAIT_L(0); PG8_MMA(0, 1, At, B1); PG8_BAR;
;             PG8_LDA(At, 1, 1); PG8_STAGE(PG8_SA(1, 0), a3, voffA);
;             PG8_BAR; PG8_WAIT_L(0); PG8_MMA(1, 0, At, B0); PG8_BAR; PG8_SCHED;
;             PG8_STAGE(PG8_SB(1, 1), b3 + hstep, voffB);
;             PG8_WAIT_V(6); PG8_BAR; PG8_MMA(1, 1, At, B1); PG8_BAR;
	s_waitcnt lgkmcnt(0)
	s_setprio 1
	v_mfma_f32_16x16x32_bf16 v[124:127], v[218:221], v[168:171], v[124:127]
	v_mfma_f32_16x16x32_bf16 v[120:123], v[226:229], v[168:171], v[120:123]
	v_mfma_f32_16x16x32_bf16 v[108:111], v[218:221], v[176:179], v[108:111]
	v_mfma_f32_16x16x32_bf16 v[104:107], v[226:229], v[176:179], v[104:107]
	v_mfma_f32_16x16x32_bf16 v[92:95], v[218:221], v[188:191], v[92:95]
	v_mfma_f32_16x16x32_bf16 v[88:91], v[226:229], v[188:191], v[88:91]
	v_mfma_f32_16x16x32_bf16 v[76:79], v[218:221], v[210:213], v[76:79]
	v_mfma_f32_16x16x32_bf16 v[72:75], v[226:229], v[210:213], v[72:75]
	v_mfma_f32_16x16x32_bf16 v[124:127], v[222:225], v[172:175], v[124:127]
	v_mfma_f32_16x16x32_bf16 v[120:123], v[230:233], v[172:175], v[120:123]
	v_mfma_f32_16x16x32_bf16 v[108:111], v[222:225], v[180:183], v[108:111]
	v_mfma_f32_16x16x32_bf16 v[104:107], v[230:233], v[180:183], v[104:107]
	v_mfma_f32_16x16x32_bf16 v[92:95], v[222:225], v[206:209], v[92:95]
	v_mfma_f32_16x16x32_bf16 v[88:91], v[230:233], v[206:209], v[88:91]
	v_mfma_f32_16x16x32_bf16 v[76:79], v[222:225], v[214:217], v[76:79]
	v_mfma_f32_16x16x32_bf16 v[72:75], v[230:233], v[214:217], v[72:75]
	s_setprio 0
	s_add_i32 m0, s57, 0xffffff80
	s_barrier
	ds_read_b128 v[168:171], v150 offset:49152
	ds_read_b128 v[172:175], v150 offset:50176
	ds_read_b128 v[176:179], v150 offset:51200
	ds_read_b128 v[180:183], v150 offset:52224
	ds_read_b128 v[188:191], v150 offset:53248
	ds_read_b128 v[206:209], v150 offset:54272
	ds_read_b128 v[210:213], v150 offset:55296
	global_load_lds_dwordx4 v128, s[42:43] offset:128
	s_add_i32 m0, s58, 0xffffff80
	ds_read_b128 v[214:217], v150 offset:56320
	global_load_lds_dwordx4 v132, s[42:43] offset:128
	s_barrier
	s_waitcnt lgkmcnt(0)
	s_setprio 1
	v_mfma_f32_16x16x32_bf16 v[52:55], v[144:147], v[168:171], v[52:55]
	v_mfma_f32_16x16x32_bf16 v[48:51], v[160:163], v[168:171], v[48:51]
	v_mfma_f32_16x16x32_bf16 v[36:39], v[144:147], v[176:179], v[36:39]
	v_mfma_f32_16x16x32_bf16 v[32:35], v[160:163], v[176:179], v[32:35]
	v_mfma_f32_16x16x32_bf16 v[20:23], v[144:147], v[188:191], v[20:23]
	v_mfma_f32_16x16x32_bf16 v[16:19], v[160:163], v[188:191], v[16:19]
	v_mfma_f32_16x16x32_bf16 v[4:7], v[144:147], v[210:213], v[4:7]
	v_mfma_f32_16x16x32_bf16 v[0:3], v[160:163], v[210:213], v[0:3]
	v_mfma_f32_16x16x32_bf16 v[52:55], v[156:159], v[172:175], v[52:55]
	v_mfma_f32_16x16x32_bf16 v[48:51], v[164:167], v[172:175], v[48:51]
	v_mfma_f32_16x16x32_bf16 v[36:39], v[156:159], v[180:183], v[36:39]
	v_mfma_f32_16x16x32_bf16 v[32:35], v[164:167], v[180:183], v[32:35]
	v_mfma_f32_16x16x32_bf16 v[20:23], v[156:159], v[206:209], v[20:23]
	v_mfma_f32_16x16x32_bf16 v[16:19], v[164:167], v[206:209], v[16:19]
	v_mfma_f32_16x16x32_bf16 v[4:7], v[156:159], v[214:217], v[4:7]
	v_mfma_f32_16x16x32_bf16 v[0:3], v[164:167], v[214:217], v[0:3]
	s_setprio 0
	s_barrier
	s_add_i32 s4, s5, s50
	s_mov_b32 m0, s4
	s_add_u32 s0, s40, 0x80080
	s_addc_u32 s1, s41, 0
	global_load_lds_dwordx4 v130, s[0:1]
	s_add_i32 m0, s4, 0x2000
	s_add_i32 s68, s68, 2
	global_load_lds_dwordx4 v134, s[0:1]
	s_add_u32 s8, s8, 0x100
	s_addc_u32 s9, s9, 0
	s_add_u32 s66, s66, 0x100
	s_addc_u32 s67, s67, 0
	s_cmp_gt_u32 s68, 29
	s_waitcnt vmcnt(6)
	s_barrier
	s_setprio 1
	v_mfma_f32_16x16x32_bf16 v[60:63], v[218:221], v[168:171], v[60:63]
	v_mfma_f32_16x16x32_bf16 v[56:59], v[226:229], v[168:171], v[56:59]
	v_mfma_f32_16x16x32_bf16 v[44:47], v[218:221], v[176:179], v[44:47]
	v_mfma_f32_16x16x32_bf16 v[40:43], v[226:229], v[176:179], v[40:43]
	v_mfma_f32_16x16x32_bf16 v[28:31], v[218:221], v[188:191], v[28:31]
	v_mfma_f32_16x16x32_bf16 v[24:27], v[226:229], v[188:191], v[24:27]
	v_mfma_f32_16x16x32_bf16 v[12:15], v[218:221], v[210:213], v[12:15]
	v_mfma_f32_16x16x32_bf16 v[8:11], v[226:229], v[210:213], v[8:11]
	v_mfma_f32_16x16x32_bf16 v[60:63], v[222:225], v[172:175], v[60:63]
	v_mfma_f32_16x16x32_bf16 v[56:59], v[230:233], v[172:175], v[56:59]
	v_mfma_f32_16x16x32_bf16 v[44:47], v[222:225], v[180:183], v[44:47]
	v_mfma_f32_16x16x32_bf16 v[40:43], v[230:233], v[180:183], v[40:43]
	v_mfma_f32_16x16x32_bf16 v[28:31], v[222:225], v[206:209], v[28:31]
	v_mfma_f32_16x16x32_bf16 v[24:27], v[230:233], v[206:209], v[24:27]
	v_mfma_f32_16x16x32_bf16 v[12:15], v[222:225], v[214:217], v[12:15]
	v_mfma_f32_16x16x32_bf16 v[8:11], v[230:233], v[214:217], v[8:11]
	s_setprio 0
	s_cbranch_scc0 .Lrot_1668
	s_barrier

;     DI size_t aoff(const Unit& u, size_t tstep) const { return (size_t)u.pm * tstep; }
;     DI size_t boff(const Unit& u, size_t tstep) const { return (size_t)u.pn * tstep; }
;     DI bool next(int i, Unit& u) const { const long L = (long)i * G + c; if (L >= np) return false; u.pm = pmv; u.pn = (int)(L % nN); u.ks = (int)(L / nN); return true; }
;     DI size_t aoff(const Unit& u, size_t) const { return (size_t)u.ks * kbytes; }
;     DI size_t boff(const Unit& u, size_t tstep) const { return (size_t)u.pn * tstep + (size_t)u.ks * kbytes; }
;     DI bool next(int i, Unit& u) const { Unit t; if (!S.next(i / 3, t)) return false; u.pm = t.pm; u.pn = t.pn; u.ks = i % 3; return true; }
;     DI size_t aoff(const Unit& u, size_t tstep) const { return (u.ks < 2 ? offU : offOA) + (size_t)u.pm * tstep; }
; #define PG8_WAIT_V(n) asm volatile("s_waitcnt vmcnt(" #n ")" ::: "memory")
; template <class Epi, class Sched>
; DI void gemm_phase(LAS unsigned char* lds, const Gemm g, const Sched& S, const Epi& E) {
;     ...
;         const bool has_next = S.next(ui + 1, nxt);
;         const char* nA = has_next ? (const char*)g.A + S.aoff(nxt, tstep) : cA; const char* nB = has_next ? (const char*)g.Bt + S.boff(nxt, tstep) : cB;
;         for (int t = 0; t < nt; t += 2) {
;             if constexpr (Epi::HAS_MID) { if (t == E.mid_t(nt)) { int fr3 = fr, fq3 = fq; asm volatile("" : "+v"(fr3), "+v"(fq3)); E.mid(acc, cur, wr, wc, fr3, fq3); } }
;             const bool last = (t == nt - 2);
;             const char* a1 = cA + (size_t)(t + 1) * kstep;
;             const char* a2 = last ? nA : cA + (size_t)(t + 2) * kstep; const char* b2 = last ? nB : cB + (size_t)(t + 2) * kstep;
;             const char* a3 = a2 + kstep; const char* b3 = b2 + kstep;
;             PG8_LDB(B0, 0, 0); PG8_SCHED; PG8_LDA(At, 0, 0); PG8_STAGE(PG8_SA(1, 1), a1 + hstep, voffA);
;             PG8_WAIT_L(8); PG8_BAR; PG8_WAIT_L(0); PG8_MMA(0, 0, At, B0); PG8_BAR; PG8_SCHED;
;             PG8_LDB(B1, 0, 1); PG8_STAGE(PG8_SB(0, 0), b2, voffB);
;             PG8_BAR; PG8_WAIT_L(0); PG8_MMA(0, 1, At, B1); PG8_BAR;
;             PG8_LDA(At, 0, 1); PG8_STAGE(PG8_SA(0, 0), a2, voffA);
;             PG8_BAR; PG8_WAIT_L(0); PG8_MMA(1, 0, At, B0); PG8_BAR; PG8_SCHED;
;             PG8_STAGE(PG8_SB(0, 1), b2 + hstep, voffB);
;             PG8_WAIT_V(6); PG8_BAR; PG8_MMA(1, 1, At, B1); PG8_BAR;
.LBB0_1745:
	s_add_u32 s38, s38, 0x160080
	s_addc_u32 s39, s39, 0
	s_add_u32 s35, s40, 0x100
	v_mov_b32_e32 v0, 0
	s_addc_u32 s67, s41, 0
	s_mov_b32 s68, -2
	s_waitcnt lgkmcnt(0)
	ds_read_b128 v[144:147], v155
	ds_read_b128 v[160:163], v155 offset:1024
	ds_read_b128 v[164:167], v155 offset:2048
	ds_read_b128 v[168:171], v155 offset:3072
	s_add_u32 s0, s38, 0xffea0080
	s_addc_u32 s1, s39, -1
	s_cmpk_eq_i32 s68, 0x54
	s_cselect_b32 s43, s9, s1
	s_cselect_b32 s42, s8, s0
	s_cselect_b32 s41, s11, s67
	s_cselect_b32 s40, s10, s35
	s_add_i32 m0, s52, 0xc000
	ds_read_b128 v[172:175], v156
	ds_read_b128 v[176:179], v156 offset:1024
	ds_read_b128 v[180:183], v156 offset:2048
	ds_read_b128 v[188:191], v156 offset:3072
	ds_read_b128 v[206:209], v156 offset:4096
	ds_read_b128 v[210:213], v156 offset:5120
	ds_read_b128 v[214:217], v156 offset:6144
	global_load_lds_dwordx4 v136, s[38:39]
	s_add_i32 m0, s52, 0xe000
	ds_read_b128 v[218:221], v156 offset:7168
	global_load_lds_dwordx4 v138, s[38:39]
	s_waitcnt lgkmcnt(8)
	s_barrier
	s_waitcnt lgkmcnt(0)
	s_setprio 1
	v_mfma_f32_16x16x32_bf16 v[124:127], v[144:147], v[172:175], 0
	v_mfma_f32_16x16x32_bf16 v[120:123], v[164:167], v[172:175], 0
	v_mfma_f32_16x16x32_bf16 v[108:111], v[144:147], v[180:183], 0
	v_mfma_f32_16x16x32_bf16 v[104:107], v[164:167], v[180:183], 0
	v_mfma_f32_16x16x32_bf16 v[92:95], v[144:147], v[206:209], 0
	v_mfma_f32_16x16x32_bf16 v[88:91], v[164:167], v[206:209], 0
	v_mfma_f32_16x16x32_bf16 v[76:79], v[144:147], v[214:217], 0
	v_mfma_f32_16x16x32_bf16 v[72:75], v[164:167], v[214:217], 0
	v_mfma_f32_16x16x32_bf16 v[124:127], v[160:163], v[176:179], v[124:127]
	v_mfma_f32_16x16x32_bf16 v[120:123], v[168:171], v[176:179], v[120:123]
	v_mfma_f32_16x16x32_bf16 v[108:111], v[160:163], v[188:191], v[108:111]
	v_mfma_f32_16x16x32_bf16 v[104:107], v[168:171], v[188:191], v[104:107]
	v_mfma_f32_16x16x32_bf16 v[92:95], v[160:163], v[210:213], v[92:95]
	v_mfma_f32_16x16x32_bf16 v[88:91], v[168:171], v[210:213], v[88:91]
	v_mfma_f32_16x16x32_bf16 v[76:79], v[160:163], v[218:221], v[76:79]
	v_mfma_f32_16x16x32_bf16 v[72:75], v[168:171], v[218:221], v[72:75]
	s_setprio 0
	s_barrier
	s_add_i32 s0, s61, s51
	s_mov_b32 m0, s0
	ds_read_b128 v[222:225], v157
	ds_read_b128 v[226:229], v157 offset:1024
	ds_read_b128 v[230:233], v157 offset:2048
	global_load_lds_dwordx4 v130, s[40:41]
	s_add_i32 m0, s0, 0x2000
	ds_read_b128 v[234:237], v157 offset:3072
	global_load_lds_dwordx4 v134, s[40:41]
	s_barrier
	s_waitcnt lgkmcnt(0)
	s_setprio 1
	v_mfma_f32_16x16x32_bf16 v[116:119], v[222:225], v[172:175], 0
	v_mfma_f32_16x16x32_bf16 v[112:115], v[230:233], v[172:175], 0
	v_mfma_f32_16x16x32_bf16 v[100:103], v[222:225], v[180:183], 0
	v_mfma_f32_16x16x32_bf16 v[96:99], v[230:233], v[180:183], 0
	v_mfma_f32_16x16x32_bf16 v[84:87], v[222:225], v[206:209], 0
	v_mfma_f32_16x16x32_bf16 v[80:83], v[230:233], v[206:209], 0
	v_mfma_f32_16x16x32_bf16 v[68:71], v[222:225], v[214:217], 0
	v_mfma_f32_16x16x32_bf16 v[64:67], v[230:233], v[214:217], 0
	v_mfma_f32_16x16x32_bf16 v[116:119], v[226:229], v[176:179], v[116:119]
	v_mfma_f32_16x16x32_bf16 v[112:115], v[234:237], v[176:179], v[112:115]
	v_mfma_f32_16x16x32_bf16 v[100:103], v[226:229], v[188:191], v[100:103]
	v_mfma_f32_16x16x32_bf16 v[96:99], v[234:237], v[188:191], v[96:99]
	v_mfma_f32_16x16x32_bf16 v[84:87], v[226:229], v[210:213], v[84:87]
	v_mfma_f32_16x16x32_bf16 v[80:83], v[234:237], v[210:213], v[80:83]
	v_mfma_f32_16x16x32_bf16 v[68:71], v[226:229], v[218:221], v[68:71]
	v_mfma_f32_16x16x32_bf16 v[64:67], v[234:237], v[218:221], v[64:67]
	s_setprio 0
	s_mov_b32 m0, s52
	s_barrier
	ds_read_b128 v[172:175], v156 offset:16384
	ds_read_b128 v[176:179], v156 offset:17408
	ds_read_b128 v[180:183], v156 offset:18432
	ds_read_b128 v[188:191], v156 offset:19456
	ds_read_b128 v[206:209], v156 offset:20480
	ds_read_b128 v[210:213], v156 offset:21504
	ds_read_b128 v[214:217], v156 offset:22528
	global_load_lds_dwordx4 v128, s[42:43]
	s_mov_b32 m0, s53
	ds_read_b128 v[218:221], v156 offset:23552
	global_load_lds_dwordx4 v132, s[42:43]
	s_barrier
	s_waitcnt lgkmcnt(0)
	s_setprio 1
	v_mfma_f32_16x16x32_bf16 v[60:63], v[144:147], v[172:175], 0
	v_mfma_f32_16x16x32_bf16 v[56:59], v[164:167], v[172:175], 0
	v_mfma_f32_16x16x32_bf16 v[44:47], v[144:147], v[180:183], 0
	v_mfma_f32_16x16x32_bf16 v[40:43], v[164:167], v[180:183], 0
	v_mfma_f32_16x16x32_bf16 v[28:31], v[144:147], v[206:209], 0
	v_mfma_f32_16x16x32_bf16 v[24:27], v[164:167], v[206:209], 0
	v_mfma_f32_16x16x32_bf16 v[12:15], v[144:147], v[214:217], 0
	v_mfma_f32_16x16x32_bf16 v[8:11], v[164:167], v[214:217], 0
	v_mfma_f32_16x16x32_bf16 v[60:63], v[160:163], v[176:179], v[60:63]
	v_mfma_f32_16x16x32_bf16 v[56:59], v[168:171], v[176:179], v[56:59]
	v_mfma_f32_16x16x32_bf16 v[44:47], v[160:163], v[188:191], v[44:47]
	v_mfma_f32_16x16x32_bf16 v[40:43], v[168:171], v[188:191], v[40:43]
	v_mfma_f32_16x16x32_bf16 v[28:31], v[160:163], v[210:213], v[28:31]
	v_mfma_f32_16x16x32_bf16 v[24:27], v[168:171], v[210:213], v[24:27]
	v_mfma_f32_16x16x32_bf16 v[12:15], v[160:163], v[218:221], v[12:15]
	v_mfma_f32_16x16x32_bf16 v[8:11], v[168:171], v[218:221], v[8:11]
	s_setprio 0
	s_barrier
	s_add_i32 s4, s62, s51
	s_mov_b32 m0, s4
	s_add_u32 s0, s40, 0x160000
	s_addc_u32 s1, s41, 0
	global_load_lds_dwordx4 v130, s[0:1]
	s_add_i32 m0, s4, 0x2000
	s_add_i32 s4, 0, 0x18000
	global_load_lds_dwordx4 v134, s[0:1]
	s_waitcnt vmcnt(6)
	s_barrier
; #define PG8_STAGE(bufoff, gbase, voff) do { _Pragma("unroll") for (int _i = 0; _i < 2; ++_i) \
;         __builtin_amdgcn_global_load_lds((const unsigned*)((const char*)(gbase) + (voff)[_i]), (LAS unsigned*)(lds + (bufoff) + ldsw + _i * 8192), 16, 0, 0); } while (0)
; #define PG8_LDA(dst, b, h) do { _Pragma("unroll") for (int m = 0; m < 4; ++m) _Pragma("unroll") for (int k = 0; k < 2; ++k) dst[m][k] = *(const LAS bf16x8*)(lds + PG8_SA(b, h) + aoff + m * 2048 + k * 1024); } while (0)
; #define PG8_LDB(dst, b, h) do { _Pragma("unroll") for (int n = 0; n < 2; ++n) _Pragma("unroll") for (int k = 0; k < 2; ++k) dst[n][k] = *(const LAS bf16x8*)(lds + PG8_SB(b, h) + boff + n * 2048 + k * 1024); } while (0)
; #define PG8_MMA(ai, bj, At, Bt) do { __builtin_amdgcn_s_setprio(1); _Pragma("unroll") for (int m = 0; m < 4; ++m) _Pragma("unroll") for (int n = 0; n < 2; ++n) _Pragma("unroll") for (int k = 0; k < 2; ++k) \
;         acc[ai][bj][m][n] = __builtin_amdgcn_mfma_f32_16x16x32_bf16(Bt[n][k], At[m][k], acc[ai][bj][m][n], 0, 0, 0); __builtin_amdgcn_s_setprio(0); } while (0)
; #define PG8_WAIT_V(n) asm volatile("s_waitcnt vmcnt(" #n ")" ::: "memory")
; #define PG8_WAIT_L(n) asm volatile("s_waitcnt lgkmcnt(" #n ")" ::: "memory")
; #define PG8_BAR __builtin_amdgcn_s_barrier()
; #define PG8_SCHED __builtin_amdgcn_sched_barrier(0)
; template <class Epi, class Sched>
; DI void gemm_phase(LAS unsigned char* lds, const Gemm g, const Sched& S, const Epi& E) {
;     ...
;             PG8_WAIT_V(6); PG8_BAR; PG8_MMA(1, 1, At, B1); PG8_BAR;
;             PG8_LDB(B0, 1, 0); PG8_SCHED; PG8_LDA(At, 1, 0); PG8_STAGE(PG8_SA(0, 1), a2 + hstep, voffA);
;             PG8_WAIT_L(8); PG8_BAR; PG8_WAIT_L(0); PG8_MMA(0, 0, At, B0); PG8_BAR; PG8_SCHED;
	s_setprio 1
	v_mfma_f32_16x16x32_bf16 v[52:55], v[222:225], v[172:175], 0
	v_mfma_f32_16x16x32_bf16 v[48:51], v[230:233], v[172:175], 0
	v_mfma_f32_16x16x32_bf16 v[36:39], v[222:225], v[180:183], 0
	v_mfma_f32_16x16x32_bf16 v[32:35], v[230:233], v[180:183], 0
	v_mfma_f32_16x16x32_bf16 v[20:23], v[222:225], v[206:209], 0
	v_mfma_f32_16x16x32_bf16 v[16:19], v[230:233], v[206:209], 0
	v_mfma_f32_16x16x32_bf16 v[4:7], v[222:225], v[214:217], 0
	v_mfma_f32_16x16x32_bf16 v[0:3], v[230:233], v[214:217], 0
	v_mfma_f32_16x16x32_bf16 v[52:55], v[226:229], v[176:179], v[52:55]
	v_mfma_f32_16x16x32_bf16 v[48:51], v[234:237], v[176:179], v[48:51]
	v_mfma_f32_16x16x32_bf16 v[36:39], v[226:229], v[188:191], v[36:39]
	v_mfma_f32_16x16x32_bf16 v[32:35], v[234:237], v[188:191], v[32:35]
	v_mfma_f32_16x16x32_bf16 v[20:23], v[226:229], v[210:213], v[20:23]
	v_mfma_f32_16x16x32_bf16 v[16:19], v[234:237], v[210:213], v[16:19]
	v_mfma_f32_16x16x32_bf16 v[4:7], v[226:229], v[218:221], v[4:7]
	v_mfma_f32_16x16x32_bf16 v[0:3], v[234:237], v[218:221], v[0:3]
	s_setprio 0
	v_add_u32_e32 v202, s4, v154
	s_barrier
	ds_read_b128 v[144:147], v202
	ds_read_b128 v[160:163], v202 offset:1024
	ds_read_b128 v[164:167], v202 offset:2048
	ds_read_b128 v[168:171], v202 offset:3072
	s_add_u32 s0, s42, 0x160000
	s_addc_u32 s1, s43, 0
	s_mov_b32 m0, s54
	ds_read_b128 v[172:175], v156 offset:32768
	ds_read_b128 v[176:179], v156 offset:33792
	ds_read_b128 v[180:183], v156 offset:34816
	ds_read_b128 v[188:191], v156 offset:35840
	ds_read_b128 v[206:209], v156 offset:36864
	ds_read_b128 v[210:213], v156 offset:37888
	ds_read_b128 v[214:217], v156 offset:38912
	global_load_lds_dwordx4 v128, s[0:1]
	s_mov_b32 m0, s55
	ds_read_b128 v[218:221], v156 offset:39936
	global_load_lds_dwordx4 v132, s[0:1]
	s_waitcnt lgkmcnt(8)
	s_barrier
	s_waitcnt lgkmcnt(0)
	s_setprio 1
	v_mfma_f32_16x16x32_bf16 v[124:127], v[144:147], v[172:175], v[124:127]
	v_mfma_f32_16x16x32_bf16 v[120:123], v[164:167], v[172:175], v[120:123]
	v_mfma_f32_16x16x32_bf16 v[108:111], v[144:147], v[180:183], v[108:111]
	v_mfma_f32_16x16x32_bf16 v[104:107], v[164:167], v[180:183], v[104:107]
	v_mfma_f32_16x16x32_bf16 v[92:95], v[144:147], v[206:209], v[92:95]
	v_mfma_f32_16x16x32_bf16 v[88:91], v[164:167], v[206:209], v[88:91]
	v_mfma_f32_16x16x32_bf16 v[76:79], v[144:147], v[214:217], v[76:79]
	v_mfma_f32_16x16x32_bf16 v[72:75], v[164:167], v[214:217], v[72:75]
	v_mfma_f32_16x16x32_bf16 v[124:127], v[160:163], v[176:179], v[124:127]
	v_mfma_f32_16x16x32_bf16 v[120:123], v[168:171], v[176:179], v[120:123]
	v_mfma_f32_16x16x32_bf16 v[108:111], v[160:163], v[188:191], v[108:111]
	v_mfma_f32_16x16x32_bf16 v[104:107], v[168:171], v[188:191], v[104:107]
	v_mfma_f32_16x16x32_bf16 v[92:95], v[160:163], v[210:213], v[92:95]
	v_mfma_f32_16x16x32_bf16 v[88:91], v[168:171], v[210:213], v[88:91]
	v_mfma_f32_16x16x32_bf16 v[76:79], v[160:163], v[218:221], v[76:79]
	v_mfma_f32_16x16x32_bf16 v[72:75], v[168:171], v[218:221], v[72:75]
	s_setprio 0
	s_barrier
	s_add_i32 s5, 0, 0x1c000
	s_add_i32 s0, s4, s51
	v_add_u32_e32 v203, s5, v154
	s_add_i32 m0, s0, 0xffffff80
	ds_read_b128 v[222:225], v203
	ds_read_b128 v[226:229], v203 offset:1024
	ds_read_b128 v[230:233], v203 offset:2048
	global_load_lds_dwordx4 v130, s[40:41] offset:128
	s_add_i32 m0, s0, 0x1f80
	ds_read_b128 v[234:237], v203 offset:3072
	global_load_lds_dwordx4 v134, s[40:41] offset:128
	s_barrier
; #define PG8_STAGE(bufoff, gbase, voff) do { _Pragma("unroll") for (int _i = 0; _i < 2; ++_i) \
;         __builtin_amdgcn_global_load_lds((const unsigned*)((const char*)(gbase) + (voff)[_i]), (LAS unsigned*)(lds + (bufoff) + ldsw + _i * 8192), 16, 0, 0); } while (0)
; #define PG8_LDA(dst, b, h) do { _Pragma("unroll") for (int m = 0; m < 4; ++m) _Pragma("unroll") for (int k = 0; k < 2; ++k) dst[m][k] = *(const LAS bf16x8*)(lds + PG8_SA(b, h) + aoff + m * 2048 + k * 1024); } while (0)
; #define PG8_LDB(dst, b, h) do { _Pragma("unroll") for (int n = 0; n < 2; ++n) _Pragma("unroll") for (int k = 0; k < 2; ++k) dst[n][k] = *(const LAS bf16x8*)(lds + PG8_SB(b, h) + boff + n * 2048 + k * 1024); } while (0)
; #define PG8_MMA(ai, bj, At, Bt) do { __builtin_amdgcn_s_setprio(1); _Pragma("unroll") for (int m = 0; m < 4; ++m) _Pragma("unroll") for (int n = 0; n < 2; ++n) _Pragma("unroll") for (int k = 0; k < 2; ++k) \
;         acc[ai][bj][m][n] = __builtin_amdgcn_mfma_f32_16x16x32_bf16(Bt[n][k], At[m][k], acc[ai][bj][m][n], 0, 0, 0); __builtin_amdgcn_s_setprio(0); } while (0)
; #define PG8_WAIT_V(n) asm volatile("s_waitcnt vmcnt(" #n ")" ::: "memory")
; #define PG8_WAIT_L(n) asm volatile("s_waitcnt lgkmcnt(" #n ")" ::: "memory")
; #define PG8_BAR __builtin_amdgcn_s_barrier()
; #define PG8_SCHED __builtin_amdgcn_sched_barrier(0)
; template <class Epi, class Sched>
; DI void gemm_phase(LAS unsigned char* lds, const Gemm g, const Sched& S, const Epi& E) {
;     ...
;             PG8_WAIT_L(8); PG8_BAR; PG8_WAIT_L(0); PG8_MMA(0, 0, At, B0); PG8_BAR; PG8_SCHED;
;             PG8_LDB(B1, 1, 1); PG8_STAGE(PG8_SB(1, 0), b3, voffB);
;             PG8_BAR; PG8_WAIT_L(0); PG8_MMA(0, 1, At, B1); PG8_BAR;
;             PG8_LDA(At, 1, 1); PG8_STAGE(PG8_SA(1, 0), a3, voffA);
;             PG8_BAR; PG8_WAIT_L(0); PG8_MMA(1, 0, At, B0); PG8_BAR; PG8_SCHED;
;             PG8_STAGE(PG8_SB(1, 1), b3 + hstep, voffB);
;             PG8_WAIT_V(6); PG8_BAR; PG8_MMA(1, 1, At, B1); PG8_BAR;
	s_waitcnt lgkmcnt(0)
	s_setprio 1
	v_mfma_f32_16x16x32_bf16 v[116:119], v[222:225], v[172:175], v[116:119]
	v_mfma_f32_16x16x32_bf16 v[112:115], v[230:233], v[172:175], v[112:115]
	v_mfma_f32_16x16x32_bf16 v[100:103], v[222:225], v[180:183], v[100:103]
	v_mfma_f32_16x16x32_bf16 v[96:99], v[230:233], v[180:183], v[96:99]
	v_mfma_f32_16x16x32_bf16 v[84:87], v[222:225], v[206:209], v[84:87]
	v_mfma_f32_16x16x32_bf16 v[80:83], v[230:233], v[206:209], v[80:83]
	v_mfma_f32_16x16x32_bf16 v[68:71], v[222:225], v[214:217], v[68:71]
	v_mfma_f32_16x16x32_bf16 v[64:67], v[230:233], v[214:217], v[64:67]
	v_mfma_f32_16x16x32_bf16 v[116:119], v[226:229], v[176:179], v[116:119]
	v_mfma_f32_16x16x32_bf16 v[112:115], v[234:237], v[176:179], v[112:115]
	v_mfma_f32_16x16x32_bf16 v[100:103], v[226:229], v[188:191], v[100:103]
	v_mfma_f32_16x16x32_bf16 v[96:99], v[234:237], v[188:191], v[96:99]
	v_mfma_f32_16x16x32_bf16 v[84:87], v[226:229], v[210:213], v[84:87]
	v_mfma_f32_16x16x32_bf16 v[80:83], v[234:237], v[210:213], v[80:83]
	v_mfma_f32_16x16x32_bf16 v[68:71], v[226:229], v[218:221], v[68:71]
	v_mfma_f32_16x16x32_bf16 v[64:67], v[234:237], v[218:221], v[64:67]
	s_setprio 0
	s_add_i32 m0, s59, 0xffffff80
	s_barrier
	ds_read_b128 v[172:175], v156 offset:49152
	ds_read_b128 v[176:179], v156 offset:50176
	ds_read_b128 v[180:183], v156 offset:51200
	ds_read_b128 v[188:191], v156 offset:52224
	ds_read_b128 v[206:209], v156 offset:53248
	ds_read_b128 v[210:213], v156 offset:54272
	ds_read_b128 v[214:217], v156 offset:55296
	global_load_lds_dwordx4 v128, s[42:43] offset:128
	s_add_i32 m0, s60, 0xffffff80
	ds_read_b128 v[218:221], v156 offset:56320
	global_load_lds_dwordx4 v132, s[42:43] offset:128
	s_barrier
	s_waitcnt lgkmcnt(0)
	s_setprio 1
	v_mfma_f32_16x16x32_bf16 v[60:63], v[144:147], v[172:175], v[60:63]
	v_mfma_f32_16x16x32_bf16 v[56:59], v[164:167], v[172:175], v[56:59]
	v_mfma_f32_16x16x32_bf16 v[44:47], v[144:147], v[180:183], v[44:47]
	v_mfma_f32_16x16x32_bf16 v[40:43], v[164:167], v[180:183], v[40:43]
	v_mfma_f32_16x16x32_bf16 v[28:31], v[144:147], v[206:209], v[28:31]
	v_mfma_f32_16x16x32_bf16 v[24:27], v[164:167], v[206:209], v[24:27]
	v_mfma_f32_16x16x32_bf16 v[12:15], v[144:147], v[214:217], v[12:15]
	v_mfma_f32_16x16x32_bf16 v[8:11], v[164:167], v[214:217], v[8:11]
	v_mfma_f32_16x16x32_bf16 v[60:63], v[160:163], v[176:179], v[60:63]
	v_mfma_f32_16x16x32_bf16 v[56:59], v[168:171], v[176:179], v[56:59]
	v_mfma_f32_16x16x32_bf16 v[44:47], v[160:163], v[188:191], v[44:47]
	v_mfma_f32_16x16x32_bf16 v[40:43], v[168:171], v[188:191], v[40:43]
	v_mfma_f32_16x16x32_bf16 v[28:31], v[160:163], v[210:213], v[28:31]
	v_mfma_f32_16x16x32_bf16 v[24:27], v[168:171], v[210:213], v[24:27]
	v_mfma_f32_16x16x32_bf16 v[12:15], v[160:163], v[218:221], v[12:15]
	v_mfma_f32_16x16x32_bf16 v[8:11], v[168:171], v[218:221], v[8:11]
	s_setprio 0
	s_barrier
	s_add_i32 s4, s5, s51
	s_mov_b32 m0, s4
	s_add_u32 s0, s40, 0x160080
	s_addc_u32 s1, s41, 0
	global_load_lds_dwordx4 v130, s[0:1]
	s_add_i32 m0, s4, 0x2000
	s_nop 0
	global_load_lds_dwordx4 v134, s[0:1]
	s_waitcnt vmcnt(6)
	s_barrier
	s_setprio 1
	v_mfma_f32_16x16x32_bf16 v[52:55], v[222:225], v[172:175], v[52:55]
	v_mfma_f32_16x16x32_bf16 v[48:51], v[230:233], v[172:175], v[48:51]
	v_mfma_f32_16x16x32_bf16 v[36:39], v[222:225], v[180:183], v[36:39]
	v_mfma_f32_16x16x32_bf16 v[32:35], v[230:233], v[180:183], v[32:35]
	v_mfma_f32_16x16x32_bf16 v[20:23], v[222:225], v[206:209], v[20:23]
	v_mfma_f32_16x16x32_bf16 v[16:19], v[230:233], v[206:209], v[16:19]
	v_mfma_f32_16x16x32_bf16 v[4:7], v[222:225], v[214:217], v[4:7]
	v_mfma_f32_16x16x32_bf16 v[0:3], v[230:233], v[214:217], v[0:3]
	v_mfma_f32_16x16x32_bf16 v[52:55], v[226:229], v[176:179], v[52:55]
	v_mfma_f32_16x16x32_bf16 v[48:51], v[234:237], v[176:179], v[48:51]
	v_mfma_f32_16x16x32_bf16 v[36:39], v[226:229], v[188:191], v[36:39]
	v_mfma_f32_16x16x32_bf16 v[32:35], v[234:237], v[188:191], v[32:35]
	v_mfma_f32_16x16x32_bf16 v[20:23], v[226:229], v[210:213], v[20:23]
	v_mfma_f32_16x16x32_bf16 v[16:19], v[234:237], v[210:213], v[16:19]
	v_mfma_f32_16x16x32_bf16 v[4:7], v[226:229], v[218:221], v[4:7]
	v_mfma_f32_16x16x32_bf16 v[0:3], v[234:237], v[218:221], v[0:3]
	s_setprio 0
	s_add_i32 s68, s68, 2
	s_add_u32 s38, s38, 0x100
	s_addc_u32 s39, s39, 0
	s_add_u32 s35, s35, 0x100
	s_addc_u32 s67, s67, 0
	s_cmpk_gt_u32 s68, 0x55
	s_cbranch_scc0 .Lrot_1746
	s_barrier
	s_branch .Lpeel_done_1746

; #define PG8_STAGE(bufoff, gbase, voff) do { _Pragma("unroll") for (int _i = 0; _i < 2; ++_i) \
;         __builtin_amdgcn_global_load_lds((const unsigned*)((const char*)(gbase) + (voff)[_i]), (LAS unsigned*)(lds + (bufoff) + ldsw + _i * 8192), 16, 0, 0); } while (0)
; #define PG8_LDA(dst, b, h) do { _Pragma("unroll") for (int m = 0; m < 4; ++m) _Pragma("unroll") for (int k = 0; k < 2; ++k) dst[m][k] = *(const LAS bf16x8*)(lds + PG8_SA(b, h) + aoff + m * 2048 + k * 1024); } while (0)
; #define PG8_LDB(dst, b, h) do { _Pragma("unroll") for (int n = 0; n < 2; ++n) _Pragma("unroll") for (int k = 0; k < 2; ++k) dst[n][k] = *(const LAS bf16x8*)(lds + PG8_SB(b, h) + boff + n * 2048 + k * 1024); } while (0)
; #define PG8_MMA(ai, bj, At, Bt) do { __builtin_amdgcn_s_setprio(1); _Pragma("unroll") for (int m = 0; m < 4; ++m) _Pragma("unroll") for (int n = 0; n < 2; ++n) _Pragma("unroll") for (int k = 0; k < 2; ++k) \
;         acc[ai][bj][m][n] = __builtin_amdgcn_mfma_f32_16x16x32_bf16(Bt[n][k], At[m][k], acc[ai][bj][m][n], 0, 0, 0); __builtin_amdgcn_s_setprio(0); } while (0)
; #define PG8_WAIT_V(n) asm volatile("s_waitcnt vmcnt(" #n ")" ::: "memory")
; #define PG8_WAIT_L(n) asm volatile("s_waitcnt lgkmcnt(" #n ")" ::: "memory")
; #define PG8_BAR __builtin_amdgcn_s_barrier()
; #define PG8_SCHED __builtin_amdgcn_sched_barrier(0)
; template <class Epi, class Sched>
; DI void gemm_phase(LAS unsigned char* lds, const Gemm g, const Sched& S, const Epi& E) {
;     ...
;             PG8_LDB(B0, 0, 0); PG8_SCHED; PG8_LDA(At, 0, 0); PG8_STAGE(PG8_SA(1, 1), a1 + hstep, voffA);
;             PG8_WAIT_L(8); PG8_BAR; PG8_WAIT_L(0); PG8_MMA(0, 0, At, B0); PG8_BAR; PG8_SCHED;
;             PG8_LDB(B1, 0, 1); PG8_STAGE(PG8_SB(0, 0), b2, voffB);
;             PG8_BAR; PG8_WAIT_L(0); PG8_MMA(0, 1, At, B1); PG8_BAR;
;             PG8_LDA(At, 0, 1); PG8_STAGE(PG8_SA(0, 0), a2, voffA);
;             PG8_BAR; PG8_WAIT_L(0); PG8_MMA(1, 0, At, B0); PG8_BAR; PG8_SCHED;
;             PG8_STAGE(PG8_SB(0, 1), b2 + hstep, voffB);
;             PG8_WAIT_V(6); PG8_BAR; PG8_MMA(1, 1, At, B1); PG8_BAR;
.LBB0_1746:
	ds_read_b128 v[144:147], v155
	ds_read_b128 v[160:163], v155 offset:1024
	ds_read_b128 v[164:167], v155 offset:2048
	ds_read_b128 v[168:171], v155 offset:3072
	s_add_u32 s0, s38, 0xffea0080
	s_addc_u32 s1, s39, -1
	s_cmpk_eq_i32 s68, 0x54
	s_cselect_b32 s43, s9, s1
	s_cselect_b32 s42, s8, s0
	s_cselect_b32 s41, s11, s67
	s_cselect_b32 s40, s10, s35
	s_add_i32 m0, s52, 0xc000
	ds_read_b128 v[172:175], v156
	ds_read_b128 v[176:179], v156 offset:1024
	ds_read_b128 v[180:183], v156 offset:2048
	ds_read_b128 v[188:191], v156 offset:3072
	ds_read_b128 v[206:209], v156 offset:4096
	ds_read_b128 v[210:213], v156 offset:5120
	ds_read_b128 v[214:217], v156 offset:6144
	global_load_lds_dwordx4 v136, s[38:39]
	s_add_i32 m0, s52, 0xe000
	ds_read_b128 v[218:221], v156 offset:7168
	global_load_lds_dwordx4 v138, s[38:39]
	s_waitcnt lgkmcnt(8)
	s_barrier
	s_waitcnt lgkmcnt(0)
	s_setprio 1
	v_mfma_f32_16x16x32_bf16 v[124:127], v[144:147], v[172:175], v[124:127]
	v_mfma_f32_16x16x32_bf16 v[120:123], v[164:167], v[172:175], v[120:123]
	v_mfma_f32_16x16x32_bf16 v[108:111], v[144:147], v[180:183], v[108:111]
	v_mfma_f32_16x16x32_bf16 v[104:107], v[164:167], v[180:183], v[104:107]
	v_mfma_f32_16x16x32_bf16 v[92:95], v[144:147], v[206:209], v[92:95]
	v_mfma_f32_16x16x32_bf16 v[88:91], v[164:167], v[206:209], v[88:91]
	v_mfma_f32_16x16x32_bf16 v[76:79], v[144:147], v[214:217], v[76:79]
	v_mfma_f32_16x16x32_bf16 v[72:75], v[164:167], v[214:217], v[72:75]
	v_mfma_f32_16x16x32_bf16 v[124:127], v[160:163], v[176:179], v[124:127]
	v_mfma_f32_16x16x32_bf16 v[120:123], v[168:171], v[176:179], v[120:123]
	v_mfma_f32_16x16x32_bf16 v[108:111], v[160:163], v[188:191], v[108:111]
	v_mfma_f32_16x16x32_bf16 v[104:107], v[168:171], v[188:191], v[104:107]
	v_mfma_f32_16x16x32_bf16 v[92:95], v[160:163], v[210:213], v[92:95]
	v_mfma_f32_16x16x32_bf16 v[88:91], v[168:171], v[210:213], v[88:91]
	v_mfma_f32_16x16x32_bf16 v[76:79], v[160:163], v[218:221], v[76:79]
	v_mfma_f32_16x16x32_bf16 v[72:75], v[168:171], v[218:221], v[72:75]
	s_setprio 0
	s_barrier
	s_add_i32 s0, s61, s51
	s_mov_b32 m0, s0
	ds_read_b128 v[222:225], v157
	ds_read_b128 v[226:229], v157 offset:1024
	ds_read_b128 v[230:233], v157 offset:2048
	global_load_lds_dwordx4 v130, s[40:41]
	s_add_i32 m0, s0, 0x2000
	ds_read_b128 v[234:237], v157 offset:3072
	global_load_lds_dwordx4 v134, s[40:41]
	s_barrier
	s_waitcnt lgkmcnt(0)
	s_setprio 1
	v_mfma_f32_16x16x32_bf16 v[116:119], v[222:225], v[172:175], v[116:119]
	v_mfma_f32_16x16x32_bf16 v[112:115], v[230:233], v[172:175], v[112:115]
	v_mfma_f32_16x16x32_bf16 v[100:103], v[222:225], v[180:183], v[100:103]
	v_mfma_f32_16x16x32_bf16 v[96:99], v[230:233], v[180:183], v[96:99]
	v_mfma_f32_16x16x32_bf16 v[84:87], v[222:225], v[206:209], v[84:87]
	v_mfma_f32_16x16x32_bf16 v[80:83], v[230:233], v[206:209], v[80:83]
	v_mfma_f32_16x16x32_bf16 v[68:71], v[222:225], v[214:217], v[68:71]
	v_mfma_f32_16x16x32_bf16 v[64:67], v[230:233], v[214:217], v[64:67]
	v_mfma_f32_16x16x32_bf16 v[116:119], v[226:229], v[176:179], v[116:119]
	v_mfma_f32_16x16x32_bf16 v[112:115], v[234:237], v[176:179], v[112:115]
	v_mfma_f32_16x16x32_bf16 v[100:103], v[226:229], v[188:191], v[100:103]
	v_mfma_f32_16x16x32_bf16 v[96:99], v[234:237], v[188:191], v[96:99]
	v_mfma_f32_16x16x32_bf16 v[84:87], v[226:229], v[210:213], v[84:87]
	v_mfma_f32_16x16x32_bf16 v[80:83], v[234:237], v[210:213], v[80:83]
	v_mfma_f32_16x16x32_bf16 v[68:71], v[226:229], v[218:221], v[68:71]
	v_mfma_f32_16x16x32_bf16 v[64:67], v[234:237], v[218:221], v[64:67]
	s_setprio 0
	s_mov_b32 m0, s52
	s_barrier
	ds_read_b128 v[172:175], v156 offset:16384
	ds_read_b128 v[176:179], v156 offset:17408
	ds_read_b128 v[180:183], v156 offset:18432
	ds_read_b128 v[188:191], v156 offset:19456
	ds_read_b128 v[206:209], v156 offset:20480
	ds_read_b128 v[210:213], v156 offset:21504
	ds_read_b128 v[214:217], v156 offset:22528
	global_load_lds_dwordx4 v128, s[42:43]
	s_mov_b32 m0, s53
	ds_read_b128 v[218:221], v156 offset:23552
	global_load_lds_dwordx4 v132, s[42:43]
	s_barrier
	s_waitcnt lgkmcnt(0)
	s_setprio 1
	v_mfma_f32_16x16x32_bf16 v[60:63], v[144:147], v[172:175], v[60:63]
	v_mfma_f32_16x16x32_bf16 v[56:59], v[164:167], v[172:175], v[56:59]
	v_mfma_f32_16x16x32_bf16 v[44:47], v[144:147], v[180:183], v[44:47]
	v_mfma_f32_16x16x32_bf16 v[40:43], v[164:167], v[180:183], v[40:43]
	v_mfma_f32_16x16x32_bf16 v[28:31], v[144:147], v[206:209], v[28:31]
	v_mfma_f32_16x16x32_bf16 v[24:27], v[164:167], v[206:209], v[24:27]
	v_mfma_f32_16x16x32_bf16 v[12:15], v[144:147], v[214:217], v[12:15]
	v_mfma_f32_16x16x32_bf16 v[8:11], v[164:167], v[214:217], v[8:11]
	v_mfma_f32_16x16x32_bf16 v[60:63], v[160:163], v[176:179], v[60:63]
	v_mfma_f32_16x16x32_bf16 v[56:59], v[168:171], v[176:179], v[56:59]
	v_mfma_f32_16x16x32_bf16 v[44:47], v[160:163], v[188:191], v[44:47]
	v_mfma_f32_16x16x32_bf16 v[40:43], v[168:171], v[188:191], v[40:43]
	v_mfma_f32_16x16x32_bf16 v[28:31], v[160:163], v[210:213], v[28:31]
	v_mfma_f32_16x16x32_bf16 v[24:27], v[168:171], v[210:213], v[24:27]
	v_mfma_f32_16x16x32_bf16 v[12:15], v[160:163], v[218:221], v[12:15]
	v_mfma_f32_16x16x32_bf16 v[8:11], v[168:171], v[218:221], v[8:11]
	s_setprio 0
	s_barrier
	s_add_i32 s4, s62, s51
	s_mov_b32 m0, s4
	s_add_u32 s0, s40, 0x160000
	s_addc_u32 s1, s41, 0
	global_load_lds_dwordx4 v130, s[0:1]
	s_add_i32 m0, s4, 0x2000
	s_add_i32 s4, 0, 0x18000
	global_load_lds_dwordx4 v134, s[0:1]
	s_waitcnt vmcnt(6)
	s_barrier
; #define PG8_STAGE(bufoff, gbase, voff) do { _Pragma("unroll") for (int _i = 0; _i < 2; ++_i) \
;         __builtin_amdgcn_global_load_lds((const unsigned*)((const char*)(gbase) + (voff)[_i]), (LAS unsigned*)(lds + (bufoff) + ldsw + _i * 8192), 16, 0, 0); } while (0)
; #define PG8_LDA(dst, b, h) do { _Pragma("unroll") for (int m = 0; m < 4; ++m) _Pragma("unroll") for (int k = 0; k < 2; ++k) dst[m][k] = *(const LAS bf16x8*)(lds + PG8_SA(b, h) + aoff + m * 2048 + k * 1024); } while (0)
; #define PG8_LDB(dst, b, h) do { _Pragma("unroll") for (int n = 0; n < 2; ++n) _Pragma("unroll") for (int k = 0; k < 2; ++k) dst[n][k] = *(const LAS bf16x8*)(lds + PG8_SB(b, h) + boff + n * 2048 + k * 1024); } while (0)
; #define PG8_MMA(ai, bj, At, Bt) do { __builtin_amdgcn_s_setprio(1); _Pragma("unroll") for (int m = 0; m < 4; ++m) _Pragma("unroll") for (int n = 0; n < 2; ++n) _Pragma("unroll") for (int k = 0; k < 2; ++k) \
;         acc[ai][bj][m][n] = __builtin_amdgcn_mfma_f32_16x16x32_bf16(Bt[n][k], At[m][k], acc[ai][bj][m][n], 0, 0, 0); __builtin_amdgcn_s_setprio(0); } while (0)
; #define PG8_WAIT_V(n) asm volatile("s_waitcnt vmcnt(" #n ")" ::: "memory")
; #define PG8_WAIT_L(n) asm volatile("s_waitcnt lgkmcnt(" #n ")" ::: "memory")
; #define PG8_BAR __builtin_amdgcn_s_barrier()
; #define PG8_SCHED __builtin_amdgcn_sched_barrier(0)
; template <class Epi, class Sched>
; DI void gemm_phase(LAS unsigned char* lds, const Gemm g, const Sched& S, const Epi& E) {
;     ...
;             PG8_WAIT_V(6); PG8_BAR; PG8_MMA(1, 1, At, B1); PG8_BAR;
;             PG8_LDB(B0, 1, 0); PG8_SCHED; PG8_LDA(At, 1, 0); PG8_STAGE(PG8_SA(0, 1), a2 + hstep, voffA);
;             PG8_WAIT_L(8); PG8_BAR; PG8_WAIT_L(0); PG8_MMA(0, 0, At, B0); PG8_BAR; PG8_SCHED;
	s_setprio 1
	v_mfma_f32_16x16x32_bf16 v[52:55], v[222:225], v[172:175], v[52:55]
	v_mfma_f32_16x16x32_bf16 v[48:51], v[230:233], v[172:175], v[48:51]
	v_mfma_f32_16x16x32_bf16 v[36:39], v[222:225], v[180:183], v[36:39]
	v_mfma_f32_16x16x32_bf16 v[32:35], v[230:233], v[180:183], v[32:35]
	v_mfma_f32_16x16x32_bf16 v[20:23], v[222:225], v[206:209], v[20:23]
	v_mfma_f32_16x16x32_bf16 v[16:19], v[230:233], v[206:209], v[16:19]
	v_mfma_f32_16x16x32_bf16 v[4:7], v[222:225], v[214:217], v[4:7]
	v_mfma_f32_16x16x32_bf16 v[0:3], v[230:233], v[214:217], v[0:3]
	v_mfma_f32_16x16x32_bf16 v[52:55], v[226:229], v[176:179], v[52:55]
	v_mfma_f32_16x16x32_bf16 v[48:51], v[234:237], v[176:179], v[48:51]
	v_mfma_f32_16x16x32_bf16 v[36:39], v[226:229], v[188:191], v[36:39]
	v_mfma_f32_16x16x32_bf16 v[32:35], v[234:237], v[188:191], v[32:35]
	v_mfma_f32_16x16x32_bf16 v[20:23], v[226:229], v[210:213], v[20:23]
	v_mfma_f32_16x16x32_bf16 v[16:19], v[234:237], v[210:213], v[16:19]
	v_mfma_f32_16x16x32_bf16 v[4:7], v[226:229], v[218:221], v[4:7]
	v_mfma_f32_16x16x32_bf16 v[0:3], v[234:237], v[218:221], v[0:3]
	s_setprio 0
	s_barrier
	ds_read_b128 v[144:147], v202
	ds_read_b128 v[160:163], v202 offset:1024
	ds_read_b128 v[164:167], v202 offset:2048
	ds_read_b128 v[168:171], v202 offset:3072
	s_add_u32 s0, s42, 0x160000
	s_addc_u32 s1, s43, 0
	s_mov_b32 m0, s54
	ds_read_b128 v[172:175], v156 offset:32768
	ds_read_b128 v[176:179], v156 offset:33792
	ds_read_b128 v[180:183], v156 offset:34816
	ds_read_b128 v[188:191], v156 offset:35840
	ds_read_b128 v[206:209], v156 offset:36864
	ds_read_b128 v[210:213], v156 offset:37888
	ds_read_b128 v[214:217], v156 offset:38912
	global_load_lds_dwordx4 v128, s[0:1]
	s_mov_b32 m0, s55
	ds_read_b128 v[218:221], v156 offset:39936
	global_load_lds_dwordx4 v132, s[0:1]
	s_waitcnt lgkmcnt(8)
	s_barrier
	s_waitcnt lgkmcnt(0)
	s_setprio 1
	v_mfma_f32_16x16x32_bf16 v[124:127], v[144:147], v[172:175], v[124:127]
	v_mfma_f32_16x16x32_bf16 v[120:123], v[164:167], v[172:175], v[120:123]
	v_mfma_f32_16x16x32_bf16 v[108:111], v[144:147], v[180:183], v[108:111]
	v_mfma_f32_16x16x32_bf16 v[104:107], v[164:167], v[180:183], v[104:107]
	v_mfma_f32_16x16x32_bf16 v[92:95], v[144:147], v[206:209], v[92:95]
	v_mfma_f32_16x16x32_bf16 v[88:91], v[164:167], v[206:209], v[88:91]
	v_mfma_f32_16x16x32_bf16 v[76:79], v[144:147], v[214:217], v[76:79]
	v_mfma_f32_16x16x32_bf16 v[72:75], v[164:167], v[214:217], v[72:75]
	v_mfma_f32_16x16x32_bf16 v[124:127], v[160:163], v[176:179], v[124:127]
	v_mfma_f32_16x16x32_bf16 v[120:123], v[168:171], v[176:179], v[120:123]
	v_mfma_f32_16x16x32_bf16 v[108:111], v[160:163], v[188:191], v[108:111]
	v_mfma_f32_16x16x32_bf16 v[104:107], v[168:171], v[188:191], v[104:107]
	v_mfma_f32_16x16x32_bf16 v[92:95], v[160:163], v[210:213], v[92:95]
	v_mfma_f32_16x16x32_bf16 v[88:91], v[168:171], v[210:213], v[88:91]
	v_mfma_f32_16x16x32_bf16 v[76:79], v[160:163], v[218:221], v[76:79]
	v_mfma_f32_16x16x32_bf16 v[72:75], v[168:171], v[218:221], v[72:75]
	s_setprio 0
	s_barrier
	s_add_i32 s5, 0, 0x1c000
	s_add_i32 s0, s4, s51
	s_add_i32 m0, s0, 0xffffff80
	ds_read_b128 v[222:225], v203
	ds_read_b128 v[226:229], v203 offset:1024
	ds_read_b128 v[230:233], v203 offset:2048
	global_load_lds_dwordx4 v130, s[40:41] offset:128
	s_add_i32 m0, s0, 0x1f80
	ds_read_b128 v[234:237], v203 offset:3072
	global_load_lds_dwordx4 v134, s[40:41] offset:128
	s_barrier
; #define PG8_STAGE(bufoff, gbase, voff) do { _Pragma("unroll") for (int _i = 0; _i < 2; ++_i) \
;         __builtin_amdgcn_global_load_lds((const unsigned*)((const char*)(gbase) + (voff)[_i]), (LAS unsigned*)(lds + (bufoff) + ldsw + _i * 8192), 16, 0, 0); } while (0)
; #define PG8_LDA(dst, b, h) do { _Pragma("unroll") for (int m = 0; m < 4; ++m) _Pragma("unroll") for (int k = 0; k < 2; ++k) dst[m][k] = *(const LAS bf16x8*)(lds + PG8_SA(b, h) + aoff + m * 2048 + k * 1024); } while (0)
; #define PG8_LDB(dst, b, h) do { _Pragma("unroll") for (int n = 0; n < 2; ++n) _Pragma("unroll") for (int k = 0; k < 2; ++k) dst[n][k] = *(const LAS bf16x8*)(lds + PG8_SB(b, h) + boff + n * 2048 + k * 1024); } while (0)
; #define PG8_MMA(ai, bj, At, Bt) do { __builtin_amdgcn_s_setprio(1); _Pragma("unroll") for (int m = 0; m < 4; ++m) _Pragma("unroll") for (int n = 0; n < 2; ++n) _Pragma("unroll") for (int k = 0; k < 2; ++k) \
;         acc[ai][bj][m][n] = __builtin_amdgcn_mfma_f32_16x16x32_bf16(Bt[n][k], At[m][k], acc[ai][bj][m][n], 0, 0, 0); __builtin_amdgcn_s_setprio(0); } while (0)
; #define PG8_WAIT_V(n) asm volatile("s_waitcnt vmcnt(" #n ")" ::: "memory")
; #define PG8_WAIT_L(n) asm volatile("s_waitcnt lgkmcnt(" #n ")" ::: "memory")
; #define PG8_BAR __builtin_amdgcn_s_barrier()
; #define PG8_SCHED __builtin_amdgcn_sched_barrier(0)
; template <class Epi, class Sched>
; DI void gemm_phase(LAS unsigned char* lds, const Gemm g, const Sched& S, const Epi& E) {
;     ...
;             PG8_WAIT_L(8); PG8_BAR; PG8_WAIT_L(0); PG8_MMA(0, 0, At, B0); PG8_BAR; PG8_SCHED;
;             PG8_LDB(B1, 1, 1); PG8_STAGE(PG8_SB(1, 0), b3, voffB);
;             PG8_BAR; PG8_WAIT_L(0); PG8_MMA(0, 1, At, B1); PG8_BAR;
;             PG8_LDA(At, 1, 1); PG8_STAGE(PG8_SA(1, 0), a3, voffA);
;             PG8_BAR; PG8_WAIT_L(0); PG8_MMA(1, 0, At, B0); PG8_BAR; PG8_SCHED;
;             PG8_STAGE(PG8_SB(1, 1), b3 + hstep, voffB);
;             PG8_WAIT_V(6); PG8_BAR; PG8_MMA(1, 1, At, B1); PG8_BAR;
	s_waitcnt lgkmcnt(0)
	s_setprio 1
	v_mfma_f32_16x16x32_bf16 v[116:119], v[222:225], v[172:175], v[116:119]
	v_mfma_f32_16x16x32_bf16 v[112:115], v[230:233], v[172:175], v[112:115]
	v_mfma_f32_16x16x32_bf16 v[100:103], v[222:225], v[180:183], v[100:103]
	v_mfma_f32_16x16x32_bf16 v[96:99], v[230:233], v[180:183], v[96:99]
	v_mfma_f32_16x16x32_bf16 v[84:87], v[222:225], v[206:209], v[84:87]
	v_mfma_f32_16x16x32_bf16 v[80:83], v[230:233], v[206:209], v[80:83]
	v_mfma_f32_16x16x32_bf16 v[68:71], v[222:225], v[214:217], v[68:71]
	v_mfma_f32_16x16x32_bf16 v[64:67], v[230:233], v[214:217], v[64:67]
	v_mfma_f32_16x16x32_bf16 v[116:119], v[226:229], v[176:179], v[116:119]
	v_mfma_f32_16x16x32_bf16 v[112:115], v[234:237], v[176:179], v[112:115]
	v_mfma_f32_16x16x32_bf16 v[100:103], v[226:229], v[188:191], v[100:103]
	v_mfma_f32_16x16x32_bf16 v[96:99], v[234:237], v[188:191], v[96:99]
	v_mfma_f32_16x16x32_bf16 v[84:87], v[226:229], v[210:213], v[84:87]
	v_mfma_f32_16x16x32_bf16 v[80:83], v[234:237], v[210:213], v[80:83]
	v_mfma_f32_16x16x32_bf16 v[68:71], v[226:229], v[218:221], v[68:71]
	v_mfma_f32_16x16x32_bf16 v[64:67], v[234:237], v[218:221], v[64:67]
	s_setprio 0
	s_add_i32 m0, s59, 0xffffff80
	s_barrier
	ds_read_b128 v[172:175], v156 offset:49152
	ds_read_b128 v[176:179], v156 offset:50176
	ds_read_b128 v[180:183], v156 offset:51200
	ds_read_b128 v[188:191], v156 offset:52224
	ds_read_b128 v[206:209], v156 offset:53248
	ds_read_b128 v[210:213], v156 offset:54272
	ds_read_b128 v[214:217], v156 offset:55296
	global_load_lds_dwordx4 v128, s[42:43] offset:128
	s_add_i32 m0, s60, 0xffffff80
	ds_read_b128 v[218:221], v156 offset:56320
	global_load_lds_dwordx4 v132, s[42:43] offset:128
	s_barrier
	s_waitcnt lgkmcnt(0)
	s_setprio 1
	v_mfma_f32_16x16x32_bf16 v[60:63], v[144:147], v[172:175], v[60:63]
	v_mfma_f32_16x16x32_bf16 v[56:59], v[164:167], v[172:175], v[56:59]
	v_mfma_f32_16x16x32_bf16 v[44:47], v[144:147], v[180:183], v[44:47]
	v_mfma_f32_16x16x32_bf16 v[40:43], v[164:167], v[180:183], v[40:43]
	v_mfma_f32_16x16x32_bf16 v[28:31], v[144:147], v[206:209], v[28:31]
	v_mfma_f32_16x16x32_bf16 v[24:27], v[164:167], v[206:209], v[24:27]
	v_mfma_f32_16x16x32_bf16 v[12:15], v[144:147], v[214:217], v[12:15]
	v_mfma_f32_16x16x32_bf16 v[8:11], v[164:167], v[214:217], v[8:11]
	v_mfma_f32_16x16x32_bf16 v[60:63], v[160:163], v[176:179], v[60:63]
	v_mfma_f32_16x16x32_bf16 v[56:59], v[168:171], v[176:179], v[56:59]
	v_mfma_f32_16x16x32_bf16 v[44:47], v[160:163], v[188:191], v[44:47]
	v_mfma_f32_16x16x32_bf16 v[40:43], v[168:171], v[188:191], v[40:43]
	v_mfma_f32_16x16x32_bf16 v[28:31], v[160:163], v[210:213], v[28:31]
	v_mfma_f32_16x16x32_bf16 v[24:27], v[168:171], v[210:213], v[24:27]
	v_mfma_f32_16x16x32_bf16 v[12:15], v[160:163], v[218:221], v[12:15]
	v_mfma_f32_16x16x32_bf16 v[8:11], v[168:171], v[218:221], v[8:11]
	s_setprio 0
	s_barrier
	s_add_i32 s4, s5, s51
	s_mov_b32 m0, s4
	s_add_u32 s0, s40, 0x160080
	s_addc_u32 s1, s41, 0
	global_load_lds_dwordx4 v130, s[0:1]
	s_add_i32 m0, s4, 0x2000
	s_nop 0
	global_load_lds_dwordx4 v134, s[0:1]
	s_waitcnt vmcnt(6)
	s_barrier
	s_setprio 1
	v_mfma_f32_16x16x32_bf16 v[52:55], v[222:225], v[172:175], v[52:55]
	v_mfma_f32_16x16x32_bf16 v[48:51], v[230:233], v[172:175], v[48:51]
	v_mfma_f32_16x16x32_bf16 v[36:39], v[222:225], v[180:183], v[36:39]
	v_mfma_f32_16x16x32_bf16 v[32:35], v[230:233], v[180:183], v[32:35]
	v_mfma_f32_16x16x32_bf16 v[20:23], v[222:225], v[206:209], v[20:23]
	v_mfma_f32_16x16x32_bf16 v[16:19], v[230:233], v[206:209], v[16:19]
	v_mfma_f32_16x16x32_bf16 v[4:7], v[222:225], v[214:217], v[4:7]
	v_mfma_f32_16x16x32_bf16 v[0:3], v[230:233], v[214:217], v[0:3]
	v_mfma_f32_16x16x32_bf16 v[52:55], v[226:229], v[176:179], v[52:55]
	v_mfma_f32_16x16x32_bf16 v[48:51], v[234:237], v[176:179], v[48:51]
	v_mfma_f32_16x16x32_bf16 v[36:39], v[226:229], v[188:191], v[36:39]
	v_mfma_f32_16x16x32_bf16 v[32:35], v[234:237], v[188:191], v[32:35]
	v_mfma_f32_16x16x32_bf16 v[20:23], v[226:229], v[210:213], v[20:23]
	v_mfma_f32_16x16x32_bf16 v[16:19], v[234:237], v[210:213], v[16:19]
	v_mfma_f32_16x16x32_bf16 v[4:7], v[226:229], v[218:221], v[4:7]
	v_mfma_f32_16x16x32_bf16 v[0:3], v[234:237], v[218:221], v[0:3]
	s_setprio 0
	s_add_i32 s68, s68, 2
	s_add_u32 s38, s38, 0x100
	s_addc_u32 s39, s39, 0
	s_add_u32 s35, s35, 0x100
	s_addc_u32 s67, s67, 0
	s_cmpk_gt_u32 s68, 0x55
	s_cbranch_scc0 .Lrot_1746
	s_barrier

;     DI size_t aoff(const Unit& u, size_t tstep) const { return (size_t)u.pm * tstep; }
;     DI size_t boff(const Unit& u, size_t tstep) const { return (size_t)u.pn * tstep; }
;     DI bool next(int i, Unit& u) const { const long L = (long)i * G + c; if (L >= np) return false; u.pm = pmv; u.pn = (int)(L % nN); u.ks = (int)(L / nN); return true; }
;     DI size_t aoff(const Unit& u, size_t) const { return (size_t)u.ks * kbytes; }
;     DI size_t boff(const Unit& u, size_t tstep) const { return (size_t)u.pn * tstep + (size_t)u.ks * kbytes; }
;     DI bool next(int i, Unit& u) const { Unit t; if (!S.next(i / 3, t)) return false; u.pm = t.pm; u.pn = t.pn; u.ks = i % 3; return true; }
;     DI size_t aoff(const Unit& u, size_t tstep) const { return (u.ks < 2 ? offU : offOA) + (size_t)u.pm * tstep; }
; #define PG8_WAIT_V(n) asm volatile("s_waitcnt vmcnt(" #n ")" ::: "memory")
; template <class Epi, class Sched>
; DI void gemm_phase(LAS unsigned char* lds, const Gemm g, const Sched& S, const Epi& E) {
;     ...
;         const bool has_next = S.next(ui + 1, nxt);
;         const char* nA = has_next ? (const char*)g.A + S.aoff(nxt, tstep) : cA; const char* nB = has_next ? (const char*)g.Bt + S.boff(nxt, tstep) : cB;
;         for (int t = 0; t < nt; t += 2) {
;             if constexpr (Epi::HAS_MID) { if (t == E.mid_t(nt)) { int fr3 = fr, fq3 = fq; asm volatile("" : "+v"(fr3), "+v"(fq3)); E.mid(acc, cur, wr, wc, fr3, fq3); } }
;             const bool last = (t == nt - 2);
;             const char* a1 = cA + (size_t)(t + 1) * kstep;
;             const char* a2 = last ? nA : cA + (size_t)(t + 2) * kstep; const char* b2 = last ? nB : cB + (size_t)(t + 2) * kstep;
;             const char* a3 = a2 + kstep; const char* b3 = b2 + kstep;
;             PG8_LDB(B0, 0, 0); PG8_SCHED; PG8_LDA(At, 0, 0); PG8_STAGE(PG8_SA(1, 1), a1 + hstep, voffA);
;             PG8_WAIT_L(8); PG8_BAR; PG8_WAIT_L(0); PG8_MMA(0, 0, At, B0); PG8_BAR; PG8_SCHED;
;             PG8_LDB(B1, 0, 1); PG8_STAGE(PG8_SB(0, 0), b2, voffB);
;             PG8_BAR; PG8_WAIT_L(0); PG8_MMA(0, 1, At, B1); PG8_BAR;
;             PG8_LDA(At, 0, 1); PG8_STAGE(PG8_SA(0, 0), a2, voffA);
;             PG8_BAR; PG8_WAIT_L(0); PG8_MMA(1, 0, At, B0); PG8_BAR; PG8_SCHED;
;             PG8_STAGE(PG8_SB(0, 1), b2 + hstep, voffB);
;             PG8_WAIT_V(6); PG8_BAR; PG8_MMA(1, 1, At, B1); PG8_BAR;
.LBB0_1774:
	s_add_u32 s28, s38, s28
	s_addc_u32 s29, s39, s29
	s_and_b64 s[0:1], s[8:9], exec
	s_cselect_b32 s15, s29, s37
	s_cselect_b32 s17, s28, s36
	s_add_u32 s8, s36, 0x160080
	s_addc_u32 s9, s37, 0
	s_add_u32 s64, s30, 0x100
	v_mov_b32_e32 v0, 0
	s_addc_u32 s65, s31, 0
	s_mov_b32 s66, -2
	ds_read_b128 v[146:149], v141
	ds_read_b128 v[154:157], v141 offset:1024
	ds_read_b128 v[158:161], v141 offset:2048
	ds_read_b128 v[162:165], v141 offset:3072
	s_mov_b32 m0, s56
	ds_read_b128 v[166:169], v142
	ds_read_b128 v[170:173], v142 offset:1024
	ds_read_b128 v[174:177], v142 offset:2048
	ds_read_b128 v[178:181], v142 offset:3072
	ds_read_b128 v[188:191], v142 offset:4096
	ds_read_b128 v[206:209], v142 offset:5120
	ds_read_b128 v[210:213], v142 offset:6144
	global_load_lds_dwordx4 v132, s[8:9]
	s_mov_b32 m0, s57
	ds_read_b128 v[214:217], v142 offset:7168
	global_load_lds_dwordx4 v134, s[8:9]
	s_add_u32 s0, s8, 0xffea0080
	s_addc_u32 s1, s9, -1
	s_cmp_eq_u32 s66, 4
	s_cselect_b32 s37, s15, s1
	s_cselect_b32 s36, s17, s0
	s_cselect_b32 s31, s19, s65
	s_cselect_b32 s30, s18, s64
	s_waitcnt lgkmcnt(8)
	s_barrier
	s_waitcnt lgkmcnt(0)
	s_setprio 1
	v_mfma_f32_16x16x32_bf16 v[124:127], v[146:149], v[166:169], 0
	v_mfma_f32_16x16x32_bf16 v[120:123], v[158:161], v[166:169], 0
	v_mfma_f32_16x16x32_bf16 v[116:119], v[146:149], v[174:177], 0
	v_mfma_f32_16x16x32_bf16 v[112:115], v[158:161], v[174:177], 0
	v_mfma_f32_16x16x32_bf16 v[104:107], v[146:149], v[188:191], 0
	v_mfma_f32_16x16x32_bf16 v[96:99], v[158:161], v[188:191], 0
	v_mfma_f32_16x16x32_bf16 v[88:91], v[146:149], v[210:213], 0
	v_mfma_f32_16x16x32_bf16 v[80:83], v[158:161], v[210:213], 0
	v_mfma_f32_16x16x32_bf16 v[124:127], v[154:157], v[170:173], v[124:127]
	v_mfma_f32_16x16x32_bf16 v[120:123], v[162:165], v[170:173], v[120:123]
	v_mfma_f32_16x16x32_bf16 v[116:119], v[154:157], v[178:181], v[116:119]
	v_mfma_f32_16x16x32_bf16 v[112:115], v[162:165], v[178:181], v[112:115]
	v_mfma_f32_16x16x32_bf16 v[104:107], v[154:157], v[206:209], v[104:107]
	v_mfma_f32_16x16x32_bf16 v[96:99], v[162:165], v[206:209], v[96:99]
	v_mfma_f32_16x16x32_bf16 v[88:91], v[154:157], v[214:217], v[88:91]
	v_mfma_f32_16x16x32_bf16 v[80:83], v[162:165], v[214:217], v[80:83]
	s_setprio 0
	s_barrier
	s_mov_b32 m0, s58
	ds_read_b128 v[218:221], v143
	ds_read_b128 v[222:225], v143 offset:1024
	ds_read_b128 v[226:229], v143 offset:2048
	global_load_lds_dwordx4 v130, s[30:31]
	s_mov_b32 m0, s59
	ds_read_b128 v[230:233], v143 offset:3072
	global_load_lds_dwordx4 v128, s[30:31]
	s_barrier
	s_waitcnt lgkmcnt(0)
	s_setprio 1
	v_mfma_f32_16x16x32_bf16 v[108:111], v[218:221], v[166:169], 0
	v_mfma_f32_16x16x32_bf16 v[100:103], v[226:229], v[166:169], 0
	v_mfma_f32_16x16x32_bf16 v[92:95], v[218:221], v[174:177], 0
	v_mfma_f32_16x16x32_bf16 v[84:87], v[226:229], v[174:177], 0
	v_mfma_f32_16x16x32_bf16 v[76:79], v[218:221], v[188:191], 0
	v_mfma_f32_16x16x32_bf16 v[72:75], v[226:229], v[188:191], 0
	v_mfma_f32_16x16x32_bf16 v[68:71], v[218:221], v[210:213], 0
	v_mfma_f32_16x16x32_bf16 v[64:67], v[226:229], v[210:213], 0
	v_mfma_f32_16x16x32_bf16 v[108:111], v[222:225], v[170:173], v[108:111]
	v_mfma_f32_16x16x32_bf16 v[100:103], v[230:233], v[170:173], v[100:103]
	v_mfma_f32_16x16x32_bf16 v[92:95], v[222:225], v[178:181], v[92:95]
	v_mfma_f32_16x16x32_bf16 v[84:87], v[230:233], v[178:181], v[84:87]
	v_mfma_f32_16x16x32_bf16 v[76:79], v[222:225], v[206:209], v[76:79]
	v_mfma_f32_16x16x32_bf16 v[72:75], v[230:233], v[206:209], v[72:75]
	v_mfma_f32_16x16x32_bf16 v[68:71], v[222:225], v[214:217], v[68:71]
	v_mfma_f32_16x16x32_bf16 v[64:67], v[230:233], v[214:217], v[64:67]
	s_setprio 0
	s_mov_b32 m0, s40
	s_barrier
	ds_read_b128 v[166:169], v142 offset:16384
	ds_read_b128 v[170:173], v142 offset:17408
	ds_read_b128 v[174:177], v142 offset:18432
	ds_read_b128 v[178:181], v142 offset:19456
	ds_read_b128 v[188:191], v142 offset:20480
	ds_read_b128 v[206:209], v142 offset:21504
	ds_read_b128 v[210:213], v142 offset:22528
	global_load_lds_dwordx4 v130, s[36:37]
	s_mov_b32 m0, s41
	ds_read_b128 v[214:217], v142 offset:23552
	global_load_lds_dwordx4 v128, s[36:37]
	s_barrier
	s_waitcnt lgkmcnt(0)
	s_setprio 1
	v_mfma_f32_16x16x32_bf16 v[60:63], v[146:149], v[166:169], 0
	v_mfma_f32_16x16x32_bf16 v[56:59], v[158:161], v[166:169], 0
	v_mfma_f32_16x16x32_bf16 v[52:55], v[146:149], v[174:177], 0
	v_mfma_f32_16x16x32_bf16 v[48:51], v[158:161], v[174:177], 0
	v_mfma_f32_16x16x32_bf16 v[40:43], v[146:149], v[188:191], 0
	v_mfma_f32_16x16x32_bf16 v[32:35], v[158:161], v[188:191], 0
	v_mfma_f32_16x16x32_bf16 v[24:27], v[146:149], v[210:213], 0
	v_mfma_f32_16x16x32_bf16 v[16:19], v[158:161], v[210:213], 0
	v_mfma_f32_16x16x32_bf16 v[60:63], v[154:157], v[170:173], v[60:63]
	v_mfma_f32_16x16x32_bf16 v[56:59], v[162:165], v[170:173], v[56:59]
	v_mfma_f32_16x16x32_bf16 v[52:55], v[154:157], v[178:181], v[52:55]
	v_mfma_f32_16x16x32_bf16 v[48:51], v[162:165], v[178:181], v[48:51]
	v_mfma_f32_16x16x32_bf16 v[40:43], v[154:157], v[206:209], v[40:43]
	v_mfma_f32_16x16x32_bf16 v[32:35], v[162:165], v[206:209], v[32:35]
	v_mfma_f32_16x16x32_bf16 v[24:27], v[154:157], v[214:217], v[24:27]
	v_mfma_f32_16x16x32_bf16 v[16:19], v[162:165], v[214:217], v[16:19]
	s_setprio 0
	s_barrier
	s_add_u32 s0, s30, 0x160000
	s_addc_u32 s1, s31, 0
	s_mov_b32 m0, s60
	s_nop 0
	global_load_lds_dwordx4 v130, s[0:1]
	s_mov_b32 m0, s61
	s_nop 0
	global_load_lds_dwordx4 v128, s[0:1]
	s_waitcnt vmcnt(6)
	s_barrier
; #define PG8_STAGE(bufoff, gbase, voff) do { _Pragma("unroll") for (int _i = 0; _i < 2; ++_i) \
;         __builtin_amdgcn_global_load_lds((const unsigned*)((const char*)(gbase) + (voff)[_i]), (LAS unsigned*)(lds + (bufoff) + ldsw + _i * 8192), 16, 0, 0); } while (0)
; #define PG8_LDA(dst, b, h) do { _Pragma("unroll") for (int m = 0; m < 4; ++m) _Pragma("unroll") for (int k = 0; k < 2; ++k) dst[m][k] = *(const LAS bf16x8*)(lds + PG8_SA(b, h) + aoff + m * 2048 + k * 1024); } while (0)
; #define PG8_LDB(dst, b, h) do { _Pragma("unroll") for (int n = 0; n < 2; ++n) _Pragma("unroll") for (int k = 0; k < 2; ++k) dst[n][k] = *(const LAS bf16x8*)(lds + PG8_SB(b, h) + boff + n * 2048 + k * 1024); } while (0)
; #define PG8_MMA(ai, bj, At, Bt) do { __builtin_amdgcn_s_setprio(1); _Pragma("unroll") for (int m = 0; m < 4; ++m) _Pragma("unroll") for (int n = 0; n < 2; ++n) _Pragma("unroll") for (int k = 0; k < 2; ++k) \
;         acc[ai][bj][m][n] = __builtin_amdgcn_mfma_f32_16x16x32_bf16(Bt[n][k], At[m][k], acc[ai][bj][m][n], 0, 0, 0); __builtin_amdgcn_s_setprio(0); } while (0)
; #define PG8_WAIT_V(n) asm volatile("s_waitcnt vmcnt(" #n ")" ::: "memory")
; #define PG8_WAIT_L(n) asm volatile("s_waitcnt lgkmcnt(" #n ")" ::: "memory")
; #define PG8_BAR __builtin_amdgcn_s_barrier()
; #define PG8_SCHED __builtin_amdgcn_sched_barrier(0)
; template <class Epi, class Sched>
; DI void gemm_phase(LAS unsigned char* lds, const Gemm g, const Sched& S, const Epi& E) {
;     ...
;             PG8_WAIT_V(6); PG8_BAR; PG8_MMA(1, 1, At, B1); PG8_BAR;
;             PG8_LDB(B0, 1, 0); PG8_SCHED; PG8_LDA(At, 1, 0); PG8_STAGE(PG8_SA(0, 1), a2 + hstep, voffA);
;             PG8_WAIT_L(8); PG8_BAR; PG8_WAIT_L(0); PG8_MMA(0, 0, At, B0); PG8_BAR; PG8_SCHED;
;             PG8_LDB(B1, 1, 1); PG8_STAGE(PG8_SB(1, 0), b3, voffB);
	s_setprio 1
	v_mfma_f32_16x16x32_bf16 v[44:47], v[218:221], v[166:169], 0
	v_mfma_f32_16x16x32_bf16 v[36:39], v[226:229], v[166:169], 0
	v_mfma_f32_16x16x32_bf16 v[28:31], v[218:221], v[174:177], 0
	v_mfma_f32_16x16x32_bf16 v[20:23], v[226:229], v[174:177], 0
	v_mfma_f32_16x16x32_bf16 v[12:15], v[218:221], v[188:191], 0
	v_mfma_f32_16x16x32_bf16 v[8:11], v[226:229], v[188:191], 0
	v_mfma_f32_16x16x32_bf16 v[4:7], v[218:221], v[210:213], 0
	v_mfma_f32_16x16x32_bf16 v[0:3], v[226:229], v[210:213], 0
	v_mfma_f32_16x16x32_bf16 v[44:47], v[222:225], v[170:173], v[44:47]
	v_mfma_f32_16x16x32_bf16 v[36:39], v[230:233], v[170:173], v[36:39]
	v_mfma_f32_16x16x32_bf16 v[28:31], v[222:225], v[178:181], v[28:31]
	v_mfma_f32_16x16x32_bf16 v[20:23], v[230:233], v[178:181], v[20:23]
	v_mfma_f32_16x16x32_bf16 v[12:15], v[222:225], v[206:209], v[12:15]
	v_mfma_f32_16x16x32_bf16 v[8:11], v[230:233], v[206:209], v[8:11]
	v_mfma_f32_16x16x32_bf16 v[4:7], v[222:225], v[214:217], v[4:7]
	v_mfma_f32_16x16x32_bf16 v[0:3], v[230:233], v[214:217], v[0:3]
	s_setprio 0
	s_barrier
	ds_read_b128 v[146:149], v144
	ds_read_b128 v[154:157], v144 offset:1024
	ds_read_b128 v[158:161], v144 offset:2048
	ds_read_b128 v[162:165], v144 offset:3072
	s_add_u32 s0, s36, 0x160000
	s_addc_u32 s1, s37, 0
	s_mov_b32 m0, s42
	ds_read_b128 v[166:169], v142 offset:32768
	ds_read_b128 v[170:173], v142 offset:33792
	ds_read_b128 v[174:177], v142 offset:34816
	ds_read_b128 v[178:181], v142 offset:35840
	ds_read_b128 v[188:191], v142 offset:36864
	ds_read_b128 v[206:209], v142 offset:37888
	ds_read_b128 v[210:213], v142 offset:38912
	global_load_lds_dwordx4 v130, s[0:1]
	s_mov_b32 m0, s43
	ds_read_b128 v[214:217], v142 offset:39936
	global_load_lds_dwordx4 v128, s[0:1]
	s_waitcnt lgkmcnt(8)
	s_barrier
	s_waitcnt lgkmcnt(0)
	s_setprio 1
	v_mfma_f32_16x16x32_bf16 v[124:127], v[146:149], v[166:169], v[124:127]
	v_mfma_f32_16x16x32_bf16 v[120:123], v[158:161], v[166:169], v[120:123]
	v_mfma_f32_16x16x32_bf16 v[116:119], v[146:149], v[174:177], v[116:119]
	v_mfma_f32_16x16x32_bf16 v[112:115], v[158:161], v[174:177], v[112:115]
	v_mfma_f32_16x16x32_bf16 v[104:107], v[146:149], v[188:191], v[104:107]
	v_mfma_f32_16x16x32_bf16 v[96:99], v[158:161], v[188:191], v[96:99]
	v_mfma_f32_16x16x32_bf16 v[88:91], v[146:149], v[210:213], v[88:91]
	v_mfma_f32_16x16x32_bf16 v[80:83], v[158:161], v[210:213], v[80:83]
	v_mfma_f32_16x16x32_bf16 v[124:127], v[154:157], v[170:173], v[124:127]
	v_mfma_f32_16x16x32_bf16 v[120:123], v[162:165], v[170:173], v[120:123]
	v_mfma_f32_16x16x32_bf16 v[116:119], v[154:157], v[178:181], v[116:119]
	v_mfma_f32_16x16x32_bf16 v[112:115], v[162:165], v[178:181], v[112:115]
	v_mfma_f32_16x16x32_bf16 v[104:107], v[154:157], v[206:209], v[104:107]
	v_mfma_f32_16x16x32_bf16 v[96:99], v[162:165], v[206:209], v[96:99]
	v_mfma_f32_16x16x32_bf16 v[88:91], v[154:157], v[214:217], v[88:91]
	v_mfma_f32_16x16x32_bf16 v[80:83], v[162:165], v[214:217], v[80:83]
	s_setprio 0
	s_barrier
	s_add_i32 s4, 0, 0x1c000
	s_add_i32 s0, s62, s35
	v_add_u32_e32 v145, s4, v140
	s_add_i32 m0, s0, 0xffffff80
	ds_read_b128 v[218:221], v145
	ds_read_b128 v[222:225], v145 offset:1024
	ds_read_b128 v[226:229], v145 offset:2048
	global_load_lds_dwordx4 v130, s[30:31] offset:128
	s_add_i32 m0, s0, 0x1f80
	ds_read_b128 v[230:233], v145 offset:3072
	global_load_lds_dwordx4 v128, s[30:31] offset:128
	s_barrier
; #define PG8_STAGE(bufoff, gbase, voff) do { _Pragma("unroll") for (int _i = 0; _i < 2; ++_i) \
;         __builtin_amdgcn_global_load_lds((const unsigned*)((const char*)(gbase) + (voff)[_i]), (LAS unsigned*)(lds + (bufoff) + ldsw + _i * 8192), 16, 0, 0); } while (0)
; #define PG8_LDA(dst, b, h) do { _Pragma("unroll") for (int m = 0; m < 4; ++m) _Pragma("unroll") for (int k = 0; k < 2; ++k) dst[m][k] = *(const LAS bf16x8*)(lds + PG8_SA(b, h) + aoff + m * 2048 + k * 1024); } while (0)
; #define PG8_MMA(ai, bj, At, Bt) do { __builtin_amdgcn_s_setprio(1); _Pragma("unroll") for (int m = 0; m < 4; ++m) _Pragma("unroll") for (int n = 0; n < 2; ++n) _Pragma("unroll") for (int k = 0; k < 2; ++k) \
;         acc[ai][bj][m][n] = __builtin_amdgcn_mfma_f32_16x16x32_bf16(Bt[n][k], At[m][k], acc[ai][bj][m][n], 0, 0, 0); __builtin_amdgcn_s_setprio(0); } while (0)
; #define PG8_WAIT_V(n) asm volatile("s_waitcnt vmcnt(" #n ")" ::: "memory")
; #define PG8_WAIT_L(n) asm volatile("s_waitcnt lgkmcnt(" #n ")" ::: "memory")
; #define PG8_BAR __builtin_amdgcn_s_barrier()
; #define PG8_SCHED __builtin_amdgcn_sched_barrier(0)
; template <class Epi, class Sched>
; DI void gemm_phase(LAS unsigned char* lds, const Gemm g, const Sched& S, const Epi& E) {
;     ...
;             PG8_BAR; PG8_WAIT_L(0); PG8_MMA(0, 1, At, B1); PG8_BAR;
;             PG8_LDA(At, 1, 1); PG8_STAGE(PG8_SA(1, 0), a3, voffA);
;             PG8_BAR; PG8_WAIT_L(0); PG8_MMA(1, 0, At, B0); PG8_BAR; PG8_SCHED;
;             PG8_STAGE(PG8_SB(1, 1), b3 + hstep, voffB);
;             PG8_WAIT_V(6); PG8_BAR; PG8_MMA(1, 1, At, B1); PG8_BAR;
	s_waitcnt lgkmcnt(0)
	s_setprio 1
	v_mfma_f32_16x16x32_bf16 v[108:111], v[218:221], v[166:169], v[108:111]
	v_mfma_f32_16x16x32_bf16 v[100:103], v[226:229], v[166:169], v[100:103]
	v_mfma_f32_16x16x32_bf16 v[92:95], v[218:221], v[174:177], v[92:95]
	v_mfma_f32_16x16x32_bf16 v[84:87], v[226:229], v[174:177], v[84:87]
	v_mfma_f32_16x16x32_bf16 v[76:79], v[218:221], v[188:191], v[76:79]
	v_mfma_f32_16x16x32_bf16 v[72:75], v[226:229], v[188:191], v[72:75]
	v_mfma_f32_16x16x32_bf16 v[68:71], v[218:221], v[210:213], v[68:71]
	v_mfma_f32_16x16x32_bf16 v[64:67], v[226:229], v[210:213], v[64:67]
	v_mfma_f32_16x16x32_bf16 v[108:111], v[222:225], v[170:173], v[108:111]
	v_mfma_f32_16x16x32_bf16 v[100:103], v[230:233], v[170:173], v[100:103]
	v_mfma_f32_16x16x32_bf16 v[92:95], v[222:225], v[178:181], v[92:95]
	v_mfma_f32_16x16x32_bf16 v[84:87], v[230:233], v[178:181], v[84:87]
	v_mfma_f32_16x16x32_bf16 v[76:79], v[222:225], v[206:209], v[76:79]
	v_mfma_f32_16x16x32_bf16 v[72:75], v[230:233], v[206:209], v[72:75]
	v_mfma_f32_16x16x32_bf16 v[68:71], v[222:225], v[214:217], v[68:71]
	v_mfma_f32_16x16x32_bf16 v[64:67], v[230:233], v[214:217], v[64:67]
	s_setprio 0
	s_add_i32 m0, s54, 0xffffff80
	s_barrier
	ds_read_b128 v[166:169], v142 offset:49152
	ds_read_b128 v[170:173], v142 offset:50176
	ds_read_b128 v[174:177], v142 offset:51200
	ds_read_b128 v[178:181], v142 offset:52224
	ds_read_b128 v[188:191], v142 offset:53248
	ds_read_b128 v[206:209], v142 offset:54272
	ds_read_b128 v[210:213], v142 offset:55296
	global_load_lds_dwordx4 v130, s[36:37] offset:128
	s_add_i32 m0, s55, 0xffffff80
	ds_read_b128 v[214:217], v142 offset:56320
	global_load_lds_dwordx4 v128, s[36:37] offset:128
	s_barrier
	s_waitcnt lgkmcnt(0)
	s_setprio 1
	v_mfma_f32_16x16x32_bf16 v[60:63], v[146:149], v[166:169], v[60:63]
	v_mfma_f32_16x16x32_bf16 v[56:59], v[158:161], v[166:169], v[56:59]
	v_mfma_f32_16x16x32_bf16 v[52:55], v[146:149], v[174:177], v[52:55]
	v_mfma_f32_16x16x32_bf16 v[48:51], v[158:161], v[174:177], v[48:51]
	v_mfma_f32_16x16x32_bf16 v[40:43], v[146:149], v[188:191], v[40:43]
	v_mfma_f32_16x16x32_bf16 v[32:35], v[158:161], v[188:191], v[32:35]
	v_mfma_f32_16x16x32_bf16 v[24:27], v[146:149], v[210:213], v[24:27]
	v_mfma_f32_16x16x32_bf16 v[16:19], v[158:161], v[210:213], v[16:19]
	v_mfma_f32_16x16x32_bf16 v[60:63], v[154:157], v[170:173], v[60:63]
	v_mfma_f32_16x16x32_bf16 v[56:59], v[162:165], v[170:173], v[56:59]
	v_mfma_f32_16x16x32_bf16 v[52:55], v[154:157], v[178:181], v[52:55]
	v_mfma_f32_16x16x32_bf16 v[48:51], v[162:165], v[178:181], v[48:51]
	v_mfma_f32_16x16x32_bf16 v[40:43], v[154:157], v[206:209], v[40:43]
	v_mfma_f32_16x16x32_bf16 v[32:35], v[162:165], v[206:209], v[32:35]
	v_mfma_f32_16x16x32_bf16 v[24:27], v[154:157], v[214:217], v[24:27]
	v_mfma_f32_16x16x32_bf16 v[16:19], v[162:165], v[214:217], v[16:19]
	s_setprio 0
	s_barrier
	s_add_i32 s4, s4, s35
	s_mov_b32 m0, s4
	s_add_u32 s0, s30, 0x160080
	s_addc_u32 s1, s31, 0
	global_load_lds_dwordx4 v130, s[0:1]
	s_add_i32 m0, s4, 0x2000
	s_add_i32 s66, s66, 2
	global_load_lds_dwordx4 v128, s[0:1]
	s_add_u32 s8, s8, 0x100
	s_addc_u32 s9, s9, 0
	s_add_u32 s64, s64, 0x100
	s_addc_u32 s65, s65, 0
	s_cmp_gt_u32 s66, 5
	s_waitcnt vmcnt(6)
	s_barrier
	s_setprio 1
	v_mfma_f32_16x16x32_bf16 v[44:47], v[218:221], v[166:169], v[44:47]
	v_mfma_f32_16x16x32_bf16 v[36:39], v[226:229], v[166:169], v[36:39]
	v_mfma_f32_16x16x32_bf16 v[28:31], v[218:221], v[174:177], v[28:31]
	v_mfma_f32_16x16x32_bf16 v[20:23], v[226:229], v[174:177], v[20:23]
	v_mfma_f32_16x16x32_bf16 v[12:15], v[218:221], v[188:191], v[12:15]
	v_mfma_f32_16x16x32_bf16 v[8:11], v[226:229], v[188:191], v[8:11]
	v_mfma_f32_16x16x32_bf16 v[4:7], v[218:221], v[210:213], v[4:7]
	v_mfma_f32_16x16x32_bf16 v[0:3], v[226:229], v[210:213], v[0:3]
	v_mfma_f32_16x16x32_bf16 v[44:47], v[222:225], v[170:173], v[44:47]
	v_mfma_f32_16x16x32_bf16 v[36:39], v[230:233], v[170:173], v[36:39]
	v_mfma_f32_16x16x32_bf16 v[28:31], v[222:225], v[178:181], v[28:31]
	v_mfma_f32_16x16x32_bf16 v[20:23], v[230:233], v[178:181], v[20:23]
	v_mfma_f32_16x16x32_bf16 v[12:15], v[222:225], v[206:209], v[12:15]
	v_mfma_f32_16x16x32_bf16 v[8:11], v[230:233], v[206:209], v[8:11]
	v_mfma_f32_16x16x32_bf16 v[4:7], v[222:225], v[214:217], v[4:7]
	v_mfma_f32_16x16x32_bf16 v[0:3], v[230:233], v[214:217], v[0:3]
	s_setprio 0
	s_cbranch_scc0 .Lrot_1775
	s_barrier
	s_branch .Lpeel_done_1775

; #define PG8_STAGE(bufoff, gbase, voff) do { _Pragma("unroll") for (int _i = 0; _i < 2; ++_i) \
;         __builtin_amdgcn_global_load_lds((const unsigned*)((const char*)(gbase) + (voff)[_i]), (LAS unsigned*)(lds + (bufoff) + ldsw + _i * 8192), 16, 0, 0); } while (0)
; #define PG8_LDA(dst, b, h) do { _Pragma("unroll") for (int m = 0; m < 4; ++m) _Pragma("unroll") for (int k = 0; k < 2; ++k) dst[m][k] = *(const LAS bf16x8*)(lds + PG8_SA(b, h) + aoff + m * 2048 + k * 1024); } while (0)
; #define PG8_LDB(dst, b, h) do { _Pragma("unroll") for (int n = 0; n < 2; ++n) _Pragma("unroll") for (int k = 0; k < 2; ++k) dst[n][k] = *(const LAS bf16x8*)(lds + PG8_SB(b, h) + boff + n * 2048 + k * 1024); } while (0)
; #define PG8_MMA(ai, bj, At, Bt) do { __builtin_amdgcn_s_setprio(1); _Pragma("unroll") for (int m = 0; m < 4; ++m) _Pragma("unroll") for (int n = 0; n < 2; ++n) _Pragma("unroll") for (int k = 0; k < 2; ++k) \
;         acc[ai][bj][m][n] = __builtin_amdgcn_mfma_f32_16x16x32_bf16(Bt[n][k], At[m][k], acc[ai][bj][m][n], 0, 0, 0); __builtin_amdgcn_s_setprio(0); } while (0)
; #define PG8_WAIT_V(n) asm volatile("s_waitcnt vmcnt(" #n ")" ::: "memory")
; #define PG8_WAIT_L(n) asm volatile("s_waitcnt lgkmcnt(" #n ")" ::: "memory")
; #define PG8_BAR __builtin_amdgcn_s_barrier()
; #define PG8_SCHED __builtin_amdgcn_sched_barrier(0)
; template <class Epi, class Sched>
; DI void gemm_phase(LAS unsigned char* lds, const Gemm g, const Sched& S, const Epi& E) {
;     ...
;             PG8_LDB(B0, 0, 0); PG8_SCHED; PG8_LDA(At, 0, 0); PG8_STAGE(PG8_SA(1, 1), a1 + hstep, voffA);
;             PG8_WAIT_L(8); PG8_BAR; PG8_WAIT_L(0); PG8_MMA(0, 0, At, B0); PG8_BAR; PG8_SCHED;
;             PG8_LDB(B1, 0, 1); PG8_STAGE(PG8_SB(0, 0), b2, voffB);
;             PG8_BAR; PG8_WAIT_L(0); PG8_MMA(0, 1, At, B1); PG8_BAR;
;             PG8_LDA(At, 0, 1); PG8_STAGE(PG8_SA(0, 0), a2, voffA);
;             PG8_BAR; PG8_WAIT_L(0); PG8_MMA(1, 0, At, B0); PG8_BAR; PG8_SCHED;
;             PG8_STAGE(PG8_SB(0, 1), b2 + hstep, voffB);
;             PG8_WAIT_V(6); PG8_BAR; PG8_MMA(1, 1, At, B1); PG8_BAR;
.LBB0_1775:
	ds_read_b128 v[146:149], v141
	ds_read_b128 v[154:157], v141 offset:1024
	ds_read_b128 v[158:161], v141 offset:2048
	ds_read_b128 v[162:165], v141 offset:3072
	s_mov_b32 m0, s56
	ds_read_b128 v[166:169], v142
	ds_read_b128 v[170:173], v142 offset:1024
	ds_read_b128 v[174:177], v142 offset:2048
	ds_read_b128 v[178:181], v142 offset:3072
	ds_read_b128 v[188:191], v142 offset:4096
	ds_read_b128 v[206:209], v142 offset:5120
	ds_read_b128 v[210:213], v142 offset:6144
	global_load_lds_dwordx4 v132, s[8:9]
	s_mov_b32 m0, s57
	ds_read_b128 v[214:217], v142 offset:7168
	global_load_lds_dwordx4 v134, s[8:9]
	s_add_u32 s0, s8, 0xffea0080
	s_addc_u32 s1, s9, -1
	s_cmp_eq_u32 s66, 4
	s_cselect_b32 s37, s15, s1
	s_cselect_b32 s36, s17, s0
	s_cselect_b32 s31, s19, s65
	s_cselect_b32 s30, s18, s64
	s_waitcnt lgkmcnt(8)
	s_barrier
	s_waitcnt lgkmcnt(0)
	s_setprio 1
	v_mfma_f32_16x16x32_bf16 v[124:127], v[146:149], v[166:169], v[124:127]
	v_mfma_f32_16x16x32_bf16 v[120:123], v[158:161], v[166:169], v[120:123]
	v_mfma_f32_16x16x32_bf16 v[116:119], v[146:149], v[174:177], v[116:119]
	v_mfma_f32_16x16x32_bf16 v[112:115], v[158:161], v[174:177], v[112:115]
	v_mfma_f32_16x16x32_bf16 v[104:107], v[146:149], v[188:191], v[104:107]
	v_mfma_f32_16x16x32_bf16 v[96:99], v[158:161], v[188:191], v[96:99]
	v_mfma_f32_16x16x32_bf16 v[88:91], v[146:149], v[210:213], v[88:91]
	v_mfma_f32_16x16x32_bf16 v[80:83], v[158:161], v[210:213], v[80:83]
	v_mfma_f32_16x16x32_bf16 v[124:127], v[154:157], v[170:173], v[124:127]
	v_mfma_f32_16x16x32_bf16 v[120:123], v[162:165], v[170:173], v[120:123]
	v_mfma_f32_16x16x32_bf16 v[116:119], v[154:157], v[178:181], v[116:119]
	v_mfma_f32_16x16x32_bf16 v[112:115], v[162:165], v[178:181], v[112:115]
	v_mfma_f32_16x16x32_bf16 v[104:107], v[154:157], v[206:209], v[104:107]
	v_mfma_f32_16x16x32_bf16 v[96:99], v[162:165], v[206:209], v[96:99]
	v_mfma_f32_16x16x32_bf16 v[88:91], v[154:157], v[214:217], v[88:91]
	v_mfma_f32_16x16x32_bf16 v[80:83], v[162:165], v[214:217], v[80:83]
	s_setprio 0
	s_barrier
	s_mov_b32 m0, s58
	ds_read_b128 v[218:221], v143
	ds_read_b128 v[222:225], v143 offset:1024
	ds_read_b128 v[226:229], v143 offset:2048
	global_load_lds_dwordx4 v130, s[30:31]
	s_mov_b32 m0, s59
	ds_read_b128 v[230:233], v143 offset:3072
	global_load_lds_dwordx4 v128, s[30:31]
	s_barrier
	s_waitcnt lgkmcnt(0)
	s_setprio 1
	v_mfma_f32_16x16x32_bf16 v[108:111], v[218:221], v[166:169], v[108:111]
	v_mfma_f32_16x16x32_bf16 v[100:103], v[226:229], v[166:169], v[100:103]
	v_mfma_f32_16x16x32_bf16 v[92:95], v[218:221], v[174:177], v[92:95]
	v_mfma_f32_16x16x32_bf16 v[84:87], v[226:229], v[174:177], v[84:87]
	v_mfma_f32_16x16x32_bf16 v[76:79], v[218:221], v[188:191], v[76:79]
	v_mfma_f32_16x16x32_bf16 v[72:75], v[226:229], v[188:191], v[72:75]
	v_mfma_f32_16x16x32_bf16 v[68:71], v[218:221], v[210:213], v[68:71]
	v_mfma_f32_16x16x32_bf16 v[64:67], v[226:229], v[210:213], v[64:67]
	v_mfma_f32_16x16x32_bf16 v[108:111], v[222:225], v[170:173], v[108:111]
	v_mfma_f32_16x16x32_bf16 v[100:103], v[230:233], v[170:173], v[100:103]
	v_mfma_f32_16x16x32_bf16 v[92:95], v[222:225], v[178:181], v[92:95]
	v_mfma_f32_16x16x32_bf16 v[84:87], v[230:233], v[178:181], v[84:87]
	v_mfma_f32_16x16x32_bf16 v[76:79], v[222:225], v[206:209], v[76:79]
	v_mfma_f32_16x16x32_bf16 v[72:75], v[230:233], v[206:209], v[72:75]
	v_mfma_f32_16x16x32_bf16 v[68:71], v[222:225], v[214:217], v[68:71]
	v_mfma_f32_16x16x32_bf16 v[64:67], v[230:233], v[214:217], v[64:67]
	s_setprio 0
	s_mov_b32 m0, s40
	s_barrier
	ds_read_b128 v[166:169], v142 offset:16384
	ds_read_b128 v[170:173], v142 offset:17408
	ds_read_b128 v[174:177], v142 offset:18432
	ds_read_b128 v[178:181], v142 offset:19456
	ds_read_b128 v[188:191], v142 offset:20480
	ds_read_b128 v[206:209], v142 offset:21504
	ds_read_b128 v[210:213], v142 offset:22528
	global_load_lds_dwordx4 v130, s[36:37]
	s_mov_b32 m0, s41
	ds_read_b128 v[214:217], v142 offset:23552
	global_load_lds_dwordx4 v128, s[36:37]
	s_barrier
	s_waitcnt lgkmcnt(0)
	s_setprio 1
	v_mfma_f32_16x16x32_bf16 v[60:63], v[146:149], v[166:169], v[60:63]
	v_mfma_f32_16x16x32_bf16 v[56:59], v[158:161], v[166:169], v[56:59]
	v_mfma_f32_16x16x32_bf16 v[52:55], v[146:149], v[174:177], v[52:55]
	v_mfma_f32_16x16x32_bf16 v[48:51], v[158:161], v[174:177], v[48:51]
	v_mfma_f32_16x16x32_bf16 v[40:43], v[146:149], v[188:191], v[40:43]
	v_mfma_f32_16x16x32_bf16 v[32:35], v[158:161], v[188:191], v[32:35]
	v_mfma_f32_16x16x32_bf16 v[24:27], v[146:149], v[210:213], v[24:27]
	v_mfma_f32_16x16x32_bf16 v[16:19], v[158:161], v[210:213], v[16:19]
	v_mfma_f32_16x16x32_bf16 v[60:63], v[154:157], v[170:173], v[60:63]
	v_mfma_f32_16x16x32_bf16 v[56:59], v[162:165], v[170:173], v[56:59]
	v_mfma_f32_16x16x32_bf16 v[52:55], v[154:157], v[178:181], v[52:55]
	v_mfma_f32_16x16x32_bf16 v[48:51], v[162:165], v[178:181], v[48:51]
	v_mfma_f32_16x16x32_bf16 v[40:43], v[154:157], v[206:209], v[40:43]
	v_mfma_f32_16x16x32_bf16 v[32:35], v[162:165], v[206:209], v[32:35]
	v_mfma_f32_16x16x32_bf16 v[24:27], v[154:157], v[214:217], v[24:27]
	v_mfma_f32_16x16x32_bf16 v[16:19], v[162:165], v[214:217], v[16:19]
	s_setprio 0
	s_barrier
	s_add_u32 s0, s30, 0x160000
	s_addc_u32 s1, s31, 0
	s_mov_b32 m0, s60
	s_nop 0
	global_load_lds_dwordx4 v130, s[0:1]
	s_mov_b32 m0, s61
	s_nop 0
	global_load_lds_dwordx4 v128, s[0:1]
	s_waitcnt vmcnt(6)
	s_barrier
; #define PG8_STAGE(bufoff, gbase, voff) do { _Pragma("unroll") for (int _i = 0; _i < 2; ++_i) \
;         __builtin_amdgcn_global_load_lds((const unsigned*)((const char*)(gbase) + (voff)[_i]), (LAS unsigned*)(lds + (bufoff) + ldsw + _i * 8192), 16, 0, 0); } while (0)
; #define PG8_LDA(dst, b, h) do { _Pragma("unroll") for (int m = 0; m < 4; ++m) _Pragma("unroll") for (int k = 0; k < 2; ++k) dst[m][k] = *(const LAS bf16x8*)(lds + PG8_SA(b, h) + aoff + m * 2048 + k * 1024); } while (0)
; #define PG8_LDB(dst, b, h) do { _Pragma("unroll") for (int n = 0; n < 2; ++n) _Pragma("unroll") for (int k = 0; k < 2; ++k) dst[n][k] = *(const LAS bf16x8*)(lds + PG8_SB(b, h) + boff + n * 2048 + k * 1024); } while (0)
; #define PG8_MMA(ai, bj, At, Bt) do { __builtin_amdgcn_s_setprio(1); _Pragma("unroll") for (int m = 0; m < 4; ++m) _Pragma("unroll") for (int n = 0; n < 2; ++n) _Pragma("unroll") for (int k = 0; k < 2; ++k) \
;         acc[ai][bj][m][n] = __builtin_amdgcn_mfma_f32_16x16x32_bf16(Bt[n][k], At[m][k], acc[ai][bj][m][n], 0, 0, 0); __builtin_amdgcn_s_setprio(0); } while (0)
; #define PG8_WAIT_V(n) asm volatile("s_waitcnt vmcnt(" #n ")" ::: "memory")
; #define PG8_WAIT_L(n) asm volatile("s_waitcnt lgkmcnt(" #n ")" ::: "memory")
; #define PG8_BAR __builtin_amdgcn_s_barrier()
; #define PG8_SCHED __builtin_amdgcn_sched_barrier(0)
; template <class Epi, class Sched>
; DI void gemm_phase(LAS unsigned char* lds, const Gemm g, const Sched& S, const Epi& E) {
;     ...
;             PG8_WAIT_V(6); PG8_BAR; PG8_MMA(1, 1, At, B1); PG8_BAR;
;             PG8_LDB(B0, 1, 0); PG8_SCHED; PG8_LDA(At, 1, 0); PG8_STAGE(PG8_SA(0, 1), a2 + hstep, voffA);
;             PG8_WAIT_L(8); PG8_BAR; PG8_WAIT_L(0); PG8_MMA(0, 0, At, B0); PG8_BAR; PG8_SCHED;
;             PG8_LDB(B1, 1, 1); PG8_STAGE(PG8_SB(1, 0), b3, voffB);
	s_setprio 1
	v_mfma_f32_16x16x32_bf16 v[44:47], v[218:221], v[166:169], v[44:47]
	v_mfma_f32_16x16x32_bf16 v[36:39], v[226:229], v[166:169], v[36:39]
	v_mfma_f32_16x16x32_bf16 v[28:31], v[218:221], v[174:177], v[28:31]
	v_mfma_f32_16x16x32_bf16 v[20:23], v[226:229], v[174:177], v[20:23]
	v_mfma_f32_16x16x32_bf16 v[12:15], v[218:221], v[188:191], v[12:15]
	v_mfma_f32_16x16x32_bf16 v[8:11], v[226:229], v[188:191], v[8:11]
	v_mfma_f32_16x16x32_bf16 v[4:7], v[218:221], v[210:213], v[4:7]
	v_mfma_f32_16x16x32_bf16 v[0:3], v[226:229], v[210:213], v[0:3]
	v_mfma_f32_16x16x32_bf16 v[44:47], v[222:225], v[170:173], v[44:47]
	v_mfma_f32_16x16x32_bf16 v[36:39], v[230:233], v[170:173], v[36:39]
	v_mfma_f32_16x16x32_bf16 v[28:31], v[222:225], v[178:181], v[28:31]
	v_mfma_f32_16x16x32_bf16 v[20:23], v[230:233], v[178:181], v[20:23]
	v_mfma_f32_16x16x32_bf16 v[12:15], v[222:225], v[206:209], v[12:15]
	v_mfma_f32_16x16x32_bf16 v[8:11], v[230:233], v[206:209], v[8:11]
	v_mfma_f32_16x16x32_bf16 v[4:7], v[222:225], v[214:217], v[4:7]
	v_mfma_f32_16x16x32_bf16 v[0:3], v[230:233], v[214:217], v[0:3]
	s_setprio 0
	s_barrier
	ds_read_b128 v[146:149], v144
	ds_read_b128 v[154:157], v144 offset:1024
	ds_read_b128 v[158:161], v144 offset:2048
	ds_read_b128 v[162:165], v144 offset:3072
	s_add_u32 s0, s36, 0x160000
	s_addc_u32 s1, s37, 0
	s_mov_b32 m0, s42
	ds_read_b128 v[166:169], v142 offset:32768
	ds_read_b128 v[170:173], v142 offset:33792
	ds_read_b128 v[174:177], v142 offset:34816
	ds_read_b128 v[178:181], v142 offset:35840
	ds_read_b128 v[188:191], v142 offset:36864
	ds_read_b128 v[206:209], v142 offset:37888
	ds_read_b128 v[210:213], v142 offset:38912
	global_load_lds_dwordx4 v130, s[0:1]
	s_mov_b32 m0, s43
	ds_read_b128 v[214:217], v142 offset:39936
	global_load_lds_dwordx4 v128, s[0:1]
	s_waitcnt lgkmcnt(8)
	s_barrier
	s_waitcnt lgkmcnt(0)
	s_setprio 1
	v_mfma_f32_16x16x32_bf16 v[124:127], v[146:149], v[166:169], v[124:127]
	v_mfma_f32_16x16x32_bf16 v[120:123], v[158:161], v[166:169], v[120:123]
	v_mfma_f32_16x16x32_bf16 v[116:119], v[146:149], v[174:177], v[116:119]
	v_mfma_f32_16x16x32_bf16 v[112:115], v[158:161], v[174:177], v[112:115]
	v_mfma_f32_16x16x32_bf16 v[104:107], v[146:149], v[188:191], v[104:107]
	v_mfma_f32_16x16x32_bf16 v[96:99], v[158:161], v[188:191], v[96:99]
	v_mfma_f32_16x16x32_bf16 v[88:91], v[146:149], v[210:213], v[88:91]
	v_mfma_f32_16x16x32_bf16 v[80:83], v[158:161], v[210:213], v[80:83]
	v_mfma_f32_16x16x32_bf16 v[124:127], v[154:157], v[170:173], v[124:127]
	v_mfma_f32_16x16x32_bf16 v[120:123], v[162:165], v[170:173], v[120:123]
	v_mfma_f32_16x16x32_bf16 v[116:119], v[154:157], v[178:181], v[116:119]
	v_mfma_f32_16x16x32_bf16 v[112:115], v[162:165], v[178:181], v[112:115]
	v_mfma_f32_16x16x32_bf16 v[104:107], v[154:157], v[206:209], v[104:107]
	v_mfma_f32_16x16x32_bf16 v[96:99], v[162:165], v[206:209], v[96:99]
	v_mfma_f32_16x16x32_bf16 v[88:91], v[154:157], v[214:217], v[88:91]
	v_mfma_f32_16x16x32_bf16 v[80:83], v[162:165], v[214:217], v[80:83]
	s_setprio 0
	s_barrier
	s_add_i32 s4, 0, 0x1c000
	s_add_i32 s0, s62, s35
	v_add_u32_e32 v145, s4, v140
	s_add_i32 m0, s0, 0xffffff80
	ds_read_b128 v[218:221], v145
	ds_read_b128 v[222:225], v145 offset:1024
	ds_read_b128 v[226:229], v145 offset:2048
	global_load_lds_dwordx4 v130, s[30:31] offset:128
	s_add_i32 m0, s0, 0x1f80
	ds_read_b128 v[230:233], v145 offset:3072
	global_load_lds_dwordx4 v128, s[30:31] offset:128
	s_barrier
; #define PG8_STAGE(bufoff, gbase, voff) do { _Pragma("unroll") for (int _i = 0; _i < 2; ++_i) \
;         __builtin_amdgcn_global_load_lds((const unsigned*)((const char*)(gbase) + (voff)[_i]), (LAS unsigned*)(lds + (bufoff) + ldsw + _i * 8192), 16, 0, 0); } while (0)
; #define PG8_LDA(dst, b, h) do { _Pragma("unroll") for (int m = 0; m < 4; ++m) _Pragma("unroll") for (int k = 0; k < 2; ++k) dst[m][k] = *(const LAS bf16x8*)(lds + PG8_SA(b, h) + aoff + m * 2048 + k * 1024); } while (0)
; #define PG8_MMA(ai, bj, At, Bt) do { __builtin_amdgcn_s_setprio(1); _Pragma("unroll") for (int m = 0; m < 4; ++m) _Pragma("unroll") for (int n = 0; n < 2; ++n) _Pragma("unroll") for (int k = 0; k < 2; ++k) \
;         acc[ai][bj][m][n] = __builtin_amdgcn_mfma_f32_16x16x32_bf16(Bt[n][k], At[m][k], acc[ai][bj][m][n], 0, 0, 0); __builtin_amdgcn_s_setprio(0); } while (0)
; #define PG8_WAIT_V(n) asm volatile("s_waitcnt vmcnt(" #n ")" ::: "memory")
; #define PG8_WAIT_L(n) asm volatile("s_waitcnt lgkmcnt(" #n ")" ::: "memory")
; #define PG8_BAR __builtin_amdgcn_s_barrier()
; #define PG8_SCHED __builtin_amdgcn_sched_barrier(0)
; template <class Epi, class Sched>
; DI void gemm_phase(LAS unsigned char* lds, const Gemm g, const Sched& S, const Epi& E) {
;     ...
;         for (int t = 0; t < nt; t += 2) {
;     ...
;             PG8_BAR; PG8_WAIT_L(0); PG8_MMA(0, 1, At, B1); PG8_BAR;
;             PG8_LDA(At, 1, 1); PG8_STAGE(PG8_SA(1, 0), a3, voffA);
;             PG8_BAR; PG8_WAIT_L(0); PG8_MMA(1, 0, At, B0); PG8_BAR; PG8_SCHED;
;             PG8_STAGE(PG8_SB(1, 1), b3 + hstep, voffB);
;             PG8_WAIT_V(6); PG8_BAR; PG8_MMA(1, 1, At, B1); PG8_BAR;
	s_waitcnt lgkmcnt(0)
	s_setprio 1
	v_mfma_f32_16x16x32_bf16 v[108:111], v[218:221], v[166:169], v[108:111]
	v_mfma_f32_16x16x32_bf16 v[100:103], v[226:229], v[166:169], v[100:103]
	v_mfma_f32_16x16x32_bf16 v[92:95], v[218:221], v[174:177], v[92:95]
	v_mfma_f32_16x16x32_bf16 v[84:87], v[226:229], v[174:177], v[84:87]
	v_mfma_f32_16x16x32_bf16 v[76:79], v[218:221], v[188:191], v[76:79]
	v_mfma_f32_16x16x32_bf16 v[72:75], v[226:229], v[188:191], v[72:75]
	v_mfma_f32_16x16x32_bf16 v[68:71], v[218:221], v[210:213], v[68:71]
	v_mfma_f32_16x16x32_bf16 v[64:67], v[226:229], v[210:213], v[64:67]
	v_mfma_f32_16x16x32_bf16 v[108:111], v[222:225], v[170:173], v[108:111]
	v_mfma_f32_16x16x32_bf16 v[100:103], v[230:233], v[170:173], v[100:103]
	v_mfma_f32_16x16x32_bf16 v[92:95], v[222:225], v[178:181], v[92:95]
	v_mfma_f32_16x16x32_bf16 v[84:87], v[230:233], v[178:181], v[84:87]
	v_mfma_f32_16x16x32_bf16 v[76:79], v[222:225], v[206:209], v[76:79]
	v_mfma_f32_16x16x32_bf16 v[72:75], v[230:233], v[206:209], v[72:75]
	v_mfma_f32_16x16x32_bf16 v[68:71], v[222:225], v[214:217], v[68:71]
	v_mfma_f32_16x16x32_bf16 v[64:67], v[230:233], v[214:217], v[64:67]
	s_setprio 0
	s_add_i32 m0, s54, 0xffffff80
	s_barrier
	ds_read_b128 v[166:169], v142 offset:49152
	ds_read_b128 v[170:173], v142 offset:50176
	ds_read_b128 v[174:177], v142 offset:51200
	ds_read_b128 v[178:181], v142 offset:52224
	ds_read_b128 v[188:191], v142 offset:53248
	ds_read_b128 v[206:209], v142 offset:54272
	ds_read_b128 v[210:213], v142 offset:55296
	global_load_lds_dwordx4 v130, s[36:37] offset:128
	s_add_i32 m0, s55, 0xffffff80
	ds_read_b128 v[214:217], v142 offset:56320
	global_load_lds_dwordx4 v128, s[36:37] offset:128
	s_barrier
	s_waitcnt lgkmcnt(0)
	s_setprio 1
	v_mfma_f32_16x16x32_bf16 v[60:63], v[146:149], v[166:169], v[60:63]
	v_mfma_f32_16x16x32_bf16 v[56:59], v[158:161], v[166:169], v[56:59]
	v_mfma_f32_16x16x32_bf16 v[52:55], v[146:149], v[174:177], v[52:55]
	v_mfma_f32_16x16x32_bf16 v[48:51], v[158:161], v[174:177], v[48:51]
	v_mfma_f32_16x16x32_bf16 v[40:43], v[146:149], v[188:191], v[40:43]
	v_mfma_f32_16x16x32_bf16 v[32:35], v[158:161], v[188:191], v[32:35]
	v_mfma_f32_16x16x32_bf16 v[24:27], v[146:149], v[210:213], v[24:27]
	v_mfma_f32_16x16x32_bf16 v[16:19], v[158:161], v[210:213], v[16:19]
	v_mfma_f32_16x16x32_bf16 v[60:63], v[154:157], v[170:173], v[60:63]
	v_mfma_f32_16x16x32_bf16 v[56:59], v[162:165], v[170:173], v[56:59]
	v_mfma_f32_16x16x32_bf16 v[52:55], v[154:157], v[178:181], v[52:55]
	v_mfma_f32_16x16x32_bf16 v[48:51], v[162:165], v[178:181], v[48:51]
	v_mfma_f32_16x16x32_bf16 v[40:43], v[154:157], v[206:209], v[40:43]
	v_mfma_f32_16x16x32_bf16 v[32:35], v[162:165], v[206:209], v[32:35]
	v_mfma_f32_16x16x32_bf16 v[24:27], v[154:157], v[214:217], v[24:27]
	v_mfma_f32_16x16x32_bf16 v[16:19], v[162:165], v[214:217], v[16:19]
	s_setprio 0
	s_barrier
	s_add_i32 s4, s4, s35
	s_mov_b32 m0, s4
	s_add_u32 s0, s30, 0x160080
	s_addc_u32 s1, s31, 0
	global_load_lds_dwordx4 v130, s[0:1]
	s_add_i32 m0, s4, 0x2000
	s_add_i32 s66, s66, 2
	global_load_lds_dwordx4 v128, s[0:1]
	s_add_u32 s8, s8, 0x100
	s_addc_u32 s9, s9, 0
	s_add_u32 s64, s64, 0x100
	s_addc_u32 s65, s65, 0
	s_cmp_gt_u32 s66, 5
	s_waitcnt vmcnt(6)
	s_barrier
	s_setprio 1
	v_mfma_f32_16x16x32_bf16 v[44:47], v[218:221], v[166:169], v[44:47]
	v_mfma_f32_16x16x32_bf16 v[36:39], v[226:229], v[166:169], v[36:39]
	v_mfma_f32_16x16x32_bf16 v[28:31], v[218:221], v[174:177], v[28:31]
	v_mfma_f32_16x16x32_bf16 v[20:23], v[226:229], v[174:177], v[20:23]
	v_mfma_f32_16x16x32_bf16 v[12:15], v[218:221], v[188:191], v[12:15]
	v_mfma_f32_16x16x32_bf16 v[8:11], v[226:229], v[188:191], v[8:11]
	v_mfma_f32_16x16x32_bf16 v[4:7], v[218:221], v[210:213], v[4:7]
	v_mfma_f32_16x16x32_bf16 v[0:3], v[226:229], v[210:213], v[0:3]
	v_mfma_f32_16x16x32_bf16 v[44:47], v[222:225], v[170:173], v[44:47]
	v_mfma_f32_16x16x32_bf16 v[36:39], v[230:233], v[170:173], v[36:39]
	v_mfma_f32_16x16x32_bf16 v[28:31], v[222:225], v[178:181], v[28:31]
	v_mfma_f32_16x16x32_bf16 v[20:23], v[230:233], v[178:181], v[20:23]
	v_mfma_f32_16x16x32_bf16 v[12:15], v[222:225], v[206:209], v[12:15]
	v_mfma_f32_16x16x32_bf16 v[8:11], v[230:233], v[206:209], v[8:11]
	v_mfma_f32_16x16x32_bf16 v[4:7], v[222:225], v[214:217], v[4:7]
	v_mfma_f32_16x16x32_bf16 v[0:3], v[230:233], v[214:217], v[0:3]
	s_setprio 0
	s_cbranch_scc0 .Lrot_1775
	s_barrier

; #define PG8_STAGE(bufoff, gbase, voff) do { _Pragma("unroll") for (int _i = 0; _i < 2; ++_i) \
;         __builtin_amdgcn_global_load_lds((const unsigned*)((const char*)(gbase) + (voff)[_i]), (LAS unsigned*)(lds + (bufoff) + ldsw + _i * 8192), 16, 0, 0); } while (0)
; #define PG8_LDA(dst, b, h) do { _Pragma("unroll") for (int m = 0; m < 4; ++m) _Pragma("unroll") for (int k = 0; k < 2; ++k) dst[m][k] = *(const LAS bf16x8*)(lds + PG8_SA(b, h) + aoff + m * 2048 + k * 1024); } while (0)
; #define PG8_LDB(dst, b, h) do { _Pragma("unroll") for (int n = 0; n < 2; ++n) _Pragma("unroll") for (int k = 0; k < 2; ++k) dst[n][k] = *(const LAS bf16x8*)(lds + PG8_SB(b, h) + boff + n * 2048 + k * 1024); } while (0)
; #define PG8_MMA(ai, bj, At, Bt) do { __builtin_amdgcn_s_setprio(1); _Pragma("unroll") for (int m = 0; m < 4; ++m) _Pragma("unroll") for (int n = 0; n < 2; ++n) _Pragma("unroll") for (int k = 0; k < 2; ++k) \
;         acc[ai][bj][m][n] = __builtin_amdgcn_mfma_f32_16x16x32_bf16(Bt[n][k], At[m][k], acc[ai][bj][m][n], 0, 0, 0); __builtin_amdgcn_s_setprio(0); } while (0)
; #define PG8_WAIT_V(n) asm volatile("s_waitcnt vmcnt(" #n ")" ::: "memory")
; #define PG8_WAIT_L(n) asm volatile("s_waitcnt lgkmcnt(" #n ")" ::: "memory")
; #define PG8_BAR __builtin_amdgcn_s_barrier()
; #define PG8_SCHED __builtin_amdgcn_sched_barrier(0)
; template <class Epi, class Sched>
; DI void gemm_phase(LAS unsigned char* lds, const Gemm g, const Sched& S, const Epi& E) {
;     ...
;             const bool last = (t == nt - 2);
;             const char* a1 = cA + (size_t)(t + 1) * kstep;
;             const char* a2 = last ? nA : cA + (size_t)(t + 2) * kstep; const char* b2 = last ? nB : cB + (size_t)(t + 2) * kstep;
;             const char* a3 = a2 + kstep; const char* b3 = b2 + kstep;
;             PG8_LDB(B0, 0, 0); PG8_SCHED; PG8_LDA(At, 0, 0); PG8_STAGE(PG8_SA(1, 1), a1 + hstep, voffA);
;             PG8_WAIT_L(8); PG8_BAR; PG8_WAIT_L(0); PG8_MMA(0, 0, At, B0); PG8_BAR; PG8_SCHED;
;             PG8_LDB(B1, 0, 1); PG8_STAGE(PG8_SB(0, 0), b2, voffB);
;             PG8_BAR; PG8_WAIT_L(0); PG8_MMA(0, 1, At, B1); PG8_BAR;
;             PG8_LDA(At, 0, 1); PG8_STAGE(PG8_SA(0, 0), a2, voffA);
;             PG8_BAR; PG8_WAIT_L(0); PG8_MMA(1, 0, At, B0); PG8_BAR; PG8_SCHED;
;             PG8_STAGE(PG8_SB(0, 1), b2 + hstep, voffB);
;             PG8_WAIT_V(6); PG8_BAR; PG8_MMA(1, 1, At, B1); PG8_BAR;
.LBB0_1920:
	v_add_u32_e32 v161, s62, v157
	s_add_u32 s0, s38, s8
	ds_read_b128 v[148:151], v161
	ds_read_b128 v[162:165], v161 offset:1024
	ds_read_b128 v[166:169], v161 offset:2048
	ds_read_b128 v[170:173], v161 offset:3072
	s_addc_u32 s1, s39, s9
	s_add_u32 s0, s0, 0x100
	s_addc_u32 s1, s1, 0
	s_add_u32 s4, s68, s8
	s_addc_u32 s5, s69, s9
	s_cmpk_eq_i32 s8, 0x1100
	s_cselect_b32 s43, s37, s1
	s_cselect_b32 s42, s36, s0
	s_cselect_b32 s41, s11, s5
	s_cselect_b32 s40, s10, s4
	v_lshl_add_u64 v[182:183], v[144:145], 0, s[8:9]
	s_add_i32 m0, s53, 0xc000
	ds_read_b128 v[174:177], v158
	ds_read_b128 v[178:181], v158 offset:1024
	ds_read_b128 v[188:191], v158 offset:2048
	ds_read_b128 v[196:199], v158 offset:3072
	ds_read_b128 v[200:203], v158 offset:4096
	ds_read_b128 v[206:209], v158 offset:5120
	ds_read_b128 v[210:213], v158 offset:6144
	ds_read_b128 v[214:217], v158 offset:7168
	global_load_lds_dwordx4 v[182:183], off
	v_lshl_add_u64 v[182:183], v[146:147], 0, s[8:9]
	s_add_i32 m0, s53, 0xe000
	s_nop 0
	global_load_lds_dwordx4 v[182:183], off
	s_waitcnt lgkmcnt(8)
	s_barrier
	s_waitcnt lgkmcnt(0)
	s_setprio 1
	v_mfma_f32_16x16x32_bf16 v[124:127], v[148:151], v[174:177], v[124:127]
	v_mfma_f32_16x16x32_bf16 v[120:123], v[166:169], v[174:177], v[120:123]
	v_mfma_f32_16x16x32_bf16 v[108:111], v[148:151], v[188:191], v[108:111]
	v_mfma_f32_16x16x32_bf16 v[104:107], v[166:169], v[188:191], v[104:107]
	v_mfma_f32_16x16x32_bf16 v[92:95], v[148:151], v[200:203], v[92:95]
	v_mfma_f32_16x16x32_bf16 v[88:91], v[166:169], v[200:203], v[88:91]
	v_mfma_f32_16x16x32_bf16 v[76:79], v[148:151], v[210:213], v[76:79]
	v_mfma_f32_16x16x32_bf16 v[72:75], v[166:169], v[210:213], v[72:75]
	v_mfma_f32_16x16x32_bf16 v[124:127], v[162:165], v[178:181], v[124:127]
	v_mfma_f32_16x16x32_bf16 v[120:123], v[170:173], v[178:181], v[120:123]
	v_mfma_f32_16x16x32_bf16 v[108:111], v[162:165], v[196:199], v[108:111]
	v_mfma_f32_16x16x32_bf16 v[104:107], v[170:173], v[196:199], v[104:107]
	v_mfma_f32_16x16x32_bf16 v[92:95], v[162:165], v[206:209], v[92:95]
	v_mfma_f32_16x16x32_bf16 v[88:91], v[170:173], v[206:209], v[88:91]
	v_mfma_f32_16x16x32_bf16 v[76:79], v[162:165], v[214:217], v[76:79]
	v_mfma_f32_16x16x32_bf16 v[72:75], v[170:173], v[214:217], v[72:75]
	s_setprio 0
	s_barrier
	s_add_i32 s0, s62, s52
	v_add_u32_e32 v161, s63, v157
	s_mov_b32 m0, s0
	ds_read_b128 v[218:221], v161
	ds_read_b128 v[222:225], v161 offset:1024
	ds_read_b128 v[226:229], v161 offset:2048
	global_load_lds_dwordx4 v130, s[40:41]
	s_add_i32 m0, s0, 0x2000
	ds_read_b128 v[230:233], v161 offset:3072
	global_load_lds_dwordx4 v134, s[40:41]
	s_barrier
	s_waitcnt lgkmcnt(0)
	s_setprio 1
	v_mfma_f32_16x16x32_bf16 v[116:119], v[218:221], v[174:177], v[116:119]
	v_mfma_f32_16x16x32_bf16 v[112:115], v[226:229], v[174:177], v[112:115]
	v_mfma_f32_16x16x32_bf16 v[100:103], v[218:221], v[188:191], v[100:103]
	v_mfma_f32_16x16x32_bf16 v[96:99], v[226:229], v[188:191], v[96:99]
	v_mfma_f32_16x16x32_bf16 v[84:87], v[218:221], v[200:203], v[84:87]
	v_mfma_f32_16x16x32_bf16 v[80:83], v[226:229], v[200:203], v[80:83]
	v_mfma_f32_16x16x32_bf16 v[68:71], v[218:221], v[210:213], v[68:71]
	v_mfma_f32_16x16x32_bf16 v[64:67], v[226:229], v[210:213], v[64:67]
	v_mfma_f32_16x16x32_bf16 v[116:119], v[222:225], v[178:181], v[116:119]
	v_mfma_f32_16x16x32_bf16 v[112:115], v[230:233], v[178:181], v[112:115]
	v_mfma_f32_16x16x32_bf16 v[100:103], v[222:225], v[196:199], v[100:103]
	v_mfma_f32_16x16x32_bf16 v[96:99], v[230:233], v[196:199], v[96:99]
	v_mfma_f32_16x16x32_bf16 v[84:87], v[222:225], v[206:209], v[84:87]
	v_mfma_f32_16x16x32_bf16 v[80:83], v[230:233], v[206:209], v[80:83]
	v_mfma_f32_16x16x32_bf16 v[68:71], v[222:225], v[214:217], v[68:71]
	v_mfma_f32_16x16x32_bf16 v[64:67], v[230:233], v[214:217], v[64:67]
	s_setprio 0
	s_mov_b32 m0, s53
	s_barrier
	ds_read_b128 v[174:177], v158 offset:16384
	ds_read_b128 v[178:181], v158 offset:17408
	ds_read_b128 v[188:191], v158 offset:18432
	ds_read_b128 v[196:199], v158 offset:19456
	ds_read_b128 v[200:203], v158 offset:20480
	ds_read_b128 v[206:209], v158 offset:21504
	ds_read_b128 v[210:213], v158 offset:22528
	global_load_lds_dwordx4 v128, s[42:43]
	s_mov_b32 m0, s54
	ds_read_b128 v[214:217], v158 offset:23552
	global_load_lds_dwordx4 v132, s[42:43]
	s_barrier
	s_waitcnt lgkmcnt(0)
	s_setprio 1
	v_mfma_f32_16x16x32_bf16 v[60:63], v[148:151], v[174:177], v[60:63]
	v_mfma_f32_16x16x32_bf16 v[56:59], v[166:169], v[174:177], v[56:59]
	v_mfma_f32_16x16x32_bf16 v[44:47], v[148:151], v[188:191], v[44:47]
	v_mfma_f32_16x16x32_bf16 v[40:43], v[166:169], v[188:191], v[40:43]
	v_mfma_f32_16x16x32_bf16 v[28:31], v[148:151], v[200:203], v[28:31]
	v_mfma_f32_16x16x32_bf16 v[24:27], v[166:169], v[200:203], v[24:27]
	v_mfma_f32_16x16x32_bf16 v[12:15], v[148:151], v[210:213], v[12:15]
	v_mfma_f32_16x16x32_bf16 v[8:11], v[166:169], v[210:213], v[8:11]
	v_mfma_f32_16x16x32_bf16 v[60:63], v[162:165], v[178:181], v[60:63]
	v_mfma_f32_16x16x32_bf16 v[56:59], v[170:173], v[178:181], v[56:59]
	v_mfma_f32_16x16x32_bf16 v[44:47], v[162:165], v[196:199], v[44:47]
	v_mfma_f32_16x16x32_bf16 v[40:43], v[170:173], v[196:199], v[40:43]
	v_mfma_f32_16x16x32_bf16 v[28:31], v[162:165], v[206:209], v[28:31]
	v_mfma_f32_16x16x32_bf16 v[24:27], v[170:173], v[206:209], v[24:27]
	v_mfma_f32_16x16x32_bf16 v[12:15], v[162:165], v[214:217], v[12:15]
	v_mfma_f32_16x16x32_bf16 v[8:11], v[170:173], v[214:217], v[8:11]
	s_setprio 0
	s_barrier
	s_add_i32 s4, s63, s52
	s_mov_b32 m0, s4
	s_add_u32 s0, s40, 0x90000
	s_addc_u32 s1, s41, 0
	global_load_lds_dwordx4 v130, s[0:1]
	s_add_i32 m0, s4, 0x2000
	s_add_i32 s4, 0, 0x18000
	global_load_lds_dwordx4 v134, s[0:1]
	s_waitcnt vmcnt(6)
	s_barrier
; #define PG8_STAGE(bufoff, gbase, voff) do { _Pragma("unroll") for (int _i = 0; _i < 2; ++_i) \
;         __builtin_amdgcn_global_load_lds((const unsigned*)((const char*)(gbase) + (voff)[_i]), (LAS unsigned*)(lds + (bufoff) + ldsw + _i * 8192), 16, 0, 0); } while (0)
; #define PG8_LDA(dst, b, h) do { _Pragma("unroll") for (int m = 0; m < 4; ++m) _Pragma("unroll") for (int k = 0; k < 2; ++k) dst[m][k] = *(const LAS bf16x8*)(lds + PG8_SA(b, h) + aoff + m * 2048 + k * 1024); } while (0)
; #define PG8_LDB(dst, b, h) do { _Pragma("unroll") for (int n = 0; n < 2; ++n) _Pragma("unroll") for (int k = 0; k < 2; ++k) dst[n][k] = *(const LAS bf16x8*)(lds + PG8_SB(b, h) + boff + n * 2048 + k * 1024); } while (0)
; #define PG8_MMA(ai, bj, At, Bt) do { __builtin_amdgcn_s_setprio(1); _Pragma("unroll") for (int m = 0; m < 4; ++m) _Pragma("unroll") for (int n = 0; n < 2; ++n) _Pragma("unroll") for (int k = 0; k < 2; ++k) \
;         acc[ai][bj][m][n] = __builtin_amdgcn_mfma_f32_16x16x32_bf16(Bt[n][k], At[m][k], acc[ai][bj][m][n], 0, 0, 0); __builtin_amdgcn_s_setprio(0); } while (0)
; #define PG8_WAIT_V(n) asm volatile("s_waitcnt vmcnt(" #n ")" ::: "memory")
; #define PG8_WAIT_L(n) asm volatile("s_waitcnt lgkmcnt(" #n ")" ::: "memory")
; #define PG8_BAR __builtin_amdgcn_s_barrier()
; #define PG8_SCHED __builtin_amdgcn_sched_barrier(0)
; template <class Epi, class Sched>
; DI void gemm_phase(LAS unsigned char* lds, const Gemm g, const Sched& S, const Epi& E) {
;     ...
;             PG8_WAIT_V(6); PG8_BAR; PG8_MMA(1, 1, At, B1); PG8_BAR;
;             PG8_LDB(B0, 1, 0); PG8_SCHED; PG8_LDA(At, 1, 0); PG8_STAGE(PG8_SA(0, 1), a2 + hstep, voffA);
;             PG8_WAIT_L(8); PG8_BAR; PG8_WAIT_L(0); PG8_MMA(0, 0, At, B0); PG8_BAR; PG8_SCHED;
;             PG8_LDB(B1, 1, 1); PG8_STAGE(PG8_SB(1, 0), b3, voffB);
;             PG8_BAR; PG8_WAIT_L(0); PG8_MMA(0, 1, At, B1); PG8_BAR;
;             PG8_LDA(At, 1, 1); PG8_STAGE(PG8_SA(1, 0), a3, voffA);
	s_setprio 1
	v_mfma_f32_16x16x32_bf16 v[52:55], v[218:221], v[174:177], v[52:55]
	v_mfma_f32_16x16x32_bf16 v[48:51], v[226:229], v[174:177], v[48:51]
	v_mfma_f32_16x16x32_bf16 v[36:39], v[218:221], v[188:191], v[36:39]
	v_mfma_f32_16x16x32_bf16 v[32:35], v[226:229], v[188:191], v[32:35]
	v_mfma_f32_16x16x32_bf16 v[20:23], v[218:221], v[200:203], v[20:23]
	v_mfma_f32_16x16x32_bf16 v[16:19], v[226:229], v[200:203], v[16:19]
	v_mfma_f32_16x16x32_bf16 v[4:7], v[218:221], v[210:213], v[4:7]
	v_mfma_f32_16x16x32_bf16 v[0:3], v[226:229], v[210:213], v[0:3]
	v_mfma_f32_16x16x32_bf16 v[52:55], v[222:225], v[178:181], v[52:55]
	v_mfma_f32_16x16x32_bf16 v[48:51], v[230:233], v[178:181], v[48:51]
	v_mfma_f32_16x16x32_bf16 v[36:39], v[222:225], v[196:199], v[36:39]
	v_mfma_f32_16x16x32_bf16 v[32:35], v[230:233], v[196:199], v[32:35]
	v_mfma_f32_16x16x32_bf16 v[20:23], v[222:225], v[206:209], v[20:23]
	v_mfma_f32_16x16x32_bf16 v[16:19], v[230:233], v[206:209], v[16:19]
	v_mfma_f32_16x16x32_bf16 v[4:7], v[222:225], v[214:217], v[4:7]
	v_mfma_f32_16x16x32_bf16 v[0:3], v[230:233], v[214:217], v[0:3]
	s_setprio 0
	v_add_u32_e32 v161, s4, v157
	s_barrier
	ds_read_b128 v[148:151], v161
	ds_read_b128 v[162:165], v161 offset:1024
	ds_read_b128 v[166:169], v161 offset:2048
	ds_read_b128 v[170:173], v161 offset:3072
	s_add_u32 s0, s42, 0x90000
	s_addc_u32 s1, s43, 0
	s_mov_b32 m0, s55
	ds_read_b128 v[174:177], v158 offset:32768
	ds_read_b128 v[178:181], v158 offset:33792
	ds_read_b128 v[188:191], v158 offset:34816
	ds_read_b128 v[196:199], v158 offset:35840
	ds_read_b128 v[200:203], v158 offset:36864
	ds_read_b128 v[206:209], v158 offset:37888
	ds_read_b128 v[210:213], v158 offset:38912
	global_load_lds_dwordx4 v128, s[0:1]
	s_mov_b32 m0, s56
	ds_read_b128 v[214:217], v158 offset:39936
	global_load_lds_dwordx4 v132, s[0:1]
	s_waitcnt lgkmcnt(8)
	s_barrier
	s_waitcnt lgkmcnt(0)
	s_setprio 1
	v_mfma_f32_16x16x32_bf16 v[124:127], v[148:151], v[174:177], v[124:127]
	v_mfma_f32_16x16x32_bf16 v[120:123], v[166:169], v[174:177], v[120:123]
	v_mfma_f32_16x16x32_bf16 v[108:111], v[148:151], v[188:191], v[108:111]
	v_mfma_f32_16x16x32_bf16 v[104:107], v[166:169], v[188:191], v[104:107]
	v_mfma_f32_16x16x32_bf16 v[92:95], v[148:151], v[200:203], v[92:95]
	v_mfma_f32_16x16x32_bf16 v[88:91], v[166:169], v[200:203], v[88:91]
	v_mfma_f32_16x16x32_bf16 v[76:79], v[148:151], v[210:213], v[76:79]
	v_mfma_f32_16x16x32_bf16 v[72:75], v[166:169], v[210:213], v[72:75]
	v_mfma_f32_16x16x32_bf16 v[124:127], v[162:165], v[178:181], v[124:127]
	v_mfma_f32_16x16x32_bf16 v[120:123], v[170:173], v[178:181], v[120:123]
	v_mfma_f32_16x16x32_bf16 v[108:111], v[162:165], v[196:199], v[108:111]
	v_mfma_f32_16x16x32_bf16 v[104:107], v[170:173], v[196:199], v[104:107]
	v_mfma_f32_16x16x32_bf16 v[92:95], v[162:165], v[206:209], v[92:95]
	v_mfma_f32_16x16x32_bf16 v[88:91], v[170:173], v[206:209], v[88:91]
	v_mfma_f32_16x16x32_bf16 v[76:79], v[162:165], v[214:217], v[76:79]
	v_mfma_f32_16x16x32_bf16 v[72:75], v[170:173], v[214:217], v[72:75]
	s_setprio 0
	s_barrier
	s_add_i32 s5, 0, 0x1c000
	s_add_i32 s0, s4, s52
	v_add_u32_e32 v161, s5, v157
	s_add_i32 m0, s0, 0xffffff80
	ds_read_b128 v[218:221], v161
	ds_read_b128 v[222:225], v161 offset:1024
	ds_read_b128 v[226:229], v161 offset:2048
	global_load_lds_dwordx4 v130, s[40:41] offset:128
	s_add_i32 m0, s0, 0x1f80
	ds_read_b128 v[230:233], v161 offset:3072
	global_load_lds_dwordx4 v134, s[40:41] offset:128
	s_barrier
; #define PG8_STAGE(bufoff, gbase, voff) do { _Pragma("unroll") for (int _i = 0; _i < 2; ++_i) \
;         __builtin_amdgcn_global_load_lds((const unsigned*)((const char*)(gbase) + (voff)[_i]), (LAS unsigned*)(lds + (bufoff) + ldsw + _i * 8192), 16, 0, 0); } while (0)
; #define PG8_MMA(ai, bj, At, Bt) do { __builtin_amdgcn_s_setprio(1); _Pragma("unroll") for (int m = 0; m < 4; ++m) _Pragma("unroll") for (int n = 0; n < 2; ++n) _Pragma("unroll") for (int k = 0; k < 2; ++k) \
;         acc[ai][bj][m][n] = __builtin_amdgcn_mfma_f32_16x16x32_bf16(Bt[n][k], At[m][k], acc[ai][bj][m][n], 0, 0, 0); __builtin_amdgcn_s_setprio(0); } while (0)
; #define PG8_WAIT_V(n) asm volatile("s_waitcnt vmcnt(" #n ")" ::: "memory")
; #define PG8_WAIT_L(n) asm volatile("s_waitcnt lgkmcnt(" #n ")" ::: "memory")
; #define PG8_BAR __builtin_amdgcn_s_barrier()
; #define PG8_SCHED __builtin_amdgcn_sched_barrier(0)
; template <class Epi, class Sched>
; DI void gemm_phase(LAS unsigned char* lds, const Gemm g, const Sched& S, const Epi& E) {
;     ...
;         for (int t = 0; t < nt; t += 2) {
;     ...
;             PG8_BAR; PG8_WAIT_L(0); PG8_MMA(1, 0, At, B0); PG8_BAR; PG8_SCHED;
;             PG8_STAGE(PG8_SB(1, 1), b3 + hstep, voffB);
;             PG8_WAIT_V(6); PG8_BAR; PG8_MMA(1, 1, At, B1); PG8_BAR;
	s_waitcnt lgkmcnt(0)
	s_setprio 1
	v_mfma_f32_16x16x32_bf16 v[116:119], v[218:221], v[174:177], v[116:119]
	v_mfma_f32_16x16x32_bf16 v[112:115], v[226:229], v[174:177], v[112:115]
	v_mfma_f32_16x16x32_bf16 v[100:103], v[218:221], v[188:191], v[100:103]
	v_mfma_f32_16x16x32_bf16 v[96:99], v[226:229], v[188:191], v[96:99]
	v_mfma_f32_16x16x32_bf16 v[84:87], v[218:221], v[200:203], v[84:87]
	v_mfma_f32_16x16x32_bf16 v[80:83], v[226:229], v[200:203], v[80:83]
	v_mfma_f32_16x16x32_bf16 v[68:71], v[218:221], v[210:213], v[68:71]
	v_mfma_f32_16x16x32_bf16 v[64:67], v[226:229], v[210:213], v[64:67]
	v_mfma_f32_16x16x32_bf16 v[116:119], v[222:225], v[178:181], v[116:119]
	v_mfma_f32_16x16x32_bf16 v[112:115], v[230:233], v[178:181], v[112:115]
	v_mfma_f32_16x16x32_bf16 v[100:103], v[222:225], v[196:199], v[100:103]
	v_mfma_f32_16x16x32_bf16 v[96:99], v[230:233], v[196:199], v[96:99]
	v_mfma_f32_16x16x32_bf16 v[84:87], v[222:225], v[206:209], v[84:87]
	v_mfma_f32_16x16x32_bf16 v[80:83], v[230:233], v[206:209], v[80:83]
	v_mfma_f32_16x16x32_bf16 v[68:71], v[222:225], v[214:217], v[68:71]
	v_mfma_f32_16x16x32_bf16 v[64:67], v[230:233], v[214:217], v[64:67]
	s_setprio 0
	s_add_i32 m0, s59, 0xffffff80
	s_barrier
	ds_read_b128 v[174:177], v158 offset:49152
	ds_read_b128 v[178:181], v158 offset:50176
	ds_read_b128 v[188:191], v158 offset:51200
	ds_read_b128 v[196:199], v158 offset:52224
	ds_read_b128 v[200:203], v158 offset:53248
	ds_read_b128 v[206:209], v158 offset:54272
	ds_read_b128 v[210:213], v158 offset:55296
	global_load_lds_dwordx4 v128, s[42:43] offset:128
	s_add_i32 m0, s60, 0xffffff80
	ds_read_b128 v[214:217], v158 offset:56320
	global_load_lds_dwordx4 v132, s[42:43] offset:128
	s_barrier
	s_waitcnt lgkmcnt(0)
	s_setprio 1
	v_mfma_f32_16x16x32_bf16 v[60:63], v[148:151], v[174:177], v[60:63]
	v_mfma_f32_16x16x32_bf16 v[56:59], v[166:169], v[174:177], v[56:59]
	v_mfma_f32_16x16x32_bf16 v[44:47], v[148:151], v[188:191], v[44:47]
	v_mfma_f32_16x16x32_bf16 v[40:43], v[166:169], v[188:191], v[40:43]
	v_mfma_f32_16x16x32_bf16 v[28:31], v[148:151], v[200:203], v[28:31]
	v_mfma_f32_16x16x32_bf16 v[24:27], v[166:169], v[200:203], v[24:27]
	v_mfma_f32_16x16x32_bf16 v[12:15], v[148:151], v[210:213], v[12:15]
	v_mfma_f32_16x16x32_bf16 v[8:11], v[166:169], v[210:213], v[8:11]
	v_mfma_f32_16x16x32_bf16 v[60:63], v[162:165], v[178:181], v[60:63]
	v_mfma_f32_16x16x32_bf16 v[56:59], v[170:173], v[178:181], v[56:59]
	v_mfma_f32_16x16x32_bf16 v[44:47], v[162:165], v[196:199], v[44:47]
	v_mfma_f32_16x16x32_bf16 v[40:43], v[170:173], v[196:199], v[40:43]
	v_mfma_f32_16x16x32_bf16 v[28:31], v[162:165], v[206:209], v[28:31]
	v_mfma_f32_16x16x32_bf16 v[24:27], v[170:173], v[206:209], v[24:27]
	v_mfma_f32_16x16x32_bf16 v[12:15], v[162:165], v[214:217], v[12:15]
	v_mfma_f32_16x16x32_bf16 v[8:11], v[170:173], v[214:217], v[8:11]
	s_setprio 0
	s_barrier
	s_add_i32 s4, s5, s52
	s_mov_b32 m0, s4
	s_add_u32 s0, s40, 0x90080
	s_addc_u32 s1, s41, 0
	global_load_lds_dwordx4 v130, s[0:1]
	s_add_i32 m0, s4, 0x2000
	s_nop 0
	global_load_lds_dwordx4 v134, s[0:1]
	s_waitcnt vmcnt(6)
	s_barrier
	s_setprio 1
	v_mfma_f32_16x16x32_bf16 v[52:55], v[218:221], v[174:177], v[52:55]
	v_mfma_f32_16x16x32_bf16 v[48:51], v[226:229], v[174:177], v[48:51]
	v_mfma_f32_16x16x32_bf16 v[36:39], v[218:221], v[188:191], v[36:39]
	v_mfma_f32_16x16x32_bf16 v[32:35], v[226:229], v[188:191], v[32:35]
	v_mfma_f32_16x16x32_bf16 v[20:23], v[218:221], v[200:203], v[20:23]
	v_mfma_f32_16x16x32_bf16 v[16:19], v[226:229], v[200:203], v[16:19]
	v_mfma_f32_16x16x32_bf16 v[4:7], v[218:221], v[210:213], v[4:7]
	v_mfma_f32_16x16x32_bf16 v[0:3], v[226:229], v[210:213], v[0:3]
	v_mfma_f32_16x16x32_bf16 v[52:55], v[222:225], v[178:181], v[52:55]
	v_mfma_f32_16x16x32_bf16 v[48:51], v[230:233], v[178:181], v[48:51]
	v_mfma_f32_16x16x32_bf16 v[36:39], v[222:225], v[196:199], v[36:39]
	v_mfma_f32_16x16x32_bf16 v[32:35], v[230:233], v[196:199], v[32:35]
	v_mfma_f32_16x16x32_bf16 v[20:23], v[222:225], v[206:209], v[20:23]
	v_mfma_f32_16x16x32_bf16 v[16:19], v[230:233], v[206:209], v[16:19]
	v_mfma_f32_16x16x32_bf16 v[4:7], v[222:225], v[214:217], v[4:7]
	v_mfma_f32_16x16x32_bf16 v[0:3], v[230:233], v[214:217], v[0:3]
	s_setprio 0
	s_add_i32 s70, s70, 2
	s_add_u32 s8, s8, 0x100
	s_addc_u32 s9, s9, 0
	s_cmp_gt_u32 s70, 33
	s_barrier
	s_cbranch_scc1 .LBB0_1908
